# all s_setprio flips removed from the GEMM K-loops (compute/load segments run at equal priority)
# speedup vs baseline: 1.0088x; 1.0060x over previous
; #define PG8_STAGE(bufoff, gbase, voff) do { _Pragma("unroll") for (int _i = 0; _i < 2; ++_i) \
;         __builtin_amdgcn_global_load_lds((const unsigned*)((const char*)(gbase) + (voff)[_i]), (PG8_LAS unsigned*)(lds + (bufoff) + ldsw + _i * 8192), 16, 0, 0); } while (0)
; #define PG8_LDA(dst, b, h) do { _Pragma("unroll") for (int m = 0; m < 4; ++m) _Pragma("unroll") for (int k = 0; k < 2; ++k) dst[m][k] = *(const PG8_LAS bf16x8*)(lds + PG8_SA(b, h) + aoff + m * 2048 + k * 1024); } while (0)
; #define PG8_LDB(dst, b, h) do { _Pragma("unroll") for (int n = 0; n < 2; ++n) _Pragma("unroll") for (int k = 0; k < 2; ++k) dst[n][k] = *(const PG8_LAS bf16x8*)(lds + PG8_SB(b, h) + boff + n * 2048 + k * 1024); } while (0)
; #define PG8_SCHED __builtin_amdgcn_sched_barrier(0)
; template <class Epi, class Sched, bool ALIGN_EPI = false, bool SP2 = false>
; __device__ __forceinline__ void gemm_phase(PG8_LAS unsigned char* lds, const Gemm g, const Sched& S, const Epi& E) {
;     ...
;         const bool has_next = S.next(ui + 1, nxt);
;         const char* nA = has_next ? (const char*)g.A + (size_t)nxt.pm * tstep : cA; const char* nB = has_next ? (const char*)g.Bt + (size_t)nxt.pn * tstep : cB;
; #pragma nounroll
;         for (int t = 0; t < nt; t += 2) {
;             const bool last = (t == nt - 2);
;             const char* a1 = cA + (size_t)(t + 1) * kstep;
;             const char* a2 = last ? nA : cA + (size_t)(t + 2) * kstep; const char* b2 = last ? nB : cB + (size_t)(t + 2) * kstep;
;             const char* a3 = a2 + kstep; const char* b3 = b2 + kstep;
;             if (last && has_next) S.a_ready(nxt);
;             if constexpr (SP2) {
;             PG8_LDB(B0, 0, 0); PG8_LDB(B1, 0, 1); PG8_SCHED; PG8_LDA(At, 0, 0); PG8_STAGE(PG8_SA(1, 1), a1 + hstep, voffA);
.LBB0_490:
	s_ashr_i32 s11, s10, 31
	s_lshl_b64 s[12:13], s[10:11], 19
	s_add_u32 s12, s24, s12
	s_addc_u32 s13, s25, s13
	s_and_b64 s[14:15], s[2:3], exec
	s_cselect_b32 s11, s13, s19
	s_cselect_b32 s52, s12, s18
	s_ashr_i32 s9, s8, 31
	s_lshl_b64 s[14:15], s[8:9], 19
	s_add_u32 s14, s26, s14
	s_addc_u32 s15, s27, s15
	s_and_b64 s[22:23], s[2:3], exec
	s_cselect_b32 s9, s15, s21
	s_cselect_b32 s53, s14, s20
	s_add_u32 s18, s18, 0x40080
	s_addc_u32 s19, s19, 0
	s_add_u32 s56, s20, 0x100
	s_addc_u32 s57, s21, 0
	s_mov_b32 s60, -2
	ds_read_b128 v[156:159], v151
	ds_read_b128 v[160:163], v151 offset:1024
	ds_read_b128 v[164:167], v151 offset:2048
	ds_read_b128 v[168:171], v151 offset:3072
	ds_read_b128 v[174:177], v152
	ds_read_b128 v[178:181], v152 offset:1024
	ds_read_b128 v[182:185], v152 offset:2048
	ds_read_b128 v[186:189], v152 offset:3072
	s_add_u32 s20, s18, 0xfffc0080
	s_addc_u32 s21, s19, -1
	s_cmp_eq_u32 s60, 12
	s_cselect_b32 s23, s11, s21
	s_cselect_b32 s22, s52, s20
	s_cselect_b32 s21, s9, s57
	s_cselect_b32 s20, s53, s56

; #define PG8_STAGE(bufoff, gbase, voff) do { _Pragma("unroll") for (int _i = 0; _i < 2; ++_i) \
;         __builtin_amdgcn_global_load_lds((const unsigned*)((const char*)(gbase) + (voff)[_i]), (PG8_LAS unsigned*)(lds + (bufoff) + ldsw + _i * 8192), 16, 0, 0); } while (0)
; #define PG8_LDA(dst, b, h) do { _Pragma("unroll") for (int m = 0; m < 4; ++m) _Pragma("unroll") for (int k = 0; k < 2; ++k) dst[m][k] = *(const PG8_LAS bf16x8*)(lds + PG8_SA(b, h) + aoff + m * 2048 + k * 1024); } while (0)
; #define PG8_LDB(dst, b, h) do { _Pragma("unroll") for (int n = 0; n < 2; ++n) _Pragma("unroll") for (int k = 0; k < 2; ++k) dst[n][k] = *(const PG8_LAS bf16x8*)(lds + PG8_SB(b, h) + boff + n * 2048 + k * 1024); } while (0)
; #define PG8_MMA(ai, bj, At, Bt) do { __builtin_amdgcn_s_setprio(1); _Pragma("unroll") for (int m = 0; m < 4; ++m) _Pragma("unroll") for (int n = 0; n < 2; ++n) _Pragma("unroll") for (int k = 0; k < 2; ++k) \
;         acc[ai][bj][m][n] = __builtin_amdgcn_mfma_f32_16x16x32_bf16(Bt[n][k], At[m][k], acc[ai][bj][m][n], 0, 0, 0); __builtin_amdgcn_s_setprio(0); } while (0)
; #define PG8_WAIT_V(n) asm volatile("s_waitcnt vmcnt(" #n ")" ::: "memory")
; #define PG8_WAIT_L(n) asm volatile("s_waitcnt lgkmcnt(" #n ")" ::: "memory")
; #define PG8_BAR __builtin_amdgcn_s_barrier()
; #define PG8_SCHED __builtin_amdgcn_sched_barrier(0)
; template <class Epi, class Sched, bool ALIGN_EPI = false, bool SP2 = false>
; __device__ __forceinline__ void gemm_phase(PG8_LAS unsigned char* lds, const Gemm g, const Sched& S, const Epi& E) {
;     ...
;             PG8_LDB(B0, 0, 0); PG8_LDB(B1, 0, 1); PG8_SCHED; PG8_LDA(At, 0, 0); PG8_STAGE(PG8_SA(1, 1), a1 + hstep, voffA);
;             PG8_WAIT_V(8); PG8_WAIT_L(0); PG8_BAR; PG8_MMA(0, 0, At, B0); PG8_MMA(0, 1, At, B1); PG8_BAR; PG8_SCHED;
	v_lshl_add_u64 v[222:223], s[18:19], 0, v[142:143]
	s_add_i32 m0, s31, 0xc000
	ds_read_b128 v[190:193], v153
	ds_read_b128 v[194:197], v153 offset:1024
	ds_read_b128 v[198:201], v153 offset:2048
	ds_read_b128 v[202:205], v153 offset:3072
	ds_read_b128 v[206:209], v153 offset:4096
	ds_read_b128 v[210:213], v153 offset:5120
	ds_read_b128 v[214:217], v153 offset:6144
	ds_read_b128 v[218:221], v153 offset:7168
	global_load_lds_dwordx4 v[222:223], off
	v_lshl_add_u64 v[222:223], s[18:19], 0, v[144:145]
	s_add_i32 m0, s31, 0xe000
	s_nop 0
	global_load_lds_dwordx4 v[222:223], off
	s_waitcnt vmcnt(24)
	s_waitcnt lgkmcnt(0)
	s_barrier
	s_waitcnt lgkmcnt(0)
	v_mfma_f32_16x16x32_bf16 v[126:129], v[156:159], v[190:193], 0
	v_mfma_f32_16x16x32_bf16 v[122:125], v[164:167], v[190:193], 0
	v_mfma_f32_16x16x32_bf16 v[114:117], v[156:159], v[198:201], 0
	v_mfma_f32_16x16x32_bf16 v[106:109], v[164:167], v[198:201], 0
	v_mfma_f32_16x16x32_bf16 v[98:101], v[156:159], v[206:209], 0
	v_mfma_f32_16x16x32_bf16 v[90:93], v[164:167], v[206:209], 0
	v_mfma_f32_16x16x32_bf16 v[82:85], v[156:159], v[214:217], 0
	v_mfma_f32_16x16x32_bf16 v[74:77], v[164:167], v[214:217], 0
	v_mfma_f32_16x16x32_bf16 v[126:129], v[160:163], v[194:197], v[126:129]
	v_mfma_f32_16x16x32_bf16 v[122:125], v[168:171], v[194:197], v[122:125]
	v_mfma_f32_16x16x32_bf16 v[114:117], v[160:163], v[202:205], v[114:117]
	v_mfma_f32_16x16x32_bf16 v[106:109], v[168:171], v[202:205], v[106:109]
	v_mfma_f32_16x16x32_bf16 v[98:101], v[160:163], v[210:213], v[98:101]
	v_mfma_f32_16x16x32_bf16 v[90:93], v[168:171], v[210:213], v[90:93]
	v_mfma_f32_16x16x32_bf16 v[82:85], v[160:163], v[218:221], v[82:85]
	v_mfma_f32_16x16x32_bf16 v[74:77], v[168:171], v[218:221], v[74:77]
	v_mfma_f32_16x16x32_bf16 v[118:121], v[174:177], v[190:193], 0
	v_mfma_f32_16x16x32_bf16 v[110:113], v[182:185], v[190:193], 0
	v_mfma_f32_16x16x32_bf16 v[102:105], v[174:177], v[198:201], 0
	v_mfma_f32_16x16x32_bf16 v[94:97], v[182:185], v[198:201], 0
	v_mfma_f32_16x16x32_bf16 v[86:89], v[174:177], v[206:209], 0
	v_mfma_f32_16x16x32_bf16 v[78:81], v[182:185], v[206:209], 0
	v_mfma_f32_16x16x32_bf16 v[70:73], v[174:177], v[214:217], 0
	v_mfma_f32_16x16x32_bf16 v[66:69], v[182:185], v[214:217], 0
	v_mfma_f32_16x16x32_bf16 v[118:121], v[178:181], v[194:197], v[118:121]
	v_mfma_f32_16x16x32_bf16 v[110:113], v[186:189], v[194:197], v[110:113]
	v_mfma_f32_16x16x32_bf16 v[102:105], v[178:181], v[202:205], v[102:105]
	v_mfma_f32_16x16x32_bf16 v[94:97], v[186:189], v[202:205], v[94:97]
	v_mfma_f32_16x16x32_bf16 v[86:89], v[178:181], v[210:213], v[86:89]
	v_mfma_f32_16x16x32_bf16 v[78:81], v[186:189], v[210:213], v[78:81]
	v_mfma_f32_16x16x32_bf16 v[70:73], v[178:181], v[218:221], v[70:73]
	v_mfma_f32_16x16x32_bf16 v[66:69], v[186:189], v[218:221], v[66:69]
	s_barrier

; #define PG8_STAGE(bufoff, gbase, voff) do { _Pragma("unroll") for (int _i = 0; _i < 2; ++_i) \
;         __builtin_amdgcn_global_load_lds((const unsigned*)((const char*)(gbase) + (voff)[_i]), (PG8_LAS unsigned*)(lds + (bufoff) + ldsw + _i * 8192), 16, 0, 0); } while (0)
; #define PG8_LDA(dst, b, h) do { _Pragma("unroll") for (int m = 0; m < 4; ++m) _Pragma("unroll") for (int k = 0; k < 2; ++k) dst[m][k] = *(const PG8_LAS bf16x8*)(lds + PG8_SA(b, h) + aoff + m * 2048 + k * 1024); } while (0)
; #define PG8_MMA(ai, bj, At, Bt) do { __builtin_amdgcn_s_setprio(1); _Pragma("unroll") for (int m = 0; m < 4; ++m) _Pragma("unroll") for (int n = 0; n < 2; ++n) _Pragma("unroll") for (int k = 0; k < 2; ++k) \
;         acc[ai][bj][m][n] = __builtin_amdgcn_mfma_f32_16x16x32_bf16(Bt[n][k], At[m][k], acc[ai][bj][m][n], 0, 0, 0); __builtin_amdgcn_s_setprio(0); } while (0)
; #define PG8_WAIT_V(n) asm volatile("s_waitcnt vmcnt(" #n ")" ::: "memory")
; #define PG8_WAIT_L(n) asm volatile("s_waitcnt lgkmcnt(" #n ")" ::: "memory")
; #define PG8_BAR __builtin_amdgcn_s_barrier()
; #define PG8_SCHED __builtin_amdgcn_sched_barrier(0)
; template <class Epi, class Sched, bool ALIGN_EPI = false, bool SP2 = false>
; __device__ __forceinline__ void gemm_phase(PG8_LAS unsigned char* lds, const Gemm g, const Sched& S, const Epi& E) {
;     ...
;             PG8_LDA(At, 0, 1); PG8_STAGE(PG8_SB(0, 0), b2, voffB); PG8_STAGE(PG8_SB(0, 1), b2 + hstep, voffB); PG8_STAGE(PG8_SA(0, 0), a2, voffA);
;             PG8_WAIT_V(8); PG8_WAIT_L(0); PG8_BAR; PG8_MMA(1, 0, At, B0); PG8_MMA(1, 1, At, B1); PG8_BAR; PG8_SCHED;
	s_add_i32 s61, s44, s28
	v_lshl_add_u64 v[222:223], s[20:21], 0, v[134:135]
	s_mov_b32 m0, s61
	ds_read_b128 v[190:193], v153 offset:16384
	ds_read_b128 v[194:197], v153 offset:17408
	ds_read_b128 v[198:201], v153 offset:18432
	ds_read_b128 v[202:205], v153 offset:19456
	ds_read_b128 v[206:209], v153 offset:20480
	ds_read_b128 v[210:213], v153 offset:21504
	ds_read_b128 v[214:217], v153 offset:22528
	ds_read_b128 v[218:221], v153 offset:23552
	global_load_lds_dwordx4 v[222:223], off
	s_add_i32 m0, s61, 0x2000
	s_add_u32 s62, s20, 0x40000
	v_lshl_add_u64 v[224:225], s[20:21], 0, v[130:131]
	s_addc_u32 s63, s21, 0
	s_add_i32 s61, s45, s28
	global_load_lds_dwordx4 v[224:225], off
	v_lshl_add_u64 v[226:227], s[62:63], 0, v[134:135]
	s_mov_b32 m0, s61
	v_lshl_add_u64 v[228:229], s[22:23], 0, v[132:133]
	global_load_lds_dwordx4 v[226:227], off
	v_lshl_add_u64 v[226:227], s[62:63], 0, v[130:131]
	s_add_i32 m0, s61, 0x2000
	s_nop 0
	global_load_lds_dwordx4 v[226:227], off
	v_lshl_add_u64 v[226:227], s[22:23], 0, v[136:137]
	s_mov_b32 m0, s31
	s_nop 0
	global_load_lds_dwordx4 v[226:227], off
	s_mov_b32 m0, s33
	s_nop 0
	global_load_lds_dwordx4 v[228:229], off
	s_waitcnt vmcnt(24)
	s_waitcnt lgkmcnt(0)
	s_barrier
	s_waitcnt lgkmcnt(0)
	v_mfma_f32_16x16x32_bf16 v[62:65], v[156:159], v[190:193], 0
	v_mfma_f32_16x16x32_bf16 v[58:61], v[164:167], v[190:193], 0
	v_mfma_f32_16x16x32_bf16 v[50:53], v[156:159], v[198:201], 0
	v_mfma_f32_16x16x32_bf16 v[42:45], v[164:167], v[198:201], 0
	v_mfma_f32_16x16x32_bf16 v[34:37], v[156:159], v[206:209], 0
	v_mfma_f32_16x16x32_bf16 v[26:29], v[164:167], v[206:209], 0
	v_mfma_f32_16x16x32_bf16 v[18:21], v[156:159], v[214:217], 0
	v_mfma_f32_16x16x32_bf16 v[10:13], v[164:167], v[214:217], 0
	v_mfma_f32_16x16x32_bf16 v[62:65], v[160:163], v[194:197], v[62:65]
	v_mfma_f32_16x16x32_bf16 v[58:61], v[168:171], v[194:197], v[58:61]
	v_mfma_f32_16x16x32_bf16 v[50:53], v[160:163], v[202:205], v[50:53]
	v_mfma_f32_16x16x32_bf16 v[42:45], v[168:171], v[202:205], v[42:45]
	v_mfma_f32_16x16x32_bf16 v[34:37], v[160:163], v[210:213], v[34:37]
	v_mfma_f32_16x16x32_bf16 v[26:29], v[168:171], v[210:213], v[26:29]
	v_mfma_f32_16x16x32_bf16 v[18:21], v[160:163], v[218:221], v[18:21]
	v_mfma_f32_16x16x32_bf16 v[10:13], v[168:171], v[218:221], v[10:13]
	v_mfma_f32_16x16x32_bf16 v[54:57], v[174:177], v[190:193], 0
	v_mfma_f32_16x16x32_bf16 v[46:49], v[182:185], v[190:193], 0
	v_mfma_f32_16x16x32_bf16 v[38:41], v[174:177], v[198:201], 0
	v_mfma_f32_16x16x32_bf16 v[30:33], v[182:185], v[198:201], 0
	v_mfma_f32_16x16x32_bf16 v[22:25], v[174:177], v[206:209], 0
	v_mfma_f32_16x16x32_bf16 v[14:17], v[182:185], v[206:209], 0
	v_mfma_f32_16x16x32_bf16 v[6:9], v[174:177], v[214:217], 0
	v_mfma_f32_16x16x32_bf16 v[2:5], v[182:185], v[214:217], 0
	v_mfma_f32_16x16x32_bf16 v[54:57], v[178:181], v[194:197], v[54:57]
	v_mfma_f32_16x16x32_bf16 v[46:49], v[186:189], v[194:197], v[46:49]
	v_mfma_f32_16x16x32_bf16 v[38:41], v[178:181], v[202:205], v[38:41]
	v_mfma_f32_16x16x32_bf16 v[30:33], v[186:189], v[202:205], v[30:33]
	v_mfma_f32_16x16x32_bf16 v[22:25], v[178:181], v[210:213], v[22:25]
	v_mfma_f32_16x16x32_bf16 v[14:17], v[186:189], v[210:213], v[14:17]
	v_mfma_f32_16x16x32_bf16 v[6:9], v[178:181], v[218:221], v[6:9]
	v_mfma_f32_16x16x32_bf16 v[2:5], v[186:189], v[218:221], v[2:5]
	s_barrier

; #define PG8_STAGE(bufoff, gbase, voff) do { _Pragma("unroll") for (int _i = 0; _i < 2; ++_i) \
;         __builtin_amdgcn_global_load_lds((const unsigned*)((const char*)(gbase) + (voff)[_i]), (PG8_LAS unsigned*)(lds + (bufoff) + ldsw + _i * 8192), 16, 0, 0); } while (0)
; #define PG8_LDA(dst, b, h) do { _Pragma("unroll") for (int m = 0; m < 4; ++m) _Pragma("unroll") for (int k = 0; k < 2; ++k) dst[m][k] = *(const PG8_LAS bf16x8*)(lds + PG8_SA(b, h) + aoff + m * 2048 + k * 1024); } while (0)
; #define PG8_LDB(dst, b, h) do { _Pragma("unroll") for (int n = 0; n < 2; ++n) _Pragma("unroll") for (int k = 0; k < 2; ++k) dst[n][k] = *(const PG8_LAS bf16x8*)(lds + PG8_SB(b, h) + boff + n * 2048 + k * 1024); } while (0)
; #define PG8_SCHED __builtin_amdgcn_sched_barrier(0)
; template <class Epi, class Sched, bool ALIGN_EPI = false, bool SP2 = false>
; __device__ __forceinline__ void gemm_phase(PG8_LAS unsigned char* lds, const Gemm g, const Sched& S, const Epi& E) {
;     ...
;             PG8_LDB(B0, 1, 0); PG8_LDB(B1, 1, 1); PG8_SCHED; PG8_LDA(At, 1, 0); PG8_STAGE(PG8_SA(0, 1), a2 + hstep, voffA);
	s_add_i32 s61, 0, 0x18000
	v_add_u32_e32 v138, s61, v150
	s_add_i32 s62, 0, 0x1c000
	ds_read_b128 v[156:159], v138
	ds_read_b128 v[160:163], v138 offset:1024
	ds_read_b128 v[164:167], v138 offset:2048
	ds_read_b128 v[168:171], v138 offset:3072
	v_add_u32_e32 v138, s62, v150
	ds_read_b128 v[174:177], v138
	ds_read_b128 v[178:181], v138 offset:1024
	ds_read_b128 v[182:185], v138 offset:2048
	ds_read_b128 v[186:189], v138 offset:3072

; #define PG8_STAGE(bufoff, gbase, voff) do { _Pragma("unroll") for (int _i = 0; _i < 2; ++_i) \
;         __builtin_amdgcn_global_load_lds((const unsigned*)((const char*)(gbase) + (voff)[_i]), (PG8_LAS unsigned*)(lds + (bufoff) + ldsw + _i * 8192), 16, 0, 0); } while (0)
; #define PG8_LDA(dst, b, h) do { _Pragma("unroll") for (int m = 0; m < 4; ++m) _Pragma("unroll") for (int k = 0; k < 2; ++k) dst[m][k] = *(const PG8_LAS bf16x8*)(lds + PG8_SA(b, h) + aoff + m * 2048 + k * 1024); } while (0)
; #define PG8_LDB(dst, b, h) do { _Pragma("unroll") for (int n = 0; n < 2; ++n) _Pragma("unroll") for (int k = 0; k < 2; ++k) dst[n][k] = *(const PG8_LAS bf16x8*)(lds + PG8_SB(b, h) + boff + n * 2048 + k * 1024); } while (0)
; #define PG8_MMA(ai, bj, At, Bt) do { __builtin_amdgcn_s_setprio(1); _Pragma("unroll") for (int m = 0; m < 4; ++m) _Pragma("unroll") for (int n = 0; n < 2; ++n) _Pragma("unroll") for (int k = 0; k < 2; ++k) \
;         acc[ai][bj][m][n] = __builtin_amdgcn_mfma_f32_16x16x32_bf16(Bt[n][k], At[m][k], acc[ai][bj][m][n], 0, 0, 0); __builtin_amdgcn_s_setprio(0); } while (0)
; #define PG8_WAIT_V(n) asm volatile("s_waitcnt vmcnt(" #n ")" ::: "memory")
; #define PG8_WAIT_L(n) asm volatile("s_waitcnt lgkmcnt(" #n ")" ::: "memory")
; #define PG8_BAR __builtin_amdgcn_s_barrier()
; #define PG8_SCHED __builtin_amdgcn_sched_barrier(0)
; template <class Epi, class Sched, bool ALIGN_EPI = false, bool SP2 = false>
; __device__ __forceinline__ void gemm_phase(PG8_LAS unsigned char* lds, const Gemm g, const Sched& S, const Epi& E) {
;     ...
;             PG8_LDB(B0, 1, 0); PG8_LDB(B1, 1, 1); PG8_SCHED; PG8_LDA(At, 1, 0); PG8_STAGE(PG8_SA(0, 1), a2 + hstep, voffA);
;             PG8_WAIT_V(8); PG8_WAIT_L(0); PG8_BAR; PG8_MMA(0, 0, At, B0); PG8_MMA(0, 1, At, B1); PG8_BAR; PG8_SCHED;
	s_add_u32 s22, s22, 0x40000
	s_addc_u32 s23, s23, 0
	s_mov_b32 m0, s34
	v_lshl_add_u64 v[230:231], s[22:23], 0, v[136:137]
	ds_read_b128 v[190:193], v153 offset:32768
	ds_read_b128 v[194:197], v153 offset:33792
	ds_read_b128 v[198:201], v153 offset:34816
	ds_read_b128 v[202:205], v153 offset:35840
	ds_read_b128 v[206:209], v153 offset:36864
	ds_read_b128 v[210:213], v153 offset:37888
	ds_read_b128 v[214:217], v153 offset:38912
	ds_read_b128 v[218:221], v153 offset:39936
	global_load_lds_dwordx4 v[230:231], off
	v_lshl_add_u64 v[230:231], s[22:23], 0, v[132:133]
	s_mov_b32 m0, s35
	s_nop 0
	global_load_lds_dwordx4 v[230:231], off
	s_waitcnt vmcnt(8)
	s_waitcnt lgkmcnt(0)
	s_barrier
	s_waitcnt lgkmcnt(0)
	v_mfma_f32_16x16x32_bf16 v[126:129], v[156:159], v[190:193], v[126:129]
	v_mfma_f32_16x16x32_bf16 v[122:125], v[164:167], v[190:193], v[122:125]
	v_mfma_f32_16x16x32_bf16 v[114:117], v[156:159], v[198:201], v[114:117]
	v_mfma_f32_16x16x32_bf16 v[106:109], v[164:167], v[198:201], v[106:109]
	v_mfma_f32_16x16x32_bf16 v[98:101], v[156:159], v[206:209], v[98:101]
	v_mfma_f32_16x16x32_bf16 v[90:93], v[164:167], v[206:209], v[90:93]
	v_mfma_f32_16x16x32_bf16 v[82:85], v[156:159], v[214:217], v[82:85]
	v_mfma_f32_16x16x32_bf16 v[74:77], v[164:167], v[214:217], v[74:77]
	v_mfma_f32_16x16x32_bf16 v[126:129], v[160:163], v[194:197], v[126:129]
	v_mfma_f32_16x16x32_bf16 v[122:125], v[168:171], v[194:197], v[122:125]
	v_mfma_f32_16x16x32_bf16 v[114:117], v[160:163], v[202:205], v[114:117]
	v_mfma_f32_16x16x32_bf16 v[106:109], v[168:171], v[202:205], v[106:109]
	v_mfma_f32_16x16x32_bf16 v[98:101], v[160:163], v[210:213], v[98:101]
	v_mfma_f32_16x16x32_bf16 v[90:93], v[168:171], v[210:213], v[90:93]
	v_mfma_f32_16x16x32_bf16 v[82:85], v[160:163], v[218:221], v[82:85]
	v_mfma_f32_16x16x32_bf16 v[74:77], v[168:171], v[218:221], v[74:77]
	v_mfma_f32_16x16x32_bf16 v[118:121], v[174:177], v[190:193], v[118:121]
	v_mfma_f32_16x16x32_bf16 v[110:113], v[182:185], v[190:193], v[110:113]
	v_mfma_f32_16x16x32_bf16 v[102:105], v[174:177], v[198:201], v[102:105]
	v_mfma_f32_16x16x32_bf16 v[94:97], v[182:185], v[198:201], v[94:97]
	v_mfma_f32_16x16x32_bf16 v[86:89], v[174:177], v[206:209], v[86:89]
	v_mfma_f32_16x16x32_bf16 v[78:81], v[182:185], v[206:209], v[78:81]
	v_mfma_f32_16x16x32_bf16 v[70:73], v[174:177], v[214:217], v[70:73]
	v_mfma_f32_16x16x32_bf16 v[66:69], v[182:185], v[214:217], v[66:69]
	v_mfma_f32_16x16x32_bf16 v[118:121], v[178:181], v[194:197], v[118:121]
	v_mfma_f32_16x16x32_bf16 v[110:113], v[186:189], v[194:197], v[110:113]
	v_mfma_f32_16x16x32_bf16 v[102:105], v[178:181], v[202:205], v[102:105]
	v_mfma_f32_16x16x32_bf16 v[94:97], v[186:189], v[202:205], v[94:97]
	v_mfma_f32_16x16x32_bf16 v[86:89], v[178:181], v[210:213], v[86:89]
	v_mfma_f32_16x16x32_bf16 v[78:81], v[186:189], v[210:213], v[78:81]
	v_mfma_f32_16x16x32_bf16 v[70:73], v[178:181], v[218:221], v[70:73]
	v_mfma_f32_16x16x32_bf16 v[66:69], v[186:189], v[218:221], v[66:69]
	s_barrier

; #define PG8_STAGE(bufoff, gbase, voff) do { _Pragma("unroll") for (int _i = 0; _i < 2; ++_i) \
;         __builtin_amdgcn_global_load_lds((const unsigned*)((const char*)(gbase) + (voff)[_i]), (PG8_LAS unsigned*)(lds + (bufoff) + ldsw + _i * 8192), 16, 0, 0); } while (0)
; #define PG8_LDA(dst, b, h) do { _Pragma("unroll") for (int m = 0; m < 4; ++m) _Pragma("unroll") for (int k = 0; k < 2; ++k) dst[m][k] = *(const PG8_LAS bf16x8*)(lds + PG8_SA(b, h) + aoff + m * 2048 + k * 1024); } while (0)
; #define PG8_MMA(ai, bj, At, Bt) do { __builtin_amdgcn_s_setprio(1); _Pragma("unroll") for (int m = 0; m < 4; ++m) _Pragma("unroll") for (int n = 0; n < 2; ++n) _Pragma("unroll") for (int k = 0; k < 2; ++k) \
;         acc[ai][bj][m][n] = __builtin_amdgcn_mfma_f32_16x16x32_bf16(Bt[n][k], At[m][k], acc[ai][bj][m][n], 0, 0, 0); __builtin_amdgcn_s_setprio(0); } while (0)
; #define PG8_WAIT_V(n) asm volatile("s_waitcnt vmcnt(" #n ")" ::: "memory")
; #define PG8_WAIT_L(n) asm volatile("s_waitcnt lgkmcnt(" #n ")" ::: "memory")
; #define PG8_BAR __builtin_amdgcn_s_barrier()
; #define PG8_SCHED __builtin_amdgcn_sched_barrier(0)
; template <class Epi, class Sched, bool ALIGN_EPI = false, bool SP2 = false>
; __device__ __forceinline__ void gemm_phase(PG8_LAS unsigned char* lds, const Gemm g, const Sched& S, const Epi& E) {
;     ...
;             PG8_LDA(At, 1, 1); PG8_STAGE(PG8_SB(1, 0), b3, voffB); PG8_STAGE(PG8_SB(1, 1), b3 + hstep, voffB); PG8_STAGE(PG8_SA(1, 0), a3, voffA);
;             PG8_WAIT_V(8); PG8_WAIT_L(0); PG8_BAR; PG8_MMA(1, 0, At, B0); PG8_MMA(1, 1, At, B1); PG8_BAR; PG8_SCHED;
	s_add_i32 s22, s61, s28
	v_lshl_add_u64 v[222:223], v[222:223], 0, s[4:5]
	s_mov_b32 m0, s22
	ds_read_b128 v[190:193], v153 offset:49152
	ds_read_b128 v[194:197], v153 offset:50176
	ds_read_b128 v[198:201], v153 offset:51200
	ds_read_b128 v[202:205], v153 offset:52224
	ds_read_b128 v[206:209], v153 offset:53248
	ds_read_b128 v[210:213], v153 offset:54272
	ds_read_b128 v[214:217], v153 offset:55296
	ds_read_b128 v[218:221], v153 offset:56320
	global_load_lds_dwordx4 v[222:223], off
	s_add_i32 m0, s22, 0x2000
	s_add_u32 s20, s20, 0x40080
	v_lshl_add_u64 v[222:223], v[224:225], 0, s[4:5]
	s_addc_u32 s21, s21, 0
	s_add_i32 s22, s62, s28
	global_load_lds_dwordx4 v[222:223], off
	v_lshl_add_u64 v[222:223], s[20:21], 0, v[134:135]
	s_mov_b32 m0, s22
	s_nop 0
	global_load_lds_dwordx4 v[222:223], off
	v_lshl_add_u64 v[222:223], s[20:21], 0, v[130:131]
	s_add_i32 m0, s22, 0x2000
	s_nop 0
	global_load_lds_dwordx4 v[222:223], off
	v_lshl_add_u64 v[222:223], v[226:227], 0, s[4:5]
	s_mov_b32 m0, s39
	s_nop 0
	global_load_lds_dwordx4 v[222:223], off
	v_lshl_add_u64 v[222:223], v[228:229], 0, s[4:5]
	s_mov_b32 m0, s40
	s_nop 0
	global_load_lds_dwordx4 v[222:223], off
	s_waitcnt vmcnt(8)
	s_waitcnt lgkmcnt(0)
	s_barrier
	s_waitcnt lgkmcnt(0)
	v_mfma_f32_16x16x32_bf16 v[62:65], v[156:159], v[190:193], v[62:65]
	v_mfma_f32_16x16x32_bf16 v[58:61], v[164:167], v[190:193], v[58:61]
	v_mfma_f32_16x16x32_bf16 v[50:53], v[156:159], v[198:201], v[50:53]
	v_mfma_f32_16x16x32_bf16 v[42:45], v[164:167], v[198:201], v[42:45]
	v_mfma_f32_16x16x32_bf16 v[34:37], v[156:159], v[206:209], v[34:37]
	v_mfma_f32_16x16x32_bf16 v[26:29], v[164:167], v[206:209], v[26:29]
	v_mfma_f32_16x16x32_bf16 v[18:21], v[156:159], v[214:217], v[18:21]
	v_mfma_f32_16x16x32_bf16 v[10:13], v[164:167], v[214:217], v[10:13]
	v_mfma_f32_16x16x32_bf16 v[62:65], v[160:163], v[194:197], v[62:65]
	v_mfma_f32_16x16x32_bf16 v[58:61], v[168:171], v[194:197], v[58:61]
	v_mfma_f32_16x16x32_bf16 v[50:53], v[160:163], v[202:205], v[50:53]
	v_mfma_f32_16x16x32_bf16 v[42:45], v[168:171], v[202:205], v[42:45]
	v_mfma_f32_16x16x32_bf16 v[34:37], v[160:163], v[210:213], v[34:37]
	v_mfma_f32_16x16x32_bf16 v[26:29], v[168:171], v[210:213], v[26:29]
	v_mfma_f32_16x16x32_bf16 v[18:21], v[160:163], v[218:221], v[18:21]
	v_mfma_f32_16x16x32_bf16 v[10:13], v[168:171], v[218:221], v[10:13]
	v_mfma_f32_16x16x32_bf16 v[54:57], v[174:177], v[190:193], v[54:57]
	v_mfma_f32_16x16x32_bf16 v[46:49], v[182:185], v[190:193], v[46:49]
	v_mfma_f32_16x16x32_bf16 v[38:41], v[174:177], v[198:201], v[38:41]
	v_mfma_f32_16x16x32_bf16 v[30:33], v[182:185], v[198:201], v[30:33]
	v_mfma_f32_16x16x32_bf16 v[22:25], v[174:177], v[206:209], v[22:25]
	v_mfma_f32_16x16x32_bf16 v[14:17], v[182:185], v[206:209], v[14:17]
	v_mfma_f32_16x16x32_bf16 v[6:9], v[174:177], v[214:217], v[6:9]
	v_mfma_f32_16x16x32_bf16 v[2:5], v[182:185], v[214:217], v[2:5]
	v_mfma_f32_16x16x32_bf16 v[54:57], v[178:181], v[194:197], v[54:57]
	v_mfma_f32_16x16x32_bf16 v[46:49], v[186:189], v[194:197], v[46:49]
	v_mfma_f32_16x16x32_bf16 v[38:41], v[178:181], v[202:205], v[38:41]
	v_mfma_f32_16x16x32_bf16 v[30:33], v[186:189], v[202:205], v[30:33]
	v_mfma_f32_16x16x32_bf16 v[22:25], v[178:181], v[210:213], v[22:25]
	v_mfma_f32_16x16x32_bf16 v[14:17], v[186:189], v[210:213], v[14:17]
	v_mfma_f32_16x16x32_bf16 v[6:9], v[178:181], v[218:221], v[6:9]
	v_mfma_f32_16x16x32_bf16 v[2:5], v[186:189], v[218:221], v[2:5]
	s_barrier

; #define PG8_STAGE(bufoff, gbase, voff) do { _Pragma("unroll") for (int _i = 0; _i < 2; ++_i) \
;         __builtin_amdgcn_global_load_lds((const unsigned*)((const char*)(gbase) + (voff)[_i]), (PG8_LAS unsigned*)(lds + (bufoff) + ldsw + _i * 8192), 16, 0, 0); } while (0)
; #define PG8_LDA(dst, b, h) do { _Pragma("unroll") for (int m = 0; m < 4; ++m) _Pragma("unroll") for (int k = 0; k < 2; ++k) dst[m][k] = *(const PG8_LAS bf16x8*)(lds + PG8_SA(b, h) + aoff + m * 2048 + k * 1024); } while (0)
; #define PG8_LDB(dst, b, h) do { _Pragma("unroll") for (int n = 0; n < 2; ++n) _Pragma("unroll") for (int k = 0; k < 2; ++k) dst[n][k] = *(const PG8_LAS bf16x8*)(lds + PG8_SB(b, h) + boff + n * 2048 + k * 1024); } while (0)
; #define PG8_MMA(ai, bj, At, Bt) do { __builtin_amdgcn_s_setprio(1); _Pragma("unroll") for (int m = 0; m < 4; ++m) _Pragma("unroll") for (int n = 0; n < 2; ++n) _Pragma("unroll") for (int k = 0; k < 2; ++k) \
;         acc[ai][bj][m][n] = __builtin_amdgcn_mfma_f32_16x16x32_bf16(Bt[n][k], At[m][k], acc[ai][bj][m][n], 0, 0, 0); __builtin_amdgcn_s_setprio(0); } while (0)
; #define PG8_WAIT_V(n) asm volatile("s_waitcnt vmcnt(" #n ")" ::: "memory")
; #define PG8_BAR __builtin_amdgcn_s_barrier()
; template <class Epi, class Sched, bool ALIGN_EPI = false, bool SP2 = false>
; __device__ __forceinline__ void gemm_phase(PG8_LAS unsigned char* lds, const Gemm g, const Sched& S, const Epi& E) {
;     ...
;         for (int t = 0; t < nt; t += 2) {
;             const bool last = (t == nt - 2);
;             const char* a1 = cA + (size_t)(t + 1) * kstep;
;             const char* a2 = last ? nA : cA + (size_t)(t + 2) * kstep; const char* b2 = last ? nB : cB + (size_t)(t + 2) * kstep;
;             const char* a3 = a2 + kstep; const char* b3 = b2 + kstep;
;             if (last && has_next) S.a_ready(nxt);
;             if constexpr (SP2) {
;             PG8_LDB(B0, 0, 0); PG8_LDB(B1, 0, 1); PG8_SCHED; PG8_LDA(At, 0, 0); PG8_STAGE(PG8_SA(1, 1), a1 + hstep, voffA);
;             PG8_WAIT_V(8); PG8_WAIT_L(0); PG8_BAR; PG8_MMA(0, 0, At, B0); PG8_MMA(0, 1, At, B1); PG8_BAR; PG8_SCHED;
;             PG8_LDA(At, 0, 1); PG8_STAGE(PG8_SB(0, 0), b2, voffB); PG8_STAGE(PG8_SB(0, 1), b2 + hstep, voffB); PG8_STAGE(PG8_SA(0, 0), a2, voffA);
;             PG8_WAIT_V(8); PG8_WAIT_L(0); PG8_BAR; PG8_MMA(1, 0, At, B0); PG8_MMA(1, 1, At, B1); PG8_BAR; PG8_SCHED;
	s_add_i32 s60, s60, 2
	s_add_u32 s18, s18, 0x100
	s_addc_u32 s19, s19, 0
	s_add_u32 s56, s56, 0x100
	s_addc_u32 s57, s57, 0
.LBB0_491:
	ds_read_b128 v[156:159], v151
	ds_read_b128 v[160:163], v151 offset:1024
	ds_read_b128 v[164:167], v151 offset:2048
	ds_read_b128 v[168:171], v151 offset:3072
	ds_read_b128 v[174:177], v152
	ds_read_b128 v[178:181], v152 offset:1024
	ds_read_b128 v[182:185], v152 offset:2048
	ds_read_b128 v[186:189], v152 offset:3072
	s_add_u32 s20, s18, 0xfffc0080
	s_addc_u32 s21, s19, -1
	s_cmp_eq_u32 s60, 12
	s_cselect_b32 s23, s11, s21
	s_cselect_b32 s22, s52, s20
	s_cselect_b32 s21, s9, s57
	s_cselect_b32 s20, s53, s56
	v_lshl_add_u64 v[222:223], s[18:19], 0, v[142:143]
	s_add_i32 m0, s31, 0xc000
	ds_read_b128 v[190:193], v153
	ds_read_b128 v[194:197], v153 offset:1024
	ds_read_b128 v[198:201], v153 offset:2048
	ds_read_b128 v[202:205], v153 offset:3072
	ds_read_b128 v[206:209], v153 offset:4096
	ds_read_b128 v[210:213], v153 offset:5120
	ds_read_b128 v[214:217], v153 offset:6144
	ds_read_b128 v[218:221], v153 offset:7168
	global_load_lds_dwordx4 v[222:223], off
	v_lshl_add_u64 v[222:223], s[18:19], 0, v[144:145]
	s_add_i32 m0, s31, 0xe000
	s_nop 0
	global_load_lds_dwordx4 v[222:223], off
	s_waitcnt vmcnt(8)
	s_waitcnt lgkmcnt(0)
	s_barrier
	s_waitcnt lgkmcnt(0)
	v_mfma_f32_16x16x32_bf16 v[126:129], v[156:159], v[190:193], v[126:129]
	v_mfma_f32_16x16x32_bf16 v[122:125], v[164:167], v[190:193], v[122:125]
	v_mfma_f32_16x16x32_bf16 v[114:117], v[156:159], v[198:201], v[114:117]
	v_mfma_f32_16x16x32_bf16 v[106:109], v[164:167], v[198:201], v[106:109]
	v_mfma_f32_16x16x32_bf16 v[98:101], v[156:159], v[206:209], v[98:101]
	v_mfma_f32_16x16x32_bf16 v[90:93], v[164:167], v[206:209], v[90:93]
	v_mfma_f32_16x16x32_bf16 v[82:85], v[156:159], v[214:217], v[82:85]
	v_mfma_f32_16x16x32_bf16 v[74:77], v[164:167], v[214:217], v[74:77]
	v_mfma_f32_16x16x32_bf16 v[126:129], v[160:163], v[194:197], v[126:129]
	v_mfma_f32_16x16x32_bf16 v[122:125], v[168:171], v[194:197], v[122:125]
	v_mfma_f32_16x16x32_bf16 v[114:117], v[160:163], v[202:205], v[114:117]
	v_mfma_f32_16x16x32_bf16 v[106:109], v[168:171], v[202:205], v[106:109]
	v_mfma_f32_16x16x32_bf16 v[98:101], v[160:163], v[210:213], v[98:101]
	v_mfma_f32_16x16x32_bf16 v[90:93], v[168:171], v[210:213], v[90:93]
	v_mfma_f32_16x16x32_bf16 v[82:85], v[160:163], v[218:221], v[82:85]
	v_mfma_f32_16x16x32_bf16 v[74:77], v[168:171], v[218:221], v[74:77]
	v_mfma_f32_16x16x32_bf16 v[118:121], v[174:177], v[190:193], v[118:121]
	v_mfma_f32_16x16x32_bf16 v[110:113], v[182:185], v[190:193], v[110:113]
	v_mfma_f32_16x16x32_bf16 v[102:105], v[174:177], v[198:201], v[102:105]
	v_mfma_f32_16x16x32_bf16 v[94:97], v[182:185], v[198:201], v[94:97]
	v_mfma_f32_16x16x32_bf16 v[86:89], v[174:177], v[206:209], v[86:89]
	v_mfma_f32_16x16x32_bf16 v[78:81], v[182:185], v[206:209], v[78:81]
	v_mfma_f32_16x16x32_bf16 v[70:73], v[174:177], v[214:217], v[70:73]
	v_mfma_f32_16x16x32_bf16 v[66:69], v[182:185], v[214:217], v[66:69]
	v_mfma_f32_16x16x32_bf16 v[118:121], v[178:181], v[194:197], v[118:121]
	v_mfma_f32_16x16x32_bf16 v[110:113], v[186:189], v[194:197], v[110:113]
	v_mfma_f32_16x16x32_bf16 v[102:105], v[178:181], v[202:205], v[102:105]
	v_mfma_f32_16x16x32_bf16 v[94:97], v[186:189], v[202:205], v[94:97]
	v_mfma_f32_16x16x32_bf16 v[86:89], v[178:181], v[210:213], v[86:89]
	v_mfma_f32_16x16x32_bf16 v[78:81], v[186:189], v[210:213], v[78:81]
	v_mfma_f32_16x16x32_bf16 v[70:73], v[178:181], v[218:221], v[70:73]
	v_mfma_f32_16x16x32_bf16 v[66:69], v[186:189], v[218:221], v[66:69]
	s_barrier
	s_add_i32 s61, s44, s28
	v_lshl_add_u64 v[222:223], s[20:21], 0, v[134:135]
	s_mov_b32 m0, s61
	ds_read_b128 v[190:193], v153 offset:16384
	ds_read_b128 v[194:197], v153 offset:17408
	ds_read_b128 v[198:201], v153 offset:18432
	ds_read_b128 v[202:205], v153 offset:19456
	ds_read_b128 v[206:209], v153 offset:20480
	ds_read_b128 v[210:213], v153 offset:21504
	ds_read_b128 v[214:217], v153 offset:22528
	ds_read_b128 v[218:221], v153 offset:23552
	global_load_lds_dwordx4 v[222:223], off
	s_add_i32 m0, s61, 0x2000
	s_add_u32 s62, s20, 0x40000
	v_lshl_add_u64 v[224:225], s[20:21], 0, v[130:131]
	s_addc_u32 s63, s21, 0
	s_add_i32 s61, s45, s28
	global_load_lds_dwordx4 v[224:225], off
	v_lshl_add_u64 v[226:227], s[62:63], 0, v[134:135]
	s_mov_b32 m0, s61
	v_lshl_add_u64 v[228:229], s[22:23], 0, v[132:133]
	global_load_lds_dwordx4 v[226:227], off
	v_lshl_add_u64 v[226:227], s[62:63], 0, v[130:131]
	s_add_i32 m0, s61, 0x2000
	s_nop 0
	global_load_lds_dwordx4 v[226:227], off
	v_lshl_add_u64 v[226:227], s[22:23], 0, v[136:137]
	s_mov_b32 m0, s31
	s_nop 0
	global_load_lds_dwordx4 v[226:227], off
	s_mov_b32 m0, s33
	s_nop 0
	global_load_lds_dwordx4 v[228:229], off
	s_waitcnt vmcnt(8)
	s_waitcnt lgkmcnt(0)
	s_barrier
; #define PG8_STAGE(bufoff, gbase, voff) do { _Pragma("unroll") for (int _i = 0; _i < 2; ++_i) \
;         __builtin_amdgcn_global_load_lds((const unsigned*)((const char*)(gbase) + (voff)[_i]), (PG8_LAS unsigned*)(lds + (bufoff) + ldsw + _i * 8192), 16, 0, 0); } while (0)
; #define PG8_LDA(dst, b, h) do { _Pragma("unroll") for (int m = 0; m < 4; ++m) _Pragma("unroll") for (int k = 0; k < 2; ++k) dst[m][k] = *(const PG8_LAS bf16x8*)(lds + PG8_SA(b, h) + aoff + m * 2048 + k * 1024); } while (0)
; #define PG8_LDB(dst, b, h) do { _Pragma("unroll") for (int n = 0; n < 2; ++n) _Pragma("unroll") for (int k = 0; k < 2; ++k) dst[n][k] = *(const PG8_LAS bf16x8*)(lds + PG8_SB(b, h) + boff + n * 2048 + k * 1024); } while (0)
; #define PG8_MMA(ai, bj, At, Bt) do { __builtin_amdgcn_s_setprio(1); _Pragma("unroll") for (int m = 0; m < 4; ++m) _Pragma("unroll") for (int n = 0; n < 2; ++n) _Pragma("unroll") for (int k = 0; k < 2; ++k) \
;         acc[ai][bj][m][n] = __builtin_amdgcn_mfma_f32_16x16x32_bf16(Bt[n][k], At[m][k], acc[ai][bj][m][n], 0, 0, 0); __builtin_amdgcn_s_setprio(0); } while (0)
; #define PG8_WAIT_V(n) asm volatile("s_waitcnt vmcnt(" #n ")" ::: "memory")
; #define PG8_WAIT_L(n) asm volatile("s_waitcnt lgkmcnt(" #n ")" ::: "memory")
; #define PG8_BAR __builtin_amdgcn_s_barrier()
; #define PG8_SCHED __builtin_amdgcn_sched_barrier(0)
; template <class Epi, class Sched, bool ALIGN_EPI = false, bool SP2 = false>
; __device__ __forceinline__ void gemm_phase(PG8_LAS unsigned char* lds, const Gemm g, const Sched& S, const Epi& E) {
;     ...
;             PG8_WAIT_V(8); PG8_WAIT_L(0); PG8_BAR; PG8_MMA(1, 0, At, B0); PG8_MMA(1, 1, At, B1); PG8_BAR; PG8_SCHED;
;             PG8_LDB(B0, 1, 0); PG8_LDB(B1, 1, 1); PG8_SCHED; PG8_LDA(At, 1, 0); PG8_STAGE(PG8_SA(0, 1), a2 + hstep, voffA);
;             PG8_WAIT_V(8); PG8_WAIT_L(0); PG8_BAR; PG8_MMA(0, 0, At, B0); PG8_MMA(0, 1, At, B1); PG8_BAR; PG8_SCHED;
	s_waitcnt lgkmcnt(0)
	v_mfma_f32_16x16x32_bf16 v[62:65], v[156:159], v[190:193], v[62:65]
	v_mfma_f32_16x16x32_bf16 v[58:61], v[164:167], v[190:193], v[58:61]
	v_mfma_f32_16x16x32_bf16 v[50:53], v[156:159], v[198:201], v[50:53]
	v_mfma_f32_16x16x32_bf16 v[42:45], v[164:167], v[198:201], v[42:45]
	v_mfma_f32_16x16x32_bf16 v[34:37], v[156:159], v[206:209], v[34:37]
	v_mfma_f32_16x16x32_bf16 v[26:29], v[164:167], v[206:209], v[26:29]
	v_mfma_f32_16x16x32_bf16 v[18:21], v[156:159], v[214:217], v[18:21]
	v_mfma_f32_16x16x32_bf16 v[10:13], v[164:167], v[214:217], v[10:13]
	v_mfma_f32_16x16x32_bf16 v[62:65], v[160:163], v[194:197], v[62:65]
	v_mfma_f32_16x16x32_bf16 v[58:61], v[168:171], v[194:197], v[58:61]
	v_mfma_f32_16x16x32_bf16 v[50:53], v[160:163], v[202:205], v[50:53]
	v_mfma_f32_16x16x32_bf16 v[42:45], v[168:171], v[202:205], v[42:45]
	v_mfma_f32_16x16x32_bf16 v[34:37], v[160:163], v[210:213], v[34:37]
	v_mfma_f32_16x16x32_bf16 v[26:29], v[168:171], v[210:213], v[26:29]
	v_mfma_f32_16x16x32_bf16 v[18:21], v[160:163], v[218:221], v[18:21]
	v_mfma_f32_16x16x32_bf16 v[10:13], v[168:171], v[218:221], v[10:13]
	v_mfma_f32_16x16x32_bf16 v[54:57], v[174:177], v[190:193], v[54:57]
	v_mfma_f32_16x16x32_bf16 v[46:49], v[182:185], v[190:193], v[46:49]
	v_mfma_f32_16x16x32_bf16 v[38:41], v[174:177], v[198:201], v[38:41]
	v_mfma_f32_16x16x32_bf16 v[30:33], v[182:185], v[198:201], v[30:33]
	v_mfma_f32_16x16x32_bf16 v[22:25], v[174:177], v[206:209], v[22:25]
	v_mfma_f32_16x16x32_bf16 v[14:17], v[182:185], v[206:209], v[14:17]
	v_mfma_f32_16x16x32_bf16 v[6:9], v[174:177], v[214:217], v[6:9]
	v_mfma_f32_16x16x32_bf16 v[2:5], v[182:185], v[214:217], v[2:5]
	v_mfma_f32_16x16x32_bf16 v[54:57], v[178:181], v[194:197], v[54:57]
	v_mfma_f32_16x16x32_bf16 v[46:49], v[186:189], v[194:197], v[46:49]
	v_mfma_f32_16x16x32_bf16 v[38:41], v[178:181], v[202:205], v[38:41]
	v_mfma_f32_16x16x32_bf16 v[30:33], v[186:189], v[202:205], v[30:33]
	v_mfma_f32_16x16x32_bf16 v[22:25], v[178:181], v[210:213], v[22:25]
	v_mfma_f32_16x16x32_bf16 v[14:17], v[186:189], v[210:213], v[14:17]
	v_mfma_f32_16x16x32_bf16 v[6:9], v[178:181], v[218:221], v[6:9]
	v_mfma_f32_16x16x32_bf16 v[2:5], v[186:189], v[218:221], v[2:5]
	s_barrier
	s_add_i32 s61, 0, 0x18000
	v_add_u32_e32 v138, s61, v150
	s_add_i32 s62, 0, 0x1c000
	ds_read_b128 v[156:159], v138
	ds_read_b128 v[160:163], v138 offset:1024
	ds_read_b128 v[164:167], v138 offset:2048
	ds_read_b128 v[168:171], v138 offset:3072
	v_add_u32_e32 v138, s62, v150
	ds_read_b128 v[174:177], v138
	ds_read_b128 v[178:181], v138 offset:1024
	ds_read_b128 v[182:185], v138 offset:2048
	ds_read_b128 v[186:189], v138 offset:3072
	s_add_u32 s22, s22, 0x40000
	s_addc_u32 s23, s23, 0
	s_mov_b32 m0, s34
	v_lshl_add_u64 v[230:231], s[22:23], 0, v[136:137]
	ds_read_b128 v[190:193], v153 offset:32768
	ds_read_b128 v[194:197], v153 offset:33792
	ds_read_b128 v[198:201], v153 offset:34816
	ds_read_b128 v[202:205], v153 offset:35840
	ds_read_b128 v[206:209], v153 offset:36864
	ds_read_b128 v[210:213], v153 offset:37888
	ds_read_b128 v[214:217], v153 offset:38912
	ds_read_b128 v[218:221], v153 offset:39936
	global_load_lds_dwordx4 v[230:231], off
	v_lshl_add_u64 v[230:231], s[22:23], 0, v[132:133]
	s_mov_b32 m0, s35
	s_nop 0
	global_load_lds_dwordx4 v[230:231], off
	s_waitcnt vmcnt(8)
	s_waitcnt lgkmcnt(0)
	s_barrier
	s_waitcnt lgkmcnt(0)
	v_mfma_f32_16x16x32_bf16 v[126:129], v[156:159], v[190:193], v[126:129]
	v_mfma_f32_16x16x32_bf16 v[122:125], v[164:167], v[190:193], v[122:125]
	v_mfma_f32_16x16x32_bf16 v[114:117], v[156:159], v[198:201], v[114:117]
	v_mfma_f32_16x16x32_bf16 v[106:109], v[164:167], v[198:201], v[106:109]
	v_mfma_f32_16x16x32_bf16 v[98:101], v[156:159], v[206:209], v[98:101]
	v_mfma_f32_16x16x32_bf16 v[90:93], v[164:167], v[206:209], v[90:93]
	v_mfma_f32_16x16x32_bf16 v[82:85], v[156:159], v[214:217], v[82:85]
	v_mfma_f32_16x16x32_bf16 v[74:77], v[164:167], v[214:217], v[74:77]
	v_mfma_f32_16x16x32_bf16 v[126:129], v[160:163], v[194:197], v[126:129]
	v_mfma_f32_16x16x32_bf16 v[122:125], v[168:171], v[194:197], v[122:125]
	v_mfma_f32_16x16x32_bf16 v[114:117], v[160:163], v[202:205], v[114:117]
	v_mfma_f32_16x16x32_bf16 v[106:109], v[168:171], v[202:205], v[106:109]
	v_mfma_f32_16x16x32_bf16 v[98:101], v[160:163], v[210:213], v[98:101]
	v_mfma_f32_16x16x32_bf16 v[90:93], v[168:171], v[210:213], v[90:93]
	v_mfma_f32_16x16x32_bf16 v[82:85], v[160:163], v[218:221], v[82:85]
	v_mfma_f32_16x16x32_bf16 v[74:77], v[168:171], v[218:221], v[74:77]
	v_mfma_f32_16x16x32_bf16 v[118:121], v[174:177], v[190:193], v[118:121]
	v_mfma_f32_16x16x32_bf16 v[110:113], v[182:185], v[190:193], v[110:113]
	v_mfma_f32_16x16x32_bf16 v[102:105], v[174:177], v[198:201], v[102:105]
	v_mfma_f32_16x16x32_bf16 v[94:97], v[182:185], v[198:201], v[94:97]
	v_mfma_f32_16x16x32_bf16 v[86:89], v[174:177], v[206:209], v[86:89]
	v_mfma_f32_16x16x32_bf16 v[78:81], v[182:185], v[206:209], v[78:81]
	v_mfma_f32_16x16x32_bf16 v[70:73], v[174:177], v[214:217], v[70:73]
	v_mfma_f32_16x16x32_bf16 v[66:69], v[182:185], v[214:217], v[66:69]
	v_mfma_f32_16x16x32_bf16 v[118:121], v[178:181], v[194:197], v[118:121]
	v_mfma_f32_16x16x32_bf16 v[110:113], v[186:189], v[194:197], v[110:113]
	v_mfma_f32_16x16x32_bf16 v[102:105], v[178:181], v[202:205], v[102:105]
	v_mfma_f32_16x16x32_bf16 v[94:97], v[186:189], v[202:205], v[94:97]
	v_mfma_f32_16x16x32_bf16 v[86:89], v[178:181], v[210:213], v[86:89]
	v_mfma_f32_16x16x32_bf16 v[78:81], v[186:189], v[210:213], v[78:81]
	v_mfma_f32_16x16x32_bf16 v[70:73], v[178:181], v[218:221], v[70:73]
	v_mfma_f32_16x16x32_bf16 v[66:69], v[186:189], v[218:221], v[66:69]
	s_barrier
; #define PG8_STAGE(bufoff, gbase, voff) do { _Pragma("unroll") for (int _i = 0; _i < 2; ++_i) \
;         __builtin_amdgcn_global_load_lds((const unsigned*)((const char*)(gbase) + (voff)[_i]), (PG8_LAS unsigned*)(lds + (bufoff) + ldsw + _i * 8192), 16, 0, 0); } while (0)
; #define PG8_LDA(dst, b, h) do { _Pragma("unroll") for (int m = 0; m < 4; ++m) _Pragma("unroll") for (int k = 0; k < 2; ++k) dst[m][k] = *(const PG8_LAS bf16x8*)(lds + PG8_SA(b, h) + aoff + m * 2048 + k * 1024); } while (0)
; #define PG8_MMA(ai, bj, At, Bt) do { __builtin_amdgcn_s_setprio(1); _Pragma("unroll") for (int m = 0; m < 4; ++m) _Pragma("unroll") for (int n = 0; n < 2; ++n) _Pragma("unroll") for (int k = 0; k < 2; ++k) \
;         acc[ai][bj][m][n] = __builtin_amdgcn_mfma_f32_16x16x32_bf16(Bt[n][k], At[m][k], acc[ai][bj][m][n], 0, 0, 0); __builtin_amdgcn_s_setprio(0); } while (0)
; #define PG8_WAIT_V(n) asm volatile("s_waitcnt vmcnt(" #n ")" ::: "memory")
; #define PG8_WAIT_L(n) asm volatile("s_waitcnt lgkmcnt(" #n ")" ::: "memory")
; #define PG8_BAR __builtin_amdgcn_s_barrier()
; #define PG8_SCHED __builtin_amdgcn_sched_barrier(0)
; template <class Epi, class Sched, bool ALIGN_EPI = false, bool SP2 = false>
; __device__ __forceinline__ void gemm_phase(PG8_LAS unsigned char* lds, const Gemm g, const Sched& S, const Epi& E) {
;     ...
;             PG8_LDA(At, 1, 1); PG8_STAGE(PG8_SB(1, 0), b3, voffB); PG8_STAGE(PG8_SB(1, 1), b3 + hstep, voffB); PG8_STAGE(PG8_SA(1, 0), a3, voffA);
;             PG8_WAIT_V(8); PG8_WAIT_L(0); PG8_BAR; PG8_MMA(1, 0, At, B0); PG8_MMA(1, 1, At, B1); PG8_BAR; PG8_SCHED;
;     ...
;         }
;         if constexpr (ALIGN_EPI) { if (wr == 0) PG8_BAR; }
	s_add_i32 s22, s61, s28
	v_lshl_add_u64 v[222:223], v[222:223], 0, s[4:5]
	s_mov_b32 m0, s22
	ds_read_b128 v[190:193], v153 offset:49152
	ds_read_b128 v[194:197], v153 offset:50176
	ds_read_b128 v[198:201], v153 offset:51200
	ds_read_b128 v[202:205], v153 offset:52224
	ds_read_b128 v[206:209], v153 offset:53248
	ds_read_b128 v[210:213], v153 offset:54272
	ds_read_b128 v[214:217], v153 offset:55296
	ds_read_b128 v[218:221], v153 offset:56320
	global_load_lds_dwordx4 v[222:223], off
	s_add_i32 m0, s22, 0x2000
	s_add_u32 s20, s20, 0x40080
	v_lshl_add_u64 v[222:223], v[224:225], 0, s[4:5]
	s_addc_u32 s21, s21, 0
	s_add_i32 s22, s62, s28
	global_load_lds_dwordx4 v[222:223], off
	v_lshl_add_u64 v[222:223], s[20:21], 0, v[134:135]
	s_mov_b32 m0, s22
	s_nop 0
	global_load_lds_dwordx4 v[222:223], off
	v_lshl_add_u64 v[222:223], s[20:21], 0, v[130:131]
	s_add_i32 m0, s22, 0x2000
	s_nop 0
	global_load_lds_dwordx4 v[222:223], off
	v_lshl_add_u64 v[222:223], v[226:227], 0, s[4:5]
	s_mov_b32 m0, s39
	s_nop 0
	global_load_lds_dwordx4 v[222:223], off
	v_lshl_add_u64 v[222:223], v[228:229], 0, s[4:5]
	s_mov_b32 m0, s40
	s_nop 0
	global_load_lds_dwordx4 v[222:223], off
	s_waitcnt vmcnt(8)
	s_waitcnt lgkmcnt(0)
	s_barrier
	s_waitcnt lgkmcnt(0)
	v_mfma_f32_16x16x32_bf16 v[62:65], v[156:159], v[190:193], v[62:65]
	v_mfma_f32_16x16x32_bf16 v[58:61], v[164:167], v[190:193], v[58:61]
	v_mfma_f32_16x16x32_bf16 v[50:53], v[156:159], v[198:201], v[50:53]
	v_mfma_f32_16x16x32_bf16 v[42:45], v[164:167], v[198:201], v[42:45]
	v_mfma_f32_16x16x32_bf16 v[34:37], v[156:159], v[206:209], v[34:37]
	v_mfma_f32_16x16x32_bf16 v[26:29], v[164:167], v[206:209], v[26:29]
	v_mfma_f32_16x16x32_bf16 v[18:21], v[156:159], v[214:217], v[18:21]
	v_mfma_f32_16x16x32_bf16 v[10:13], v[164:167], v[214:217], v[10:13]
	v_mfma_f32_16x16x32_bf16 v[62:65], v[160:163], v[194:197], v[62:65]
	v_mfma_f32_16x16x32_bf16 v[58:61], v[168:171], v[194:197], v[58:61]
	v_mfma_f32_16x16x32_bf16 v[50:53], v[160:163], v[202:205], v[50:53]
	v_mfma_f32_16x16x32_bf16 v[42:45], v[168:171], v[202:205], v[42:45]
	v_mfma_f32_16x16x32_bf16 v[34:37], v[160:163], v[210:213], v[34:37]
	v_mfma_f32_16x16x32_bf16 v[26:29], v[168:171], v[210:213], v[26:29]
	v_mfma_f32_16x16x32_bf16 v[18:21], v[160:163], v[218:221], v[18:21]
	v_mfma_f32_16x16x32_bf16 v[10:13], v[168:171], v[218:221], v[10:13]
	v_mfma_f32_16x16x32_bf16 v[54:57], v[174:177], v[190:193], v[54:57]
	v_mfma_f32_16x16x32_bf16 v[46:49], v[182:185], v[190:193], v[46:49]
	v_mfma_f32_16x16x32_bf16 v[38:41], v[174:177], v[198:201], v[38:41]
	v_mfma_f32_16x16x32_bf16 v[30:33], v[182:185], v[198:201], v[30:33]
	v_mfma_f32_16x16x32_bf16 v[22:25], v[174:177], v[206:209], v[22:25]
	v_mfma_f32_16x16x32_bf16 v[14:17], v[182:185], v[206:209], v[14:17]
	v_mfma_f32_16x16x32_bf16 v[6:9], v[174:177], v[214:217], v[6:9]
	v_mfma_f32_16x16x32_bf16 v[2:5], v[182:185], v[214:217], v[2:5]
	v_mfma_f32_16x16x32_bf16 v[54:57], v[178:181], v[194:197], v[54:57]
	v_mfma_f32_16x16x32_bf16 v[46:49], v[186:189], v[194:197], v[46:49]
	v_mfma_f32_16x16x32_bf16 v[38:41], v[178:181], v[202:205], v[38:41]
	v_mfma_f32_16x16x32_bf16 v[30:33], v[186:189], v[202:205], v[30:33]
	v_mfma_f32_16x16x32_bf16 v[22:25], v[178:181], v[210:213], v[22:25]
	v_mfma_f32_16x16x32_bf16 v[14:17], v[186:189], v[210:213], v[14:17]
	v_mfma_f32_16x16x32_bf16 v[6:9], v[178:181], v[218:221], v[6:9]
	v_mfma_f32_16x16x32_bf16 v[2:5], v[186:189], v[218:221], v[2:5]
	s_barrier
	s_add_i32 s60, s60, 2
	s_add_u32 s18, s18, 0x100
	s_addc_u32 s19, s19, 0
	s_add_u32 s56, s56, 0x100
	s_addc_u32 s57, s57, 0
	s_cmp_gt_u32 s60, 13
	s_cbranch_scc0 .LBB0_491
	s_and_b64 vcc, exec, s[6:7]
	s_cbranch_vccz .LBB0_494
	s_barrier

; #define PG8_STAGE(bufoff, gbase, voff) do { _Pragma("unroll") for (int _i = 0; _i < 2; ++_i) \
;         __builtin_amdgcn_global_load_lds((const unsigned*)((const char*)(gbase) + (voff)[_i]), (PG8_LAS unsigned*)(lds + (bufoff) + ldsw + _i * 8192), 16, 0, 0); } while (0)
; #define PG8_LDA(dst, b, h) do { _Pragma("unroll") for (int m = 0; m < 4; ++m) _Pragma("unroll") for (int k = 0; k < 2; ++k) dst[m][k] = *(const PG8_LAS bf16x8*)(lds + PG8_SA(b, h) + aoff + m * 2048 + k * 1024); } while (0)
; #define PG8_LDB(dst, b, h) do { _Pragma("unroll") for (int n = 0; n < 2; ++n) _Pragma("unroll") for (int k = 0; k < 2; ++k) dst[n][k] = *(const PG8_LAS bf16x8*)(lds + PG8_SB(b, h) + boff + n * 2048 + k * 1024); } while (0)
; #define PG8_SCHED __builtin_amdgcn_sched_barrier(0)
; template <class Epi, class Sched, bool ALIGN_EPI = false, bool SP2 = false>
; __device__ __forceinline__ void gemm_phase(PG8_LAS unsigned char* lds, const Gemm g, const Sched& S, const Epi& E) {
;     ...
;         const bool has_next = S.next(ui + 1, nxt);
;         const char* nA = has_next ? (const char*)g.A + (size_t)nxt.pm * tstep : cA; const char* nB = has_next ? (const char*)g.Bt + (size_t)nxt.pn * tstep : cB;
; #pragma nounroll
;         for (int t = 0; t < nt; t += 2) {
;             const bool last = (t == nt - 2);
;             const char* a1 = cA + (size_t)(t + 1) * kstep;
;             const char* a2 = last ? nA : cA + (size_t)(t + 2) * kstep; const char* b2 = last ? nB : cB + (size_t)(t + 2) * kstep;
;             const char* a3 = a2 + kstep; const char* b3 = b2 + kstep;
;             if (last && has_next) S.a_ready(nxt);
;             if constexpr (SP2) {
;             PG8_LDB(B0, 0, 0); PG8_LDB(B1, 0, 1); PG8_SCHED; PG8_LDA(At, 0, 0); PG8_STAGE(PG8_SA(1, 1), a1 + hstep, voffA);
.LBB0_688:
	s_ashr_i32 s23, s22, 31
	s_lshl_b64 s[24:25], s[22:23], 19
	s_add_u32 s24, s33, s24
	s_addc_u32 s25, s38, s25
	s_and_b64 s[26:27], s[2:3], exec
	s_cselect_b32 s23, s25, s29
	s_cselect_b32 s70, s24, s28
	s_ashr_i32 s21, s20, 31
	s_lshl_b64 s[26:27], s[20:21], 19
	s_add_u32 s26, s39, s26
	s_addc_u32 s27, s40, s27
	s_and_b64 s[34:35], s[2:3], exec
	s_cselect_b32 s21, s27, s31
	s_cselect_b32 s71, s26, s30
	s_add_u32 s28, s28, 0x40080
	s_addc_u32 s29, s29, 0
	s_add_u32 s72, s30, 0x100
	s_addc_u32 s73, s31, 0
	s_mov_b32 s74, -2
	ds_read_b128 v[148:151], v157
	ds_read_b128 v[152:155], v157 offset:1024
	ds_read_b128 v[160:163], v157 offset:2048
	ds_read_b128 v[164:167], v157 offset:3072
	ds_read_b128 v[168:171], v158
	ds_read_b128 v[174:177], v158 offset:1024
	ds_read_b128 v[178:181], v158 offset:2048
	ds_read_b128 v[182:185], v158 offset:3072
	s_add_u32 s30, s28, 0xfffc0080
	s_addc_u32 s31, s29, -1
	s_cmp_eq_u32 s74, 12
	s_cselect_b32 s35, s23, s31
	s_cselect_b32 s34, s70, s30
	s_cselect_b32 s31, s21, s73
	s_cselect_b32 s30, s71, s72

; #define PG8_STAGE(bufoff, gbase, voff) do { _Pragma("unroll") for (int _i = 0; _i < 2; ++_i) \
;         __builtin_amdgcn_global_load_lds((const unsigned*)((const char*)(gbase) + (voff)[_i]), (PG8_LAS unsigned*)(lds + (bufoff) + ldsw + _i * 8192), 16, 0, 0); } while (0)
; #define PG8_LDA(dst, b, h) do { _Pragma("unroll") for (int m = 0; m < 4; ++m) _Pragma("unroll") for (int k = 0; k < 2; ++k) dst[m][k] = *(const PG8_LAS bf16x8*)(lds + PG8_SA(b, h) + aoff + m * 2048 + k * 1024); } while (0)
; #define PG8_LDB(dst, b, h) do { _Pragma("unroll") for (int n = 0; n < 2; ++n) _Pragma("unroll") for (int k = 0; k < 2; ++k) dst[n][k] = *(const PG8_LAS bf16x8*)(lds + PG8_SB(b, h) + boff + n * 2048 + k * 1024); } while (0)
; #define PG8_MMA(ai, bj, At, Bt) do { __builtin_amdgcn_s_setprio(1); _Pragma("unroll") for (int m = 0; m < 4; ++m) _Pragma("unroll") for (int n = 0; n < 2; ++n) _Pragma("unroll") for (int k = 0; k < 2; ++k) \
;         acc[ai][bj][m][n] = __builtin_amdgcn_mfma_f32_16x16x32_bf16(Bt[n][k], At[m][k], acc[ai][bj][m][n], 0, 0, 0); __builtin_amdgcn_s_setprio(0); } while (0)
; #define PG8_WAIT_V(n) asm volatile("s_waitcnt vmcnt(" #n ")" ::: "memory")
; #define PG8_WAIT_L(n) asm volatile("s_waitcnt lgkmcnt(" #n ")" ::: "memory")
; #define PG8_BAR __builtin_amdgcn_s_barrier()
; #define PG8_SCHED __builtin_amdgcn_sched_barrier(0)
; template <class Epi, class Sched, bool ALIGN_EPI = false, bool SP2 = false>
; __device__ __forceinline__ void gemm_phase(PG8_LAS unsigned char* lds, const Gemm g, const Sched& S, const Epi& E) {
;     ...
;     f32x4 acc[2][2][4][2];
; #pragma unroll
;     for (int a = 0; a < 2; ++a)
; #pragma unroll
;         for (int b = 0; b < 2; ++b)
; #pragma unroll
;             for (int m = 0; m < 4; ++m)
; #pragma unroll
;                 for (int n = 0; n < 2; ++n) acc[a][b][m][n] = (f32x4){0.f, 0.f, 0.f, 0.f};
;     ...
;             PG8_LDB(B0, 0, 0); PG8_LDB(B1, 0, 1); PG8_SCHED; PG8_LDA(At, 0, 0); PG8_STAGE(PG8_SA(1, 1), a1 + hstep, voffA);
;             PG8_WAIT_V(8); PG8_WAIT_L(0); PG8_BAR; PG8_MMA(0, 0, At, B0); PG8_MMA(0, 1, At, B1); PG8_BAR; PG8_SCHED;
	v_lshl_add_u64 v[218:219], s[28:29], 0, v[140:141]
	s_add_i32 m0, s44, 0xc000
	ds_read_b128 v[186:189], v159
	ds_read_b128 v[190:193], v159 offset:1024
	ds_read_b128 v[194:197], v159 offset:2048
	ds_read_b128 v[198:201], v159 offset:3072
	ds_read_b128 v[202:205], v159 offset:4096
	ds_read_b128 v[206:209], v159 offset:5120
	ds_read_b128 v[210:213], v159 offset:6144
	ds_read_b128 v[214:217], v159 offset:7168
	global_load_lds_dwordx4 v[218:219], off
	v_lshl_add_u64 v[218:219], s[28:29], 0, v[142:143]
	s_add_i32 m0, s44, 0xe000
	s_nop 0
	global_load_lds_dwordx4 v[218:219], off
	s_waitcnt vmcnt(24)
	s_waitcnt lgkmcnt(0)
	s_barrier
	s_waitcnt lgkmcnt(0)
	v_mfma_f32_16x16x32_bf16 v[126:129], v[148:151], v[186:189], 0
	v_mfma_f32_16x16x32_bf16 v[122:125], v[160:163], v[186:189], 0
	v_mfma_f32_16x16x32_bf16 v[114:117], v[148:151], v[194:197], 0
	v_mfma_f32_16x16x32_bf16 v[106:109], v[160:163], v[194:197], 0
	v_mfma_f32_16x16x32_bf16 v[98:101], v[148:151], v[202:205], 0
	v_mfma_f32_16x16x32_bf16 v[90:93], v[160:163], v[202:205], 0
	v_mfma_f32_16x16x32_bf16 v[82:85], v[148:151], v[210:213], 0
	v_mfma_f32_16x16x32_bf16 v[74:77], v[160:163], v[210:213], 0
	v_mfma_f32_16x16x32_bf16 v[126:129], v[152:155], v[190:193], v[126:129]
	v_mfma_f32_16x16x32_bf16 v[122:125], v[164:167], v[190:193], v[122:125]
	v_mfma_f32_16x16x32_bf16 v[114:117], v[152:155], v[198:201], v[114:117]
	v_mfma_f32_16x16x32_bf16 v[106:109], v[164:167], v[198:201], v[106:109]
	v_mfma_f32_16x16x32_bf16 v[98:101], v[152:155], v[206:209], v[98:101]
	v_mfma_f32_16x16x32_bf16 v[90:93], v[164:167], v[206:209], v[90:93]
	v_mfma_f32_16x16x32_bf16 v[82:85], v[152:155], v[214:217], v[82:85]
	v_mfma_f32_16x16x32_bf16 v[74:77], v[164:167], v[214:217], v[74:77]
	v_mfma_f32_16x16x32_bf16 v[118:121], v[168:171], v[186:189], 0
	v_mfma_f32_16x16x32_bf16 v[110:113], v[178:181], v[186:189], 0
	v_mfma_f32_16x16x32_bf16 v[102:105], v[168:171], v[194:197], 0
	v_mfma_f32_16x16x32_bf16 v[94:97], v[178:181], v[194:197], 0
	v_mfma_f32_16x16x32_bf16 v[86:89], v[168:171], v[202:205], 0
	v_mfma_f32_16x16x32_bf16 v[78:81], v[178:181], v[202:205], 0
	v_mfma_f32_16x16x32_bf16 v[70:73], v[168:171], v[210:213], 0
	v_mfma_f32_16x16x32_bf16 v[66:69], v[178:181], v[210:213], 0
	v_mfma_f32_16x16x32_bf16 v[118:121], v[174:177], v[190:193], v[118:121]
	v_mfma_f32_16x16x32_bf16 v[110:113], v[182:185], v[190:193], v[110:113]
	v_mfma_f32_16x16x32_bf16 v[102:105], v[174:177], v[198:201], v[102:105]
	v_mfma_f32_16x16x32_bf16 v[94:97], v[182:185], v[198:201], v[94:97]
	v_mfma_f32_16x16x32_bf16 v[86:89], v[174:177], v[206:209], v[86:89]
	v_mfma_f32_16x16x32_bf16 v[78:81], v[182:185], v[206:209], v[78:81]
	v_mfma_f32_16x16x32_bf16 v[70:73], v[174:177], v[214:217], v[70:73]
	v_mfma_f32_16x16x32_bf16 v[66:69], v[182:185], v[214:217], v[66:69]
	s_barrier

; #define PG8_STAGE(bufoff, gbase, voff) do { _Pragma("unroll") for (int _i = 0; _i < 2; ++_i) \
;         __builtin_amdgcn_global_load_lds((const unsigned*)((const char*)(gbase) + (voff)[_i]), (PG8_LAS unsigned*)(lds + (bufoff) + ldsw + _i * 8192), 16, 0, 0); } while (0)
; #define PG8_LDA(dst, b, h) do { _Pragma("unroll") for (int m = 0; m < 4; ++m) _Pragma("unroll") for (int k = 0; k < 2; ++k) dst[m][k] = *(const PG8_LAS bf16x8*)(lds + PG8_SA(b, h) + aoff + m * 2048 + k * 1024); } while (0)
; #define PG8_MMA(ai, bj, At, Bt) do { __builtin_amdgcn_s_setprio(1); _Pragma("unroll") for (int m = 0; m < 4; ++m) _Pragma("unroll") for (int n = 0; n < 2; ++n) _Pragma("unroll") for (int k = 0; k < 2; ++k) \
;         acc[ai][bj][m][n] = __builtin_amdgcn_mfma_f32_16x16x32_bf16(Bt[n][k], At[m][k], acc[ai][bj][m][n], 0, 0, 0); __builtin_amdgcn_s_setprio(0); } while (0)
; #define PG8_WAIT_V(n) asm volatile("s_waitcnt vmcnt(" #n ")" ::: "memory")
; #define PG8_WAIT_L(n) asm volatile("s_waitcnt lgkmcnt(" #n ")" ::: "memory")
; #define PG8_BAR __builtin_amdgcn_s_barrier()
; #define PG8_SCHED __builtin_amdgcn_sched_barrier(0)
; template <class Epi, class Sched, bool ALIGN_EPI = false, bool SP2 = false>
; __device__ __forceinline__ void gemm_phase(PG8_LAS unsigned char* lds, const Gemm g, const Sched& S, const Epi& E) {
;     ...
;             PG8_LDA(At, 0, 1); PG8_STAGE(PG8_SB(0, 0), b2, voffB); PG8_STAGE(PG8_SB(0, 1), b2 + hstep, voffB); PG8_STAGE(PG8_SA(0, 0), a2, voffA);
;             PG8_WAIT_V(8); PG8_WAIT_L(0); PG8_BAR; PG8_MMA(1, 0, At, B0); PG8_MMA(1, 1, At, B1); PG8_BAR; PG8_SCHED;
	s_add_i32 s75, s63, s41
	v_lshl_add_u64 v[218:219], s[30:31], 0, v[136:137]
	s_mov_b32 m0, s75
	ds_read_b128 v[186:189], v159 offset:16384
	ds_read_b128 v[190:193], v159 offset:17408
	ds_read_b128 v[194:197], v159 offset:18432
	ds_read_b128 v[198:201], v159 offset:19456
	ds_read_b128 v[202:205], v159 offset:20480
	ds_read_b128 v[206:209], v159 offset:21504
	ds_read_b128 v[210:213], v159 offset:22528
	ds_read_b128 v[214:217], v159 offset:23552
	global_load_lds_dwordx4 v[218:219], off
	s_add_i32 m0, s75, 0x2000
	s_add_u32 s76, s30, 0x40000
	v_lshl_add_u64 v[220:221], s[30:31], 0, v[132:133]
	s_addc_u32 s77, s31, 0
	s_add_i32 s75, s66, s41
	global_load_lds_dwordx4 v[220:221], off
	v_lshl_add_u64 v[222:223], s[76:77], 0, v[136:137]
	s_mov_b32 m0, s75
	v_lshl_add_u64 v[224:225], s[34:35], 0, v[134:135]
	global_load_lds_dwordx4 v[222:223], off
	v_lshl_add_u64 v[222:223], s[76:77], 0, v[132:133]
	s_add_i32 m0, s75, 0x2000
	s_nop 0
	global_load_lds_dwordx4 v[222:223], off
	v_lshl_add_u64 v[222:223], s[34:35], 0, v[138:139]
	s_mov_b32 m0, s44
	s_nop 0
	global_load_lds_dwordx4 v[222:223], off
	s_mov_b32 m0, s45
	s_nop 0
	global_load_lds_dwordx4 v[224:225], off
	s_waitcnt vmcnt(24)
	s_waitcnt lgkmcnt(0)
	s_barrier
	s_waitcnt lgkmcnt(0)
	v_mfma_f32_16x16x32_bf16 v[62:65], v[148:151], v[186:189], 0
	v_mfma_f32_16x16x32_bf16 v[58:61], v[160:163], v[186:189], 0
	v_mfma_f32_16x16x32_bf16 v[50:53], v[148:151], v[194:197], 0
	v_mfma_f32_16x16x32_bf16 v[42:45], v[160:163], v[194:197], 0
	v_mfma_f32_16x16x32_bf16 v[34:37], v[148:151], v[202:205], 0
	v_mfma_f32_16x16x32_bf16 v[26:29], v[160:163], v[202:205], 0
	v_mfma_f32_16x16x32_bf16 v[18:21], v[148:151], v[210:213], 0
	v_mfma_f32_16x16x32_bf16 v[10:13], v[160:163], v[210:213], 0
	v_mfma_f32_16x16x32_bf16 v[62:65], v[152:155], v[190:193], v[62:65]
	v_mfma_f32_16x16x32_bf16 v[58:61], v[164:167], v[190:193], v[58:61]
	v_mfma_f32_16x16x32_bf16 v[50:53], v[152:155], v[198:201], v[50:53]
	v_mfma_f32_16x16x32_bf16 v[42:45], v[164:167], v[198:201], v[42:45]
	v_mfma_f32_16x16x32_bf16 v[34:37], v[152:155], v[206:209], v[34:37]
	v_mfma_f32_16x16x32_bf16 v[26:29], v[164:167], v[206:209], v[26:29]
	v_mfma_f32_16x16x32_bf16 v[18:21], v[152:155], v[214:217], v[18:21]
	v_mfma_f32_16x16x32_bf16 v[10:13], v[164:167], v[214:217], v[10:13]
	v_mfma_f32_16x16x32_bf16 v[54:57], v[168:171], v[186:189], 0
	v_mfma_f32_16x16x32_bf16 v[46:49], v[178:181], v[186:189], 0
	v_mfma_f32_16x16x32_bf16 v[38:41], v[168:171], v[194:197], 0
	v_mfma_f32_16x16x32_bf16 v[30:33], v[178:181], v[194:197], 0
	v_mfma_f32_16x16x32_bf16 v[22:25], v[168:171], v[202:205], 0
	v_mfma_f32_16x16x32_bf16 v[14:17], v[178:181], v[202:205], 0
	v_mfma_f32_16x16x32_bf16 v[6:9], v[168:171], v[210:213], 0
	v_mfma_f32_16x16x32_bf16 v[2:5], v[178:181], v[210:213], 0
	v_mfma_f32_16x16x32_bf16 v[54:57], v[174:177], v[190:193], v[54:57]
	v_mfma_f32_16x16x32_bf16 v[46:49], v[182:185], v[190:193], v[46:49]
	v_mfma_f32_16x16x32_bf16 v[38:41], v[174:177], v[198:201], v[38:41]
	v_mfma_f32_16x16x32_bf16 v[30:33], v[182:185], v[198:201], v[30:33]
	v_mfma_f32_16x16x32_bf16 v[22:25], v[174:177], v[206:209], v[22:25]
	v_mfma_f32_16x16x32_bf16 v[14:17], v[182:185], v[206:209], v[14:17]
	v_mfma_f32_16x16x32_bf16 v[6:9], v[174:177], v[214:217], v[6:9]
	v_mfma_f32_16x16x32_bf16 v[2:5], v[182:185], v[214:217], v[2:5]
	s_barrier

; #define PG8_STAGE(bufoff, gbase, voff) do { _Pragma("unroll") for (int _i = 0; _i < 2; ++_i) \
;         __builtin_amdgcn_global_load_lds((const unsigned*)((const char*)(gbase) + (voff)[_i]), (PG8_LAS unsigned*)(lds + (bufoff) + ldsw + _i * 8192), 16, 0, 0); } while (0)
; #define PG8_LDA(dst, b, h) do { _Pragma("unroll") for (int m = 0; m < 4; ++m) _Pragma("unroll") for (int k = 0; k < 2; ++k) dst[m][k] = *(const PG8_LAS bf16x8*)(lds + PG8_SA(b, h) + aoff + m * 2048 + k * 1024); } while (0)
; #define PG8_LDB(dst, b, h) do { _Pragma("unroll") for (int n = 0; n < 2; ++n) _Pragma("unroll") for (int k = 0; k < 2; ++k) dst[n][k] = *(const PG8_LAS bf16x8*)(lds + PG8_SB(b, h) + boff + n * 2048 + k * 1024); } while (0)
; #define PG8_SCHED __builtin_amdgcn_sched_barrier(0)
; template <class Epi, class Sched, bool ALIGN_EPI = false, bool SP2 = false>
; __device__ __forceinline__ void gemm_phase(PG8_LAS unsigned char* lds, const Gemm g, const Sched& S, const Epi& E) {
;     ...
;             PG8_LDB(B0, 1, 0); PG8_LDB(B1, 1, 1); PG8_SCHED; PG8_LDA(At, 1, 0); PG8_STAGE(PG8_SA(0, 1), a2 + hstep, voffA);
	s_add_i32 s75, 0, 0x18000
	s_add_i32 s76, 0, 0x1c000
	v_add_u32_e32 v164, s75, v131
	v_add_u32_e32 v182, s76, v131
	ds_read_b128 v[148:151], v164
	ds_read_b128 v[152:155], v164 offset:1024
	ds_read_b128 v[160:163], v164 offset:2048
	ds_read_b128 v[164:167], v164 offset:3072
	ds_read_b128 v[168:171], v182
	ds_read_b128 v[174:177], v182 offset:1024
	ds_read_b128 v[178:181], v182 offset:2048
	ds_read_b128 v[182:185], v182 offset:3072

; #define PG8_STAGE(bufoff, gbase, voff) do { _Pragma("unroll") for (int _i = 0; _i < 2; ++_i) \
;         __builtin_amdgcn_global_load_lds((const unsigned*)((const char*)(gbase) + (voff)[_i]), (PG8_LAS unsigned*)(lds + (bufoff) + ldsw + _i * 8192), 16, 0, 0); } while (0)
; #define PG8_LDA(dst, b, h) do { _Pragma("unroll") for (int m = 0; m < 4; ++m) _Pragma("unroll") for (int k = 0; k < 2; ++k) dst[m][k] = *(const PG8_LAS bf16x8*)(lds + PG8_SA(b, h) + aoff + m * 2048 + k * 1024); } while (0)
; #define PG8_LDB(dst, b, h) do { _Pragma("unroll") for (int n = 0; n < 2; ++n) _Pragma("unroll") for (int k = 0; k < 2; ++k) dst[n][k] = *(const PG8_LAS bf16x8*)(lds + PG8_SB(b, h) + boff + n * 2048 + k * 1024); } while (0)
; #define PG8_MMA(ai, bj, At, Bt) do { __builtin_amdgcn_s_setprio(1); _Pragma("unroll") for (int m = 0; m < 4; ++m) _Pragma("unroll") for (int n = 0; n < 2; ++n) _Pragma("unroll") for (int k = 0; k < 2; ++k) \
;         acc[ai][bj][m][n] = __builtin_amdgcn_mfma_f32_16x16x32_bf16(Bt[n][k], At[m][k], acc[ai][bj][m][n], 0, 0, 0); __builtin_amdgcn_s_setprio(0); } while (0)
; #define PG8_WAIT_V(n) asm volatile("s_waitcnt vmcnt(" #n ")" ::: "memory")
; #define PG8_WAIT_L(n) asm volatile("s_waitcnt lgkmcnt(" #n ")" ::: "memory")
; #define PG8_BAR __builtin_amdgcn_s_barrier()
; #define PG8_SCHED __builtin_amdgcn_sched_barrier(0)
; template <class Epi, class Sched, bool ALIGN_EPI = false, bool SP2 = false>
; __device__ __forceinline__ void gemm_phase(PG8_LAS unsigned char* lds, const Gemm g, const Sched& S, const Epi& E) {
;     ...
;             PG8_LDB(B0, 1, 0); PG8_LDB(B1, 1, 1); PG8_SCHED; PG8_LDA(At, 1, 0); PG8_STAGE(PG8_SA(0, 1), a2 + hstep, voffA);
;             PG8_WAIT_V(8); PG8_WAIT_L(0); PG8_BAR; PG8_MMA(0, 0, At, B0); PG8_MMA(0, 1, At, B1); PG8_BAR; PG8_SCHED;
	s_add_u32 s34, s34, 0x40000
	s_addc_u32 s35, s35, 0
	s_mov_b32 m0, s52
	v_lshl_add_u64 v[226:227], s[34:35], 0, v[138:139]
	ds_read_b128 v[186:189], v159 offset:32768
	ds_read_b128 v[190:193], v159 offset:33792
	ds_read_b128 v[194:197], v159 offset:34816
	ds_read_b128 v[198:201], v159 offset:35840
	ds_read_b128 v[202:205], v159 offset:36864
	ds_read_b128 v[206:209], v159 offset:37888
	ds_read_b128 v[210:213], v159 offset:38912
	ds_read_b128 v[214:217], v159 offset:39936
	global_load_lds_dwordx4 v[226:227], off
	v_lshl_add_u64 v[226:227], s[34:35], 0, v[134:135]
	s_mov_b32 m0, s53
	s_nop 0
	global_load_lds_dwordx4 v[226:227], off
	s_waitcnt vmcnt(8)
	s_waitcnt lgkmcnt(0)
	s_barrier
	s_waitcnt lgkmcnt(0)
	v_mfma_f32_16x16x32_bf16 v[126:129], v[148:151], v[186:189], v[126:129]
	v_mfma_f32_16x16x32_bf16 v[122:125], v[160:163], v[186:189], v[122:125]
	v_mfma_f32_16x16x32_bf16 v[114:117], v[148:151], v[194:197], v[114:117]
	v_mfma_f32_16x16x32_bf16 v[106:109], v[160:163], v[194:197], v[106:109]
	v_mfma_f32_16x16x32_bf16 v[98:101], v[148:151], v[202:205], v[98:101]
	v_mfma_f32_16x16x32_bf16 v[90:93], v[160:163], v[202:205], v[90:93]
	v_mfma_f32_16x16x32_bf16 v[82:85], v[148:151], v[210:213], v[82:85]
	v_mfma_f32_16x16x32_bf16 v[74:77], v[160:163], v[210:213], v[74:77]
	v_mfma_f32_16x16x32_bf16 v[126:129], v[152:155], v[190:193], v[126:129]
	v_mfma_f32_16x16x32_bf16 v[122:125], v[164:167], v[190:193], v[122:125]
	v_mfma_f32_16x16x32_bf16 v[114:117], v[152:155], v[198:201], v[114:117]
	v_mfma_f32_16x16x32_bf16 v[106:109], v[164:167], v[198:201], v[106:109]
	v_mfma_f32_16x16x32_bf16 v[98:101], v[152:155], v[206:209], v[98:101]
	v_mfma_f32_16x16x32_bf16 v[90:93], v[164:167], v[206:209], v[90:93]
	v_mfma_f32_16x16x32_bf16 v[82:85], v[152:155], v[214:217], v[82:85]
	v_mfma_f32_16x16x32_bf16 v[74:77], v[164:167], v[214:217], v[74:77]
	v_mfma_f32_16x16x32_bf16 v[118:121], v[168:171], v[186:189], v[118:121]
	v_mfma_f32_16x16x32_bf16 v[110:113], v[178:181], v[186:189], v[110:113]
	v_mfma_f32_16x16x32_bf16 v[102:105], v[168:171], v[194:197], v[102:105]
	v_mfma_f32_16x16x32_bf16 v[94:97], v[178:181], v[194:197], v[94:97]
	v_mfma_f32_16x16x32_bf16 v[86:89], v[168:171], v[202:205], v[86:89]
	v_mfma_f32_16x16x32_bf16 v[78:81], v[178:181], v[202:205], v[78:81]
	v_mfma_f32_16x16x32_bf16 v[70:73], v[168:171], v[210:213], v[70:73]
	v_mfma_f32_16x16x32_bf16 v[66:69], v[178:181], v[210:213], v[66:69]
	v_mfma_f32_16x16x32_bf16 v[118:121], v[174:177], v[190:193], v[118:121]
	v_mfma_f32_16x16x32_bf16 v[110:113], v[182:185], v[190:193], v[110:113]
	v_mfma_f32_16x16x32_bf16 v[102:105], v[174:177], v[198:201], v[102:105]
	v_mfma_f32_16x16x32_bf16 v[94:97], v[182:185], v[198:201], v[94:97]
	v_mfma_f32_16x16x32_bf16 v[86:89], v[174:177], v[206:209], v[86:89]
	v_mfma_f32_16x16x32_bf16 v[78:81], v[182:185], v[206:209], v[78:81]
	v_mfma_f32_16x16x32_bf16 v[70:73], v[174:177], v[214:217], v[70:73]
	v_mfma_f32_16x16x32_bf16 v[66:69], v[182:185], v[214:217], v[66:69]
	s_barrier

; #define PG8_STAGE(bufoff, gbase, voff) do { _Pragma("unroll") for (int _i = 0; _i < 2; ++_i) \
;         __builtin_amdgcn_global_load_lds((const unsigned*)((const char*)(gbase) + (voff)[_i]), (PG8_LAS unsigned*)(lds + (bufoff) + ldsw + _i * 8192), 16, 0, 0); } while (0)
; #define PG8_LDA(dst, b, h) do { _Pragma("unroll") for (int m = 0; m < 4; ++m) _Pragma("unroll") for (int k = 0; k < 2; ++k) dst[m][k] = *(const PG8_LAS bf16x8*)(lds + PG8_SA(b, h) + aoff + m * 2048 + k * 1024); } while (0)
; #define PG8_MMA(ai, bj, At, Bt) do { __builtin_amdgcn_s_setprio(1); _Pragma("unroll") for (int m = 0; m < 4; ++m) _Pragma("unroll") for (int n = 0; n < 2; ++n) _Pragma("unroll") for (int k = 0; k < 2; ++k) \
;         acc[ai][bj][m][n] = __builtin_amdgcn_mfma_f32_16x16x32_bf16(Bt[n][k], At[m][k], acc[ai][bj][m][n], 0, 0, 0); __builtin_amdgcn_s_setprio(0); } while (0)
; #define PG8_WAIT_V(n) asm volatile("s_waitcnt vmcnt(" #n ")" ::: "memory")
; #define PG8_WAIT_L(n) asm volatile("s_waitcnt lgkmcnt(" #n ")" ::: "memory")
; #define PG8_BAR __builtin_amdgcn_s_barrier()
; #define PG8_SCHED __builtin_amdgcn_sched_barrier(0)
; template <class Epi, class Sched, bool ALIGN_EPI = false, bool SP2 = false>
; __device__ __forceinline__ void gemm_phase(PG8_LAS unsigned char* lds, const Gemm g, const Sched& S, const Epi& E) {
;     ...
;             PG8_LDA(At, 1, 1); PG8_STAGE(PG8_SB(1, 0), b3, voffB); PG8_STAGE(PG8_SB(1, 1), b3 + hstep, voffB); PG8_STAGE(PG8_SA(1, 0), a3, voffA);
;             PG8_WAIT_V(8); PG8_WAIT_L(0); PG8_BAR; PG8_MMA(1, 0, At, B0); PG8_MMA(1, 1, At, B1); PG8_BAR; PG8_SCHED;
	s_add_i32 s34, s75, s41
	v_lshl_add_u64 v[218:219], v[218:219], 0, s[10:11]
	s_mov_b32 m0, s34
	ds_read_b128 v[186:189], v159 offset:49152
	ds_read_b128 v[190:193], v159 offset:50176
	ds_read_b128 v[194:197], v159 offset:51200
	ds_read_b128 v[198:201], v159 offset:52224
	ds_read_b128 v[202:205], v159 offset:53248
	ds_read_b128 v[206:209], v159 offset:54272
	ds_read_b128 v[210:213], v159 offset:55296
	ds_read_b128 v[214:217], v159 offset:56320
	global_load_lds_dwordx4 v[218:219], off
	s_add_i32 m0, s34, 0x2000
	s_add_u32 s30, s30, 0x40080
	v_lshl_add_u64 v[218:219], v[220:221], 0, s[10:11]
	s_addc_u32 s31, s31, 0
	s_add_i32 s34, s76, s41
	global_load_lds_dwordx4 v[218:219], off
	v_lshl_add_u64 v[218:219], s[30:31], 0, v[136:137]
	s_mov_b32 m0, s34
	s_nop 0
	global_load_lds_dwordx4 v[218:219], off
	v_lshl_add_u64 v[218:219], s[30:31], 0, v[132:133]
	s_add_i32 m0, s34, 0x2000
	s_nop 0
	global_load_lds_dwordx4 v[218:219], off
	v_lshl_add_u64 v[218:219], v[222:223], 0, s[10:11]
	s_mov_b32 m0, s57
	s_nop 0
	global_load_lds_dwordx4 v[218:219], off
	v_lshl_add_u64 v[218:219], v[224:225], 0, s[10:11]
	s_mov_b32 m0, s60
	s_nop 0
	global_load_lds_dwordx4 v[218:219], off
	s_waitcnt vmcnt(8)
	s_waitcnt lgkmcnt(0)
	s_barrier
	s_waitcnt lgkmcnt(0)
	v_mfma_f32_16x16x32_bf16 v[62:65], v[148:151], v[186:189], v[62:65]
	v_mfma_f32_16x16x32_bf16 v[58:61], v[160:163], v[186:189], v[58:61]
	v_mfma_f32_16x16x32_bf16 v[50:53], v[148:151], v[194:197], v[50:53]
	v_mfma_f32_16x16x32_bf16 v[42:45], v[160:163], v[194:197], v[42:45]
	v_mfma_f32_16x16x32_bf16 v[34:37], v[148:151], v[202:205], v[34:37]
	v_mfma_f32_16x16x32_bf16 v[26:29], v[160:163], v[202:205], v[26:29]
	v_mfma_f32_16x16x32_bf16 v[18:21], v[148:151], v[210:213], v[18:21]
	v_mfma_f32_16x16x32_bf16 v[10:13], v[160:163], v[210:213], v[10:13]
	v_mfma_f32_16x16x32_bf16 v[62:65], v[152:155], v[190:193], v[62:65]
	v_mfma_f32_16x16x32_bf16 v[58:61], v[164:167], v[190:193], v[58:61]
	v_mfma_f32_16x16x32_bf16 v[50:53], v[152:155], v[198:201], v[50:53]
	v_mfma_f32_16x16x32_bf16 v[42:45], v[164:167], v[198:201], v[42:45]
	v_mfma_f32_16x16x32_bf16 v[34:37], v[152:155], v[206:209], v[34:37]
	v_mfma_f32_16x16x32_bf16 v[26:29], v[164:167], v[206:209], v[26:29]
	v_mfma_f32_16x16x32_bf16 v[18:21], v[152:155], v[214:217], v[18:21]
	v_mfma_f32_16x16x32_bf16 v[10:13], v[164:167], v[214:217], v[10:13]
	v_mfma_f32_16x16x32_bf16 v[54:57], v[168:171], v[186:189], v[54:57]
	v_mfma_f32_16x16x32_bf16 v[46:49], v[178:181], v[186:189], v[46:49]
	v_mfma_f32_16x16x32_bf16 v[38:41], v[168:171], v[194:197], v[38:41]
	v_mfma_f32_16x16x32_bf16 v[30:33], v[178:181], v[194:197], v[30:33]
	v_mfma_f32_16x16x32_bf16 v[22:25], v[168:171], v[202:205], v[22:25]
	v_mfma_f32_16x16x32_bf16 v[14:17], v[178:181], v[202:205], v[14:17]
	v_mfma_f32_16x16x32_bf16 v[6:9], v[168:171], v[210:213], v[6:9]
	v_mfma_f32_16x16x32_bf16 v[2:5], v[178:181], v[210:213], v[2:5]
	v_mfma_f32_16x16x32_bf16 v[54:57], v[174:177], v[190:193], v[54:57]
	v_mfma_f32_16x16x32_bf16 v[46:49], v[182:185], v[190:193], v[46:49]
	v_mfma_f32_16x16x32_bf16 v[38:41], v[174:177], v[198:201], v[38:41]
	v_mfma_f32_16x16x32_bf16 v[30:33], v[182:185], v[198:201], v[30:33]
	v_mfma_f32_16x16x32_bf16 v[22:25], v[174:177], v[206:209], v[22:25]
	v_mfma_f32_16x16x32_bf16 v[14:17], v[182:185], v[206:209], v[14:17]
	v_mfma_f32_16x16x32_bf16 v[6:9], v[174:177], v[214:217], v[6:9]
	v_mfma_f32_16x16x32_bf16 v[2:5], v[182:185], v[214:217], v[2:5]
	s_barrier

; #define PG8_STAGE(bufoff, gbase, voff) do { _Pragma("unroll") for (int _i = 0; _i < 2; ++_i) \
;         __builtin_amdgcn_global_load_lds((const unsigned*)((const char*)(gbase) + (voff)[_i]), (PG8_LAS unsigned*)(lds + (bufoff) + ldsw + _i * 8192), 16, 0, 0); } while (0)
; #define PG8_LDA(dst, b, h) do { _Pragma("unroll") for (int m = 0; m < 4; ++m) _Pragma("unroll") for (int k = 0; k < 2; ++k) dst[m][k] = *(const PG8_LAS bf16x8*)(lds + PG8_SA(b, h) + aoff + m * 2048 + k * 1024); } while (0)
; #define PG8_LDB(dst, b, h) do { _Pragma("unroll") for (int n = 0; n < 2; ++n) _Pragma("unroll") for (int k = 0; k < 2; ++k) dst[n][k] = *(const PG8_LAS bf16x8*)(lds + PG8_SB(b, h) + boff + n * 2048 + k * 1024); } while (0)
; #define PG8_MMA(ai, bj, At, Bt) do { __builtin_amdgcn_s_setprio(1); _Pragma("unroll") for (int m = 0; m < 4; ++m) _Pragma("unroll") for (int n = 0; n < 2; ++n) _Pragma("unroll") for (int k = 0; k < 2; ++k) \
;         acc[ai][bj][m][n] = __builtin_amdgcn_mfma_f32_16x16x32_bf16(Bt[n][k], At[m][k], acc[ai][bj][m][n], 0, 0, 0); __builtin_amdgcn_s_setprio(0); } while (0)
; #define PG8_WAIT_V(n) asm volatile("s_waitcnt vmcnt(" #n ")" ::: "memory")
; #define PG8_WAIT_L(n) asm volatile("s_waitcnt lgkmcnt(" #n ")" ::: "memory")
; #define PG8_BAR __builtin_amdgcn_s_barrier()
; #define PG8_SCHED __builtin_amdgcn_sched_barrier(0)
; template <class Epi, class Sched, bool ALIGN_EPI = false, bool SP2 = false>
; __device__ __forceinline__ void gemm_phase(PG8_LAS unsigned char* lds, const Gemm g, const Sched& S, const Epi& E) {
;     ...
;         for (int t = 0; t < nt; t += 2) {
;             const bool last = (t == nt - 2);
;             const char* a1 = cA + (size_t)(t + 1) * kstep;
;             const char* a2 = last ? nA : cA + (size_t)(t + 2) * kstep; const char* b2 = last ? nB : cB + (size_t)(t + 2) * kstep;
;             const char* a3 = a2 + kstep; const char* b3 = b2 + kstep;
;             if (last && has_next) S.a_ready(nxt);
;             if constexpr (SP2) {
;             PG8_LDB(B0, 0, 0); PG8_LDB(B1, 0, 1); PG8_SCHED; PG8_LDA(At, 0, 0); PG8_STAGE(PG8_SA(1, 1), a1 + hstep, voffA);
;             PG8_WAIT_V(8); PG8_WAIT_L(0); PG8_BAR; PG8_MMA(0, 0, At, B0); PG8_MMA(0, 1, At, B1); PG8_BAR; PG8_SCHED;
;             PG8_LDA(At, 0, 1); PG8_STAGE(PG8_SB(0, 0), b2, voffB); PG8_STAGE(PG8_SB(0, 1), b2 + hstep, voffB); PG8_STAGE(PG8_SA(0, 0), a2, voffA);
	s_add_i32 s74, s74, 2
	s_add_u32 s28, s28, 0x100
	s_addc_u32 s29, s29, 0
	s_add_u32 s72, s72, 0x100
	s_addc_u32 s73, s73, 0
.LBB0_689:
	ds_read_b128 v[148:151], v157
	ds_read_b128 v[152:155], v157 offset:1024
	ds_read_b128 v[160:163], v157 offset:2048
	ds_read_b128 v[164:167], v157 offset:3072
	ds_read_b128 v[168:171], v158
	ds_read_b128 v[174:177], v158 offset:1024
	ds_read_b128 v[178:181], v158 offset:2048
	ds_read_b128 v[182:185], v158 offset:3072
	s_add_u32 s30, s28, 0xfffc0080
	s_addc_u32 s31, s29, -1
	s_cmp_eq_u32 s74, 12
	s_cselect_b32 s35, s23, s31
	s_cselect_b32 s34, s70, s30
	s_cselect_b32 s31, s21, s73
	s_cselect_b32 s30, s71, s72
	v_lshl_add_u64 v[218:219], s[28:29], 0, v[140:141]
	s_add_i32 m0, s44, 0xc000
	ds_read_b128 v[186:189], v159
	ds_read_b128 v[190:193], v159 offset:1024
	ds_read_b128 v[194:197], v159 offset:2048
	ds_read_b128 v[198:201], v159 offset:3072
	ds_read_b128 v[202:205], v159 offset:4096
	ds_read_b128 v[206:209], v159 offset:5120
	ds_read_b128 v[210:213], v159 offset:6144
	ds_read_b128 v[214:217], v159 offset:7168
	global_load_lds_dwordx4 v[218:219], off
	v_lshl_add_u64 v[218:219], s[28:29], 0, v[142:143]
	s_add_i32 m0, s44, 0xe000
	s_nop 0
	global_load_lds_dwordx4 v[218:219], off
	s_waitcnt vmcnt(8)
	s_waitcnt lgkmcnt(0)
	s_barrier
	s_waitcnt lgkmcnt(0)
	v_mfma_f32_16x16x32_bf16 v[126:129], v[148:151], v[186:189], v[126:129]
	v_mfma_f32_16x16x32_bf16 v[122:125], v[160:163], v[186:189], v[122:125]
	v_mfma_f32_16x16x32_bf16 v[114:117], v[148:151], v[194:197], v[114:117]
	v_mfma_f32_16x16x32_bf16 v[106:109], v[160:163], v[194:197], v[106:109]
	v_mfma_f32_16x16x32_bf16 v[98:101], v[148:151], v[202:205], v[98:101]
	v_mfma_f32_16x16x32_bf16 v[90:93], v[160:163], v[202:205], v[90:93]
	v_mfma_f32_16x16x32_bf16 v[82:85], v[148:151], v[210:213], v[82:85]
	v_mfma_f32_16x16x32_bf16 v[74:77], v[160:163], v[210:213], v[74:77]
	v_mfma_f32_16x16x32_bf16 v[126:129], v[152:155], v[190:193], v[126:129]
	v_mfma_f32_16x16x32_bf16 v[122:125], v[164:167], v[190:193], v[122:125]
	v_mfma_f32_16x16x32_bf16 v[114:117], v[152:155], v[198:201], v[114:117]
	v_mfma_f32_16x16x32_bf16 v[106:109], v[164:167], v[198:201], v[106:109]
	v_mfma_f32_16x16x32_bf16 v[98:101], v[152:155], v[206:209], v[98:101]
	v_mfma_f32_16x16x32_bf16 v[90:93], v[164:167], v[206:209], v[90:93]
	v_mfma_f32_16x16x32_bf16 v[82:85], v[152:155], v[214:217], v[82:85]
	v_mfma_f32_16x16x32_bf16 v[74:77], v[164:167], v[214:217], v[74:77]
	v_mfma_f32_16x16x32_bf16 v[118:121], v[168:171], v[186:189], v[118:121]
	v_mfma_f32_16x16x32_bf16 v[110:113], v[178:181], v[186:189], v[110:113]
	v_mfma_f32_16x16x32_bf16 v[102:105], v[168:171], v[194:197], v[102:105]
	v_mfma_f32_16x16x32_bf16 v[94:97], v[178:181], v[194:197], v[94:97]
	v_mfma_f32_16x16x32_bf16 v[86:89], v[168:171], v[202:205], v[86:89]
	v_mfma_f32_16x16x32_bf16 v[78:81], v[178:181], v[202:205], v[78:81]
	v_mfma_f32_16x16x32_bf16 v[70:73], v[168:171], v[210:213], v[70:73]
	v_mfma_f32_16x16x32_bf16 v[66:69], v[178:181], v[210:213], v[66:69]
	v_mfma_f32_16x16x32_bf16 v[118:121], v[174:177], v[190:193], v[118:121]
	v_mfma_f32_16x16x32_bf16 v[110:113], v[182:185], v[190:193], v[110:113]
	v_mfma_f32_16x16x32_bf16 v[102:105], v[174:177], v[198:201], v[102:105]
	v_mfma_f32_16x16x32_bf16 v[94:97], v[182:185], v[198:201], v[94:97]
	v_mfma_f32_16x16x32_bf16 v[86:89], v[174:177], v[206:209], v[86:89]
	v_mfma_f32_16x16x32_bf16 v[78:81], v[182:185], v[206:209], v[78:81]
	v_mfma_f32_16x16x32_bf16 v[70:73], v[174:177], v[214:217], v[70:73]
	v_mfma_f32_16x16x32_bf16 v[66:69], v[182:185], v[214:217], v[66:69]
	s_barrier
	s_add_i32 s75, s63, s41
	v_lshl_add_u64 v[218:219], s[30:31], 0, v[136:137]
	s_mov_b32 m0, s75
	ds_read_b128 v[186:189], v159 offset:16384
	ds_read_b128 v[190:193], v159 offset:17408
	ds_read_b128 v[194:197], v159 offset:18432
	ds_read_b128 v[198:201], v159 offset:19456
	ds_read_b128 v[202:205], v159 offset:20480
	ds_read_b128 v[206:209], v159 offset:21504
	ds_read_b128 v[210:213], v159 offset:22528
	ds_read_b128 v[214:217], v159 offset:23552
	global_load_lds_dwordx4 v[218:219], off
	s_add_i32 m0, s75, 0x2000
	s_add_u32 s76, s30, 0x40000
	v_lshl_add_u64 v[220:221], s[30:31], 0, v[132:133]
	s_addc_u32 s77, s31, 0
	s_add_i32 s75, s66, s41
	global_load_lds_dwordx4 v[220:221], off
	v_lshl_add_u64 v[222:223], s[76:77], 0, v[136:137]
	s_mov_b32 m0, s75
	v_lshl_add_u64 v[224:225], s[34:35], 0, v[134:135]
	global_load_lds_dwordx4 v[222:223], off
	v_lshl_add_u64 v[222:223], s[76:77], 0, v[132:133]
	s_add_i32 m0, s75, 0x2000
	s_nop 0
	global_load_lds_dwordx4 v[222:223], off
	v_lshl_add_u64 v[222:223], s[34:35], 0, v[138:139]
	s_mov_b32 m0, s44
	s_nop 0
	global_load_lds_dwordx4 v[222:223], off
	s_mov_b32 m0, s45
	s_nop 0
	global_load_lds_dwordx4 v[224:225], off
	s_waitcnt vmcnt(8)
	s_waitcnt lgkmcnt(0)
	s_barrier
; #define PG8_STAGE(bufoff, gbase, voff) do { _Pragma("unroll") for (int _i = 0; _i < 2; ++_i) \
;         __builtin_amdgcn_global_load_lds((const unsigned*)((const char*)(gbase) + (voff)[_i]), (PG8_LAS unsigned*)(lds + (bufoff) + ldsw + _i * 8192), 16, 0, 0); } while (0)
; #define PG8_LDA(dst, b, h) do { _Pragma("unroll") for (int m = 0; m < 4; ++m) _Pragma("unroll") for (int k = 0; k < 2; ++k) dst[m][k] = *(const PG8_LAS bf16x8*)(lds + PG8_SA(b, h) + aoff + m * 2048 + k * 1024); } while (0)
; #define PG8_LDB(dst, b, h) do { _Pragma("unroll") for (int n = 0; n < 2; ++n) _Pragma("unroll") for (int k = 0; k < 2; ++k) dst[n][k] = *(const PG8_LAS bf16x8*)(lds + PG8_SB(b, h) + boff + n * 2048 + k * 1024); } while (0)
; #define PG8_MMA(ai, bj, At, Bt) do { __builtin_amdgcn_s_setprio(1); _Pragma("unroll") for (int m = 0; m < 4; ++m) _Pragma("unroll") for (int n = 0; n < 2; ++n) _Pragma("unroll") for (int k = 0; k < 2; ++k) \
;         acc[ai][bj][m][n] = __builtin_amdgcn_mfma_f32_16x16x32_bf16(Bt[n][k], At[m][k], acc[ai][bj][m][n], 0, 0, 0); __builtin_amdgcn_s_setprio(0); } while (0)
; #define PG8_WAIT_V(n) asm volatile("s_waitcnt vmcnt(" #n ")" ::: "memory")
; #define PG8_WAIT_L(n) asm volatile("s_waitcnt lgkmcnt(" #n ")" ::: "memory")
; #define PG8_BAR __builtin_amdgcn_s_barrier()
; #define PG8_SCHED __builtin_amdgcn_sched_barrier(0)
; template <class Epi, class Sched, bool ALIGN_EPI = false, bool SP2 = false>
; __device__ __forceinline__ void gemm_phase(PG8_LAS unsigned char* lds, const Gemm g, const Sched& S, const Epi& E) {
;     ...
;             PG8_WAIT_V(8); PG8_WAIT_L(0); PG8_BAR; PG8_MMA(1, 0, At, B0); PG8_MMA(1, 1, At, B1); PG8_BAR; PG8_SCHED;
;             PG8_LDB(B0, 1, 0); PG8_LDB(B1, 1, 1); PG8_SCHED; PG8_LDA(At, 1, 0); PG8_STAGE(PG8_SA(0, 1), a2 + hstep, voffA);
;             PG8_WAIT_V(8); PG8_WAIT_L(0); PG8_BAR; PG8_MMA(0, 0, At, B0); PG8_MMA(0, 1, At, B1); PG8_BAR; PG8_SCHED;
	s_waitcnt lgkmcnt(0)
	v_mfma_f32_16x16x32_bf16 v[62:65], v[148:151], v[186:189], v[62:65]
	v_mfma_f32_16x16x32_bf16 v[58:61], v[160:163], v[186:189], v[58:61]
	v_mfma_f32_16x16x32_bf16 v[50:53], v[148:151], v[194:197], v[50:53]
	v_mfma_f32_16x16x32_bf16 v[42:45], v[160:163], v[194:197], v[42:45]
	v_mfma_f32_16x16x32_bf16 v[34:37], v[148:151], v[202:205], v[34:37]
	v_mfma_f32_16x16x32_bf16 v[26:29], v[160:163], v[202:205], v[26:29]
	v_mfma_f32_16x16x32_bf16 v[18:21], v[148:151], v[210:213], v[18:21]
	v_mfma_f32_16x16x32_bf16 v[10:13], v[160:163], v[210:213], v[10:13]
	v_mfma_f32_16x16x32_bf16 v[62:65], v[152:155], v[190:193], v[62:65]
	v_mfma_f32_16x16x32_bf16 v[58:61], v[164:167], v[190:193], v[58:61]
	v_mfma_f32_16x16x32_bf16 v[50:53], v[152:155], v[198:201], v[50:53]
	v_mfma_f32_16x16x32_bf16 v[42:45], v[164:167], v[198:201], v[42:45]
	v_mfma_f32_16x16x32_bf16 v[34:37], v[152:155], v[206:209], v[34:37]
	v_mfma_f32_16x16x32_bf16 v[26:29], v[164:167], v[206:209], v[26:29]
	v_mfma_f32_16x16x32_bf16 v[18:21], v[152:155], v[214:217], v[18:21]
	v_mfma_f32_16x16x32_bf16 v[10:13], v[164:167], v[214:217], v[10:13]
	v_mfma_f32_16x16x32_bf16 v[54:57], v[168:171], v[186:189], v[54:57]
	v_mfma_f32_16x16x32_bf16 v[46:49], v[178:181], v[186:189], v[46:49]
	v_mfma_f32_16x16x32_bf16 v[38:41], v[168:171], v[194:197], v[38:41]
	v_mfma_f32_16x16x32_bf16 v[30:33], v[178:181], v[194:197], v[30:33]
	v_mfma_f32_16x16x32_bf16 v[22:25], v[168:171], v[202:205], v[22:25]
	v_mfma_f32_16x16x32_bf16 v[14:17], v[178:181], v[202:205], v[14:17]
	v_mfma_f32_16x16x32_bf16 v[6:9], v[168:171], v[210:213], v[6:9]
	v_mfma_f32_16x16x32_bf16 v[2:5], v[178:181], v[210:213], v[2:5]
	v_mfma_f32_16x16x32_bf16 v[54:57], v[174:177], v[190:193], v[54:57]
	v_mfma_f32_16x16x32_bf16 v[46:49], v[182:185], v[190:193], v[46:49]
	v_mfma_f32_16x16x32_bf16 v[38:41], v[174:177], v[198:201], v[38:41]
	v_mfma_f32_16x16x32_bf16 v[30:33], v[182:185], v[198:201], v[30:33]
	v_mfma_f32_16x16x32_bf16 v[22:25], v[174:177], v[206:209], v[22:25]
	v_mfma_f32_16x16x32_bf16 v[14:17], v[182:185], v[206:209], v[14:17]
	v_mfma_f32_16x16x32_bf16 v[6:9], v[174:177], v[214:217], v[6:9]
	v_mfma_f32_16x16x32_bf16 v[2:5], v[182:185], v[214:217], v[2:5]
	s_barrier
	s_add_i32 s75, 0, 0x18000
	s_add_i32 s76, 0, 0x1c000
	v_add_u32_e32 v164, s75, v131
	v_add_u32_e32 v182, s76, v131
	ds_read_b128 v[148:151], v164
	ds_read_b128 v[152:155], v164 offset:1024
	ds_read_b128 v[160:163], v164 offset:2048
	ds_read_b128 v[164:167], v164 offset:3072
	ds_read_b128 v[168:171], v182
	ds_read_b128 v[174:177], v182 offset:1024
	ds_read_b128 v[178:181], v182 offset:2048
	ds_read_b128 v[182:185], v182 offset:3072
	s_add_u32 s34, s34, 0x40000
	s_addc_u32 s35, s35, 0
	s_mov_b32 m0, s52
	v_lshl_add_u64 v[226:227], s[34:35], 0, v[138:139]
	ds_read_b128 v[186:189], v159 offset:32768
	ds_read_b128 v[190:193], v159 offset:33792
	ds_read_b128 v[194:197], v159 offset:34816
	ds_read_b128 v[198:201], v159 offset:35840
	ds_read_b128 v[202:205], v159 offset:36864
	ds_read_b128 v[206:209], v159 offset:37888
	ds_read_b128 v[210:213], v159 offset:38912
	ds_read_b128 v[214:217], v159 offset:39936
	global_load_lds_dwordx4 v[226:227], off
	v_lshl_add_u64 v[226:227], s[34:35], 0, v[134:135]
	s_mov_b32 m0, s53
	s_nop 0
	global_load_lds_dwordx4 v[226:227], off
	s_waitcnt vmcnt(8)
	s_waitcnt lgkmcnt(0)
	s_barrier
	s_waitcnt lgkmcnt(0)
	v_mfma_f32_16x16x32_bf16 v[126:129], v[148:151], v[186:189], v[126:129]
	v_mfma_f32_16x16x32_bf16 v[122:125], v[160:163], v[186:189], v[122:125]
	v_mfma_f32_16x16x32_bf16 v[114:117], v[148:151], v[194:197], v[114:117]
	v_mfma_f32_16x16x32_bf16 v[106:109], v[160:163], v[194:197], v[106:109]
	v_mfma_f32_16x16x32_bf16 v[98:101], v[148:151], v[202:205], v[98:101]
	v_mfma_f32_16x16x32_bf16 v[90:93], v[160:163], v[202:205], v[90:93]
	v_mfma_f32_16x16x32_bf16 v[82:85], v[148:151], v[210:213], v[82:85]
	v_mfma_f32_16x16x32_bf16 v[74:77], v[160:163], v[210:213], v[74:77]
	v_mfma_f32_16x16x32_bf16 v[126:129], v[152:155], v[190:193], v[126:129]
	v_mfma_f32_16x16x32_bf16 v[122:125], v[164:167], v[190:193], v[122:125]
	v_mfma_f32_16x16x32_bf16 v[114:117], v[152:155], v[198:201], v[114:117]
	v_mfma_f32_16x16x32_bf16 v[106:109], v[164:167], v[198:201], v[106:109]
	v_mfma_f32_16x16x32_bf16 v[98:101], v[152:155], v[206:209], v[98:101]
	v_mfma_f32_16x16x32_bf16 v[90:93], v[164:167], v[206:209], v[90:93]
	v_mfma_f32_16x16x32_bf16 v[82:85], v[152:155], v[214:217], v[82:85]
	v_mfma_f32_16x16x32_bf16 v[74:77], v[164:167], v[214:217], v[74:77]
	v_mfma_f32_16x16x32_bf16 v[118:121], v[168:171], v[186:189], v[118:121]
	v_mfma_f32_16x16x32_bf16 v[110:113], v[178:181], v[186:189], v[110:113]
	v_mfma_f32_16x16x32_bf16 v[102:105], v[168:171], v[194:197], v[102:105]
	v_mfma_f32_16x16x32_bf16 v[94:97], v[178:181], v[194:197], v[94:97]
	v_mfma_f32_16x16x32_bf16 v[86:89], v[168:171], v[202:205], v[86:89]
	v_mfma_f32_16x16x32_bf16 v[78:81], v[178:181], v[202:205], v[78:81]
	v_mfma_f32_16x16x32_bf16 v[70:73], v[168:171], v[210:213], v[70:73]
	v_mfma_f32_16x16x32_bf16 v[66:69], v[178:181], v[210:213], v[66:69]
	v_mfma_f32_16x16x32_bf16 v[118:121], v[174:177], v[190:193], v[118:121]
	v_mfma_f32_16x16x32_bf16 v[110:113], v[182:185], v[190:193], v[110:113]
	v_mfma_f32_16x16x32_bf16 v[102:105], v[174:177], v[198:201], v[102:105]
	v_mfma_f32_16x16x32_bf16 v[94:97], v[182:185], v[198:201], v[94:97]
	v_mfma_f32_16x16x32_bf16 v[86:89], v[174:177], v[206:209], v[86:89]
	v_mfma_f32_16x16x32_bf16 v[78:81], v[182:185], v[206:209], v[78:81]
	v_mfma_f32_16x16x32_bf16 v[70:73], v[174:177], v[214:217], v[70:73]
	v_mfma_f32_16x16x32_bf16 v[66:69], v[182:185], v[214:217], v[66:69]
	s_barrier
; #define PG8_STAGE(bufoff, gbase, voff) do { _Pragma("unroll") for (int _i = 0; _i < 2; ++_i) \
;         __builtin_amdgcn_global_load_lds((const unsigned*)((const char*)(gbase) + (voff)[_i]), (PG8_LAS unsigned*)(lds + (bufoff) + ldsw + _i * 8192), 16, 0, 0); } while (0)
; #define PG8_LDA(dst, b, h) do { _Pragma("unroll") for (int m = 0; m < 4; ++m) _Pragma("unroll") for (int k = 0; k < 2; ++k) dst[m][k] = *(const PG8_LAS bf16x8*)(lds + PG8_SA(b, h) + aoff + m * 2048 + k * 1024); } while (0)
; #define PG8_MMA(ai, bj, At, Bt) do { __builtin_amdgcn_s_setprio(1); _Pragma("unroll") for (int m = 0; m < 4; ++m) _Pragma("unroll") for (int n = 0; n < 2; ++n) _Pragma("unroll") for (int k = 0; k < 2; ++k) \
;         acc[ai][bj][m][n] = __builtin_amdgcn_mfma_f32_16x16x32_bf16(Bt[n][k], At[m][k], acc[ai][bj][m][n], 0, 0, 0); __builtin_amdgcn_s_setprio(0); } while (0)
; #define PG8_WAIT_V(n) asm volatile("s_waitcnt vmcnt(" #n ")" ::: "memory")
; #define PG8_WAIT_L(n) asm volatile("s_waitcnt lgkmcnt(" #n ")" ::: "memory")
; #define PG8_BAR __builtin_amdgcn_s_barrier()
; #define PG8_SCHED __builtin_amdgcn_sched_barrier(0)
; template <class Epi, class Sched, bool ALIGN_EPI = false, bool SP2 = false>
; __device__ __forceinline__ void gemm_phase(PG8_LAS unsigned char* lds, const Gemm g, const Sched& S, const Epi& E) {
;     ...
;             PG8_LDA(At, 1, 1); PG8_STAGE(PG8_SB(1, 0), b3, voffB); PG8_STAGE(PG8_SB(1, 1), b3 + hstep, voffB); PG8_STAGE(PG8_SA(1, 0), a3, voffA);
;             PG8_WAIT_V(8); PG8_WAIT_L(0); PG8_BAR; PG8_MMA(1, 0, At, B0); PG8_MMA(1, 1, At, B1); PG8_BAR; PG8_SCHED;
;     ...
;         }
;         if constexpr (ALIGN_EPI) { if (wr == 0) PG8_BAR; }
	s_add_i32 s34, s75, s41
	v_lshl_add_u64 v[218:219], v[218:219], 0, s[10:11]
	s_mov_b32 m0, s34
	ds_read_b128 v[186:189], v159 offset:49152
	ds_read_b128 v[190:193], v159 offset:50176
	ds_read_b128 v[194:197], v159 offset:51200
	ds_read_b128 v[198:201], v159 offset:52224
	ds_read_b128 v[202:205], v159 offset:53248
	ds_read_b128 v[206:209], v159 offset:54272
	ds_read_b128 v[210:213], v159 offset:55296
	ds_read_b128 v[214:217], v159 offset:56320
	global_load_lds_dwordx4 v[218:219], off
	s_add_i32 m0, s34, 0x2000
	s_add_u32 s30, s30, 0x40080
	v_lshl_add_u64 v[218:219], v[220:221], 0, s[10:11]
	s_addc_u32 s31, s31, 0
	s_add_i32 s34, s76, s41
	global_load_lds_dwordx4 v[218:219], off
	v_lshl_add_u64 v[218:219], s[30:31], 0, v[136:137]
	s_mov_b32 m0, s34
	s_nop 0
	global_load_lds_dwordx4 v[218:219], off
	v_lshl_add_u64 v[218:219], s[30:31], 0, v[132:133]
	s_add_i32 m0, s34, 0x2000
	s_nop 0
	global_load_lds_dwordx4 v[218:219], off
	v_lshl_add_u64 v[218:219], v[222:223], 0, s[10:11]
	s_mov_b32 m0, s57
	s_nop 0
	global_load_lds_dwordx4 v[218:219], off
	v_lshl_add_u64 v[218:219], v[224:225], 0, s[10:11]
	s_mov_b32 m0, s60
	s_nop 0
	global_load_lds_dwordx4 v[218:219], off
	s_waitcnt vmcnt(8)
	s_waitcnt lgkmcnt(0)
	s_barrier
	s_waitcnt lgkmcnt(0)
	v_mfma_f32_16x16x32_bf16 v[62:65], v[148:151], v[186:189], v[62:65]
	v_mfma_f32_16x16x32_bf16 v[58:61], v[160:163], v[186:189], v[58:61]
	v_mfma_f32_16x16x32_bf16 v[50:53], v[148:151], v[194:197], v[50:53]
	v_mfma_f32_16x16x32_bf16 v[42:45], v[160:163], v[194:197], v[42:45]
	v_mfma_f32_16x16x32_bf16 v[34:37], v[148:151], v[202:205], v[34:37]
	v_mfma_f32_16x16x32_bf16 v[26:29], v[160:163], v[202:205], v[26:29]
	v_mfma_f32_16x16x32_bf16 v[18:21], v[148:151], v[210:213], v[18:21]
	v_mfma_f32_16x16x32_bf16 v[10:13], v[160:163], v[210:213], v[10:13]
	v_mfma_f32_16x16x32_bf16 v[62:65], v[152:155], v[190:193], v[62:65]
	v_mfma_f32_16x16x32_bf16 v[58:61], v[164:167], v[190:193], v[58:61]
	v_mfma_f32_16x16x32_bf16 v[50:53], v[152:155], v[198:201], v[50:53]
	v_mfma_f32_16x16x32_bf16 v[42:45], v[164:167], v[198:201], v[42:45]
	v_mfma_f32_16x16x32_bf16 v[34:37], v[152:155], v[206:209], v[34:37]
	v_mfma_f32_16x16x32_bf16 v[26:29], v[164:167], v[206:209], v[26:29]
	v_mfma_f32_16x16x32_bf16 v[18:21], v[152:155], v[214:217], v[18:21]
	v_mfma_f32_16x16x32_bf16 v[10:13], v[164:167], v[214:217], v[10:13]
	v_mfma_f32_16x16x32_bf16 v[54:57], v[168:171], v[186:189], v[54:57]
	v_mfma_f32_16x16x32_bf16 v[46:49], v[178:181], v[186:189], v[46:49]
	v_mfma_f32_16x16x32_bf16 v[38:41], v[168:171], v[194:197], v[38:41]
	v_mfma_f32_16x16x32_bf16 v[30:33], v[178:181], v[194:197], v[30:33]
	v_mfma_f32_16x16x32_bf16 v[22:25], v[168:171], v[202:205], v[22:25]
	v_mfma_f32_16x16x32_bf16 v[14:17], v[178:181], v[202:205], v[14:17]
	v_mfma_f32_16x16x32_bf16 v[6:9], v[168:171], v[210:213], v[6:9]
	v_mfma_f32_16x16x32_bf16 v[2:5], v[178:181], v[210:213], v[2:5]
	v_mfma_f32_16x16x32_bf16 v[54:57], v[174:177], v[190:193], v[54:57]
	v_mfma_f32_16x16x32_bf16 v[46:49], v[182:185], v[190:193], v[46:49]
	v_mfma_f32_16x16x32_bf16 v[38:41], v[174:177], v[198:201], v[38:41]
	v_mfma_f32_16x16x32_bf16 v[30:33], v[182:185], v[198:201], v[30:33]
	v_mfma_f32_16x16x32_bf16 v[22:25], v[174:177], v[206:209], v[22:25]
	v_mfma_f32_16x16x32_bf16 v[14:17], v[182:185], v[206:209], v[14:17]
	v_mfma_f32_16x16x32_bf16 v[6:9], v[174:177], v[214:217], v[6:9]
	v_mfma_f32_16x16x32_bf16 v[2:5], v[182:185], v[214:217], v[2:5]
	s_barrier
	s_add_i32 s74, s74, 2
	s_add_u32 s28, s28, 0x100
	s_addc_u32 s29, s29, 0
	s_add_u32 s72, s72, 0x100
	s_addc_u32 s73, s73, 0
	s_cmp_gt_u32 s74, 13
	s_cbranch_scc0 .LBB0_689
	s_and_b64 vcc, exec, s[12:13]
	s_cbranch_vccz .LBB0_692
	s_barrier

; #define PG8_STAGE(bufoff, gbase, voff) do { _Pragma("unroll") for (int _i = 0; _i < 2; ++_i) \
;         __builtin_amdgcn_global_load_lds((const unsigned*)((const char*)(gbase) + (voff)[_i]), (PG8_LAS unsigned*)(lds + (bufoff) + ldsw + _i * 8192), 16, 0, 0); } while (0)
; #define PG8_LDA(dst, b, h) do { _Pragma("unroll") for (int m = 0; m < 4; ++m) _Pragma("unroll") for (int k = 0; k < 2; ++k) dst[m][k] = *(const PG8_LAS bf16x8*)(lds + PG8_SA(b, h) + aoff + m * 2048 + k * 1024); } while (0)
; #define PG8_LDB(dst, b, h) do { _Pragma("unroll") for (int n = 0; n < 2; ++n) _Pragma("unroll") for (int k = 0; k < 2; ++k) dst[n][k] = *(const PG8_LAS bf16x8*)(lds + PG8_SB(b, h) + boff + n * 2048 + k * 1024); } while (0)
; #define PG8_SCHED __builtin_amdgcn_sched_barrier(0)
; template <class Epi, class Sched, bool ALIGN_EPI = false, bool SP2 = false>
; __device__ __forceinline__ void gemm_phase(PG8_LAS unsigned char* lds, const Gemm g, const Sched& S, const Epi& E) {
;     ...
;         for (int t = 0; t < nt; t += 2) {
;             const bool last = (t == nt - 2);
;             const char* a1 = cA + (size_t)(t + 1) * kstep;
;             const char* a2 = last ? nA : cA + (size_t)(t + 2) * kstep; const char* b2 = last ? nB : cB + (size_t)(t + 2) * kstep;
;             const char* a3 = a2 + kstep; const char* b3 = b2 + kstep;
;             if (last && has_next) S.a_ready(nxt);
;             if constexpr (SP2) {
;             PG8_LDB(B0, 0, 0); PG8_LDB(B1, 0, 1); PG8_SCHED; PG8_LDA(At, 0, 0); PG8_STAGE(PG8_SA(1, 1), a1 + hstep, voffA);
.LBB0_864:
	s_cmp_gt_i32 s33, 7
	s_cselect_b32 s98, 2, 0
	s_add_i32 s101, s98, -2
	s_add_u32 s4, s8, 0x18080
	s_addc_u32 s5, s9, 0
	s_add_u32 s35, s6, 0x100
	s_addc_u32 s70, s7, 0
	s_mov_b32 s71, -2
	ds_read_b128 v[148:151], v170
	ds_read_b128 v[152:155], v170 offset:1024
	ds_read_b128 v[156:159], v170 offset:2048
	ds_read_b128 v[160:163], v170 offset:3072
	ds_read_b128 v[164:167], v171
	ds_read_b128 v[176:179], v171 offset:1024
	ds_read_b128 v[180:183], v171 offset:2048
	ds_read_b128 v[184:187], v171 offset:3072
	s_add_u32 s6, s4, 0xfffe8080
	s_addc_u32 s7, s5, -1
	s_cmp_eq_u32 s71, s101
	s_cselect_b32 s9, s29, s7
	s_cselect_b32 s8, s28, s6
	s_cselect_b32 s7, s31, s70
	s_cselect_b32 s6, s30, s35

; #define PG8_STAGE(bufoff, gbase, voff) do { _Pragma("unroll") for (int _i = 0; _i < 2; ++_i) \
;         __builtin_amdgcn_global_load_lds((const unsigned*)((const char*)(gbase) + (voff)[_i]), (PG8_LAS unsigned*)(lds + (bufoff) + ldsw + _i * 8192), 16, 0, 0); } while (0)
; #define PG8_LDA(dst, b, h) do { _Pragma("unroll") for (int m = 0; m < 4; ++m) _Pragma("unroll") for (int k = 0; k < 2; ++k) dst[m][k] = *(const PG8_LAS bf16x8*)(lds + PG8_SA(b, h) + aoff + m * 2048 + k * 1024); } while (0)
; #define PG8_LDB(dst, b, h) do { _Pragma("unroll") for (int n = 0; n < 2; ++n) _Pragma("unroll") for (int k = 0; k < 2; ++k) dst[n][k] = *(const PG8_LAS bf16x8*)(lds + PG8_SB(b, h) + boff + n * 2048 + k * 1024); } while (0)
; #define PG8_MMA(ai, bj, At, Bt) do { __builtin_amdgcn_s_setprio(1); _Pragma("unroll") for (int m = 0; m < 4; ++m) _Pragma("unroll") for (int n = 0; n < 2; ++n) _Pragma("unroll") for (int k = 0; k < 2; ++k) \
;         acc[ai][bj][m][n] = __builtin_amdgcn_mfma_f32_16x16x32_bf16(Bt[n][k], At[m][k], acc[ai][bj][m][n], 0, 0, 0); __builtin_amdgcn_s_setprio(0); } while (0)
; #define PG8_WAIT_V(n) asm volatile("s_waitcnt vmcnt(" #n ")" ::: "memory")
; #define PG8_WAIT_L(n) asm volatile("s_waitcnt lgkmcnt(" #n ")" ::: "memory")
; #define PG8_BAR __builtin_amdgcn_s_barrier()
; #define PG8_SCHED __builtin_amdgcn_sched_barrier(0)
; template <class Epi, class Sched, bool ALIGN_EPI = false, bool SP2 = false>
; __device__ __forceinline__ void gemm_phase(PG8_LAS unsigned char* lds, const Gemm g, const Sched& S, const Epi& E) {
;     ...
;     f32x4 acc[2][2][4][2];
; #pragma unroll
;     for (int a = 0; a < 2; ++a)
; #pragma unroll
;         for (int b = 0; b < 2; ++b)
; #pragma unroll
;             for (int m = 0; m < 4; ++m)
; #pragma unroll
;                 for (int n = 0; n < 2; ++n) acc[a][b][m][n] = (f32x4){0.f, 0.f, 0.f, 0.f};
;     ...
;             PG8_LDB(B0, 0, 0); PG8_LDB(B1, 0, 1); PG8_SCHED; PG8_LDA(At, 0, 0); PG8_STAGE(PG8_SA(1, 1), a1 + hstep, voffA);
;             PG8_WAIT_V(8); PG8_WAIT_L(0); PG8_BAR; PG8_MMA(0, 0, At, B0); PG8_MMA(0, 1, At, B1); PG8_BAR; PG8_SCHED;
	v_lshl_add_u64 v[220:221], s[4:5], 0, v[140:141]
	s_add_i32 m0, s43, 0xc000
	ds_read_b128 v[188:191], v174
	ds_read_b128 v[192:195], v174 offset:1024
	ds_read_b128 v[196:199], v174 offset:2048
	ds_read_b128 v[200:203], v174 offset:3072
	ds_read_b128 v[204:207], v174 offset:4096
	ds_read_b128 v[208:211], v174 offset:5120
	ds_read_b128 v[212:215], v174 offset:6144
	ds_read_b128 v[216:219], v174 offset:7168
	global_load_lds_dwordx4 v[220:221], off
	v_lshl_add_u64 v[220:221], s[4:5], 0, v[142:143]
	s_add_i32 m0, s43, 0xe000
	s_nop 0
	global_load_lds_dwordx4 v[220:221], off
	s_waitcnt vmcnt(8)
	s_waitcnt lgkmcnt(0)
	s_barrier
	s_waitcnt lgkmcnt(0)
	v_mfma_f32_16x16x32_bf16 v[126:129], v[148:151], v[188:191], 0
	v_mfma_f32_16x16x32_bf16 v[122:125], v[156:159], v[188:191], 0
	v_mfma_f32_16x16x32_bf16 v[110:113], v[148:151], v[196:199], 0
	v_mfma_f32_16x16x32_bf16 v[106:109], v[156:159], v[196:199], 0
	v_mfma_f32_16x16x32_bf16 v[94:97], v[148:151], v[204:207], 0
	v_mfma_f32_16x16x32_bf16 v[90:93], v[156:159], v[204:207], 0
	v_mfma_f32_16x16x32_bf16 v[78:81], v[148:151], v[212:215], 0
	v_mfma_f32_16x16x32_bf16 v[74:77], v[156:159], v[212:215], 0
	v_mfma_f32_16x16x32_bf16 v[126:129], v[152:155], v[192:195], v[126:129]
	v_mfma_f32_16x16x32_bf16 v[122:125], v[160:163], v[192:195], v[122:125]
	v_mfma_f32_16x16x32_bf16 v[110:113], v[152:155], v[200:203], v[110:113]
	v_mfma_f32_16x16x32_bf16 v[106:109], v[160:163], v[200:203], v[106:109]
	v_mfma_f32_16x16x32_bf16 v[94:97], v[152:155], v[208:211], v[94:97]
	v_mfma_f32_16x16x32_bf16 v[90:93], v[160:163], v[208:211], v[90:93]
	v_mfma_f32_16x16x32_bf16 v[78:81], v[152:155], v[216:219], v[78:81]
	v_mfma_f32_16x16x32_bf16 v[74:77], v[160:163], v[216:219], v[74:77]
	v_mfma_f32_16x16x32_bf16 v[118:121], v[164:167], v[188:191], 0
	v_mfma_f32_16x16x32_bf16 v[114:117], v[180:183], v[188:191], 0
	v_mfma_f32_16x16x32_bf16 v[102:105], v[164:167], v[196:199], 0
	v_mfma_f32_16x16x32_bf16 v[98:101], v[180:183], v[196:199], 0
	v_mfma_f32_16x16x32_bf16 v[86:89], v[164:167], v[204:207], 0
	v_mfma_f32_16x16x32_bf16 v[82:85], v[180:183], v[204:207], 0
	v_mfma_f32_16x16x32_bf16 v[70:73], v[164:167], v[212:215], 0
	v_mfma_f32_16x16x32_bf16 v[66:69], v[180:183], v[212:215], 0
	v_mfma_f32_16x16x32_bf16 v[118:121], v[176:179], v[192:195], v[118:121]
	v_mfma_f32_16x16x32_bf16 v[114:117], v[184:187], v[192:195], v[114:117]
	v_mfma_f32_16x16x32_bf16 v[102:105], v[176:179], v[200:203], v[102:105]
	v_mfma_f32_16x16x32_bf16 v[98:101], v[184:187], v[200:203], v[98:101]
	v_mfma_f32_16x16x32_bf16 v[86:89], v[176:179], v[208:211], v[86:89]
	v_mfma_f32_16x16x32_bf16 v[82:85], v[184:187], v[208:211], v[82:85]
	v_mfma_f32_16x16x32_bf16 v[70:73], v[176:179], v[216:219], v[70:73]
	v_mfma_f32_16x16x32_bf16 v[66:69], v[184:187], v[216:219], v[66:69]
	s_barrier

; #define PG8_STAGE(bufoff, gbase, voff) do { _Pragma("unroll") for (int _i = 0; _i < 2; ++_i) \
;         __builtin_amdgcn_global_load_lds((const unsigned*)((const char*)(gbase) + (voff)[_i]), (PG8_LAS unsigned*)(lds + (bufoff) + ldsw + _i * 8192), 16, 0, 0); } while (0)
; #define PG8_LDA(dst, b, h) do { _Pragma("unroll") for (int m = 0; m < 4; ++m) _Pragma("unroll") for (int k = 0; k < 2; ++k) dst[m][k] = *(const PG8_LAS bf16x8*)(lds + PG8_SA(b, h) + aoff + m * 2048 + k * 1024); } while (0)
; #define PG8_MMA(ai, bj, At, Bt) do { __builtin_amdgcn_s_setprio(1); _Pragma("unroll") for (int m = 0; m < 4; ++m) _Pragma("unroll") for (int n = 0; n < 2; ++n) _Pragma("unroll") for (int k = 0; k < 2; ++k) \
;         acc[ai][bj][m][n] = __builtin_amdgcn_mfma_f32_16x16x32_bf16(Bt[n][k], At[m][k], acc[ai][bj][m][n], 0, 0, 0); __builtin_amdgcn_s_setprio(0); } while (0)
; #define PG8_WAIT_V(n) asm volatile("s_waitcnt vmcnt(" #n ")" ::: "memory")
; #define PG8_WAIT_L(n) asm volatile("s_waitcnt lgkmcnt(" #n ")" ::: "memory")
; #define PG8_BAR __builtin_amdgcn_s_barrier()
; #define PG8_SCHED __builtin_amdgcn_sched_barrier(0)
; template <class Epi, class Sched, bool ALIGN_EPI = false, bool SP2 = false>
; __device__ __forceinline__ void gemm_phase(PG8_LAS unsigned char* lds, const Gemm g, const Sched& S, const Epi& E) {
;     ...
;             PG8_LDA(At, 0, 1); PG8_STAGE(PG8_SB(0, 0), b2, voffB); PG8_STAGE(PG8_SB(0, 1), b2 + hstep, voffB); PG8_STAGE(PG8_SA(0, 0), a2, voffA);
;             PG8_WAIT_V(8); PG8_WAIT_L(0); PG8_BAR; PG8_MMA(1, 0, At, B0); PG8_MMA(1, 1, At, B1); PG8_BAR; PG8_SCHED;
	s_add_i32 s72, s66, s42
	v_lshl_add_u64 v[220:221], s[6:7], 0, v[132:133]
	s_mov_b32 m0, s72
	ds_read_b128 v[188:191], v174 offset:16384
	ds_read_b128 v[192:195], v174 offset:17408
	ds_read_b128 v[196:199], v174 offset:18432
	ds_read_b128 v[200:203], v174 offset:19456
	ds_read_b128 v[204:207], v174 offset:20480
	ds_read_b128 v[208:211], v174 offset:21504
	ds_read_b128 v[212:215], v174 offset:22528
	ds_read_b128 v[216:219], v174 offset:23552
	global_load_lds_dwordx4 v[220:221], off
	s_add_i32 m0, s72, 0x2000
	s_add_u32 s72, s6, 0x18000
	v_lshl_add_u64 v[222:223], s[6:7], 0, v[136:137]
	s_addc_u32 s73, s7, 0
	s_add_i32 s74, s67, s42
	global_load_lds_dwordx4 v[222:223], off
	v_lshl_add_u64 v[224:225], s[72:73], 0, v[132:133]
	s_mov_b32 m0, s74
	v_lshl_add_u64 v[226:227], s[8:9], 0, v[134:135]
	global_load_lds_dwordx4 v[224:225], off
	v_lshl_add_u64 v[224:225], s[72:73], 0, v[136:137]
	s_add_i32 m0, s74, 0x2000
	s_nop 0
	global_load_lds_dwordx4 v[224:225], off
	v_lshl_add_u64 v[224:225], s[8:9], 0, v[130:131]
	s_mov_b32 m0, s43
	s_nop 0
	global_load_lds_dwordx4 v[224:225], off
	s_mov_b32 m0, s44
	s_nop 0
	global_load_lds_dwordx4 v[226:227], off
	s_waitcnt vmcnt(8)
	s_waitcnt lgkmcnt(0)
	s_barrier
	s_waitcnt lgkmcnt(0)
	v_mfma_f32_16x16x32_bf16 v[62:65], v[148:151], v[188:191], 0
	v_mfma_f32_16x16x32_bf16 v[58:61], v[156:159], v[188:191], 0
	v_mfma_f32_16x16x32_bf16 v[46:49], v[148:151], v[196:199], 0
	v_mfma_f32_16x16x32_bf16 v[42:45], v[156:159], v[196:199], 0
	v_mfma_f32_16x16x32_bf16 v[30:33], v[148:151], v[204:207], 0
	v_mfma_f32_16x16x32_bf16 v[26:29], v[156:159], v[204:207], 0
	v_mfma_f32_16x16x32_bf16 v[14:17], v[148:151], v[212:215], 0
	v_mfma_f32_16x16x32_bf16 v[10:13], v[156:159], v[212:215], 0
	v_mfma_f32_16x16x32_bf16 v[62:65], v[152:155], v[192:195], v[62:65]
	v_mfma_f32_16x16x32_bf16 v[58:61], v[160:163], v[192:195], v[58:61]
	v_mfma_f32_16x16x32_bf16 v[46:49], v[152:155], v[200:203], v[46:49]
	v_mfma_f32_16x16x32_bf16 v[42:45], v[160:163], v[200:203], v[42:45]
	v_mfma_f32_16x16x32_bf16 v[30:33], v[152:155], v[208:211], v[30:33]
	v_mfma_f32_16x16x32_bf16 v[26:29], v[160:163], v[208:211], v[26:29]
	v_mfma_f32_16x16x32_bf16 v[14:17], v[152:155], v[216:219], v[14:17]
	v_mfma_f32_16x16x32_bf16 v[10:13], v[160:163], v[216:219], v[10:13]
	v_mfma_f32_16x16x32_bf16 v[54:57], v[164:167], v[188:191], 0
	v_mfma_f32_16x16x32_bf16 v[50:53], v[180:183], v[188:191], 0
	v_mfma_f32_16x16x32_bf16 v[38:41], v[164:167], v[196:199], 0
	v_mfma_f32_16x16x32_bf16 v[34:37], v[180:183], v[196:199], 0
	v_mfma_f32_16x16x32_bf16 v[22:25], v[164:167], v[204:207], 0
	v_mfma_f32_16x16x32_bf16 v[18:21], v[180:183], v[204:207], 0
	v_mfma_f32_16x16x32_bf16 v[6:9], v[164:167], v[212:215], 0
	v_mfma_f32_16x16x32_bf16 v[2:5], v[180:183], v[212:215], 0
	v_mfma_f32_16x16x32_bf16 v[54:57], v[176:179], v[192:195], v[54:57]
	v_mfma_f32_16x16x32_bf16 v[50:53], v[184:187], v[192:195], v[50:53]
	v_mfma_f32_16x16x32_bf16 v[38:41], v[176:179], v[200:203], v[38:41]
	v_mfma_f32_16x16x32_bf16 v[34:37], v[184:187], v[200:203], v[34:37]
	v_mfma_f32_16x16x32_bf16 v[22:25], v[176:179], v[208:211], v[22:25]
	v_mfma_f32_16x16x32_bf16 v[18:21], v[184:187], v[208:211], v[18:21]
	v_mfma_f32_16x16x32_bf16 v[6:9], v[176:179], v[216:219], v[6:9]
	v_mfma_f32_16x16x32_bf16 v[2:5], v[184:187], v[216:219], v[2:5]
	s_barrier

; #define PG8_STAGE(bufoff, gbase, voff) do { _Pragma("unroll") for (int _i = 0; _i < 2; ++_i) \
;         __builtin_amdgcn_global_load_lds((const unsigned*)((const char*)(gbase) + (voff)[_i]), (PG8_LAS unsigned*)(lds + (bufoff) + ldsw + _i * 8192), 16, 0, 0); } while (0)
; #define PG8_LDA(dst, b, h) do { _Pragma("unroll") for (int m = 0; m < 4; ++m) _Pragma("unroll") for (int k = 0; k < 2; ++k) dst[m][k] = *(const PG8_LAS bf16x8*)(lds + PG8_SA(b, h) + aoff + m * 2048 + k * 1024); } while (0)
; #define PG8_LDB(dst, b, h) do { _Pragma("unroll") for (int n = 0; n < 2; ++n) _Pragma("unroll") for (int k = 0; k < 2; ++k) dst[n][k] = *(const PG8_LAS bf16x8*)(lds + PG8_SB(b, h) + boff + n * 2048 + k * 1024); } while (0)
; #define PG8_SCHED __builtin_amdgcn_sched_barrier(0)
; template <class Epi, class Sched, bool ALIGN_EPI = false, bool SP2 = false>
; __device__ __forceinline__ void gemm_phase(PG8_LAS unsigned char* lds, const Gemm g, const Sched& S, const Epi& E) {
;     ...
;             PG8_LDB(B0, 1, 0); PG8_LDB(B1, 1, 1); PG8_SCHED; PG8_LDA(At, 1, 0); PG8_STAGE(PG8_SA(0, 1), a2 + hstep, voffA);
	s_add_i32 s72, 0, 0x18000
	v_add_u32_e32 v138, s72, v168
	s_add_i32 s73, 0, 0x1c000
	ds_read_b128 v[148:151], v138
	ds_read_b128 v[152:155], v138 offset:1024
	ds_read_b128 v[156:159], v138 offset:2048
	ds_read_b128 v[160:163], v138 offset:3072
	v_add_u32_e32 v138, s73, v168
	ds_read_b128 v[164:167], v138
	ds_read_b128 v[176:179], v138 offset:1024
	ds_read_b128 v[180:183], v138 offset:2048
	ds_read_b128 v[184:187], v138 offset:3072

; #define PG8_STAGE(bufoff, gbase, voff) do { _Pragma("unroll") for (int _i = 0; _i < 2; ++_i) \
;         __builtin_amdgcn_global_load_lds((const unsigned*)((const char*)(gbase) + (voff)[_i]), (PG8_LAS unsigned*)(lds + (bufoff) + ldsw + _i * 8192), 16, 0, 0); } while (0)
; #define PG8_LDA(dst, b, h) do { _Pragma("unroll") for (int m = 0; m < 4; ++m) _Pragma("unroll") for (int k = 0; k < 2; ++k) dst[m][k] = *(const PG8_LAS bf16x8*)(lds + PG8_SA(b, h) + aoff + m * 2048 + k * 1024); } while (0)
; #define PG8_LDB(dst, b, h) do { _Pragma("unroll") for (int n = 0; n < 2; ++n) _Pragma("unroll") for (int k = 0; k < 2; ++k) dst[n][k] = *(const PG8_LAS bf16x8*)(lds + PG8_SB(b, h) + boff + n * 2048 + k * 1024); } while (0)
; #define PG8_MMA(ai, bj, At, Bt) do { __builtin_amdgcn_s_setprio(1); _Pragma("unroll") for (int m = 0; m < 4; ++m) _Pragma("unroll") for (int n = 0; n < 2; ++n) _Pragma("unroll") for (int k = 0; k < 2; ++k) \
;         acc[ai][bj][m][n] = __builtin_amdgcn_mfma_f32_16x16x32_bf16(Bt[n][k], At[m][k], acc[ai][bj][m][n], 0, 0, 0); __builtin_amdgcn_s_setprio(0); } while (0)
; #define PG8_WAIT_V(n) asm volatile("s_waitcnt vmcnt(" #n ")" ::: "memory")
; #define PG8_WAIT_L(n) asm volatile("s_waitcnt lgkmcnt(" #n ")" ::: "memory")
; #define PG8_BAR __builtin_amdgcn_s_barrier()
; #define PG8_SCHED __builtin_amdgcn_sched_barrier(0)
; template <class Epi, class Sched, bool ALIGN_EPI = false, bool SP2 = false>
; __device__ __forceinline__ void gemm_phase(PG8_LAS unsigned char* lds, const Gemm g, const Sched& S, const Epi& E) {
;     ...
;             PG8_LDB(B0, 1, 0); PG8_LDB(B1, 1, 1); PG8_SCHED; PG8_LDA(At, 1, 0); PG8_STAGE(PG8_SA(0, 1), a2 + hstep, voffA);
;             PG8_WAIT_V(8); PG8_WAIT_L(0); PG8_BAR; PG8_MMA(0, 0, At, B0); PG8_MMA(0, 1, At, B1); PG8_BAR; PG8_SCHED;
	s_add_u32 s8, s8, 0x18000
	s_addc_u32 s9, s9, 0
	s_mov_b32 m0, s45
	v_lshl_add_u64 v[228:229], s[8:9], 0, v[130:131]
	ds_read_b128 v[188:191], v174 offset:32768
	ds_read_b128 v[192:195], v174 offset:33792
	ds_read_b128 v[196:199], v174 offset:34816
	ds_read_b128 v[200:203], v174 offset:35840
	ds_read_b128 v[204:207], v174 offset:36864
	ds_read_b128 v[208:211], v174 offset:37888
	ds_read_b128 v[212:215], v174 offset:38912
	ds_read_b128 v[216:219], v174 offset:39936
	global_load_lds_dwordx4 v[228:229], off
	v_lshl_add_u64 v[228:229], s[8:9], 0, v[134:135]
	s_mov_b32 m0, s52
	s_nop 0
	global_load_lds_dwordx4 v[228:229], off
	s_waitcnt vmcnt(8)
	s_waitcnt lgkmcnt(0)
	s_barrier
	s_waitcnt lgkmcnt(0)
	v_mfma_f32_16x16x32_bf16 v[126:129], v[148:151], v[188:191], v[126:129]
	v_mfma_f32_16x16x32_bf16 v[122:125], v[156:159], v[188:191], v[122:125]
	v_mfma_f32_16x16x32_bf16 v[110:113], v[148:151], v[196:199], v[110:113]
	v_mfma_f32_16x16x32_bf16 v[106:109], v[156:159], v[196:199], v[106:109]
	v_mfma_f32_16x16x32_bf16 v[94:97], v[148:151], v[204:207], v[94:97]
	v_mfma_f32_16x16x32_bf16 v[90:93], v[156:159], v[204:207], v[90:93]
	v_mfma_f32_16x16x32_bf16 v[78:81], v[148:151], v[212:215], v[78:81]
	v_mfma_f32_16x16x32_bf16 v[74:77], v[156:159], v[212:215], v[74:77]
	v_mfma_f32_16x16x32_bf16 v[126:129], v[152:155], v[192:195], v[126:129]
	v_mfma_f32_16x16x32_bf16 v[122:125], v[160:163], v[192:195], v[122:125]
	v_mfma_f32_16x16x32_bf16 v[110:113], v[152:155], v[200:203], v[110:113]
	v_mfma_f32_16x16x32_bf16 v[106:109], v[160:163], v[200:203], v[106:109]
	v_mfma_f32_16x16x32_bf16 v[94:97], v[152:155], v[208:211], v[94:97]
	v_mfma_f32_16x16x32_bf16 v[90:93], v[160:163], v[208:211], v[90:93]
	v_mfma_f32_16x16x32_bf16 v[78:81], v[152:155], v[216:219], v[78:81]
	v_mfma_f32_16x16x32_bf16 v[74:77], v[160:163], v[216:219], v[74:77]
	v_mfma_f32_16x16x32_bf16 v[118:121], v[164:167], v[188:191], v[118:121]
	v_mfma_f32_16x16x32_bf16 v[114:117], v[180:183], v[188:191], v[114:117]
	v_mfma_f32_16x16x32_bf16 v[102:105], v[164:167], v[196:199], v[102:105]
	v_mfma_f32_16x16x32_bf16 v[98:101], v[180:183], v[196:199], v[98:101]
	v_mfma_f32_16x16x32_bf16 v[86:89], v[164:167], v[204:207], v[86:89]
	v_mfma_f32_16x16x32_bf16 v[82:85], v[180:183], v[204:207], v[82:85]
	v_mfma_f32_16x16x32_bf16 v[70:73], v[164:167], v[212:215], v[70:73]
	v_mfma_f32_16x16x32_bf16 v[66:69], v[180:183], v[212:215], v[66:69]
	v_mfma_f32_16x16x32_bf16 v[118:121], v[176:179], v[192:195], v[118:121]
	v_mfma_f32_16x16x32_bf16 v[114:117], v[184:187], v[192:195], v[114:117]
	v_mfma_f32_16x16x32_bf16 v[102:105], v[176:179], v[200:203], v[102:105]
	v_mfma_f32_16x16x32_bf16 v[98:101], v[184:187], v[200:203], v[98:101]
	v_mfma_f32_16x16x32_bf16 v[86:89], v[176:179], v[208:211], v[86:89]
	v_mfma_f32_16x16x32_bf16 v[82:85], v[184:187], v[208:211], v[82:85]
	v_mfma_f32_16x16x32_bf16 v[70:73], v[176:179], v[216:219], v[70:73]
	v_mfma_f32_16x16x32_bf16 v[66:69], v[184:187], v[216:219], v[66:69]
	s_barrier

; #define PG8_STAGE(bufoff, gbase, voff) do { _Pragma("unroll") for (int _i = 0; _i < 2; ++_i) \
;         __builtin_amdgcn_global_load_lds((const unsigned*)((const char*)(gbase) + (voff)[_i]), (PG8_LAS unsigned*)(lds + (bufoff) + ldsw + _i * 8192), 16, 0, 0); } while (0)
; #define PG8_LDA(dst, b, h) do { _Pragma("unroll") for (int m = 0; m < 4; ++m) _Pragma("unroll") for (int k = 0; k < 2; ++k) dst[m][k] = *(const PG8_LAS bf16x8*)(lds + PG8_SA(b, h) + aoff + m * 2048 + k * 1024); } while (0)
; #define PG8_MMA(ai, bj, At, Bt) do { __builtin_amdgcn_s_setprio(1); _Pragma("unroll") for (int m = 0; m < 4; ++m) _Pragma("unroll") for (int n = 0; n < 2; ++n) _Pragma("unroll") for (int k = 0; k < 2; ++k) \
;         acc[ai][bj][m][n] = __builtin_amdgcn_mfma_f32_16x16x32_bf16(Bt[n][k], At[m][k], acc[ai][bj][m][n], 0, 0, 0); __builtin_amdgcn_s_setprio(0); } while (0)
; #define PG8_WAIT_V(n) asm volatile("s_waitcnt vmcnt(" #n ")" ::: "memory")
; #define PG8_WAIT_L(n) asm volatile("s_waitcnt lgkmcnt(" #n ")" ::: "memory")
; #define PG8_BAR __builtin_amdgcn_s_barrier()
; #define PG8_SCHED __builtin_amdgcn_sched_barrier(0)
; template <class Epi, class Sched, bool ALIGN_EPI = false, bool SP2 = false>
; __device__ __forceinline__ void gemm_phase(PG8_LAS unsigned char* lds, const Gemm g, const Sched& S, const Epi& E) {
;     ...
;             PG8_LDA(At, 1, 1); PG8_STAGE(PG8_SB(1, 0), b3, voffB); PG8_STAGE(PG8_SB(1, 1), b3 + hstep, voffB); PG8_STAGE(PG8_SA(1, 0), a3, voffA);
;             PG8_WAIT_V(8); PG8_WAIT_L(0); PG8_BAR; PG8_MMA(1, 0, At, B0); PG8_MMA(1, 1, At, B1); PG8_BAR; PG8_SCHED;
	s_add_i32 s8, s72, s42
	v_lshl_add_u64 v[220:221], v[220:221], 0, s[14:15]
	s_mov_b32 m0, s8
	ds_read_b128 v[188:191], v174 offset:49152
	ds_read_b128 v[192:195], v174 offset:50176
	ds_read_b128 v[196:199], v174 offset:51200
	ds_read_b128 v[200:203], v174 offset:52224
	ds_read_b128 v[204:207], v174 offset:53248
	ds_read_b128 v[208:211], v174 offset:54272
	ds_read_b128 v[212:215], v174 offset:55296
	ds_read_b128 v[216:219], v174 offset:56320
	global_load_lds_dwordx4 v[220:221], off
	s_add_i32 m0, s8, 0x2000
	s_add_u32 s6, s6, 0x18080
	v_lshl_add_u64 v[220:221], v[222:223], 0, s[14:15]
	s_addc_u32 s7, s7, 0
	s_add_i32 s8, s73, s42
	global_load_lds_dwordx4 v[220:221], off
	v_lshl_add_u64 v[220:221], s[6:7], 0, v[132:133]
	s_mov_b32 m0, s8
	s_nop 0
	global_load_lds_dwordx4 v[220:221], off
	v_lshl_add_u64 v[220:221], s[6:7], 0, v[136:137]
	s_add_i32 m0, s8, 0x2000
	s_nop 0
	global_load_lds_dwordx4 v[220:221], off
	v_lshl_add_u64 v[220:221], v[224:225], 0, s[14:15]
	s_mov_b32 m0, s56
	s_nop 0
	global_load_lds_dwordx4 v[220:221], off
	v_lshl_add_u64 v[220:221], v[226:227], 0, s[14:15]
	s_mov_b32 m0, s57
	s_nop 0
	global_load_lds_dwordx4 v[220:221], off
	s_waitcnt vmcnt(8)
	s_waitcnt lgkmcnt(0)
	s_barrier
	s_waitcnt lgkmcnt(0)
	v_mfma_f32_16x16x32_bf16 v[62:65], v[148:151], v[188:191], v[62:65]
	v_mfma_f32_16x16x32_bf16 v[58:61], v[156:159], v[188:191], v[58:61]
	v_mfma_f32_16x16x32_bf16 v[46:49], v[148:151], v[196:199], v[46:49]
	v_mfma_f32_16x16x32_bf16 v[42:45], v[156:159], v[196:199], v[42:45]
	v_mfma_f32_16x16x32_bf16 v[30:33], v[148:151], v[204:207], v[30:33]
	v_mfma_f32_16x16x32_bf16 v[26:29], v[156:159], v[204:207], v[26:29]
	v_mfma_f32_16x16x32_bf16 v[14:17], v[148:151], v[212:215], v[14:17]
	v_mfma_f32_16x16x32_bf16 v[10:13], v[156:159], v[212:215], v[10:13]
	v_mfma_f32_16x16x32_bf16 v[62:65], v[152:155], v[192:195], v[62:65]
	v_mfma_f32_16x16x32_bf16 v[58:61], v[160:163], v[192:195], v[58:61]
	v_mfma_f32_16x16x32_bf16 v[46:49], v[152:155], v[200:203], v[46:49]
	v_mfma_f32_16x16x32_bf16 v[42:45], v[160:163], v[200:203], v[42:45]
	v_mfma_f32_16x16x32_bf16 v[30:33], v[152:155], v[208:211], v[30:33]
	v_mfma_f32_16x16x32_bf16 v[26:29], v[160:163], v[208:211], v[26:29]
	v_mfma_f32_16x16x32_bf16 v[14:17], v[152:155], v[216:219], v[14:17]
	v_mfma_f32_16x16x32_bf16 v[10:13], v[160:163], v[216:219], v[10:13]
	v_mfma_f32_16x16x32_bf16 v[54:57], v[164:167], v[188:191], v[54:57]
	v_mfma_f32_16x16x32_bf16 v[50:53], v[180:183], v[188:191], v[50:53]
	v_mfma_f32_16x16x32_bf16 v[38:41], v[164:167], v[196:199], v[38:41]
	v_mfma_f32_16x16x32_bf16 v[34:37], v[180:183], v[196:199], v[34:37]
	v_mfma_f32_16x16x32_bf16 v[22:25], v[164:167], v[204:207], v[22:25]
	v_mfma_f32_16x16x32_bf16 v[18:21], v[180:183], v[204:207], v[18:21]
	v_mfma_f32_16x16x32_bf16 v[6:9], v[164:167], v[212:215], v[6:9]
	v_mfma_f32_16x16x32_bf16 v[2:5], v[180:183], v[212:215], v[2:5]
	v_mfma_f32_16x16x32_bf16 v[54:57], v[176:179], v[192:195], v[54:57]
	v_mfma_f32_16x16x32_bf16 v[50:53], v[184:187], v[192:195], v[50:53]
	v_mfma_f32_16x16x32_bf16 v[38:41], v[176:179], v[200:203], v[38:41]
	v_mfma_f32_16x16x32_bf16 v[34:37], v[184:187], v[200:203], v[34:37]
	v_mfma_f32_16x16x32_bf16 v[22:25], v[176:179], v[208:211], v[22:25]
	v_mfma_f32_16x16x32_bf16 v[18:21], v[184:187], v[208:211], v[18:21]
	v_mfma_f32_16x16x32_bf16 v[6:9], v[176:179], v[216:219], v[6:9]
	v_mfma_f32_16x16x32_bf16 v[2:5], v[184:187], v[216:219], v[2:5]
	s_barrier

; #define PG8_STAGE(bufoff, gbase, voff) do { _Pragma("unroll") for (int _i = 0; _i < 2; ++_i) \
;         __builtin_amdgcn_global_load_lds((const unsigned*)((const char*)(gbase) + (voff)[_i]), (PG8_LAS unsigned*)(lds + (bufoff) + ldsw + _i * 8192), 16, 0, 0); } while (0)
; #define PG8_LDA(dst, b, h) do { _Pragma("unroll") for (int m = 0; m < 4; ++m) _Pragma("unroll") for (int k = 0; k < 2; ++k) dst[m][k] = *(const PG8_LAS bf16x8*)(lds + PG8_SA(b, h) + aoff + m * 2048 + k * 1024); } while (0)
; #define PG8_LDB(dst, b, h) do { _Pragma("unroll") for (int n = 0; n < 2; ++n) _Pragma("unroll") for (int k = 0; k < 2; ++k) dst[n][k] = *(const PG8_LAS bf16x8*)(lds + PG8_SB(b, h) + boff + n * 2048 + k * 1024); } while (0)
; #define PG8_MMA(ai, bj, At, Bt) do { __builtin_amdgcn_s_setprio(1); _Pragma("unroll") for (int m = 0; m < 4; ++m) _Pragma("unroll") for (int n = 0; n < 2; ++n) _Pragma("unroll") for (int k = 0; k < 2; ++k) \
;         acc[ai][bj][m][n] = __builtin_amdgcn_mfma_f32_16x16x32_bf16(Bt[n][k], At[m][k], acc[ai][bj][m][n], 0, 0, 0); __builtin_amdgcn_s_setprio(0); } while (0)
; #define PG8_WAIT_V(n) asm volatile("s_waitcnt vmcnt(" #n ")" ::: "memory")
; #define PG8_WAIT_L(n) asm volatile("s_waitcnt lgkmcnt(" #n ")" ::: "memory")
; #define PG8_BAR __builtin_amdgcn_s_barrier()
; #define PG8_SCHED __builtin_amdgcn_sched_barrier(0)
; template <class Epi, class Sched, bool ALIGN_EPI = false, bool SP2 = false>
; __device__ __forceinline__ void gemm_phase(PG8_LAS unsigned char* lds, const Gemm g, const Sched& S, const Epi& E) {
;     ...
;         for (int t = 0; t < nt; t += 2) {
;             const bool last = (t == nt - 2);
;             const char* a1 = cA + (size_t)(t + 1) * kstep;
;             const char* a2 = last ? nA : cA + (size_t)(t + 2) * kstep; const char* b2 = last ? nB : cB + (size_t)(t + 2) * kstep;
;             const char* a3 = a2 + kstep; const char* b3 = b2 + kstep;
;             if (last && has_next) S.a_ready(nxt);
;             if constexpr (SP2) {
;             PG8_LDB(B0, 0, 0); PG8_LDB(B1, 0, 1); PG8_SCHED; PG8_LDA(At, 0, 0); PG8_STAGE(PG8_SA(1, 1), a1 + hstep, voffA);
;             PG8_WAIT_V(8); PG8_WAIT_L(0); PG8_BAR; PG8_MMA(0, 0, At, B0); PG8_MMA(0, 1, At, B1); PG8_BAR; PG8_SCHED;
;             PG8_LDA(At, 0, 1); PG8_STAGE(PG8_SB(0, 0), b2, voffB); PG8_STAGE(PG8_SB(0, 1), b2 + hstep, voffB); PG8_STAGE(PG8_SA(0, 0), a2, voffA);
	s_add_i32 s71, s71, 2
	s_add_u32 s4, s4, 0x100
	s_addc_u32 s5, s5, 0
	s_add_u32 s35, s35, 0x100
	s_addc_u32 s70, s70, 0
	s_cmp_ge_i32 s71, s98
	s_cbranch_scc1 .Lp7_kloop_done
.LBB0_865:
	ds_read_b128 v[148:151], v170
	ds_read_b128 v[152:155], v170 offset:1024
	ds_read_b128 v[156:159], v170 offset:2048
	ds_read_b128 v[160:163], v170 offset:3072
	ds_read_b128 v[164:167], v171
	ds_read_b128 v[176:179], v171 offset:1024
	ds_read_b128 v[180:183], v171 offset:2048
	ds_read_b128 v[184:187], v171 offset:3072
	s_add_u32 s6, s4, 0xfffe8080
	s_addc_u32 s7, s5, -1
	s_cmp_eq_u32 s71, s101
	s_cselect_b32 s9, s29, s7
	s_cselect_b32 s8, s28, s6
	s_cselect_b32 s7, s31, s70
	s_cselect_b32 s6, s30, s35
	v_lshl_add_u64 v[220:221], s[4:5], 0, v[140:141]
	s_add_i32 m0, s43, 0xc000
	ds_read_b128 v[188:191], v174
	ds_read_b128 v[192:195], v174 offset:1024
	ds_read_b128 v[196:199], v174 offset:2048
	ds_read_b128 v[200:203], v174 offset:3072
	ds_read_b128 v[204:207], v174 offset:4096
	ds_read_b128 v[208:211], v174 offset:5120
	ds_read_b128 v[212:215], v174 offset:6144
	ds_read_b128 v[216:219], v174 offset:7168
	global_load_lds_dwordx4 v[220:221], off
	v_lshl_add_u64 v[220:221], s[4:5], 0, v[142:143]
	s_add_i32 m0, s43, 0xe000
	s_nop 0
	global_load_lds_dwordx4 v[220:221], off
	s_waitcnt vmcnt(8)
	s_waitcnt lgkmcnt(0)
	s_barrier
	s_waitcnt lgkmcnt(0)
	v_mfma_f32_16x16x32_bf16 v[126:129], v[148:151], v[188:191], v[126:129]
	v_mfma_f32_16x16x32_bf16 v[122:125], v[156:159], v[188:191], v[122:125]
	v_mfma_f32_16x16x32_bf16 v[110:113], v[148:151], v[196:199], v[110:113]
	v_mfma_f32_16x16x32_bf16 v[106:109], v[156:159], v[196:199], v[106:109]
	v_mfma_f32_16x16x32_bf16 v[94:97], v[148:151], v[204:207], v[94:97]
	v_mfma_f32_16x16x32_bf16 v[90:93], v[156:159], v[204:207], v[90:93]
	v_mfma_f32_16x16x32_bf16 v[78:81], v[148:151], v[212:215], v[78:81]
	v_mfma_f32_16x16x32_bf16 v[74:77], v[156:159], v[212:215], v[74:77]
	v_mfma_f32_16x16x32_bf16 v[126:129], v[152:155], v[192:195], v[126:129]
	v_mfma_f32_16x16x32_bf16 v[122:125], v[160:163], v[192:195], v[122:125]
	v_mfma_f32_16x16x32_bf16 v[110:113], v[152:155], v[200:203], v[110:113]
	v_mfma_f32_16x16x32_bf16 v[106:109], v[160:163], v[200:203], v[106:109]
	v_mfma_f32_16x16x32_bf16 v[94:97], v[152:155], v[208:211], v[94:97]
	v_mfma_f32_16x16x32_bf16 v[90:93], v[160:163], v[208:211], v[90:93]
	v_mfma_f32_16x16x32_bf16 v[78:81], v[152:155], v[216:219], v[78:81]
	v_mfma_f32_16x16x32_bf16 v[74:77], v[160:163], v[216:219], v[74:77]
	v_mfma_f32_16x16x32_bf16 v[118:121], v[164:167], v[188:191], v[118:121]
	v_mfma_f32_16x16x32_bf16 v[114:117], v[180:183], v[188:191], v[114:117]
	v_mfma_f32_16x16x32_bf16 v[102:105], v[164:167], v[196:199], v[102:105]
	v_mfma_f32_16x16x32_bf16 v[98:101], v[180:183], v[196:199], v[98:101]
	v_mfma_f32_16x16x32_bf16 v[86:89], v[164:167], v[204:207], v[86:89]
	v_mfma_f32_16x16x32_bf16 v[82:85], v[180:183], v[204:207], v[82:85]
	v_mfma_f32_16x16x32_bf16 v[70:73], v[164:167], v[212:215], v[70:73]
	v_mfma_f32_16x16x32_bf16 v[66:69], v[180:183], v[212:215], v[66:69]
	v_mfma_f32_16x16x32_bf16 v[118:121], v[176:179], v[192:195], v[118:121]
	v_mfma_f32_16x16x32_bf16 v[114:117], v[184:187], v[192:195], v[114:117]
	v_mfma_f32_16x16x32_bf16 v[102:105], v[176:179], v[200:203], v[102:105]
	v_mfma_f32_16x16x32_bf16 v[98:101], v[184:187], v[200:203], v[98:101]
	v_mfma_f32_16x16x32_bf16 v[86:89], v[176:179], v[208:211], v[86:89]
	v_mfma_f32_16x16x32_bf16 v[82:85], v[184:187], v[208:211], v[82:85]
	v_mfma_f32_16x16x32_bf16 v[70:73], v[176:179], v[216:219], v[70:73]
	v_mfma_f32_16x16x32_bf16 v[66:69], v[184:187], v[216:219], v[66:69]
	s_barrier
	s_add_i32 s72, s66, s42
	v_lshl_add_u64 v[220:221], s[6:7], 0, v[132:133]
	s_mov_b32 m0, s72
	ds_read_b128 v[188:191], v174 offset:16384
	ds_read_b128 v[192:195], v174 offset:17408
	ds_read_b128 v[196:199], v174 offset:18432
	ds_read_b128 v[200:203], v174 offset:19456
	ds_read_b128 v[204:207], v174 offset:20480
	ds_read_b128 v[208:211], v174 offset:21504
	ds_read_b128 v[212:215], v174 offset:22528
	ds_read_b128 v[216:219], v174 offset:23552
	global_load_lds_dwordx4 v[220:221], off
	s_add_i32 m0, s72, 0x2000
	s_add_u32 s72, s6, 0x18000
	v_lshl_add_u64 v[222:223], s[6:7], 0, v[136:137]
	s_addc_u32 s73, s7, 0
	s_add_i32 s74, s67, s42
	global_load_lds_dwordx4 v[222:223], off
	v_lshl_add_u64 v[224:225], s[72:73], 0, v[132:133]
	s_mov_b32 m0, s74
	v_lshl_add_u64 v[226:227], s[8:9], 0, v[134:135]
	global_load_lds_dwordx4 v[224:225], off
	v_lshl_add_u64 v[224:225], s[72:73], 0, v[136:137]
	s_add_i32 m0, s74, 0x2000
	s_nop 0
	global_load_lds_dwordx4 v[224:225], off
	v_lshl_add_u64 v[224:225], s[8:9], 0, v[130:131]
	s_mov_b32 m0, s43
	s_nop 0
	global_load_lds_dwordx4 v[224:225], off
	s_mov_b32 m0, s44
	s_nop 0
	global_load_lds_dwordx4 v[226:227], off
	s_waitcnt vmcnt(8)
	s_waitcnt lgkmcnt(0)
	s_barrier
; #define PG8_STAGE(bufoff, gbase, voff) do { _Pragma("unroll") for (int _i = 0; _i < 2; ++_i) \
;         __builtin_amdgcn_global_load_lds((const unsigned*)((const char*)(gbase) + (voff)[_i]), (PG8_LAS unsigned*)(lds + (bufoff) + ldsw + _i * 8192), 16, 0, 0); } while (0)
; #define PG8_LDA(dst, b, h) do { _Pragma("unroll") for (int m = 0; m < 4; ++m) _Pragma("unroll") for (int k = 0; k < 2; ++k) dst[m][k] = *(const PG8_LAS bf16x8*)(lds + PG8_SA(b, h) + aoff + m * 2048 + k * 1024); } while (0)
; #define PG8_LDB(dst, b, h) do { _Pragma("unroll") for (int n = 0; n < 2; ++n) _Pragma("unroll") for (int k = 0; k < 2; ++k) dst[n][k] = *(const PG8_LAS bf16x8*)(lds + PG8_SB(b, h) + boff + n * 2048 + k * 1024); } while (0)
; #define PG8_MMA(ai, bj, At, Bt) do { __builtin_amdgcn_s_setprio(1); _Pragma("unroll") for (int m = 0; m < 4; ++m) _Pragma("unroll") for (int n = 0; n < 2; ++n) _Pragma("unroll") for (int k = 0; k < 2; ++k) \
;         acc[ai][bj][m][n] = __builtin_amdgcn_mfma_f32_16x16x32_bf16(Bt[n][k], At[m][k], acc[ai][bj][m][n], 0, 0, 0); __builtin_amdgcn_s_setprio(0); } while (0)
; #define PG8_WAIT_V(n) asm volatile("s_waitcnt vmcnt(" #n ")" ::: "memory")
; #define PG8_WAIT_L(n) asm volatile("s_waitcnt lgkmcnt(" #n ")" ::: "memory")
; #define PG8_BAR __builtin_amdgcn_s_barrier()
; #define PG8_SCHED __builtin_amdgcn_sched_barrier(0)
; template <class Epi, class Sched, bool ALIGN_EPI = false, bool SP2 = false>
; __device__ __forceinline__ void gemm_phase(PG8_LAS unsigned char* lds, const Gemm g, const Sched& S, const Epi& E) {
;     ...
;             PG8_WAIT_V(8); PG8_WAIT_L(0); PG8_BAR; PG8_MMA(1, 0, At, B0); PG8_MMA(1, 1, At, B1); PG8_BAR; PG8_SCHED;
;             PG8_LDB(B0, 1, 0); PG8_LDB(B1, 1, 1); PG8_SCHED; PG8_LDA(At, 1, 0); PG8_STAGE(PG8_SA(0, 1), a2 + hstep, voffA);
;             PG8_WAIT_V(8); PG8_WAIT_L(0); PG8_BAR; PG8_MMA(0, 0, At, B0); PG8_MMA(0, 1, At, B1); PG8_BAR; PG8_SCHED;
	s_waitcnt lgkmcnt(0)
	v_mfma_f32_16x16x32_bf16 v[62:65], v[148:151], v[188:191], v[62:65]
	v_mfma_f32_16x16x32_bf16 v[58:61], v[156:159], v[188:191], v[58:61]
	v_mfma_f32_16x16x32_bf16 v[46:49], v[148:151], v[196:199], v[46:49]
	v_mfma_f32_16x16x32_bf16 v[42:45], v[156:159], v[196:199], v[42:45]
	v_mfma_f32_16x16x32_bf16 v[30:33], v[148:151], v[204:207], v[30:33]
	v_mfma_f32_16x16x32_bf16 v[26:29], v[156:159], v[204:207], v[26:29]
	v_mfma_f32_16x16x32_bf16 v[14:17], v[148:151], v[212:215], v[14:17]
	v_mfma_f32_16x16x32_bf16 v[10:13], v[156:159], v[212:215], v[10:13]
	v_mfma_f32_16x16x32_bf16 v[62:65], v[152:155], v[192:195], v[62:65]
	v_mfma_f32_16x16x32_bf16 v[58:61], v[160:163], v[192:195], v[58:61]
	v_mfma_f32_16x16x32_bf16 v[46:49], v[152:155], v[200:203], v[46:49]
	v_mfma_f32_16x16x32_bf16 v[42:45], v[160:163], v[200:203], v[42:45]
	v_mfma_f32_16x16x32_bf16 v[30:33], v[152:155], v[208:211], v[30:33]
	v_mfma_f32_16x16x32_bf16 v[26:29], v[160:163], v[208:211], v[26:29]
	v_mfma_f32_16x16x32_bf16 v[14:17], v[152:155], v[216:219], v[14:17]
	v_mfma_f32_16x16x32_bf16 v[10:13], v[160:163], v[216:219], v[10:13]
	v_mfma_f32_16x16x32_bf16 v[54:57], v[164:167], v[188:191], v[54:57]
	v_mfma_f32_16x16x32_bf16 v[50:53], v[180:183], v[188:191], v[50:53]
	v_mfma_f32_16x16x32_bf16 v[38:41], v[164:167], v[196:199], v[38:41]
	v_mfma_f32_16x16x32_bf16 v[34:37], v[180:183], v[196:199], v[34:37]
	v_mfma_f32_16x16x32_bf16 v[22:25], v[164:167], v[204:207], v[22:25]
	v_mfma_f32_16x16x32_bf16 v[18:21], v[180:183], v[204:207], v[18:21]
	v_mfma_f32_16x16x32_bf16 v[6:9], v[164:167], v[212:215], v[6:9]
	v_mfma_f32_16x16x32_bf16 v[2:5], v[180:183], v[212:215], v[2:5]
	v_mfma_f32_16x16x32_bf16 v[54:57], v[176:179], v[192:195], v[54:57]
	v_mfma_f32_16x16x32_bf16 v[50:53], v[184:187], v[192:195], v[50:53]
	v_mfma_f32_16x16x32_bf16 v[38:41], v[176:179], v[200:203], v[38:41]
	v_mfma_f32_16x16x32_bf16 v[34:37], v[184:187], v[200:203], v[34:37]
	v_mfma_f32_16x16x32_bf16 v[22:25], v[176:179], v[208:211], v[22:25]
	v_mfma_f32_16x16x32_bf16 v[18:21], v[184:187], v[208:211], v[18:21]
	v_mfma_f32_16x16x32_bf16 v[6:9], v[176:179], v[216:219], v[6:9]
	v_mfma_f32_16x16x32_bf16 v[2:5], v[184:187], v[216:219], v[2:5]
	s_barrier
	s_add_i32 s72, 0, 0x18000
	v_add_u32_e32 v138, s72, v168
	s_add_i32 s73, 0, 0x1c000
	ds_read_b128 v[148:151], v138
	ds_read_b128 v[152:155], v138 offset:1024
	ds_read_b128 v[156:159], v138 offset:2048
	ds_read_b128 v[160:163], v138 offset:3072
	v_add_u32_e32 v138, s73, v168
	ds_read_b128 v[164:167], v138
	ds_read_b128 v[176:179], v138 offset:1024
	ds_read_b128 v[180:183], v138 offset:2048
	ds_read_b128 v[184:187], v138 offset:3072
	s_add_u32 s8, s8, 0x18000
	s_addc_u32 s9, s9, 0
	s_mov_b32 m0, s45
	v_lshl_add_u64 v[228:229], s[8:9], 0, v[130:131]
	ds_read_b128 v[188:191], v174 offset:32768
	ds_read_b128 v[192:195], v174 offset:33792
	ds_read_b128 v[196:199], v174 offset:34816
	ds_read_b128 v[200:203], v174 offset:35840
	ds_read_b128 v[204:207], v174 offset:36864
	ds_read_b128 v[208:211], v174 offset:37888
	ds_read_b128 v[212:215], v174 offset:38912
	ds_read_b128 v[216:219], v174 offset:39936
	global_load_lds_dwordx4 v[228:229], off
	v_lshl_add_u64 v[228:229], s[8:9], 0, v[134:135]
	s_mov_b32 m0, s52
	s_nop 0
	global_load_lds_dwordx4 v[228:229], off
	s_waitcnt vmcnt(8)
	s_waitcnt lgkmcnt(0)
	s_barrier
	s_waitcnt lgkmcnt(0)
	v_mfma_f32_16x16x32_bf16 v[126:129], v[148:151], v[188:191], v[126:129]
	v_mfma_f32_16x16x32_bf16 v[122:125], v[156:159], v[188:191], v[122:125]
	v_mfma_f32_16x16x32_bf16 v[110:113], v[148:151], v[196:199], v[110:113]
	v_mfma_f32_16x16x32_bf16 v[106:109], v[156:159], v[196:199], v[106:109]
	v_mfma_f32_16x16x32_bf16 v[94:97], v[148:151], v[204:207], v[94:97]
	v_mfma_f32_16x16x32_bf16 v[90:93], v[156:159], v[204:207], v[90:93]
	v_mfma_f32_16x16x32_bf16 v[78:81], v[148:151], v[212:215], v[78:81]
	v_mfma_f32_16x16x32_bf16 v[74:77], v[156:159], v[212:215], v[74:77]
	v_mfma_f32_16x16x32_bf16 v[126:129], v[152:155], v[192:195], v[126:129]
	v_mfma_f32_16x16x32_bf16 v[122:125], v[160:163], v[192:195], v[122:125]
	v_mfma_f32_16x16x32_bf16 v[110:113], v[152:155], v[200:203], v[110:113]
	v_mfma_f32_16x16x32_bf16 v[106:109], v[160:163], v[200:203], v[106:109]
	v_mfma_f32_16x16x32_bf16 v[94:97], v[152:155], v[208:211], v[94:97]
	v_mfma_f32_16x16x32_bf16 v[90:93], v[160:163], v[208:211], v[90:93]
	v_mfma_f32_16x16x32_bf16 v[78:81], v[152:155], v[216:219], v[78:81]
	v_mfma_f32_16x16x32_bf16 v[74:77], v[160:163], v[216:219], v[74:77]
	v_mfma_f32_16x16x32_bf16 v[118:121], v[164:167], v[188:191], v[118:121]
	v_mfma_f32_16x16x32_bf16 v[114:117], v[180:183], v[188:191], v[114:117]
	v_mfma_f32_16x16x32_bf16 v[102:105], v[164:167], v[196:199], v[102:105]
	v_mfma_f32_16x16x32_bf16 v[98:101], v[180:183], v[196:199], v[98:101]
	v_mfma_f32_16x16x32_bf16 v[86:89], v[164:167], v[204:207], v[86:89]
	v_mfma_f32_16x16x32_bf16 v[82:85], v[180:183], v[204:207], v[82:85]
	v_mfma_f32_16x16x32_bf16 v[70:73], v[164:167], v[212:215], v[70:73]
	v_mfma_f32_16x16x32_bf16 v[66:69], v[180:183], v[212:215], v[66:69]
	v_mfma_f32_16x16x32_bf16 v[118:121], v[176:179], v[192:195], v[118:121]
	v_mfma_f32_16x16x32_bf16 v[114:117], v[184:187], v[192:195], v[114:117]
	v_mfma_f32_16x16x32_bf16 v[102:105], v[176:179], v[200:203], v[102:105]
	v_mfma_f32_16x16x32_bf16 v[98:101], v[184:187], v[200:203], v[98:101]
	v_mfma_f32_16x16x32_bf16 v[86:89], v[176:179], v[208:211], v[86:89]
	v_mfma_f32_16x16x32_bf16 v[82:85], v[184:187], v[208:211], v[82:85]
	v_mfma_f32_16x16x32_bf16 v[70:73], v[176:179], v[216:219], v[70:73]
	v_mfma_f32_16x16x32_bf16 v[66:69], v[184:187], v[216:219], v[66:69]
	s_barrier
; #define PG8_STAGE(bufoff, gbase, voff) do { _Pragma("unroll") for (int _i = 0; _i < 2; ++_i) \
;         __builtin_amdgcn_global_load_lds((const unsigned*)((const char*)(gbase) + (voff)[_i]), (PG8_LAS unsigned*)(lds + (bufoff) + ldsw + _i * 8192), 16, 0, 0); } while (0)
; #define PG8_LDA(dst, b, h) do { _Pragma("unroll") for (int m = 0; m < 4; ++m) _Pragma("unroll") for (int k = 0; k < 2; ++k) dst[m][k] = *(const PG8_LAS bf16x8*)(lds + PG8_SA(b, h) + aoff + m * 2048 + k * 1024); } while (0)
; #define PG8_MMA(ai, bj, At, Bt) do { __builtin_amdgcn_s_setprio(1); _Pragma("unroll") for (int m = 0; m < 4; ++m) _Pragma("unroll") for (int n = 0; n < 2; ++n) _Pragma("unroll") for (int k = 0; k < 2; ++k) \
;         acc[ai][bj][m][n] = __builtin_amdgcn_mfma_f32_16x16x32_bf16(Bt[n][k], At[m][k], acc[ai][bj][m][n], 0, 0, 0); __builtin_amdgcn_s_setprio(0); } while (0)
; #define PG8_WAIT_V(n) asm volatile("s_waitcnt vmcnt(" #n ")" ::: "memory")
; #define PG8_WAIT_L(n) asm volatile("s_waitcnt lgkmcnt(" #n ")" ::: "memory")
; #define PG8_BAR __builtin_amdgcn_s_barrier()
; #define PG8_SCHED __builtin_amdgcn_sched_barrier(0)
; template <class Epi, class Sched, bool ALIGN_EPI = false, bool SP2 = false>
; __device__ __forceinline__ void gemm_phase(PG8_LAS unsigned char* lds, const Gemm g, const Sched& S, const Epi& E) {
;     ...
;             PG8_LDA(At, 1, 1); PG8_STAGE(PG8_SB(1, 0), b3, voffB); PG8_STAGE(PG8_SB(1, 1), b3 + hstep, voffB); PG8_STAGE(PG8_SA(1, 0), a3, voffA);
;             PG8_WAIT_V(8); PG8_WAIT_L(0); PG8_BAR; PG8_MMA(1, 0, At, B0); PG8_MMA(1, 1, At, B1); PG8_BAR; PG8_SCHED;
	s_add_i32 s8, s72, s42
	v_lshl_add_u64 v[220:221], v[220:221], 0, s[14:15]
	s_mov_b32 m0, s8
	ds_read_b128 v[188:191], v174 offset:49152
	ds_read_b128 v[192:195], v174 offset:50176
	ds_read_b128 v[196:199], v174 offset:51200
	ds_read_b128 v[200:203], v174 offset:52224
	ds_read_b128 v[204:207], v174 offset:53248
	ds_read_b128 v[208:211], v174 offset:54272
	ds_read_b128 v[212:215], v174 offset:55296
	ds_read_b128 v[216:219], v174 offset:56320
	global_load_lds_dwordx4 v[220:221], off
	s_add_i32 m0, s8, 0x2000
	s_add_u32 s6, s6, 0x18080
	v_lshl_add_u64 v[220:221], v[222:223], 0, s[14:15]
	s_addc_u32 s7, s7, 0
	s_add_i32 s8, s73, s42
	global_load_lds_dwordx4 v[220:221], off
	v_lshl_add_u64 v[220:221], s[6:7], 0, v[132:133]
	s_mov_b32 m0, s8
	s_nop 0
	global_load_lds_dwordx4 v[220:221], off
	v_lshl_add_u64 v[220:221], s[6:7], 0, v[136:137]
	s_add_i32 m0, s8, 0x2000
	s_nop 0
	global_load_lds_dwordx4 v[220:221], off
	v_lshl_add_u64 v[220:221], v[224:225], 0, s[14:15]
	s_mov_b32 m0, s56
	s_nop 0
	global_load_lds_dwordx4 v[220:221], off
	v_lshl_add_u64 v[220:221], v[226:227], 0, s[14:15]
	s_mov_b32 m0, s57
	s_nop 0
	global_load_lds_dwordx4 v[220:221], off
	s_waitcnt vmcnt(8)
	s_waitcnt lgkmcnt(0)
	s_barrier
	s_waitcnt lgkmcnt(0)
	v_mfma_f32_16x16x32_bf16 v[62:65], v[148:151], v[188:191], v[62:65]
	v_mfma_f32_16x16x32_bf16 v[58:61], v[156:159], v[188:191], v[58:61]
	v_mfma_f32_16x16x32_bf16 v[46:49], v[148:151], v[196:199], v[46:49]
	v_mfma_f32_16x16x32_bf16 v[42:45], v[156:159], v[196:199], v[42:45]
	v_mfma_f32_16x16x32_bf16 v[30:33], v[148:151], v[204:207], v[30:33]
	v_mfma_f32_16x16x32_bf16 v[26:29], v[156:159], v[204:207], v[26:29]
	v_mfma_f32_16x16x32_bf16 v[14:17], v[148:151], v[212:215], v[14:17]
	v_mfma_f32_16x16x32_bf16 v[10:13], v[156:159], v[212:215], v[10:13]
	v_mfma_f32_16x16x32_bf16 v[62:65], v[152:155], v[192:195], v[62:65]
	v_mfma_f32_16x16x32_bf16 v[58:61], v[160:163], v[192:195], v[58:61]
	v_mfma_f32_16x16x32_bf16 v[46:49], v[152:155], v[200:203], v[46:49]
	v_mfma_f32_16x16x32_bf16 v[42:45], v[160:163], v[200:203], v[42:45]
	v_mfma_f32_16x16x32_bf16 v[30:33], v[152:155], v[208:211], v[30:33]
	v_mfma_f32_16x16x32_bf16 v[26:29], v[160:163], v[208:211], v[26:29]
	v_mfma_f32_16x16x32_bf16 v[14:17], v[152:155], v[216:219], v[14:17]
	v_mfma_f32_16x16x32_bf16 v[10:13], v[160:163], v[216:219], v[10:13]
	v_mfma_f32_16x16x32_bf16 v[54:57], v[164:167], v[188:191], v[54:57]
	v_mfma_f32_16x16x32_bf16 v[50:53], v[180:183], v[188:191], v[50:53]
	v_mfma_f32_16x16x32_bf16 v[38:41], v[164:167], v[196:199], v[38:41]
	v_mfma_f32_16x16x32_bf16 v[34:37], v[180:183], v[196:199], v[34:37]
	v_mfma_f32_16x16x32_bf16 v[22:25], v[164:167], v[204:207], v[22:25]
	v_mfma_f32_16x16x32_bf16 v[18:21], v[180:183], v[204:207], v[18:21]
	v_mfma_f32_16x16x32_bf16 v[6:9], v[164:167], v[212:215], v[6:9]
	v_mfma_f32_16x16x32_bf16 v[2:5], v[180:183], v[212:215], v[2:5]
	v_mfma_f32_16x16x32_bf16 v[54:57], v[176:179], v[192:195], v[54:57]
	v_mfma_f32_16x16x32_bf16 v[50:53], v[184:187], v[192:195], v[50:53]
	v_mfma_f32_16x16x32_bf16 v[38:41], v[176:179], v[200:203], v[38:41]
	v_mfma_f32_16x16x32_bf16 v[34:37], v[184:187], v[200:203], v[34:37]
	v_mfma_f32_16x16x32_bf16 v[22:25], v[176:179], v[208:211], v[22:25]
	v_mfma_f32_16x16x32_bf16 v[18:21], v[184:187], v[208:211], v[18:21]
	v_mfma_f32_16x16x32_bf16 v[6:9], v[176:179], v[216:219], v[6:9]
	v_mfma_f32_16x16x32_bf16 v[2:5], v[184:187], v[216:219], v[2:5]
	s_barrier
	s_add_i32 s71, s71, 2
	s_add_u32 s4, s4, 0x100
	s_addc_u32 s5, s5, 0
	s_add_u32 s35, s35, 0x100
	s_addc_u32 s70, s70, 0
	s_cmp_ge_i32 s71, s98
	s_cbranch_scc0 .LBB0_865

; #define PG8_STAGE(bufoff, gbase, voff) do { _Pragma("unroll") for (int _i = 0; _i < 2; ++_i) \
;         __builtin_amdgcn_global_load_lds((const unsigned*)((const char*)(gbase) + (voff)[_i]), (PG8_LAS unsigned*)(lds + (bufoff) + ldsw + _i * 8192), 16, 0, 0); } while (0)
; #define PG8_LDA(dst, b, h) do { _Pragma("unroll") for (int m = 0; m < 4; ++m) _Pragma("unroll") for (int k = 0; k < 2; ++k) dst[m][k] = *(const PG8_LAS bf16x8*)(lds + PG8_SA(b, h) + aoff + m * 2048 + k * 1024); } while (0)
; #define PG8_LDB(dst, b, h) do { _Pragma("unroll") for (int n = 0; n < 2; ++n) _Pragma("unroll") for (int k = 0; k < 2; ++k) dst[n][k] = *(const PG8_LAS bf16x8*)(lds + PG8_SB(b, h) + boff + n * 2048 + k * 1024); } while (0)
; #define PG8_SCHED __builtin_amdgcn_sched_barrier(0)
; template <class Epi, class Sched, bool ALIGN_EPI = false, bool SP2 = false>
; __device__ __forceinline__ void gemm_phase(PG8_LAS unsigned char* lds, const Gemm g, const Sched& S, const Epi& E) {
;     ...
;         const bool has_next = S.next(ui + 1, nxt);
;         const char* nA = has_next ? (const char*)g.A + (size_t)nxt.pm * tstep : cA; const char* nB = has_next ? (const char*)g.Bt + (size_t)nxt.pn * tstep : cB;
; #pragma nounroll
;         for (int t = 0; t < nt; t += 2) {
;             const bool last = (t == nt - 2);
;             const char* a1 = cA + (size_t)(t + 1) * kstep;
;             const char* a2 = last ? nA : cA + (size_t)(t + 2) * kstep; const char* b2 = last ? nB : cB + (size_t)(t + 2) * kstep;
;             const char* a3 = a2 + kstep; const char* b3 = b2 + kstep;
;             if (last && has_next) S.a_ready(nxt);
;             if constexpr (SP2) {
;             PG8_LDB(B0, 0, 0); PG8_LDB(B1, 0, 1); PG8_SCHED; PG8_LDA(At, 0, 0); PG8_STAGE(PG8_SA(1, 1), a1 + hstep, voffA);
.LBB0_1220:
	s_ashr_i32 s29, s28, 31
	s_lshl_b64 s[30:31], s[28:29], 19
	s_add_u32 s30, s44, s30
	s_addc_u32 s31, s45, s31
	s_and_b64 s[34:35], s[2:3], exec
	s_cselect_b32 s29, s31, s39
	s_cselect_b32 s67, s30, s38
	s_ashr_i32 s27, s26, 31
	s_lshl_b64 s[34:35], s[26:27], 19
	s_add_u32 s34, s52, s34
	s_addc_u32 s35, s53, s35
	s_and_b64 s[42:43], s[2:3], exec
	s_cselect_b32 s27, s35, s41
	s_cselect_b32 s68, s34, s40
	s_add_u32 s38, s38, 0x40080
	s_addc_u32 s39, s39, 0
	s_add_u32 s69, s40, 0x100
	s_addc_u32 s70, s41, 0
	s_mov_b32 s71, -2
	ds_read_b128 v[154:157], v150
	ds_read_b128 v[158:161], v150 offset:1024
	ds_read_b128 v[162:165], v150 offset:2048
	ds_read_b128 v[166:169], v150 offset:3072
	ds_read_b128 v[174:177], v151
	ds_read_b128 v[178:181], v151 offset:1024
	ds_read_b128 v[182:185], v151 offset:2048
	ds_read_b128 v[186:189], v151 offset:3072
	s_add_u32 s40, s38, 0xfffc0080
	s_addc_u32 s41, s39, -1
	s_cmp_eq_u32 s71, 12
	s_cselect_b32 s43, s29, s41
	s_cselect_b32 s42, s67, s40
	s_cselect_b32 s41, s27, s70
	s_cselect_b32 s40, s68, s69

; #define PG8_STAGE(bufoff, gbase, voff) do { _Pragma("unroll") for (int _i = 0; _i < 2; ++_i) \
;         __builtin_amdgcn_global_load_lds((const unsigned*)((const char*)(gbase) + (voff)[_i]), (PG8_LAS unsigned*)(lds + (bufoff) + ldsw + _i * 8192), 16, 0, 0); } while (0)
; #define PG8_LDA(dst, b, h) do { _Pragma("unroll") for (int m = 0; m < 4; ++m) _Pragma("unroll") for (int k = 0; k < 2; ++k) dst[m][k] = *(const PG8_LAS bf16x8*)(lds + PG8_SA(b, h) + aoff + m * 2048 + k * 1024); } while (0)
; #define PG8_LDB(dst, b, h) do { _Pragma("unroll") for (int n = 0; n < 2; ++n) _Pragma("unroll") for (int k = 0; k < 2; ++k) dst[n][k] = *(const PG8_LAS bf16x8*)(lds + PG8_SB(b, h) + boff + n * 2048 + k * 1024); } while (0)
; #define PG8_MMA(ai, bj, At, Bt) do { __builtin_amdgcn_s_setprio(1); _Pragma("unroll") for (int m = 0; m < 4; ++m) _Pragma("unroll") for (int n = 0; n < 2; ++n) _Pragma("unroll") for (int k = 0; k < 2; ++k) \
;         acc[ai][bj][m][n] = __builtin_amdgcn_mfma_f32_16x16x32_bf16(Bt[n][k], At[m][k], acc[ai][bj][m][n], 0, 0, 0); __builtin_amdgcn_s_setprio(0); } while (0)
; #define PG8_WAIT_V(n) asm volatile("s_waitcnt vmcnt(" #n ")" ::: "memory")
; #define PG8_WAIT_L(n) asm volatile("s_waitcnt lgkmcnt(" #n ")" ::: "memory")
; #define PG8_BAR __builtin_amdgcn_s_barrier()
; #define PG8_SCHED __builtin_amdgcn_sched_barrier(0)
; template <class Epi, class Sched, bool ALIGN_EPI = false, bool SP2 = false>
; __device__ __forceinline__ void gemm_phase(PG8_LAS unsigned char* lds, const Gemm g, const Sched& S, const Epi& E) {
;     ...
;     f32x4 acc[2][2][4][2];
; #pragma unroll
;     for (int a = 0; a < 2; ++a)
; #pragma unroll
;         for (int b = 0; b < 2; ++b)
; #pragma unroll
;             for (int m = 0; m < 4; ++m)
; #pragma unroll
;                 for (int n = 0; n < 2; ++n) acc[a][b][m][n] = (f32x4){0.f, 0.f, 0.f, 0.f};
;     ...
;             PG8_LDB(B0, 0, 0); PG8_LDB(B1, 0, 1); PG8_SCHED; PG8_LDA(At, 0, 0); PG8_STAGE(PG8_SA(1, 1), a1 + hstep, voffA);
;             PG8_WAIT_V(8); PG8_WAIT_L(0); PG8_BAR; PG8_MMA(0, 0, At, B0); PG8_MMA(0, 1, At, B1); PG8_BAR; PG8_SCHED;
	v_lshl_add_u64 v[146:147], s[38:39], 0, v[138:139]
	s_add_i32 m0, s55, 0xc000
	ds_read_b128 v[190:193], v152
	ds_read_b128 v[194:197], v152 offset:1024
	ds_read_b128 v[198:201], v152 offset:2048
	ds_read_b128 v[202:205], v152 offset:3072
	ds_read_b128 v[206:209], v152 offset:4096
	ds_read_b128 v[210:213], v152 offset:5120
	ds_read_b128 v[214:217], v152 offset:6144
	ds_read_b128 v[218:221], v152 offset:7168
	global_load_lds_dwordx4 v[146:147], off
	v_lshl_add_u64 v[146:147], s[38:39], 0, v[140:141]
	s_add_i32 m0, s55, 0xe000
	s_nop 0
	global_load_lds_dwordx4 v[146:147], off
	s_waitcnt vmcnt(24)
	s_waitcnt lgkmcnt(0)
	s_barrier
	s_waitcnt lgkmcnt(0)
	v_mfma_f32_16x16x32_bf16 v[126:129], v[154:157], v[190:193], 0
	v_mfma_f32_16x16x32_bf16 v[122:125], v[162:165], v[190:193], 0
	v_mfma_f32_16x16x32_bf16 v[110:113], v[154:157], v[198:201], 0
	v_mfma_f32_16x16x32_bf16 v[106:109], v[162:165], v[198:201], 0
	v_mfma_f32_16x16x32_bf16 v[94:97], v[154:157], v[206:209], 0
	v_mfma_f32_16x16x32_bf16 v[90:93], v[162:165], v[206:209], 0
	v_mfma_f32_16x16x32_bf16 v[78:81], v[154:157], v[214:217], 0
	v_mfma_f32_16x16x32_bf16 v[74:77], v[162:165], v[214:217], 0
	v_mfma_f32_16x16x32_bf16 v[126:129], v[158:161], v[194:197], v[126:129]
	v_mfma_f32_16x16x32_bf16 v[122:125], v[166:169], v[194:197], v[122:125]
	v_mfma_f32_16x16x32_bf16 v[110:113], v[158:161], v[202:205], v[110:113]
	v_mfma_f32_16x16x32_bf16 v[106:109], v[166:169], v[202:205], v[106:109]
	v_mfma_f32_16x16x32_bf16 v[94:97], v[158:161], v[210:213], v[94:97]
	v_mfma_f32_16x16x32_bf16 v[90:93], v[166:169], v[210:213], v[90:93]
	v_mfma_f32_16x16x32_bf16 v[78:81], v[158:161], v[218:221], v[78:81]
	v_mfma_f32_16x16x32_bf16 v[74:77], v[166:169], v[218:221], v[74:77]
	v_mfma_f32_16x16x32_bf16 v[118:121], v[174:177], v[190:193], 0
	v_mfma_f32_16x16x32_bf16 v[114:117], v[182:185], v[190:193], 0
	v_mfma_f32_16x16x32_bf16 v[102:105], v[174:177], v[198:201], 0
	v_mfma_f32_16x16x32_bf16 v[98:101], v[182:185], v[198:201], 0
	v_mfma_f32_16x16x32_bf16 v[86:89], v[174:177], v[206:209], 0
	v_mfma_f32_16x16x32_bf16 v[82:85], v[182:185], v[206:209], 0
	v_mfma_f32_16x16x32_bf16 v[70:73], v[174:177], v[214:217], 0
	v_mfma_f32_16x16x32_bf16 v[66:69], v[182:185], v[214:217], 0
	v_mfma_f32_16x16x32_bf16 v[118:121], v[178:181], v[194:197], v[118:121]
	v_mfma_f32_16x16x32_bf16 v[114:117], v[186:189], v[194:197], v[114:117]
	v_mfma_f32_16x16x32_bf16 v[102:105], v[178:181], v[202:205], v[102:105]
	v_mfma_f32_16x16x32_bf16 v[98:101], v[186:189], v[202:205], v[98:101]
	v_mfma_f32_16x16x32_bf16 v[86:89], v[178:181], v[210:213], v[86:89]
	v_mfma_f32_16x16x32_bf16 v[82:85], v[186:189], v[210:213], v[82:85]
	v_mfma_f32_16x16x32_bf16 v[70:73], v[178:181], v[218:221], v[70:73]
	v_mfma_f32_16x16x32_bf16 v[66:69], v[186:189], v[218:221], v[66:69]
	s_barrier

; #define PG8_STAGE(bufoff, gbase, voff) do { _Pragma("unroll") for (int _i = 0; _i < 2; ++_i) \
;         __builtin_amdgcn_global_load_lds((const unsigned*)((const char*)(gbase) + (voff)[_i]), (PG8_LAS unsigned*)(lds + (bufoff) + ldsw + _i * 8192), 16, 0, 0); } while (0)
; #define PG8_LDA(dst, b, h) do { _Pragma("unroll") for (int m = 0; m < 4; ++m) _Pragma("unroll") for (int k = 0; k < 2; ++k) dst[m][k] = *(const PG8_LAS bf16x8*)(lds + PG8_SA(b, h) + aoff + m * 2048 + k * 1024); } while (0)
; #define PG8_MMA(ai, bj, At, Bt) do { __builtin_amdgcn_s_setprio(1); _Pragma("unroll") for (int m = 0; m < 4; ++m) _Pragma("unroll") for (int n = 0; n < 2; ++n) _Pragma("unroll") for (int k = 0; k < 2; ++k) \
;         acc[ai][bj][m][n] = __builtin_amdgcn_mfma_f32_16x16x32_bf16(Bt[n][k], At[m][k], acc[ai][bj][m][n], 0, 0, 0); __builtin_amdgcn_s_setprio(0); } while (0)
; #define PG8_WAIT_V(n) asm volatile("s_waitcnt vmcnt(" #n ")" ::: "memory")
; #define PG8_WAIT_L(n) asm volatile("s_waitcnt lgkmcnt(" #n ")" ::: "memory")
; #define PG8_BAR __builtin_amdgcn_s_barrier()
; #define PG8_SCHED __builtin_amdgcn_sched_barrier(0)
; template <class Epi, class Sched, bool ALIGN_EPI = false, bool SP2 = false>
; __device__ __forceinline__ void gemm_phase(PG8_LAS unsigned char* lds, const Gemm g, const Sched& S, const Epi& E) {
;     ...
;             PG8_LDA(At, 0, 1); PG8_STAGE(PG8_SB(0, 0), b2, voffB); PG8_STAGE(PG8_SB(0, 1), b2 + hstep, voffB); PG8_STAGE(PG8_SA(0, 0), a2, voffA);
;             PG8_WAIT_V(8); PG8_WAIT_L(0); PG8_BAR; PG8_MMA(1, 0, At, B0); PG8_MMA(1, 1, At, B1); PG8_BAR; PG8_SCHED;
	s_add_i32 s72, s64, s54
	v_lshl_add_u64 v[146:147], s[40:41], 0, v[132:133]
	s_mov_b32 m0, s72
	ds_read_b128 v[190:193], v152 offset:16384
	ds_read_b128 v[194:197], v152 offset:17408
	ds_read_b128 v[198:201], v152 offset:18432
	ds_read_b128 v[202:205], v152 offset:19456
	ds_read_b128 v[206:209], v152 offset:20480
	ds_read_b128 v[210:213], v152 offset:21504
	ds_read_b128 v[214:217], v152 offset:22528
	ds_read_b128 v[218:221], v152 offset:23552
	global_load_lds_dwordx4 v[146:147], off
	s_add_i32 m0, s72, 0x2000
	s_add_u32 s72, s40, 0x40000
	v_lshl_add_u64 v[170:171], s[40:41], 0, v[136:137]
	s_addc_u32 s73, s41, 0
	s_add_i32 s74, s65, s54
	global_load_lds_dwordx4 v[170:171], off
	v_lshl_add_u64 v[222:223], s[72:73], 0, v[132:133]
	s_mov_b32 m0, s74
	v_lshl_add_u64 v[224:225], s[42:43], 0, v[134:135]
	global_load_lds_dwordx4 v[222:223], off
	v_lshl_add_u64 v[222:223], s[72:73], 0, v[136:137]
	s_add_i32 m0, s74, 0x2000
	s_nop 0
	global_load_lds_dwordx4 v[222:223], off
	v_lshl_add_u64 v[222:223], s[42:43], 0, v[130:131]
	s_mov_b32 m0, s55
	s_nop 0
	global_load_lds_dwordx4 v[222:223], off
	s_mov_b32 m0, s56
	s_nop 0
	global_load_lds_dwordx4 v[224:225], off
	s_waitcnt vmcnt(24)
	s_waitcnt lgkmcnt(0)
	s_barrier
	s_waitcnt lgkmcnt(0)
	v_mfma_f32_16x16x32_bf16 v[62:65], v[154:157], v[190:193], 0
	v_mfma_f32_16x16x32_bf16 v[58:61], v[162:165], v[190:193], 0
	v_mfma_f32_16x16x32_bf16 v[46:49], v[154:157], v[198:201], 0
	v_mfma_f32_16x16x32_bf16 v[42:45], v[162:165], v[198:201], 0
	v_mfma_f32_16x16x32_bf16 v[30:33], v[154:157], v[206:209], 0
	v_mfma_f32_16x16x32_bf16 v[26:29], v[162:165], v[206:209], 0
	v_mfma_f32_16x16x32_bf16 v[14:17], v[154:157], v[214:217], 0
	v_mfma_f32_16x16x32_bf16 v[10:13], v[162:165], v[214:217], 0
	v_mfma_f32_16x16x32_bf16 v[62:65], v[158:161], v[194:197], v[62:65]
	v_mfma_f32_16x16x32_bf16 v[58:61], v[166:169], v[194:197], v[58:61]
	v_mfma_f32_16x16x32_bf16 v[46:49], v[158:161], v[202:205], v[46:49]
	v_mfma_f32_16x16x32_bf16 v[42:45], v[166:169], v[202:205], v[42:45]
	v_mfma_f32_16x16x32_bf16 v[30:33], v[158:161], v[210:213], v[30:33]
	v_mfma_f32_16x16x32_bf16 v[26:29], v[166:169], v[210:213], v[26:29]
	v_mfma_f32_16x16x32_bf16 v[14:17], v[158:161], v[218:221], v[14:17]
	v_mfma_f32_16x16x32_bf16 v[10:13], v[166:169], v[218:221], v[10:13]
	v_mfma_f32_16x16x32_bf16 v[54:57], v[174:177], v[190:193], 0
	v_mfma_f32_16x16x32_bf16 v[50:53], v[182:185], v[190:193], 0
	v_mfma_f32_16x16x32_bf16 v[38:41], v[174:177], v[198:201], 0
	v_mfma_f32_16x16x32_bf16 v[34:37], v[182:185], v[198:201], 0
	v_mfma_f32_16x16x32_bf16 v[22:25], v[174:177], v[206:209], 0
	v_mfma_f32_16x16x32_bf16 v[18:21], v[182:185], v[206:209], 0
	v_mfma_f32_16x16x32_bf16 v[6:9], v[174:177], v[214:217], 0
	v_mfma_f32_16x16x32_bf16 v[2:5], v[182:185], v[214:217], 0
	v_mfma_f32_16x16x32_bf16 v[54:57], v[178:181], v[194:197], v[54:57]
	v_mfma_f32_16x16x32_bf16 v[50:53], v[186:189], v[194:197], v[50:53]
	v_mfma_f32_16x16x32_bf16 v[38:41], v[178:181], v[202:205], v[38:41]
	v_mfma_f32_16x16x32_bf16 v[34:37], v[186:189], v[202:205], v[34:37]
	v_mfma_f32_16x16x32_bf16 v[22:25], v[178:181], v[210:213], v[22:25]
	v_mfma_f32_16x16x32_bf16 v[18:21], v[186:189], v[210:213], v[18:21]
	v_mfma_f32_16x16x32_bf16 v[6:9], v[178:181], v[218:221], v[6:9]
	v_mfma_f32_16x16x32_bf16 v[2:5], v[186:189], v[218:221], v[2:5]
	s_barrier

; #define PG8_STAGE(bufoff, gbase, voff) do { _Pragma("unroll") for (int _i = 0; _i < 2; ++_i) \
;         __builtin_amdgcn_global_load_lds((const unsigned*)((const char*)(gbase) + (voff)[_i]), (PG8_LAS unsigned*)(lds + (bufoff) + ldsw + _i * 8192), 16, 0, 0); } while (0)
; #define PG8_LDA(dst, b, h) do { _Pragma("unroll") for (int m = 0; m < 4; ++m) _Pragma("unroll") for (int k = 0; k < 2; ++k) dst[m][k] = *(const PG8_LAS bf16x8*)(lds + PG8_SA(b, h) + aoff + m * 2048 + k * 1024); } while (0)
; #define PG8_LDB(dst, b, h) do { _Pragma("unroll") for (int n = 0; n < 2; ++n) _Pragma("unroll") for (int k = 0; k < 2; ++k) dst[n][k] = *(const PG8_LAS bf16x8*)(lds + PG8_SB(b, h) + boff + n * 2048 + k * 1024); } while (0)
; #define PG8_SCHED __builtin_amdgcn_sched_barrier(0)
; template <class Epi, class Sched, bool ALIGN_EPI = false, bool SP2 = false>
; __device__ __forceinline__ void gemm_phase(PG8_LAS unsigned char* lds, const Gemm g, const Sched& S, const Epi& E) {
;     ...
;             PG8_LDB(B0, 1, 0); PG8_LDB(B1, 1, 1); PG8_SCHED; PG8_LDA(At, 1, 0); PG8_STAGE(PG8_SA(0, 1), a2 + hstep, voffA);
	s_add_i32 s72, 0, 0x18000
	v_add_u32_e32 v153, s72, v148
	s_add_i32 s73, 0, 0x1c000
	ds_read_b128 v[154:157], v153
	ds_read_b128 v[158:161], v153 offset:1024
	ds_read_b128 v[162:165], v153 offset:2048
	ds_read_b128 v[166:169], v153 offset:3072
	v_add_u32_e32 v153, s73, v148
	ds_read_b128 v[174:177], v153
	ds_read_b128 v[178:181], v153 offset:1024
	ds_read_b128 v[182:185], v153 offset:2048
	ds_read_b128 v[186:189], v153 offset:3072

; #define PG8_STAGE(bufoff, gbase, voff) do { _Pragma("unroll") for (int _i = 0; _i < 2; ++_i) \
;         __builtin_amdgcn_global_load_lds((const unsigned*)((const char*)(gbase) + (voff)[_i]), (PG8_LAS unsigned*)(lds + (bufoff) + ldsw + _i * 8192), 16, 0, 0); } while (0)
; #define PG8_LDA(dst, b, h) do { _Pragma("unroll") for (int m = 0; m < 4; ++m) _Pragma("unroll") for (int k = 0; k < 2; ++k) dst[m][k] = *(const PG8_LAS bf16x8*)(lds + PG8_SA(b, h) + aoff + m * 2048 + k * 1024); } while (0)
; #define PG8_LDB(dst, b, h) do { _Pragma("unroll") for (int n = 0; n < 2; ++n) _Pragma("unroll") for (int k = 0; k < 2; ++k) dst[n][k] = *(const PG8_LAS bf16x8*)(lds + PG8_SB(b, h) + boff + n * 2048 + k * 1024); } while (0)
; #define PG8_MMA(ai, bj, At, Bt) do { __builtin_amdgcn_s_setprio(1); _Pragma("unroll") for (int m = 0; m < 4; ++m) _Pragma("unroll") for (int n = 0; n < 2; ++n) _Pragma("unroll") for (int k = 0; k < 2; ++k) \
;         acc[ai][bj][m][n] = __builtin_amdgcn_mfma_f32_16x16x32_bf16(Bt[n][k], At[m][k], acc[ai][bj][m][n], 0, 0, 0); __builtin_amdgcn_s_setprio(0); } while (0)
; #define PG8_WAIT_V(n) asm volatile("s_waitcnt vmcnt(" #n ")" ::: "memory")
; #define PG8_WAIT_L(n) asm volatile("s_waitcnt lgkmcnt(" #n ")" ::: "memory")
; #define PG8_BAR __builtin_amdgcn_s_barrier()
; #define PG8_SCHED __builtin_amdgcn_sched_barrier(0)
; template <class Epi, class Sched, bool ALIGN_EPI = false, bool SP2 = false>
; __device__ __forceinline__ void gemm_phase(PG8_LAS unsigned char* lds, const Gemm g, const Sched& S, const Epi& E) {
;     ...
;             PG8_LDB(B0, 1, 0); PG8_LDB(B1, 1, 1); PG8_SCHED; PG8_LDA(At, 1, 0); PG8_STAGE(PG8_SA(0, 1), a2 + hstep, voffA);
;             PG8_WAIT_V(8); PG8_WAIT_L(0); PG8_BAR; PG8_MMA(0, 0, At, B0); PG8_MMA(0, 1, At, B1); PG8_BAR; PG8_SCHED;
	s_add_u32 s42, s42, 0x40000
	s_addc_u32 s43, s43, 0
	s_mov_b32 m0, s57
	v_lshl_add_u64 v[226:227], s[42:43], 0, v[130:131]
	ds_read_b128 v[190:193], v152 offset:32768
	ds_read_b128 v[194:197], v152 offset:33792
	ds_read_b128 v[198:201], v152 offset:34816
	ds_read_b128 v[202:205], v152 offset:35840
	ds_read_b128 v[206:209], v152 offset:36864
	ds_read_b128 v[210:213], v152 offset:37888
	ds_read_b128 v[214:217], v152 offset:38912
	ds_read_b128 v[218:221], v152 offset:39936
	global_load_lds_dwordx4 v[226:227], off
	v_lshl_add_u64 v[226:227], s[42:43], 0, v[134:135]
	s_mov_b32 m0, s58
	s_nop 0
	global_load_lds_dwordx4 v[226:227], off
	s_waitcnt vmcnt(8)
	s_waitcnt lgkmcnt(0)
	s_barrier
	s_waitcnt lgkmcnt(0)
	v_mfma_f32_16x16x32_bf16 v[126:129], v[154:157], v[190:193], v[126:129]
	v_mfma_f32_16x16x32_bf16 v[122:125], v[162:165], v[190:193], v[122:125]
	v_mfma_f32_16x16x32_bf16 v[110:113], v[154:157], v[198:201], v[110:113]
	v_mfma_f32_16x16x32_bf16 v[106:109], v[162:165], v[198:201], v[106:109]
	v_mfma_f32_16x16x32_bf16 v[94:97], v[154:157], v[206:209], v[94:97]
	v_mfma_f32_16x16x32_bf16 v[90:93], v[162:165], v[206:209], v[90:93]
	v_mfma_f32_16x16x32_bf16 v[78:81], v[154:157], v[214:217], v[78:81]
	v_mfma_f32_16x16x32_bf16 v[74:77], v[162:165], v[214:217], v[74:77]
	v_mfma_f32_16x16x32_bf16 v[126:129], v[158:161], v[194:197], v[126:129]
	v_mfma_f32_16x16x32_bf16 v[122:125], v[166:169], v[194:197], v[122:125]
	v_mfma_f32_16x16x32_bf16 v[110:113], v[158:161], v[202:205], v[110:113]
	v_mfma_f32_16x16x32_bf16 v[106:109], v[166:169], v[202:205], v[106:109]
	v_mfma_f32_16x16x32_bf16 v[94:97], v[158:161], v[210:213], v[94:97]
	v_mfma_f32_16x16x32_bf16 v[90:93], v[166:169], v[210:213], v[90:93]
	v_mfma_f32_16x16x32_bf16 v[78:81], v[158:161], v[218:221], v[78:81]
	v_mfma_f32_16x16x32_bf16 v[74:77], v[166:169], v[218:221], v[74:77]
	v_mfma_f32_16x16x32_bf16 v[118:121], v[174:177], v[190:193], v[118:121]
	v_mfma_f32_16x16x32_bf16 v[114:117], v[182:185], v[190:193], v[114:117]
	v_mfma_f32_16x16x32_bf16 v[102:105], v[174:177], v[198:201], v[102:105]
	v_mfma_f32_16x16x32_bf16 v[98:101], v[182:185], v[198:201], v[98:101]
	v_mfma_f32_16x16x32_bf16 v[86:89], v[174:177], v[206:209], v[86:89]
	v_mfma_f32_16x16x32_bf16 v[82:85], v[182:185], v[206:209], v[82:85]
	v_mfma_f32_16x16x32_bf16 v[70:73], v[174:177], v[214:217], v[70:73]
	v_mfma_f32_16x16x32_bf16 v[66:69], v[182:185], v[214:217], v[66:69]
	v_mfma_f32_16x16x32_bf16 v[118:121], v[178:181], v[194:197], v[118:121]
	v_mfma_f32_16x16x32_bf16 v[114:117], v[186:189], v[194:197], v[114:117]
	v_mfma_f32_16x16x32_bf16 v[102:105], v[178:181], v[202:205], v[102:105]
	v_mfma_f32_16x16x32_bf16 v[98:101], v[186:189], v[202:205], v[98:101]
	v_mfma_f32_16x16x32_bf16 v[86:89], v[178:181], v[210:213], v[86:89]
	v_mfma_f32_16x16x32_bf16 v[82:85], v[186:189], v[210:213], v[82:85]
	v_mfma_f32_16x16x32_bf16 v[70:73], v[178:181], v[218:221], v[70:73]
	v_mfma_f32_16x16x32_bf16 v[66:69], v[186:189], v[218:221], v[66:69]
	s_barrier

; #define PG8_STAGE(bufoff, gbase, voff) do { _Pragma("unroll") for (int _i = 0; _i < 2; ++_i) \
;         __builtin_amdgcn_global_load_lds((const unsigned*)((const char*)(gbase) + (voff)[_i]), (PG8_LAS unsigned*)(lds + (bufoff) + ldsw + _i * 8192), 16, 0, 0); } while (0)
; #define PG8_LDA(dst, b, h) do { _Pragma("unroll") for (int m = 0; m < 4; ++m) _Pragma("unroll") for (int k = 0; k < 2; ++k) dst[m][k] = *(const PG8_LAS bf16x8*)(lds + PG8_SA(b, h) + aoff + m * 2048 + k * 1024); } while (0)
; #define PG8_MMA(ai, bj, At, Bt) do { __builtin_amdgcn_s_setprio(1); _Pragma("unroll") for (int m = 0; m < 4; ++m) _Pragma("unroll") for (int n = 0; n < 2; ++n) _Pragma("unroll") for (int k = 0; k < 2; ++k) \
;         acc[ai][bj][m][n] = __builtin_amdgcn_mfma_f32_16x16x32_bf16(Bt[n][k], At[m][k], acc[ai][bj][m][n], 0, 0, 0); __builtin_amdgcn_s_setprio(0); } while (0)
; #define PG8_WAIT_V(n) asm volatile("s_waitcnt vmcnt(" #n ")" ::: "memory")
; #define PG8_WAIT_L(n) asm volatile("s_waitcnt lgkmcnt(" #n ")" ::: "memory")
; #define PG8_BAR __builtin_amdgcn_s_barrier()
; #define PG8_SCHED __builtin_amdgcn_sched_barrier(0)
; template <class Epi, class Sched, bool ALIGN_EPI = false, bool SP2 = false>
; __device__ __forceinline__ void gemm_phase(PG8_LAS unsigned char* lds, const Gemm g, const Sched& S, const Epi& E) {
;     ...
;             PG8_LDA(At, 1, 1); PG8_STAGE(PG8_SB(1, 0), b3, voffB); PG8_STAGE(PG8_SB(1, 1), b3 + hstep, voffB); PG8_STAGE(PG8_SA(1, 0), a3, voffA);
;             PG8_WAIT_V(8); PG8_WAIT_L(0); PG8_BAR; PG8_MMA(1, 0, At, B0); PG8_MMA(1, 1, At, B1); PG8_BAR; PG8_SCHED;
	s_add_i32 s42, s72, s54
	v_lshl_add_u64 v[146:147], v[146:147], 0, s[10:11]
	s_mov_b32 m0, s42
	ds_read_b128 v[190:193], v152 offset:49152
	ds_read_b128 v[194:197], v152 offset:50176
	ds_read_b128 v[198:201], v152 offset:51200
	ds_read_b128 v[202:205], v152 offset:52224
	ds_read_b128 v[206:209], v152 offset:53248
	ds_read_b128 v[210:213], v152 offset:54272
	ds_read_b128 v[214:217], v152 offset:55296
	ds_read_b128 v[218:221], v152 offset:56320
	global_load_lds_dwordx4 v[146:147], off
	s_add_i32 m0, s42, 0x2000
	s_add_u32 s40, s40, 0x40080
	v_lshl_add_u64 v[146:147], v[170:171], 0, s[10:11]
	s_addc_u32 s41, s41, 0
	s_add_i32 s42, s73, s54
	global_load_lds_dwordx4 v[146:147], off
	v_lshl_add_u64 v[146:147], s[40:41], 0, v[132:133]
	s_mov_b32 m0, s42
	s_nop 0
	global_load_lds_dwordx4 v[146:147], off
	v_lshl_add_u64 v[146:147], s[40:41], 0, v[136:137]
	s_add_i32 m0, s42, 0x2000
	s_nop 0
	global_load_lds_dwordx4 v[146:147], off
	v_lshl_add_u64 v[146:147], v[222:223], 0, s[10:11]
	s_mov_b32 m0, s60
	s_nop 0
	global_load_lds_dwordx4 v[146:147], off
	v_lshl_add_u64 v[146:147], v[224:225], 0, s[10:11]
	s_mov_b32 m0, s61
	s_nop 0
	global_load_lds_dwordx4 v[146:147], off
	s_waitcnt vmcnt(8)
	s_waitcnt lgkmcnt(0)
	s_barrier
	s_waitcnt lgkmcnt(0)
	v_mfma_f32_16x16x32_bf16 v[62:65], v[154:157], v[190:193], v[62:65]
	v_mfma_f32_16x16x32_bf16 v[58:61], v[162:165], v[190:193], v[58:61]
	v_mfma_f32_16x16x32_bf16 v[46:49], v[154:157], v[198:201], v[46:49]
	v_mfma_f32_16x16x32_bf16 v[42:45], v[162:165], v[198:201], v[42:45]
	v_mfma_f32_16x16x32_bf16 v[30:33], v[154:157], v[206:209], v[30:33]
	v_mfma_f32_16x16x32_bf16 v[26:29], v[162:165], v[206:209], v[26:29]
	v_mfma_f32_16x16x32_bf16 v[14:17], v[154:157], v[214:217], v[14:17]
	v_mfma_f32_16x16x32_bf16 v[10:13], v[162:165], v[214:217], v[10:13]
	v_mfma_f32_16x16x32_bf16 v[62:65], v[158:161], v[194:197], v[62:65]
	v_mfma_f32_16x16x32_bf16 v[58:61], v[166:169], v[194:197], v[58:61]
	v_mfma_f32_16x16x32_bf16 v[46:49], v[158:161], v[202:205], v[46:49]
	v_mfma_f32_16x16x32_bf16 v[42:45], v[166:169], v[202:205], v[42:45]
	v_mfma_f32_16x16x32_bf16 v[30:33], v[158:161], v[210:213], v[30:33]
	v_mfma_f32_16x16x32_bf16 v[26:29], v[166:169], v[210:213], v[26:29]
	v_mfma_f32_16x16x32_bf16 v[14:17], v[158:161], v[218:221], v[14:17]
	v_mfma_f32_16x16x32_bf16 v[10:13], v[166:169], v[218:221], v[10:13]
	v_mfma_f32_16x16x32_bf16 v[54:57], v[174:177], v[190:193], v[54:57]
	v_mfma_f32_16x16x32_bf16 v[50:53], v[182:185], v[190:193], v[50:53]
	v_mfma_f32_16x16x32_bf16 v[38:41], v[174:177], v[198:201], v[38:41]
	v_mfma_f32_16x16x32_bf16 v[34:37], v[182:185], v[198:201], v[34:37]
	v_mfma_f32_16x16x32_bf16 v[22:25], v[174:177], v[206:209], v[22:25]
	v_mfma_f32_16x16x32_bf16 v[18:21], v[182:185], v[206:209], v[18:21]
	v_mfma_f32_16x16x32_bf16 v[6:9], v[174:177], v[214:217], v[6:9]
	v_mfma_f32_16x16x32_bf16 v[2:5], v[182:185], v[214:217], v[2:5]
	v_mfma_f32_16x16x32_bf16 v[54:57], v[178:181], v[194:197], v[54:57]
	v_mfma_f32_16x16x32_bf16 v[50:53], v[186:189], v[194:197], v[50:53]
	v_mfma_f32_16x16x32_bf16 v[38:41], v[178:181], v[202:205], v[38:41]
	v_mfma_f32_16x16x32_bf16 v[34:37], v[186:189], v[202:205], v[34:37]
	v_mfma_f32_16x16x32_bf16 v[22:25], v[178:181], v[210:213], v[22:25]
	v_mfma_f32_16x16x32_bf16 v[18:21], v[186:189], v[210:213], v[18:21]
	v_mfma_f32_16x16x32_bf16 v[6:9], v[178:181], v[218:221], v[6:9]
	v_mfma_f32_16x16x32_bf16 v[2:5], v[186:189], v[218:221], v[2:5]
	s_barrier

; #define PG8_STAGE(bufoff, gbase, voff) do { _Pragma("unroll") for (int _i = 0; _i < 2; ++_i) \
;         __builtin_amdgcn_global_load_lds((const unsigned*)((const char*)(gbase) + (voff)[_i]), (PG8_LAS unsigned*)(lds + (bufoff) + ldsw + _i * 8192), 16, 0, 0); } while (0)
; #define PG8_LDA(dst, b, h) do { _Pragma("unroll") for (int m = 0; m < 4; ++m) _Pragma("unroll") for (int k = 0; k < 2; ++k) dst[m][k] = *(const PG8_LAS bf16x8*)(lds + PG8_SA(b, h) + aoff + m * 2048 + k * 1024); } while (0)
; #define PG8_LDB(dst, b, h) do { _Pragma("unroll") for (int n = 0; n < 2; ++n) _Pragma("unroll") for (int k = 0; k < 2; ++k) dst[n][k] = *(const PG8_LAS bf16x8*)(lds + PG8_SB(b, h) + boff + n * 2048 + k * 1024); } while (0)
; #define PG8_MMA(ai, bj, At, Bt) do { __builtin_amdgcn_s_setprio(1); _Pragma("unroll") for (int m = 0; m < 4; ++m) _Pragma("unroll") for (int n = 0; n < 2; ++n) _Pragma("unroll") for (int k = 0; k < 2; ++k) \
;         acc[ai][bj][m][n] = __builtin_amdgcn_mfma_f32_16x16x32_bf16(Bt[n][k], At[m][k], acc[ai][bj][m][n], 0, 0, 0); __builtin_amdgcn_s_setprio(0); } while (0)
; #define PG8_WAIT_V(n) asm volatile("s_waitcnt vmcnt(" #n ")" ::: "memory")
; #define PG8_WAIT_L(n) asm volatile("s_waitcnt lgkmcnt(" #n ")" ::: "memory")
; #define PG8_BAR __builtin_amdgcn_s_barrier()
; #define PG8_SCHED __builtin_amdgcn_sched_barrier(0)
; template <class Epi, class Sched, bool ALIGN_EPI = false, bool SP2 = false>
; __device__ __forceinline__ void gemm_phase(PG8_LAS unsigned char* lds, const Gemm g, const Sched& S, const Epi& E) {
;     ...
;         for (int t = 0; t < nt; t += 2) {
;             const bool last = (t == nt - 2);
;             const char* a1 = cA + (size_t)(t + 1) * kstep;
;             const char* a2 = last ? nA : cA + (size_t)(t + 2) * kstep; const char* b2 = last ? nB : cB + (size_t)(t + 2) * kstep;
;             const char* a3 = a2 + kstep; const char* b3 = b2 + kstep;
;             if (last && has_next) S.a_ready(nxt);
;             if constexpr (SP2) {
;             PG8_LDB(B0, 0, 0); PG8_LDB(B1, 0, 1); PG8_SCHED; PG8_LDA(At, 0, 0); PG8_STAGE(PG8_SA(1, 1), a1 + hstep, voffA);
;             PG8_WAIT_V(8); PG8_WAIT_L(0); PG8_BAR; PG8_MMA(0, 0, At, B0); PG8_MMA(0, 1, At, B1); PG8_BAR; PG8_SCHED;
;             PG8_LDA(At, 0, 1); PG8_STAGE(PG8_SB(0, 0), b2, voffB); PG8_STAGE(PG8_SB(0, 1), b2 + hstep, voffB); PG8_STAGE(PG8_SA(0, 0), a2, voffA);
	s_add_i32 s71, s71, 2
	s_add_u32 s38, s38, 0x100
	s_addc_u32 s39, s39, 0
	s_add_u32 s69, s69, 0x100
	s_addc_u32 s70, s70, 0
.LBB0_1221:
	ds_read_b128 v[154:157], v150
	ds_read_b128 v[158:161], v150 offset:1024
	ds_read_b128 v[162:165], v150 offset:2048
	ds_read_b128 v[166:169], v150 offset:3072
	ds_read_b128 v[174:177], v151
	ds_read_b128 v[178:181], v151 offset:1024
	ds_read_b128 v[182:185], v151 offset:2048
	ds_read_b128 v[186:189], v151 offset:3072
	s_add_u32 s40, s38, 0xfffc0080
	s_addc_u32 s41, s39, -1
	s_cmp_eq_u32 s71, 12
	s_cselect_b32 s43, s29, s41
	s_cselect_b32 s42, s67, s40
	s_cselect_b32 s41, s27, s70
	s_cselect_b32 s40, s68, s69
	v_lshl_add_u64 v[146:147], s[38:39], 0, v[138:139]
	s_add_i32 m0, s55, 0xc000
	ds_read_b128 v[190:193], v152
	ds_read_b128 v[194:197], v152 offset:1024
	ds_read_b128 v[198:201], v152 offset:2048
	ds_read_b128 v[202:205], v152 offset:3072
	ds_read_b128 v[206:209], v152 offset:4096
	ds_read_b128 v[210:213], v152 offset:5120
	ds_read_b128 v[214:217], v152 offset:6144
	ds_read_b128 v[218:221], v152 offset:7168
	global_load_lds_dwordx4 v[146:147], off
	v_lshl_add_u64 v[146:147], s[38:39], 0, v[140:141]
	s_add_i32 m0, s55, 0xe000
	s_nop 0
	global_load_lds_dwordx4 v[146:147], off
	s_waitcnt vmcnt(8)
	s_waitcnt lgkmcnt(0)
	s_barrier
	s_waitcnt lgkmcnt(0)
	v_mfma_f32_16x16x32_bf16 v[126:129], v[154:157], v[190:193], v[126:129]
	v_mfma_f32_16x16x32_bf16 v[122:125], v[162:165], v[190:193], v[122:125]
	v_mfma_f32_16x16x32_bf16 v[110:113], v[154:157], v[198:201], v[110:113]
	v_mfma_f32_16x16x32_bf16 v[106:109], v[162:165], v[198:201], v[106:109]
	v_mfma_f32_16x16x32_bf16 v[94:97], v[154:157], v[206:209], v[94:97]
	v_mfma_f32_16x16x32_bf16 v[90:93], v[162:165], v[206:209], v[90:93]
	v_mfma_f32_16x16x32_bf16 v[78:81], v[154:157], v[214:217], v[78:81]
	v_mfma_f32_16x16x32_bf16 v[74:77], v[162:165], v[214:217], v[74:77]
	v_mfma_f32_16x16x32_bf16 v[126:129], v[158:161], v[194:197], v[126:129]
	v_mfma_f32_16x16x32_bf16 v[122:125], v[166:169], v[194:197], v[122:125]
	v_mfma_f32_16x16x32_bf16 v[110:113], v[158:161], v[202:205], v[110:113]
	v_mfma_f32_16x16x32_bf16 v[106:109], v[166:169], v[202:205], v[106:109]
	v_mfma_f32_16x16x32_bf16 v[94:97], v[158:161], v[210:213], v[94:97]
	v_mfma_f32_16x16x32_bf16 v[90:93], v[166:169], v[210:213], v[90:93]
	v_mfma_f32_16x16x32_bf16 v[78:81], v[158:161], v[218:221], v[78:81]
	v_mfma_f32_16x16x32_bf16 v[74:77], v[166:169], v[218:221], v[74:77]
	v_mfma_f32_16x16x32_bf16 v[118:121], v[174:177], v[190:193], v[118:121]
	v_mfma_f32_16x16x32_bf16 v[114:117], v[182:185], v[190:193], v[114:117]
	v_mfma_f32_16x16x32_bf16 v[102:105], v[174:177], v[198:201], v[102:105]
	v_mfma_f32_16x16x32_bf16 v[98:101], v[182:185], v[198:201], v[98:101]
	v_mfma_f32_16x16x32_bf16 v[86:89], v[174:177], v[206:209], v[86:89]
	v_mfma_f32_16x16x32_bf16 v[82:85], v[182:185], v[206:209], v[82:85]
	v_mfma_f32_16x16x32_bf16 v[70:73], v[174:177], v[214:217], v[70:73]
	v_mfma_f32_16x16x32_bf16 v[66:69], v[182:185], v[214:217], v[66:69]
	v_mfma_f32_16x16x32_bf16 v[118:121], v[178:181], v[194:197], v[118:121]
	v_mfma_f32_16x16x32_bf16 v[114:117], v[186:189], v[194:197], v[114:117]
	v_mfma_f32_16x16x32_bf16 v[102:105], v[178:181], v[202:205], v[102:105]
	v_mfma_f32_16x16x32_bf16 v[98:101], v[186:189], v[202:205], v[98:101]
	v_mfma_f32_16x16x32_bf16 v[86:89], v[178:181], v[210:213], v[86:89]
	v_mfma_f32_16x16x32_bf16 v[82:85], v[186:189], v[210:213], v[82:85]
	v_mfma_f32_16x16x32_bf16 v[70:73], v[178:181], v[218:221], v[70:73]
	v_mfma_f32_16x16x32_bf16 v[66:69], v[186:189], v[218:221], v[66:69]
	s_barrier
	s_add_i32 s72, s64, s54
	v_lshl_add_u64 v[146:147], s[40:41], 0, v[132:133]
	s_mov_b32 m0, s72
	ds_read_b128 v[190:193], v152 offset:16384
	ds_read_b128 v[194:197], v152 offset:17408
	ds_read_b128 v[198:201], v152 offset:18432
	ds_read_b128 v[202:205], v152 offset:19456
	ds_read_b128 v[206:209], v152 offset:20480
	ds_read_b128 v[210:213], v152 offset:21504
	ds_read_b128 v[214:217], v152 offset:22528
	ds_read_b128 v[218:221], v152 offset:23552
	global_load_lds_dwordx4 v[146:147], off
	s_add_i32 m0, s72, 0x2000
	s_add_u32 s72, s40, 0x40000
	v_lshl_add_u64 v[170:171], s[40:41], 0, v[136:137]
	s_addc_u32 s73, s41, 0
	s_add_i32 s74, s65, s54
	global_load_lds_dwordx4 v[170:171], off
	v_lshl_add_u64 v[222:223], s[72:73], 0, v[132:133]
	s_mov_b32 m0, s74
	v_lshl_add_u64 v[224:225], s[42:43], 0, v[134:135]
	global_load_lds_dwordx4 v[222:223], off
	v_lshl_add_u64 v[222:223], s[72:73], 0, v[136:137]
	s_add_i32 m0, s74, 0x2000
	s_nop 0
	global_load_lds_dwordx4 v[222:223], off
	v_lshl_add_u64 v[222:223], s[42:43], 0, v[130:131]
	s_mov_b32 m0, s55
	s_nop 0
	global_load_lds_dwordx4 v[222:223], off
	s_mov_b32 m0, s56
	s_nop 0
	global_load_lds_dwordx4 v[224:225], off
	s_waitcnt vmcnt(8)
	s_waitcnt lgkmcnt(0)
	s_barrier
; #define PG8_STAGE(bufoff, gbase, voff) do { _Pragma("unroll") for (int _i = 0; _i < 2; ++_i) \
;         __builtin_amdgcn_global_load_lds((const unsigned*)((const char*)(gbase) + (voff)[_i]), (PG8_LAS unsigned*)(lds + (bufoff) + ldsw + _i * 8192), 16, 0, 0); } while (0)
; #define PG8_LDA(dst, b, h) do { _Pragma("unroll") for (int m = 0; m < 4; ++m) _Pragma("unroll") for (int k = 0; k < 2; ++k) dst[m][k] = *(const PG8_LAS bf16x8*)(lds + PG8_SA(b, h) + aoff + m * 2048 + k * 1024); } while (0)
; #define PG8_LDB(dst, b, h) do { _Pragma("unroll") for (int n = 0; n < 2; ++n) _Pragma("unroll") for (int k = 0; k < 2; ++k) dst[n][k] = *(const PG8_LAS bf16x8*)(lds + PG8_SB(b, h) + boff + n * 2048 + k * 1024); } while (0)
; #define PG8_MMA(ai, bj, At, Bt) do { __builtin_amdgcn_s_setprio(1); _Pragma("unroll") for (int m = 0; m < 4; ++m) _Pragma("unroll") for (int n = 0; n < 2; ++n) _Pragma("unroll") for (int k = 0; k < 2; ++k) \
;         acc[ai][bj][m][n] = __builtin_amdgcn_mfma_f32_16x16x32_bf16(Bt[n][k], At[m][k], acc[ai][bj][m][n], 0, 0, 0); __builtin_amdgcn_s_setprio(0); } while (0)
; #define PG8_WAIT_V(n) asm volatile("s_waitcnt vmcnt(" #n ")" ::: "memory")
; #define PG8_WAIT_L(n) asm volatile("s_waitcnt lgkmcnt(" #n ")" ::: "memory")
; #define PG8_BAR __builtin_amdgcn_s_barrier()
; #define PG8_SCHED __builtin_amdgcn_sched_barrier(0)
; template <class Epi, class Sched, bool ALIGN_EPI = false, bool SP2 = false>
; __device__ __forceinline__ void gemm_phase(PG8_LAS unsigned char* lds, const Gemm g, const Sched& S, const Epi& E) {
;     ...
;             PG8_WAIT_V(8); PG8_WAIT_L(0); PG8_BAR; PG8_MMA(1, 0, At, B0); PG8_MMA(1, 1, At, B1); PG8_BAR; PG8_SCHED;
;             PG8_LDB(B0, 1, 0); PG8_LDB(B1, 1, 1); PG8_SCHED; PG8_LDA(At, 1, 0); PG8_STAGE(PG8_SA(0, 1), a2 + hstep, voffA);
;             PG8_WAIT_V(8); PG8_WAIT_L(0); PG8_BAR; PG8_MMA(0, 0, At, B0); PG8_MMA(0, 1, At, B1); PG8_BAR; PG8_SCHED;
	s_waitcnt lgkmcnt(0)
	v_mfma_f32_16x16x32_bf16 v[62:65], v[154:157], v[190:193], v[62:65]
	v_mfma_f32_16x16x32_bf16 v[58:61], v[162:165], v[190:193], v[58:61]
	v_mfma_f32_16x16x32_bf16 v[46:49], v[154:157], v[198:201], v[46:49]
	v_mfma_f32_16x16x32_bf16 v[42:45], v[162:165], v[198:201], v[42:45]
	v_mfma_f32_16x16x32_bf16 v[30:33], v[154:157], v[206:209], v[30:33]
	v_mfma_f32_16x16x32_bf16 v[26:29], v[162:165], v[206:209], v[26:29]
	v_mfma_f32_16x16x32_bf16 v[14:17], v[154:157], v[214:217], v[14:17]
	v_mfma_f32_16x16x32_bf16 v[10:13], v[162:165], v[214:217], v[10:13]
	v_mfma_f32_16x16x32_bf16 v[62:65], v[158:161], v[194:197], v[62:65]
	v_mfma_f32_16x16x32_bf16 v[58:61], v[166:169], v[194:197], v[58:61]
	v_mfma_f32_16x16x32_bf16 v[46:49], v[158:161], v[202:205], v[46:49]
	v_mfma_f32_16x16x32_bf16 v[42:45], v[166:169], v[202:205], v[42:45]
	v_mfma_f32_16x16x32_bf16 v[30:33], v[158:161], v[210:213], v[30:33]
	v_mfma_f32_16x16x32_bf16 v[26:29], v[166:169], v[210:213], v[26:29]
	v_mfma_f32_16x16x32_bf16 v[14:17], v[158:161], v[218:221], v[14:17]
	v_mfma_f32_16x16x32_bf16 v[10:13], v[166:169], v[218:221], v[10:13]
	v_mfma_f32_16x16x32_bf16 v[54:57], v[174:177], v[190:193], v[54:57]
	v_mfma_f32_16x16x32_bf16 v[50:53], v[182:185], v[190:193], v[50:53]
	v_mfma_f32_16x16x32_bf16 v[38:41], v[174:177], v[198:201], v[38:41]
	v_mfma_f32_16x16x32_bf16 v[34:37], v[182:185], v[198:201], v[34:37]
	v_mfma_f32_16x16x32_bf16 v[22:25], v[174:177], v[206:209], v[22:25]
	v_mfma_f32_16x16x32_bf16 v[18:21], v[182:185], v[206:209], v[18:21]
	v_mfma_f32_16x16x32_bf16 v[6:9], v[174:177], v[214:217], v[6:9]
	v_mfma_f32_16x16x32_bf16 v[2:5], v[182:185], v[214:217], v[2:5]
	v_mfma_f32_16x16x32_bf16 v[54:57], v[178:181], v[194:197], v[54:57]
	v_mfma_f32_16x16x32_bf16 v[50:53], v[186:189], v[194:197], v[50:53]
	v_mfma_f32_16x16x32_bf16 v[38:41], v[178:181], v[202:205], v[38:41]
	v_mfma_f32_16x16x32_bf16 v[34:37], v[186:189], v[202:205], v[34:37]
	v_mfma_f32_16x16x32_bf16 v[22:25], v[178:181], v[210:213], v[22:25]
	v_mfma_f32_16x16x32_bf16 v[18:21], v[186:189], v[210:213], v[18:21]
	v_mfma_f32_16x16x32_bf16 v[6:9], v[178:181], v[218:221], v[6:9]
	v_mfma_f32_16x16x32_bf16 v[2:5], v[186:189], v[218:221], v[2:5]
	s_barrier
	s_add_i32 s72, 0, 0x18000
	v_add_u32_e32 v153, s72, v148
	s_add_i32 s73, 0, 0x1c000
	ds_read_b128 v[154:157], v153
	ds_read_b128 v[158:161], v153 offset:1024
	ds_read_b128 v[162:165], v153 offset:2048
	ds_read_b128 v[166:169], v153 offset:3072
	v_add_u32_e32 v153, s73, v148
	ds_read_b128 v[174:177], v153
	ds_read_b128 v[178:181], v153 offset:1024
	ds_read_b128 v[182:185], v153 offset:2048
	ds_read_b128 v[186:189], v153 offset:3072
	s_add_u32 s42, s42, 0x40000
	s_addc_u32 s43, s43, 0
	s_mov_b32 m0, s57
	v_lshl_add_u64 v[226:227], s[42:43], 0, v[130:131]
	ds_read_b128 v[190:193], v152 offset:32768
	ds_read_b128 v[194:197], v152 offset:33792
	ds_read_b128 v[198:201], v152 offset:34816
	ds_read_b128 v[202:205], v152 offset:35840
	ds_read_b128 v[206:209], v152 offset:36864
	ds_read_b128 v[210:213], v152 offset:37888
	ds_read_b128 v[214:217], v152 offset:38912
	ds_read_b128 v[218:221], v152 offset:39936
	global_load_lds_dwordx4 v[226:227], off
	v_lshl_add_u64 v[226:227], s[42:43], 0, v[134:135]
	s_mov_b32 m0, s58
	s_nop 0
	global_load_lds_dwordx4 v[226:227], off
	s_waitcnt vmcnt(8)
	s_waitcnt lgkmcnt(0)
	s_barrier
	s_waitcnt lgkmcnt(0)
	v_mfma_f32_16x16x32_bf16 v[126:129], v[154:157], v[190:193], v[126:129]
	v_mfma_f32_16x16x32_bf16 v[122:125], v[162:165], v[190:193], v[122:125]
	v_mfma_f32_16x16x32_bf16 v[110:113], v[154:157], v[198:201], v[110:113]
	v_mfma_f32_16x16x32_bf16 v[106:109], v[162:165], v[198:201], v[106:109]
	v_mfma_f32_16x16x32_bf16 v[94:97], v[154:157], v[206:209], v[94:97]
	v_mfma_f32_16x16x32_bf16 v[90:93], v[162:165], v[206:209], v[90:93]
	v_mfma_f32_16x16x32_bf16 v[78:81], v[154:157], v[214:217], v[78:81]
	v_mfma_f32_16x16x32_bf16 v[74:77], v[162:165], v[214:217], v[74:77]
	v_mfma_f32_16x16x32_bf16 v[126:129], v[158:161], v[194:197], v[126:129]
	v_mfma_f32_16x16x32_bf16 v[122:125], v[166:169], v[194:197], v[122:125]
	v_mfma_f32_16x16x32_bf16 v[110:113], v[158:161], v[202:205], v[110:113]
	v_mfma_f32_16x16x32_bf16 v[106:109], v[166:169], v[202:205], v[106:109]
	v_mfma_f32_16x16x32_bf16 v[94:97], v[158:161], v[210:213], v[94:97]
	v_mfma_f32_16x16x32_bf16 v[90:93], v[166:169], v[210:213], v[90:93]
	v_mfma_f32_16x16x32_bf16 v[78:81], v[158:161], v[218:221], v[78:81]
	v_mfma_f32_16x16x32_bf16 v[74:77], v[166:169], v[218:221], v[74:77]
	v_mfma_f32_16x16x32_bf16 v[118:121], v[174:177], v[190:193], v[118:121]
	v_mfma_f32_16x16x32_bf16 v[114:117], v[182:185], v[190:193], v[114:117]
	v_mfma_f32_16x16x32_bf16 v[102:105], v[174:177], v[198:201], v[102:105]
	v_mfma_f32_16x16x32_bf16 v[98:101], v[182:185], v[198:201], v[98:101]
	v_mfma_f32_16x16x32_bf16 v[86:89], v[174:177], v[206:209], v[86:89]
	v_mfma_f32_16x16x32_bf16 v[82:85], v[182:185], v[206:209], v[82:85]
	v_mfma_f32_16x16x32_bf16 v[70:73], v[174:177], v[214:217], v[70:73]
	v_mfma_f32_16x16x32_bf16 v[66:69], v[182:185], v[214:217], v[66:69]
	v_mfma_f32_16x16x32_bf16 v[118:121], v[178:181], v[194:197], v[118:121]
	v_mfma_f32_16x16x32_bf16 v[114:117], v[186:189], v[194:197], v[114:117]
	v_mfma_f32_16x16x32_bf16 v[102:105], v[178:181], v[202:205], v[102:105]
	v_mfma_f32_16x16x32_bf16 v[98:101], v[186:189], v[202:205], v[98:101]
	v_mfma_f32_16x16x32_bf16 v[86:89], v[178:181], v[210:213], v[86:89]
	v_mfma_f32_16x16x32_bf16 v[82:85], v[186:189], v[210:213], v[82:85]
	v_mfma_f32_16x16x32_bf16 v[70:73], v[178:181], v[218:221], v[70:73]
	v_mfma_f32_16x16x32_bf16 v[66:69], v[186:189], v[218:221], v[66:69]
	s_barrier
; #define PG8_STAGE(bufoff, gbase, voff) do { _Pragma("unroll") for (int _i = 0; _i < 2; ++_i) \
;         __builtin_amdgcn_global_load_lds((const unsigned*)((const char*)(gbase) + (voff)[_i]), (PG8_LAS unsigned*)(lds + (bufoff) + ldsw + _i * 8192), 16, 0, 0); } while (0)
; #define PG8_LDA(dst, b, h) do { _Pragma("unroll") for (int m = 0; m < 4; ++m) _Pragma("unroll") for (int k = 0; k < 2; ++k) dst[m][k] = *(const PG8_LAS bf16x8*)(lds + PG8_SA(b, h) + aoff + m * 2048 + k * 1024); } while (0)
; #define PG8_MMA(ai, bj, At, Bt) do { __builtin_amdgcn_s_setprio(1); _Pragma("unroll") for (int m = 0; m < 4; ++m) _Pragma("unroll") for (int n = 0; n < 2; ++n) _Pragma("unroll") for (int k = 0; k < 2; ++k) \
;         acc[ai][bj][m][n] = __builtin_amdgcn_mfma_f32_16x16x32_bf16(Bt[n][k], At[m][k], acc[ai][bj][m][n], 0, 0, 0); __builtin_amdgcn_s_setprio(0); } while (0)
; #define PG8_WAIT_V(n) asm volatile("s_waitcnt vmcnt(" #n ")" ::: "memory")
; #define PG8_WAIT_L(n) asm volatile("s_waitcnt lgkmcnt(" #n ")" ::: "memory")
; #define PG8_BAR __builtin_amdgcn_s_barrier()
; #define PG8_SCHED __builtin_amdgcn_sched_barrier(0)
; template <class Epi, class Sched, bool ALIGN_EPI = false, bool SP2 = false>
; __device__ __forceinline__ void gemm_phase(PG8_LAS unsigned char* lds, const Gemm g, const Sched& S, const Epi& E) {
;     ...
;             PG8_LDA(At, 1, 1); PG8_STAGE(PG8_SB(1, 0), b3, voffB); PG8_STAGE(PG8_SB(1, 1), b3 + hstep, voffB); PG8_STAGE(PG8_SA(1, 0), a3, voffA);
;             PG8_WAIT_V(8); PG8_WAIT_L(0); PG8_BAR; PG8_MMA(1, 0, At, B0); PG8_MMA(1, 1, At, B1); PG8_BAR; PG8_SCHED;
;     ...
;         }
;         if constexpr (ALIGN_EPI) { if (wr == 0) PG8_BAR; }
	s_add_i32 s42, s72, s54
	v_lshl_add_u64 v[146:147], v[146:147], 0, s[10:11]
	s_mov_b32 m0, s42
	ds_read_b128 v[190:193], v152 offset:49152
	ds_read_b128 v[194:197], v152 offset:50176
	ds_read_b128 v[198:201], v152 offset:51200
	ds_read_b128 v[202:205], v152 offset:52224
	ds_read_b128 v[206:209], v152 offset:53248
	ds_read_b128 v[210:213], v152 offset:54272
	ds_read_b128 v[214:217], v152 offset:55296
	ds_read_b128 v[218:221], v152 offset:56320
	global_load_lds_dwordx4 v[146:147], off
	s_add_i32 m0, s42, 0x2000
	s_add_u32 s40, s40, 0x40080
	v_lshl_add_u64 v[146:147], v[170:171], 0, s[10:11]
	s_addc_u32 s41, s41, 0
	s_add_i32 s42, s73, s54
	global_load_lds_dwordx4 v[146:147], off
	v_lshl_add_u64 v[146:147], s[40:41], 0, v[132:133]
	s_mov_b32 m0, s42
	s_nop 0
	global_load_lds_dwordx4 v[146:147], off
	v_lshl_add_u64 v[146:147], s[40:41], 0, v[136:137]
	s_add_i32 m0, s42, 0x2000
	s_nop 0
	global_load_lds_dwordx4 v[146:147], off
	v_lshl_add_u64 v[146:147], v[222:223], 0, s[10:11]
	s_mov_b32 m0, s60
	s_nop 0
	global_load_lds_dwordx4 v[146:147], off
	v_lshl_add_u64 v[146:147], v[224:225], 0, s[10:11]
	s_mov_b32 m0, s61
	s_nop 0
	global_load_lds_dwordx4 v[146:147], off
	s_waitcnt vmcnt(8)
	s_waitcnt lgkmcnt(0)
	s_barrier
	s_waitcnt lgkmcnt(0)
	v_mfma_f32_16x16x32_bf16 v[62:65], v[154:157], v[190:193], v[62:65]
	v_mfma_f32_16x16x32_bf16 v[58:61], v[162:165], v[190:193], v[58:61]
	v_mfma_f32_16x16x32_bf16 v[46:49], v[154:157], v[198:201], v[46:49]
	v_mfma_f32_16x16x32_bf16 v[42:45], v[162:165], v[198:201], v[42:45]
	v_mfma_f32_16x16x32_bf16 v[30:33], v[154:157], v[206:209], v[30:33]
	v_mfma_f32_16x16x32_bf16 v[26:29], v[162:165], v[206:209], v[26:29]
	v_mfma_f32_16x16x32_bf16 v[14:17], v[154:157], v[214:217], v[14:17]
	v_mfma_f32_16x16x32_bf16 v[10:13], v[162:165], v[214:217], v[10:13]
	v_mfma_f32_16x16x32_bf16 v[62:65], v[158:161], v[194:197], v[62:65]
	v_mfma_f32_16x16x32_bf16 v[58:61], v[166:169], v[194:197], v[58:61]
	v_mfma_f32_16x16x32_bf16 v[46:49], v[158:161], v[202:205], v[46:49]
	v_mfma_f32_16x16x32_bf16 v[42:45], v[166:169], v[202:205], v[42:45]
	v_mfma_f32_16x16x32_bf16 v[30:33], v[158:161], v[210:213], v[30:33]
	v_mfma_f32_16x16x32_bf16 v[26:29], v[166:169], v[210:213], v[26:29]
	v_mfma_f32_16x16x32_bf16 v[14:17], v[158:161], v[218:221], v[14:17]
	v_mfma_f32_16x16x32_bf16 v[10:13], v[166:169], v[218:221], v[10:13]
	v_mfma_f32_16x16x32_bf16 v[54:57], v[174:177], v[190:193], v[54:57]
	v_mfma_f32_16x16x32_bf16 v[50:53], v[182:185], v[190:193], v[50:53]
	v_mfma_f32_16x16x32_bf16 v[38:41], v[174:177], v[198:201], v[38:41]
	v_mfma_f32_16x16x32_bf16 v[34:37], v[182:185], v[198:201], v[34:37]
	v_mfma_f32_16x16x32_bf16 v[22:25], v[174:177], v[206:209], v[22:25]
	v_mfma_f32_16x16x32_bf16 v[18:21], v[182:185], v[206:209], v[18:21]
	v_mfma_f32_16x16x32_bf16 v[6:9], v[174:177], v[214:217], v[6:9]
	v_mfma_f32_16x16x32_bf16 v[2:5], v[182:185], v[214:217], v[2:5]
	v_mfma_f32_16x16x32_bf16 v[54:57], v[178:181], v[194:197], v[54:57]
	v_mfma_f32_16x16x32_bf16 v[50:53], v[186:189], v[194:197], v[50:53]
	v_mfma_f32_16x16x32_bf16 v[38:41], v[178:181], v[202:205], v[38:41]
	v_mfma_f32_16x16x32_bf16 v[34:37], v[186:189], v[202:205], v[34:37]
	v_mfma_f32_16x16x32_bf16 v[22:25], v[178:181], v[210:213], v[22:25]
	v_mfma_f32_16x16x32_bf16 v[18:21], v[186:189], v[210:213], v[18:21]
	v_mfma_f32_16x16x32_bf16 v[6:9], v[178:181], v[218:221], v[6:9]
	v_mfma_f32_16x16x32_bf16 v[2:5], v[186:189], v[218:221], v[2:5]
	s_barrier
	s_add_i32 s71, s71, 2
	s_add_u32 s38, s38, 0x100
	s_addc_u32 s39, s39, 0
	s_add_u32 s69, s69, 0x100
	s_addc_u32 s70, s70, 0
	s_cmp_gt_u32 s71, 13
	s_cbranch_scc0 .LBB0_1221
	s_and_b64 vcc, exec, s[12:13]
	s_cbranch_vccz .LBB0_1224
	s_barrier

; #define PG8_STAGE(bufoff, gbase, voff) do { _Pragma("unroll") for (int _i = 0; _i < 2; ++_i) \
;         __builtin_amdgcn_global_load_lds((const unsigned*)((const char*)(gbase) + (voff)[_i]), (PG8_LAS unsigned*)(lds + (bufoff) + ldsw + _i * 8192), 16, 0, 0); } while (0)
; #define PG8_LDA(dst, b, h) do { _Pragma("unroll") for (int m = 0; m < 4; ++m) _Pragma("unroll") for (int k = 0; k < 2; ++k) dst[m][k] = *(const PG8_LAS bf16x8*)(lds + PG8_SA(b, h) + aoff + m * 2048 + k * 1024); } while (0)
; #define PG8_LDB(dst, b, h) do { _Pragma("unroll") for (int n = 0; n < 2; ++n) _Pragma("unroll") for (int k = 0; k < 2; ++k) dst[n][k] = *(const PG8_LAS bf16x8*)(lds + PG8_SB(b, h) + boff + n * 2048 + k * 1024); } while (0)
; #define PG8_SCHED __builtin_amdgcn_sched_barrier(0)
; template <class Epi, class Sched, bool ALIGN_EPI = false, bool SP2 = false>
; __device__ __forceinline__ void gemm_phase(PG8_LAS unsigned char* lds, const Gemm g, const Sched& S, const Epi& E) {
;     ...
;         const bool has_next = S.next(ui + 1, nxt);
;         const char* nA = has_next ? (const char*)g.A + (size_t)nxt.pm * tstep : cA; const char* nB = has_next ? (const char*)g.Bt + (size_t)nxt.pn * tstep : cB;
; #pragma nounroll
;         for (int t = 0; t < nt; t += 2) {
;             const bool last = (t == nt - 2);
;             const char* a1 = cA + (size_t)(t + 1) * kstep;
;             const char* a2 = last ? nA : cA + (size_t)(t + 2) * kstep; const char* b2 = last ? nB : cB + (size_t)(t + 2) * kstep;
;             const char* a3 = a2 + kstep; const char* b3 = b2 + kstep;
;             if (last && has_next) S.a_ready(nxt);
;             if constexpr (SP2) {
;             PG8_LDB(B0, 0, 0); PG8_LDB(B1, 0, 1); PG8_SCHED; PG8_LDA(At, 0, 0); PG8_STAGE(PG8_SA(1, 1), a1 + hstep, voffA);
.LBB0_1313:
	s_ashr_i32 s21, s20, 31
	s_lshl_b64 s[22:23], s[20:21], 19
	s_add_u32 s22, s38, s22
	s_addc_u32 s23, s39, s23
	s_and_b64 s[24:25], s[2:3], exec
	s_cselect_b32 s21, s23, s29
	s_cselect_b32 s60, s22, s28
	s_ashr_i32 s19, s18, 31
	s_lshl_b64 s[24:25], s[18:19], 19
	s_add_u32 s24, s40, s24
	s_addc_u32 s25, s41, s25
	s_and_b64 s[34:35], s[2:3], exec
	s_cselect_b32 s19, s25, s31
	s_cselect_b32 s61, s24, s30
	s_add_u32 s28, s28, 0x40080
	s_addc_u32 s29, s29, 0
	s_add_u32 s62, s30, 0x100
	s_addc_u32 s63, s31, 0
	s_mov_b32 s64, -2
	ds_read_b128 v[146:149], v154
	ds_read_b128 v[158:161], v154 offset:1024
	ds_read_b128 v[162:165], v154 offset:2048
	ds_read_b128 v[166:169], v154 offset:3072
	ds_read_b128 v[174:177], v155
	ds_read_b128 v[178:181], v155 offset:1024
	ds_read_b128 v[182:185], v155 offset:2048
	ds_read_b128 v[186:189], v155 offset:3072
	s_add_u32 s30, s28, 0xfffc0080
	s_addc_u32 s31, s29, -1
	s_cmp_eq_u32 s64, 12
	s_cselect_b32 s35, s21, s31
	s_cselect_b32 s34, s60, s30
	s_cselect_b32 s31, s19, s63
	s_cselect_b32 s30, s61, s62

; #define PG8_STAGE(bufoff, gbase, voff) do { _Pragma("unroll") for (int _i = 0; _i < 2; ++_i) \
;         __builtin_amdgcn_global_load_lds((const unsigned*)((const char*)(gbase) + (voff)[_i]), (PG8_LAS unsigned*)(lds + (bufoff) + ldsw + _i * 8192), 16, 0, 0); } while (0)
; #define PG8_LDA(dst, b, h) do { _Pragma("unroll") for (int m = 0; m < 4; ++m) _Pragma("unroll") for (int k = 0; k < 2; ++k) dst[m][k] = *(const PG8_LAS bf16x8*)(lds + PG8_SA(b, h) + aoff + m * 2048 + k * 1024); } while (0)
; #define PG8_LDB(dst, b, h) do { _Pragma("unroll") for (int n = 0; n < 2; ++n) _Pragma("unroll") for (int k = 0; k < 2; ++k) dst[n][k] = *(const PG8_LAS bf16x8*)(lds + PG8_SB(b, h) + boff + n * 2048 + k * 1024); } while (0)
; #define PG8_MMA(ai, bj, At, Bt) do { __builtin_amdgcn_s_setprio(1); _Pragma("unroll") for (int m = 0; m < 4; ++m) _Pragma("unroll") for (int n = 0; n < 2; ++n) _Pragma("unroll") for (int k = 0; k < 2; ++k) \
;         acc[ai][bj][m][n] = __builtin_amdgcn_mfma_f32_16x16x32_bf16(Bt[n][k], At[m][k], acc[ai][bj][m][n], 0, 0, 0); __builtin_amdgcn_s_setprio(0); } while (0)
; #define PG8_WAIT_V(n) asm volatile("s_waitcnt vmcnt(" #n ")" ::: "memory")
; #define PG8_WAIT_L(n) asm volatile("s_waitcnt lgkmcnt(" #n ")" ::: "memory")
; #define PG8_BAR __builtin_amdgcn_s_barrier()
; #define PG8_SCHED __builtin_amdgcn_sched_barrier(0)
; template <class Epi, class Sched, bool ALIGN_EPI = false, bool SP2 = false>
; __device__ __forceinline__ void gemm_phase(PG8_LAS unsigned char* lds, const Gemm g, const Sched& S, const Epi& E) {
;     ...
;     f32x4 acc[2][2][4][2];
; #pragma unroll
;     for (int a = 0; a < 2; ++a)
; #pragma unroll
;         for (int b = 0; b < 2; ++b)
; #pragma unroll
;             for (int m = 0; m < 4; ++m)
; #pragma unroll
;                 for (int n = 0; n < 2; ++n) acc[a][b][m][n] = (f32x4){0.f, 0.f, 0.f, 0.f};
;     ...
;             PG8_LDB(B0, 0, 0); PG8_LDB(B1, 0, 1); PG8_SCHED; PG8_LDA(At, 0, 0); PG8_STAGE(PG8_SA(1, 1), a1 + hstep, voffA);
;             PG8_WAIT_V(8); PG8_WAIT_L(0); PG8_BAR; PG8_MMA(0, 0, At, B0); PG8_MMA(0, 1, At, B1); PG8_BAR; PG8_SCHED;
	v_lshl_add_u64 v[150:151], s[28:29], 0, v[138:139]
	s_add_i32 m0, s27, 0xc000
	ds_read_b128 v[190:193], v156
	ds_read_b128 v[194:197], v156 offset:1024
	ds_read_b128 v[198:201], v156 offset:2048
	ds_read_b128 v[202:205], v156 offset:3072
	ds_read_b128 v[206:209], v156 offset:4096
	ds_read_b128 v[210:213], v156 offset:5120
	ds_read_b128 v[214:217], v156 offset:6144
	ds_read_b128 v[218:221], v156 offset:7168
	global_load_lds_dwordx4 v[150:151], off
	v_lshl_add_u64 v[150:151], s[28:29], 0, v[140:141]
	s_add_i32 m0, s27, 0xe000
	s_nop 0
	global_load_lds_dwordx4 v[150:151], off
	s_waitcnt vmcnt(40)
	s_waitcnt lgkmcnt(0)
	s_barrier
	s_waitcnt lgkmcnt(0)
	v_mfma_f32_16x16x32_bf16 v[126:129], v[146:149], v[190:193], 0
	v_mfma_f32_16x16x32_bf16 v[122:125], v[162:165], v[190:193], 0
	v_mfma_f32_16x16x32_bf16 v[114:117], v[146:149], v[198:201], 0
	v_mfma_f32_16x16x32_bf16 v[106:109], v[162:165], v[198:201], 0
	v_mfma_f32_16x16x32_bf16 v[98:101], v[146:149], v[206:209], 0
	v_mfma_f32_16x16x32_bf16 v[90:93], v[162:165], v[206:209], 0
	v_mfma_f32_16x16x32_bf16 v[82:85], v[146:149], v[214:217], 0
	v_mfma_f32_16x16x32_bf16 v[74:77], v[162:165], v[214:217], 0
	v_mfma_f32_16x16x32_bf16 v[126:129], v[158:161], v[194:197], v[126:129]
	v_mfma_f32_16x16x32_bf16 v[122:125], v[166:169], v[194:197], v[122:125]
	v_mfma_f32_16x16x32_bf16 v[114:117], v[158:161], v[202:205], v[114:117]
	v_mfma_f32_16x16x32_bf16 v[106:109], v[166:169], v[202:205], v[106:109]
	v_mfma_f32_16x16x32_bf16 v[98:101], v[158:161], v[210:213], v[98:101]
	v_mfma_f32_16x16x32_bf16 v[90:93], v[166:169], v[210:213], v[90:93]
	v_mfma_f32_16x16x32_bf16 v[82:85], v[158:161], v[218:221], v[82:85]
	v_mfma_f32_16x16x32_bf16 v[74:77], v[166:169], v[218:221], v[74:77]
	v_mfma_f32_16x16x32_bf16 v[118:121], v[174:177], v[190:193], 0
	v_mfma_f32_16x16x32_bf16 v[110:113], v[182:185], v[190:193], 0
	v_mfma_f32_16x16x32_bf16 v[102:105], v[174:177], v[198:201], 0
	v_mfma_f32_16x16x32_bf16 v[94:97], v[182:185], v[198:201], 0
	v_mfma_f32_16x16x32_bf16 v[86:89], v[174:177], v[206:209], 0
	v_mfma_f32_16x16x32_bf16 v[78:81], v[182:185], v[206:209], 0
	v_mfma_f32_16x16x32_bf16 v[70:73], v[174:177], v[214:217], 0
	v_mfma_f32_16x16x32_bf16 v[66:69], v[182:185], v[214:217], 0
	v_mfma_f32_16x16x32_bf16 v[118:121], v[178:181], v[194:197], v[118:121]
	v_mfma_f32_16x16x32_bf16 v[110:113], v[186:189], v[194:197], v[110:113]
	v_mfma_f32_16x16x32_bf16 v[102:105], v[178:181], v[202:205], v[102:105]
	v_mfma_f32_16x16x32_bf16 v[94:97], v[186:189], v[202:205], v[94:97]
	v_mfma_f32_16x16x32_bf16 v[86:89], v[178:181], v[210:213], v[86:89]
	v_mfma_f32_16x16x32_bf16 v[78:81], v[186:189], v[210:213], v[78:81]
	v_mfma_f32_16x16x32_bf16 v[70:73], v[178:181], v[218:221], v[70:73]
	v_mfma_f32_16x16x32_bf16 v[66:69], v[186:189], v[218:221], v[66:69]
	s_barrier

; #define PG8_STAGE(bufoff, gbase, voff) do { _Pragma("unroll") for (int _i = 0; _i < 2; ++_i) \
;         __builtin_amdgcn_global_load_lds((const unsigned*)((const char*)(gbase) + (voff)[_i]), (PG8_LAS unsigned*)(lds + (bufoff) + ldsw + _i * 8192), 16, 0, 0); } while (0)
; #define PG8_LDA(dst, b, h) do { _Pragma("unroll") for (int m = 0; m < 4; ++m) _Pragma("unroll") for (int k = 0; k < 2; ++k) dst[m][k] = *(const PG8_LAS bf16x8*)(lds + PG8_SA(b, h) + aoff + m * 2048 + k * 1024); } while (0)
; #define PG8_MMA(ai, bj, At, Bt) do { __builtin_amdgcn_s_setprio(1); _Pragma("unroll") for (int m = 0; m < 4; ++m) _Pragma("unroll") for (int n = 0; n < 2; ++n) _Pragma("unroll") for (int k = 0; k < 2; ++k) \
;         acc[ai][bj][m][n] = __builtin_amdgcn_mfma_f32_16x16x32_bf16(Bt[n][k], At[m][k], acc[ai][bj][m][n], 0, 0, 0); __builtin_amdgcn_s_setprio(0); } while (0)
; #define PG8_WAIT_V(n) asm volatile("s_waitcnt vmcnt(" #n ")" ::: "memory")
; #define PG8_WAIT_L(n) asm volatile("s_waitcnt lgkmcnt(" #n ")" ::: "memory")
; #define PG8_BAR __builtin_amdgcn_s_barrier()
; #define PG8_SCHED __builtin_amdgcn_sched_barrier(0)
; template <class Epi, class Sched, bool ALIGN_EPI = false, bool SP2 = false>
; __device__ __forceinline__ void gemm_phase(PG8_LAS unsigned char* lds, const Gemm g, const Sched& S, const Epi& E) {
;     ...
;             PG8_LDA(At, 0, 1); PG8_STAGE(PG8_SB(0, 0), b2, voffB); PG8_STAGE(PG8_SB(0, 1), b2 + hstep, voffB); PG8_STAGE(PG8_SA(0, 0), a2, voffA);
;             PG8_WAIT_V(8); PG8_WAIT_L(0); PG8_BAR; PG8_MMA(1, 0, At, B0); PG8_MMA(1, 1, At, B1); PG8_BAR; PG8_SCHED;
	s_add_i32 s65, s57, s42
	v_lshl_add_u64 v[150:151], s[30:31], 0, v[132:133]
	s_mov_b32 m0, s65
	ds_read_b128 v[190:193], v156 offset:16384
	ds_read_b128 v[194:197], v156 offset:17408
	ds_read_b128 v[198:201], v156 offset:18432
	ds_read_b128 v[202:205], v156 offset:19456
	ds_read_b128 v[206:209], v156 offset:20480
	ds_read_b128 v[210:213], v156 offset:21504
	ds_read_b128 v[214:217], v156 offset:22528
	ds_read_b128 v[218:221], v156 offset:23552
	global_load_lds_dwordx4 v[150:151], off
	s_add_i32 m0, s65, 0x2000
	s_add_u32 s66, s30, 0x40000
	v_lshl_add_u64 v[170:171], s[30:31], 0, v[136:137]
	s_addc_u32 s67, s31, 0
	s_add_i32 s65, s58, s42
	global_load_lds_dwordx4 v[170:171], off
	v_lshl_add_u64 v[222:223], s[66:67], 0, v[132:133]
	s_mov_b32 m0, s65
	v_lshl_add_u64 v[224:225], s[34:35], 0, v[134:135]
	global_load_lds_dwordx4 v[222:223], off
	v_lshl_add_u64 v[222:223], s[66:67], 0, v[136:137]
	s_add_i32 m0, s65, 0x2000
	s_nop 0
	global_load_lds_dwordx4 v[222:223], off
	v_lshl_add_u64 v[222:223], s[34:35], 0, v[130:131]
	s_mov_b32 m0, s27
	s_nop 0
	global_load_lds_dwordx4 v[222:223], off
	s_mov_b32 m0, s43
	s_nop 0
	global_load_lds_dwordx4 v[224:225], off
	s_waitcnt vmcnt(40)
	s_waitcnt lgkmcnt(0)
	s_barrier
	s_waitcnt lgkmcnt(0)
	v_mfma_f32_16x16x32_bf16 v[62:65], v[146:149], v[190:193], 0
	v_mfma_f32_16x16x32_bf16 v[58:61], v[162:165], v[190:193], 0
	v_mfma_f32_16x16x32_bf16 v[50:53], v[146:149], v[198:201], 0
	v_mfma_f32_16x16x32_bf16 v[42:45], v[162:165], v[198:201], 0
	v_mfma_f32_16x16x32_bf16 v[34:37], v[146:149], v[206:209], 0
	v_mfma_f32_16x16x32_bf16 v[26:29], v[162:165], v[206:209], 0
	v_mfma_f32_16x16x32_bf16 v[18:21], v[146:149], v[214:217], 0
	v_mfma_f32_16x16x32_bf16 v[10:13], v[162:165], v[214:217], 0
	v_mfma_f32_16x16x32_bf16 v[62:65], v[158:161], v[194:197], v[62:65]
	v_mfma_f32_16x16x32_bf16 v[58:61], v[166:169], v[194:197], v[58:61]
	v_mfma_f32_16x16x32_bf16 v[50:53], v[158:161], v[202:205], v[50:53]
	v_mfma_f32_16x16x32_bf16 v[42:45], v[166:169], v[202:205], v[42:45]
	v_mfma_f32_16x16x32_bf16 v[34:37], v[158:161], v[210:213], v[34:37]
	v_mfma_f32_16x16x32_bf16 v[26:29], v[166:169], v[210:213], v[26:29]
	v_mfma_f32_16x16x32_bf16 v[18:21], v[158:161], v[218:221], v[18:21]
	v_mfma_f32_16x16x32_bf16 v[10:13], v[166:169], v[218:221], v[10:13]
	v_mfma_f32_16x16x32_bf16 v[54:57], v[174:177], v[190:193], 0
	v_mfma_f32_16x16x32_bf16 v[46:49], v[182:185], v[190:193], 0
	v_mfma_f32_16x16x32_bf16 v[38:41], v[174:177], v[198:201], 0
	v_mfma_f32_16x16x32_bf16 v[30:33], v[182:185], v[198:201], 0
	v_mfma_f32_16x16x32_bf16 v[22:25], v[174:177], v[206:209], 0
	v_mfma_f32_16x16x32_bf16 v[14:17], v[182:185], v[206:209], 0
	v_mfma_f32_16x16x32_bf16 v[6:9], v[174:177], v[214:217], 0
	v_mfma_f32_16x16x32_bf16 v[2:5], v[182:185], v[214:217], 0
	v_mfma_f32_16x16x32_bf16 v[54:57], v[178:181], v[194:197], v[54:57]
	v_mfma_f32_16x16x32_bf16 v[46:49], v[186:189], v[194:197], v[46:49]
	v_mfma_f32_16x16x32_bf16 v[38:41], v[178:181], v[202:205], v[38:41]
	v_mfma_f32_16x16x32_bf16 v[30:33], v[186:189], v[202:205], v[30:33]
	v_mfma_f32_16x16x32_bf16 v[22:25], v[178:181], v[210:213], v[22:25]
	v_mfma_f32_16x16x32_bf16 v[14:17], v[186:189], v[210:213], v[14:17]
	v_mfma_f32_16x16x32_bf16 v[6:9], v[178:181], v[218:221], v[6:9]
	v_mfma_f32_16x16x32_bf16 v[2:5], v[186:189], v[218:221], v[2:5]
	s_barrier

; #define PG8_STAGE(bufoff, gbase, voff) do { _Pragma("unroll") for (int _i = 0; _i < 2; ++_i) \
;         __builtin_amdgcn_global_load_lds((const unsigned*)((const char*)(gbase) + (voff)[_i]), (PG8_LAS unsigned*)(lds + (bufoff) + ldsw + _i * 8192), 16, 0, 0); } while (0)
; #define PG8_LDA(dst, b, h) do { _Pragma("unroll") for (int m = 0; m < 4; ++m) _Pragma("unroll") for (int k = 0; k < 2; ++k) dst[m][k] = *(const PG8_LAS bf16x8*)(lds + PG8_SA(b, h) + aoff + m * 2048 + k * 1024); } while (0)
; #define PG8_LDB(dst, b, h) do { _Pragma("unroll") for (int n = 0; n < 2; ++n) _Pragma("unroll") for (int k = 0; k < 2; ++k) dst[n][k] = *(const PG8_LAS bf16x8*)(lds + PG8_SB(b, h) + boff + n * 2048 + k * 1024); } while (0)
; #define PG8_SCHED __builtin_amdgcn_sched_barrier(0)
; template <class Epi, class Sched, bool ALIGN_EPI = false, bool SP2 = false>
; __device__ __forceinline__ void gemm_phase(PG8_LAS unsigned char* lds, const Gemm g, const Sched& S, const Epi& E) {
;     ...
;             PG8_LDB(B0, 1, 0); PG8_LDB(B1, 1, 1); PG8_SCHED; PG8_LDA(At, 1, 0); PG8_STAGE(PG8_SA(0, 1), a2 + hstep, voffA);
	s_add_i32 s65, 0, 0x18000
	v_add_u32_e32 v157, s65, v152
	s_add_i32 s66, 0, 0x1c000
	ds_read_b128 v[146:149], v157
	ds_read_b128 v[158:161], v157 offset:1024
	ds_read_b128 v[162:165], v157 offset:2048
	ds_read_b128 v[166:169], v157 offset:3072
	v_add_u32_e32 v157, s66, v152
	ds_read_b128 v[174:177], v157
	ds_read_b128 v[178:181], v157 offset:1024
	ds_read_b128 v[182:185], v157 offset:2048
	ds_read_b128 v[186:189], v157 offset:3072

; #define PG8_STAGE(bufoff, gbase, voff) do { _Pragma("unroll") for (int _i = 0; _i < 2; ++_i) \
;         __builtin_amdgcn_global_load_lds((const unsigned*)((const char*)(gbase) + (voff)[_i]), (PG8_LAS unsigned*)(lds + (bufoff) + ldsw + _i * 8192), 16, 0, 0); } while (0)
; #define PG8_LDA(dst, b, h) do { _Pragma("unroll") for (int m = 0; m < 4; ++m) _Pragma("unroll") for (int k = 0; k < 2; ++k) dst[m][k] = *(const PG8_LAS bf16x8*)(lds + PG8_SA(b, h) + aoff + m * 2048 + k * 1024); } while (0)
; #define PG8_LDB(dst, b, h) do { _Pragma("unroll") for (int n = 0; n < 2; ++n) _Pragma("unroll") for (int k = 0; k < 2; ++k) dst[n][k] = *(const PG8_LAS bf16x8*)(lds + PG8_SB(b, h) + boff + n * 2048 + k * 1024); } while (0)
; #define PG8_MMA(ai, bj, At, Bt) do { __builtin_amdgcn_s_setprio(1); _Pragma("unroll") for (int m = 0; m < 4; ++m) _Pragma("unroll") for (int n = 0; n < 2; ++n) _Pragma("unroll") for (int k = 0; k < 2; ++k) \
;         acc[ai][bj][m][n] = __builtin_amdgcn_mfma_f32_16x16x32_bf16(Bt[n][k], At[m][k], acc[ai][bj][m][n], 0, 0, 0); __builtin_amdgcn_s_setprio(0); } while (0)
; #define PG8_WAIT_V(n) asm volatile("s_waitcnt vmcnt(" #n ")" ::: "memory")
; #define PG8_WAIT_L(n) asm volatile("s_waitcnt lgkmcnt(" #n ")" ::: "memory")
; #define PG8_BAR __builtin_amdgcn_s_barrier()
; #define PG8_SCHED __builtin_amdgcn_sched_barrier(0)
; template <class Epi, class Sched, bool ALIGN_EPI = false, bool SP2 = false>
; __device__ __forceinline__ void gemm_phase(PG8_LAS unsigned char* lds, const Gemm g, const Sched& S, const Epi& E) {
;     ...
;             PG8_LDB(B0, 1, 0); PG8_LDB(B1, 1, 1); PG8_SCHED; PG8_LDA(At, 1, 0); PG8_STAGE(PG8_SA(0, 1), a2 + hstep, voffA);
;             PG8_WAIT_V(8); PG8_WAIT_L(0); PG8_BAR; PG8_MMA(0, 0, At, B0); PG8_MMA(0, 1, At, B1); PG8_BAR; PG8_SCHED;
	s_add_u32 s34, s34, 0x40000
	s_addc_u32 s35, s35, 0
	s_mov_b32 m0, s44
	v_lshl_add_u64 v[226:227], s[34:35], 0, v[130:131]
	ds_read_b128 v[190:193], v156 offset:32768
	ds_read_b128 v[194:197], v156 offset:33792
	ds_read_b128 v[198:201], v156 offset:34816
	ds_read_b128 v[202:205], v156 offset:35840
	ds_read_b128 v[206:209], v156 offset:36864
	ds_read_b128 v[210:213], v156 offset:37888
	ds_read_b128 v[214:217], v156 offset:38912
	ds_read_b128 v[218:221], v156 offset:39936
	global_load_lds_dwordx4 v[226:227], off
	v_lshl_add_u64 v[226:227], s[34:35], 0, v[134:135]
	s_mov_b32 m0, s45
	s_nop 0
	global_load_lds_dwordx4 v[226:227], off
	s_waitcnt vmcnt(8)
	s_waitcnt lgkmcnt(0)
	s_barrier
	s_waitcnt lgkmcnt(0)
	v_mfma_f32_16x16x32_bf16 v[126:129], v[146:149], v[190:193], v[126:129]
	v_mfma_f32_16x16x32_bf16 v[122:125], v[162:165], v[190:193], v[122:125]
	v_mfma_f32_16x16x32_bf16 v[114:117], v[146:149], v[198:201], v[114:117]
	v_mfma_f32_16x16x32_bf16 v[106:109], v[162:165], v[198:201], v[106:109]
	v_mfma_f32_16x16x32_bf16 v[98:101], v[146:149], v[206:209], v[98:101]
	v_mfma_f32_16x16x32_bf16 v[90:93], v[162:165], v[206:209], v[90:93]
	v_mfma_f32_16x16x32_bf16 v[82:85], v[146:149], v[214:217], v[82:85]
	v_mfma_f32_16x16x32_bf16 v[74:77], v[162:165], v[214:217], v[74:77]
	v_mfma_f32_16x16x32_bf16 v[126:129], v[158:161], v[194:197], v[126:129]
	v_mfma_f32_16x16x32_bf16 v[122:125], v[166:169], v[194:197], v[122:125]
	v_mfma_f32_16x16x32_bf16 v[114:117], v[158:161], v[202:205], v[114:117]
	v_mfma_f32_16x16x32_bf16 v[106:109], v[166:169], v[202:205], v[106:109]
	v_mfma_f32_16x16x32_bf16 v[98:101], v[158:161], v[210:213], v[98:101]
	v_mfma_f32_16x16x32_bf16 v[90:93], v[166:169], v[210:213], v[90:93]
	v_mfma_f32_16x16x32_bf16 v[82:85], v[158:161], v[218:221], v[82:85]
	v_mfma_f32_16x16x32_bf16 v[74:77], v[166:169], v[218:221], v[74:77]
	v_mfma_f32_16x16x32_bf16 v[118:121], v[174:177], v[190:193], v[118:121]
	v_mfma_f32_16x16x32_bf16 v[110:113], v[182:185], v[190:193], v[110:113]
	v_mfma_f32_16x16x32_bf16 v[102:105], v[174:177], v[198:201], v[102:105]
	v_mfma_f32_16x16x32_bf16 v[94:97], v[182:185], v[198:201], v[94:97]
	v_mfma_f32_16x16x32_bf16 v[86:89], v[174:177], v[206:209], v[86:89]
	v_mfma_f32_16x16x32_bf16 v[78:81], v[182:185], v[206:209], v[78:81]
	v_mfma_f32_16x16x32_bf16 v[70:73], v[174:177], v[214:217], v[70:73]
	v_mfma_f32_16x16x32_bf16 v[66:69], v[182:185], v[214:217], v[66:69]
	v_mfma_f32_16x16x32_bf16 v[118:121], v[178:181], v[194:197], v[118:121]
	v_mfma_f32_16x16x32_bf16 v[110:113], v[186:189], v[194:197], v[110:113]
	v_mfma_f32_16x16x32_bf16 v[102:105], v[178:181], v[202:205], v[102:105]
	v_mfma_f32_16x16x32_bf16 v[94:97], v[186:189], v[202:205], v[94:97]
	v_mfma_f32_16x16x32_bf16 v[86:89], v[178:181], v[210:213], v[86:89]
	v_mfma_f32_16x16x32_bf16 v[78:81], v[186:189], v[210:213], v[78:81]
	v_mfma_f32_16x16x32_bf16 v[70:73], v[178:181], v[218:221], v[70:73]
	v_mfma_f32_16x16x32_bf16 v[66:69], v[186:189], v[218:221], v[66:69]
	s_barrier

; #define PG8_STAGE(bufoff, gbase, voff) do { _Pragma("unroll") for (int _i = 0; _i < 2; ++_i) \
;         __builtin_amdgcn_global_load_lds((const unsigned*)((const char*)(gbase) + (voff)[_i]), (PG8_LAS unsigned*)(lds + (bufoff) + ldsw + _i * 8192), 16, 0, 0); } while (0)
; #define PG8_LDA(dst, b, h) do { _Pragma("unroll") for (int m = 0; m < 4; ++m) _Pragma("unroll") for (int k = 0; k < 2; ++k) dst[m][k] = *(const PG8_LAS bf16x8*)(lds + PG8_SA(b, h) + aoff + m * 2048 + k * 1024); } while (0)
; #define PG8_MMA(ai, bj, At, Bt) do { __builtin_amdgcn_s_setprio(1); _Pragma("unroll") for (int m = 0; m < 4; ++m) _Pragma("unroll") for (int n = 0; n < 2; ++n) _Pragma("unroll") for (int k = 0; k < 2; ++k) \
;         acc[ai][bj][m][n] = __builtin_amdgcn_mfma_f32_16x16x32_bf16(Bt[n][k], At[m][k], acc[ai][bj][m][n], 0, 0, 0); __builtin_amdgcn_s_setprio(0); } while (0)
; #define PG8_WAIT_V(n) asm volatile("s_waitcnt vmcnt(" #n ")" ::: "memory")
; #define PG8_WAIT_L(n) asm volatile("s_waitcnt lgkmcnt(" #n ")" ::: "memory")
; #define PG8_BAR __builtin_amdgcn_s_barrier()
; #define PG8_SCHED __builtin_amdgcn_sched_barrier(0)
; template <class Epi, class Sched, bool ALIGN_EPI = false, bool SP2 = false>
; __device__ __forceinline__ void gemm_phase(PG8_LAS unsigned char* lds, const Gemm g, const Sched& S, const Epi& E) {
;     ...
;             PG8_LDA(At, 1, 1); PG8_STAGE(PG8_SB(1, 0), b3, voffB); PG8_STAGE(PG8_SB(1, 1), b3 + hstep, voffB); PG8_STAGE(PG8_SA(1, 0), a3, voffA);
;             PG8_WAIT_V(8); PG8_WAIT_L(0); PG8_BAR; PG8_MMA(1, 0, At, B0); PG8_MMA(1, 1, At, B1); PG8_BAR; PG8_SCHED;
	s_add_i32 s34, s65, s42
	v_lshl_add_u64 v[150:151], v[150:151], 0, s[8:9]
	s_mov_b32 m0, s34
	ds_read_b128 v[190:193], v156 offset:49152
	ds_read_b128 v[194:197], v156 offset:50176
	ds_read_b128 v[198:201], v156 offset:51200
	ds_read_b128 v[202:205], v156 offset:52224
	ds_read_b128 v[206:209], v156 offset:53248
	ds_read_b128 v[210:213], v156 offset:54272
	ds_read_b128 v[214:217], v156 offset:55296
	ds_read_b128 v[218:221], v156 offset:56320
	global_load_lds_dwordx4 v[150:151], off
	s_add_i32 m0, s34, 0x2000
	s_add_u32 s30, s30, 0x40080
	v_lshl_add_u64 v[150:151], v[170:171], 0, s[8:9]
	s_addc_u32 s31, s31, 0
	s_add_i32 s34, s66, s42
	global_load_lds_dwordx4 v[150:151], off
	v_lshl_add_u64 v[150:151], s[30:31], 0, v[132:133]
	s_mov_b32 m0, s34
	s_nop 0
	global_load_lds_dwordx4 v[150:151], off
	v_lshl_add_u64 v[150:151], s[30:31], 0, v[136:137]
	s_add_i32 m0, s34, 0x2000
	s_nop 0
	global_load_lds_dwordx4 v[150:151], off
	v_lshl_add_u64 v[150:151], v[222:223], 0, s[8:9]
	s_mov_b32 m0, s53
	s_nop 0
	global_load_lds_dwordx4 v[150:151], off
	v_lshl_add_u64 v[150:151], v[224:225], 0, s[8:9]
	s_mov_b32 m0, s54
	s_nop 0
	global_load_lds_dwordx4 v[150:151], off
	s_waitcnt vmcnt(8)
	s_waitcnt lgkmcnt(0)
	s_barrier
	s_waitcnt lgkmcnt(0)
	v_mfma_f32_16x16x32_bf16 v[62:65], v[146:149], v[190:193], v[62:65]
	v_mfma_f32_16x16x32_bf16 v[58:61], v[162:165], v[190:193], v[58:61]
	v_mfma_f32_16x16x32_bf16 v[50:53], v[146:149], v[198:201], v[50:53]
	v_mfma_f32_16x16x32_bf16 v[42:45], v[162:165], v[198:201], v[42:45]
	v_mfma_f32_16x16x32_bf16 v[34:37], v[146:149], v[206:209], v[34:37]
	v_mfma_f32_16x16x32_bf16 v[26:29], v[162:165], v[206:209], v[26:29]
	v_mfma_f32_16x16x32_bf16 v[18:21], v[146:149], v[214:217], v[18:21]
	v_mfma_f32_16x16x32_bf16 v[10:13], v[162:165], v[214:217], v[10:13]
	v_mfma_f32_16x16x32_bf16 v[62:65], v[158:161], v[194:197], v[62:65]
	v_mfma_f32_16x16x32_bf16 v[58:61], v[166:169], v[194:197], v[58:61]
	v_mfma_f32_16x16x32_bf16 v[50:53], v[158:161], v[202:205], v[50:53]
	v_mfma_f32_16x16x32_bf16 v[42:45], v[166:169], v[202:205], v[42:45]
	v_mfma_f32_16x16x32_bf16 v[34:37], v[158:161], v[210:213], v[34:37]
	v_mfma_f32_16x16x32_bf16 v[26:29], v[166:169], v[210:213], v[26:29]
	v_mfma_f32_16x16x32_bf16 v[18:21], v[158:161], v[218:221], v[18:21]
	v_mfma_f32_16x16x32_bf16 v[10:13], v[166:169], v[218:221], v[10:13]
	v_mfma_f32_16x16x32_bf16 v[54:57], v[174:177], v[190:193], v[54:57]
	v_mfma_f32_16x16x32_bf16 v[46:49], v[182:185], v[190:193], v[46:49]
	v_mfma_f32_16x16x32_bf16 v[38:41], v[174:177], v[198:201], v[38:41]
	v_mfma_f32_16x16x32_bf16 v[30:33], v[182:185], v[198:201], v[30:33]
	v_mfma_f32_16x16x32_bf16 v[22:25], v[174:177], v[206:209], v[22:25]
	v_mfma_f32_16x16x32_bf16 v[14:17], v[182:185], v[206:209], v[14:17]
	v_mfma_f32_16x16x32_bf16 v[6:9], v[174:177], v[214:217], v[6:9]
	v_mfma_f32_16x16x32_bf16 v[2:5], v[182:185], v[214:217], v[2:5]
	v_mfma_f32_16x16x32_bf16 v[54:57], v[178:181], v[194:197], v[54:57]
	v_mfma_f32_16x16x32_bf16 v[46:49], v[186:189], v[194:197], v[46:49]
	v_mfma_f32_16x16x32_bf16 v[38:41], v[178:181], v[202:205], v[38:41]
	v_mfma_f32_16x16x32_bf16 v[30:33], v[186:189], v[202:205], v[30:33]
	v_mfma_f32_16x16x32_bf16 v[22:25], v[178:181], v[210:213], v[22:25]
	v_mfma_f32_16x16x32_bf16 v[14:17], v[186:189], v[210:213], v[14:17]
	v_mfma_f32_16x16x32_bf16 v[6:9], v[178:181], v[218:221], v[6:9]
	v_mfma_f32_16x16x32_bf16 v[2:5], v[186:189], v[218:221], v[2:5]
	s_barrier

; #define PG8_STAGE(bufoff, gbase, voff) do { _Pragma("unroll") for (int _i = 0; _i < 2; ++_i) \
;         __builtin_amdgcn_global_load_lds((const unsigned*)((const char*)(gbase) + (voff)[_i]), (PG8_LAS unsigned*)(lds + (bufoff) + ldsw + _i * 8192), 16, 0, 0); } while (0)
; #define PG8_LDA(dst, b, h) do { _Pragma("unroll") for (int m = 0; m < 4; ++m) _Pragma("unroll") for (int k = 0; k < 2; ++k) dst[m][k] = *(const PG8_LAS bf16x8*)(lds + PG8_SA(b, h) + aoff + m * 2048 + k * 1024); } while (0)
; #define PG8_LDB(dst, b, h) do { _Pragma("unroll") for (int n = 0; n < 2; ++n) _Pragma("unroll") for (int k = 0; k < 2; ++k) dst[n][k] = *(const PG8_LAS bf16x8*)(lds + PG8_SB(b, h) + boff + n * 2048 + k * 1024); } while (0)
; #define PG8_MMA(ai, bj, At, Bt) do { __builtin_amdgcn_s_setprio(1); _Pragma("unroll") for (int m = 0; m < 4; ++m) _Pragma("unroll") for (int n = 0; n < 2; ++n) _Pragma("unroll") for (int k = 0; k < 2; ++k) \
;         acc[ai][bj][m][n] = __builtin_amdgcn_mfma_f32_16x16x32_bf16(Bt[n][k], At[m][k], acc[ai][bj][m][n], 0, 0, 0); __builtin_amdgcn_s_setprio(0); } while (0)
; #define PG8_WAIT_V(n) asm volatile("s_waitcnt vmcnt(" #n ")" ::: "memory")
; #define PG8_WAIT_L(n) asm volatile("s_waitcnt lgkmcnt(" #n ")" ::: "memory")
; #define PG8_BAR __builtin_amdgcn_s_barrier()
; #define PG8_SCHED __builtin_amdgcn_sched_barrier(0)
; template <class Epi, class Sched, bool ALIGN_EPI = false, bool SP2 = false>
; __device__ __forceinline__ void gemm_phase(PG8_LAS unsigned char* lds, const Gemm g, const Sched& S, const Epi& E) {
;     ...
;         for (int t = 0; t < nt; t += 2) {
;             const bool last = (t == nt - 2);
;             const char* a1 = cA + (size_t)(t + 1) * kstep;
;             const char* a2 = last ? nA : cA + (size_t)(t + 2) * kstep; const char* b2 = last ? nB : cB + (size_t)(t + 2) * kstep;
;             const char* a3 = a2 + kstep; const char* b3 = b2 + kstep;
;             if (last && has_next) S.a_ready(nxt);
;             if constexpr (SP2) {
;             PG8_LDB(B0, 0, 0); PG8_LDB(B1, 0, 1); PG8_SCHED; PG8_LDA(At, 0, 0); PG8_STAGE(PG8_SA(1, 1), a1 + hstep, voffA);
;             PG8_WAIT_V(8); PG8_WAIT_L(0); PG8_BAR; PG8_MMA(0, 0, At, B0); PG8_MMA(0, 1, At, B1); PG8_BAR; PG8_SCHED;
;             PG8_LDA(At, 0, 1); PG8_STAGE(PG8_SB(0, 0), b2, voffB); PG8_STAGE(PG8_SB(0, 1), b2 + hstep, voffB); PG8_STAGE(PG8_SA(0, 0), a2, voffA);
	s_add_i32 s64, s64, 2
	s_add_u32 s28, s28, 0x100
	s_addc_u32 s29, s29, 0
	s_add_u32 s62, s62, 0x100
	s_addc_u32 s63, s63, 0
.LBB0_1314:
	ds_read_b128 v[146:149], v154
	ds_read_b128 v[158:161], v154 offset:1024
	ds_read_b128 v[162:165], v154 offset:2048
	ds_read_b128 v[166:169], v154 offset:3072
	ds_read_b128 v[174:177], v155
	ds_read_b128 v[178:181], v155 offset:1024
	ds_read_b128 v[182:185], v155 offset:2048
	ds_read_b128 v[186:189], v155 offset:3072
	s_add_u32 s30, s28, 0xfffc0080
	s_addc_u32 s31, s29, -1
	s_cmp_eq_u32 s64, 12
	s_cselect_b32 s35, s21, s31
	s_cselect_b32 s34, s60, s30
	s_cselect_b32 s31, s19, s63
	s_cselect_b32 s30, s61, s62
	v_lshl_add_u64 v[150:151], s[28:29], 0, v[138:139]
	s_add_i32 m0, s27, 0xc000
	ds_read_b128 v[190:193], v156
	ds_read_b128 v[194:197], v156 offset:1024
	ds_read_b128 v[198:201], v156 offset:2048
	ds_read_b128 v[202:205], v156 offset:3072
	ds_read_b128 v[206:209], v156 offset:4096
	ds_read_b128 v[210:213], v156 offset:5120
	ds_read_b128 v[214:217], v156 offset:6144
	ds_read_b128 v[218:221], v156 offset:7168
	global_load_lds_dwordx4 v[150:151], off
	v_lshl_add_u64 v[150:151], s[28:29], 0, v[140:141]
	s_add_i32 m0, s27, 0xe000
	s_nop 0
	global_load_lds_dwordx4 v[150:151], off
	s_waitcnt vmcnt(8)
	s_waitcnt lgkmcnt(0)
	s_barrier
	s_waitcnt lgkmcnt(0)
	v_mfma_f32_16x16x32_bf16 v[126:129], v[146:149], v[190:193], v[126:129]
	v_mfma_f32_16x16x32_bf16 v[122:125], v[162:165], v[190:193], v[122:125]
	v_mfma_f32_16x16x32_bf16 v[114:117], v[146:149], v[198:201], v[114:117]
	v_mfma_f32_16x16x32_bf16 v[106:109], v[162:165], v[198:201], v[106:109]
	v_mfma_f32_16x16x32_bf16 v[98:101], v[146:149], v[206:209], v[98:101]
	v_mfma_f32_16x16x32_bf16 v[90:93], v[162:165], v[206:209], v[90:93]
	v_mfma_f32_16x16x32_bf16 v[82:85], v[146:149], v[214:217], v[82:85]
	v_mfma_f32_16x16x32_bf16 v[74:77], v[162:165], v[214:217], v[74:77]
	v_mfma_f32_16x16x32_bf16 v[126:129], v[158:161], v[194:197], v[126:129]
	v_mfma_f32_16x16x32_bf16 v[122:125], v[166:169], v[194:197], v[122:125]
	v_mfma_f32_16x16x32_bf16 v[114:117], v[158:161], v[202:205], v[114:117]
	v_mfma_f32_16x16x32_bf16 v[106:109], v[166:169], v[202:205], v[106:109]
	v_mfma_f32_16x16x32_bf16 v[98:101], v[158:161], v[210:213], v[98:101]
	v_mfma_f32_16x16x32_bf16 v[90:93], v[166:169], v[210:213], v[90:93]
	v_mfma_f32_16x16x32_bf16 v[82:85], v[158:161], v[218:221], v[82:85]
	v_mfma_f32_16x16x32_bf16 v[74:77], v[166:169], v[218:221], v[74:77]
	v_mfma_f32_16x16x32_bf16 v[118:121], v[174:177], v[190:193], v[118:121]
	v_mfma_f32_16x16x32_bf16 v[110:113], v[182:185], v[190:193], v[110:113]
	v_mfma_f32_16x16x32_bf16 v[102:105], v[174:177], v[198:201], v[102:105]
	v_mfma_f32_16x16x32_bf16 v[94:97], v[182:185], v[198:201], v[94:97]
	v_mfma_f32_16x16x32_bf16 v[86:89], v[174:177], v[206:209], v[86:89]
	v_mfma_f32_16x16x32_bf16 v[78:81], v[182:185], v[206:209], v[78:81]
	v_mfma_f32_16x16x32_bf16 v[70:73], v[174:177], v[214:217], v[70:73]
	v_mfma_f32_16x16x32_bf16 v[66:69], v[182:185], v[214:217], v[66:69]
	v_mfma_f32_16x16x32_bf16 v[118:121], v[178:181], v[194:197], v[118:121]
	v_mfma_f32_16x16x32_bf16 v[110:113], v[186:189], v[194:197], v[110:113]
	v_mfma_f32_16x16x32_bf16 v[102:105], v[178:181], v[202:205], v[102:105]
	v_mfma_f32_16x16x32_bf16 v[94:97], v[186:189], v[202:205], v[94:97]
	v_mfma_f32_16x16x32_bf16 v[86:89], v[178:181], v[210:213], v[86:89]
	v_mfma_f32_16x16x32_bf16 v[78:81], v[186:189], v[210:213], v[78:81]
	v_mfma_f32_16x16x32_bf16 v[70:73], v[178:181], v[218:221], v[70:73]
	v_mfma_f32_16x16x32_bf16 v[66:69], v[186:189], v[218:221], v[66:69]
	s_barrier
	s_add_i32 s65, s57, s42
	v_lshl_add_u64 v[150:151], s[30:31], 0, v[132:133]
	s_mov_b32 m0, s65
	ds_read_b128 v[190:193], v156 offset:16384
	ds_read_b128 v[194:197], v156 offset:17408
	ds_read_b128 v[198:201], v156 offset:18432
	ds_read_b128 v[202:205], v156 offset:19456
	ds_read_b128 v[206:209], v156 offset:20480
	ds_read_b128 v[210:213], v156 offset:21504
	ds_read_b128 v[214:217], v156 offset:22528
	ds_read_b128 v[218:221], v156 offset:23552
	global_load_lds_dwordx4 v[150:151], off
	s_add_i32 m0, s65, 0x2000
	s_add_u32 s66, s30, 0x40000
	v_lshl_add_u64 v[170:171], s[30:31], 0, v[136:137]
	s_addc_u32 s67, s31, 0
	s_add_i32 s65, s58, s42
	global_load_lds_dwordx4 v[170:171], off
	v_lshl_add_u64 v[222:223], s[66:67], 0, v[132:133]
	s_mov_b32 m0, s65
	v_lshl_add_u64 v[224:225], s[34:35], 0, v[134:135]
	global_load_lds_dwordx4 v[222:223], off
	v_lshl_add_u64 v[222:223], s[66:67], 0, v[136:137]
	s_add_i32 m0, s65, 0x2000
	s_nop 0
	global_load_lds_dwordx4 v[222:223], off
	v_lshl_add_u64 v[222:223], s[34:35], 0, v[130:131]
	s_mov_b32 m0, s27
	s_nop 0
	global_load_lds_dwordx4 v[222:223], off
	s_mov_b32 m0, s43
	s_nop 0
	global_load_lds_dwordx4 v[224:225], off
	s_waitcnt vmcnt(8)
	s_waitcnt lgkmcnt(0)
	s_barrier
; #define PG8_STAGE(bufoff, gbase, voff) do { _Pragma("unroll") for (int _i = 0; _i < 2; ++_i) \
;         __builtin_amdgcn_global_load_lds((const unsigned*)((const char*)(gbase) + (voff)[_i]), (PG8_LAS unsigned*)(lds + (bufoff) + ldsw + _i * 8192), 16, 0, 0); } while (0)
; #define PG8_LDA(dst, b, h) do { _Pragma("unroll") for (int m = 0; m < 4; ++m) _Pragma("unroll") for (int k = 0; k < 2; ++k) dst[m][k] = *(const PG8_LAS bf16x8*)(lds + PG8_SA(b, h) + aoff + m * 2048 + k * 1024); } while (0)
; #define PG8_LDB(dst, b, h) do { _Pragma("unroll") for (int n = 0; n < 2; ++n) _Pragma("unroll") for (int k = 0; k < 2; ++k) dst[n][k] = *(const PG8_LAS bf16x8*)(lds + PG8_SB(b, h) + boff + n * 2048 + k * 1024); } while (0)
; #define PG8_MMA(ai, bj, At, Bt) do { __builtin_amdgcn_s_setprio(1); _Pragma("unroll") for (int m = 0; m < 4; ++m) _Pragma("unroll") for (int n = 0; n < 2; ++n) _Pragma("unroll") for (int k = 0; k < 2; ++k) \
;         acc[ai][bj][m][n] = __builtin_amdgcn_mfma_f32_16x16x32_bf16(Bt[n][k], At[m][k], acc[ai][bj][m][n], 0, 0, 0); __builtin_amdgcn_s_setprio(0); } while (0)
; #define PG8_WAIT_V(n) asm volatile("s_waitcnt vmcnt(" #n ")" ::: "memory")
; #define PG8_WAIT_L(n) asm volatile("s_waitcnt lgkmcnt(" #n ")" ::: "memory")
; #define PG8_BAR __builtin_amdgcn_s_barrier()
; #define PG8_SCHED __builtin_amdgcn_sched_barrier(0)
; template <class Epi, class Sched, bool ALIGN_EPI = false, bool SP2 = false>
; __device__ __forceinline__ void gemm_phase(PG8_LAS unsigned char* lds, const Gemm g, const Sched& S, const Epi& E) {
;     ...
;             PG8_WAIT_V(8); PG8_WAIT_L(0); PG8_BAR; PG8_MMA(1, 0, At, B0); PG8_MMA(1, 1, At, B1); PG8_BAR; PG8_SCHED;
;             PG8_LDB(B0, 1, 0); PG8_LDB(B1, 1, 1); PG8_SCHED; PG8_LDA(At, 1, 0); PG8_STAGE(PG8_SA(0, 1), a2 + hstep, voffA);
;             PG8_WAIT_V(8); PG8_WAIT_L(0); PG8_BAR; PG8_MMA(0, 0, At, B0); PG8_MMA(0, 1, At, B1); PG8_BAR; PG8_SCHED;
	s_waitcnt lgkmcnt(0)
	v_mfma_f32_16x16x32_bf16 v[62:65], v[146:149], v[190:193], v[62:65]
	v_mfma_f32_16x16x32_bf16 v[58:61], v[162:165], v[190:193], v[58:61]
	v_mfma_f32_16x16x32_bf16 v[50:53], v[146:149], v[198:201], v[50:53]
	v_mfma_f32_16x16x32_bf16 v[42:45], v[162:165], v[198:201], v[42:45]
	v_mfma_f32_16x16x32_bf16 v[34:37], v[146:149], v[206:209], v[34:37]
	v_mfma_f32_16x16x32_bf16 v[26:29], v[162:165], v[206:209], v[26:29]
	v_mfma_f32_16x16x32_bf16 v[18:21], v[146:149], v[214:217], v[18:21]
	v_mfma_f32_16x16x32_bf16 v[10:13], v[162:165], v[214:217], v[10:13]
	v_mfma_f32_16x16x32_bf16 v[62:65], v[158:161], v[194:197], v[62:65]
	v_mfma_f32_16x16x32_bf16 v[58:61], v[166:169], v[194:197], v[58:61]
	v_mfma_f32_16x16x32_bf16 v[50:53], v[158:161], v[202:205], v[50:53]
	v_mfma_f32_16x16x32_bf16 v[42:45], v[166:169], v[202:205], v[42:45]
	v_mfma_f32_16x16x32_bf16 v[34:37], v[158:161], v[210:213], v[34:37]
	v_mfma_f32_16x16x32_bf16 v[26:29], v[166:169], v[210:213], v[26:29]
	v_mfma_f32_16x16x32_bf16 v[18:21], v[158:161], v[218:221], v[18:21]
	v_mfma_f32_16x16x32_bf16 v[10:13], v[166:169], v[218:221], v[10:13]
	v_mfma_f32_16x16x32_bf16 v[54:57], v[174:177], v[190:193], v[54:57]
	v_mfma_f32_16x16x32_bf16 v[46:49], v[182:185], v[190:193], v[46:49]
	v_mfma_f32_16x16x32_bf16 v[38:41], v[174:177], v[198:201], v[38:41]
	v_mfma_f32_16x16x32_bf16 v[30:33], v[182:185], v[198:201], v[30:33]
	v_mfma_f32_16x16x32_bf16 v[22:25], v[174:177], v[206:209], v[22:25]
	v_mfma_f32_16x16x32_bf16 v[14:17], v[182:185], v[206:209], v[14:17]
	v_mfma_f32_16x16x32_bf16 v[6:9], v[174:177], v[214:217], v[6:9]
	v_mfma_f32_16x16x32_bf16 v[2:5], v[182:185], v[214:217], v[2:5]
	v_mfma_f32_16x16x32_bf16 v[54:57], v[178:181], v[194:197], v[54:57]
	v_mfma_f32_16x16x32_bf16 v[46:49], v[186:189], v[194:197], v[46:49]
	v_mfma_f32_16x16x32_bf16 v[38:41], v[178:181], v[202:205], v[38:41]
	v_mfma_f32_16x16x32_bf16 v[30:33], v[186:189], v[202:205], v[30:33]
	v_mfma_f32_16x16x32_bf16 v[22:25], v[178:181], v[210:213], v[22:25]
	v_mfma_f32_16x16x32_bf16 v[14:17], v[186:189], v[210:213], v[14:17]
	v_mfma_f32_16x16x32_bf16 v[6:9], v[178:181], v[218:221], v[6:9]
	v_mfma_f32_16x16x32_bf16 v[2:5], v[186:189], v[218:221], v[2:5]
	s_barrier
	s_add_i32 s65, 0, 0x18000
	v_add_u32_e32 v157, s65, v152
	s_add_i32 s66, 0, 0x1c000
	ds_read_b128 v[146:149], v157
	ds_read_b128 v[158:161], v157 offset:1024
	ds_read_b128 v[162:165], v157 offset:2048
	ds_read_b128 v[166:169], v157 offset:3072
	v_add_u32_e32 v157, s66, v152
	ds_read_b128 v[174:177], v157
	ds_read_b128 v[178:181], v157 offset:1024
	ds_read_b128 v[182:185], v157 offset:2048
	ds_read_b128 v[186:189], v157 offset:3072
	s_add_u32 s34, s34, 0x40000
	s_addc_u32 s35, s35, 0
	s_mov_b32 m0, s44
	v_lshl_add_u64 v[226:227], s[34:35], 0, v[130:131]
	ds_read_b128 v[190:193], v156 offset:32768
	ds_read_b128 v[194:197], v156 offset:33792
	ds_read_b128 v[198:201], v156 offset:34816
	ds_read_b128 v[202:205], v156 offset:35840
	ds_read_b128 v[206:209], v156 offset:36864
	ds_read_b128 v[210:213], v156 offset:37888
	ds_read_b128 v[214:217], v156 offset:38912
	ds_read_b128 v[218:221], v156 offset:39936
	global_load_lds_dwordx4 v[226:227], off
	v_lshl_add_u64 v[226:227], s[34:35], 0, v[134:135]
	s_mov_b32 m0, s45
	s_nop 0
	global_load_lds_dwordx4 v[226:227], off
	s_waitcnt vmcnt(8)
	s_waitcnt lgkmcnt(0)
	s_barrier
	s_waitcnt lgkmcnt(0)
	v_mfma_f32_16x16x32_bf16 v[126:129], v[146:149], v[190:193], v[126:129]
	v_mfma_f32_16x16x32_bf16 v[122:125], v[162:165], v[190:193], v[122:125]
	v_mfma_f32_16x16x32_bf16 v[114:117], v[146:149], v[198:201], v[114:117]
	v_mfma_f32_16x16x32_bf16 v[106:109], v[162:165], v[198:201], v[106:109]
	v_mfma_f32_16x16x32_bf16 v[98:101], v[146:149], v[206:209], v[98:101]
	v_mfma_f32_16x16x32_bf16 v[90:93], v[162:165], v[206:209], v[90:93]
	v_mfma_f32_16x16x32_bf16 v[82:85], v[146:149], v[214:217], v[82:85]
	v_mfma_f32_16x16x32_bf16 v[74:77], v[162:165], v[214:217], v[74:77]
	v_mfma_f32_16x16x32_bf16 v[126:129], v[158:161], v[194:197], v[126:129]
	v_mfma_f32_16x16x32_bf16 v[122:125], v[166:169], v[194:197], v[122:125]
	v_mfma_f32_16x16x32_bf16 v[114:117], v[158:161], v[202:205], v[114:117]
	v_mfma_f32_16x16x32_bf16 v[106:109], v[166:169], v[202:205], v[106:109]
	v_mfma_f32_16x16x32_bf16 v[98:101], v[158:161], v[210:213], v[98:101]
	v_mfma_f32_16x16x32_bf16 v[90:93], v[166:169], v[210:213], v[90:93]
	v_mfma_f32_16x16x32_bf16 v[82:85], v[158:161], v[218:221], v[82:85]
	v_mfma_f32_16x16x32_bf16 v[74:77], v[166:169], v[218:221], v[74:77]
	v_mfma_f32_16x16x32_bf16 v[118:121], v[174:177], v[190:193], v[118:121]
	v_mfma_f32_16x16x32_bf16 v[110:113], v[182:185], v[190:193], v[110:113]
	v_mfma_f32_16x16x32_bf16 v[102:105], v[174:177], v[198:201], v[102:105]
	v_mfma_f32_16x16x32_bf16 v[94:97], v[182:185], v[198:201], v[94:97]
	v_mfma_f32_16x16x32_bf16 v[86:89], v[174:177], v[206:209], v[86:89]
	v_mfma_f32_16x16x32_bf16 v[78:81], v[182:185], v[206:209], v[78:81]
	v_mfma_f32_16x16x32_bf16 v[70:73], v[174:177], v[214:217], v[70:73]
	v_mfma_f32_16x16x32_bf16 v[66:69], v[182:185], v[214:217], v[66:69]
	v_mfma_f32_16x16x32_bf16 v[118:121], v[178:181], v[194:197], v[118:121]
	v_mfma_f32_16x16x32_bf16 v[110:113], v[186:189], v[194:197], v[110:113]
	v_mfma_f32_16x16x32_bf16 v[102:105], v[178:181], v[202:205], v[102:105]
	v_mfma_f32_16x16x32_bf16 v[94:97], v[186:189], v[202:205], v[94:97]
	v_mfma_f32_16x16x32_bf16 v[86:89], v[178:181], v[210:213], v[86:89]
	v_mfma_f32_16x16x32_bf16 v[78:81], v[186:189], v[210:213], v[78:81]
	v_mfma_f32_16x16x32_bf16 v[70:73], v[178:181], v[218:221], v[70:73]
	v_mfma_f32_16x16x32_bf16 v[66:69], v[186:189], v[218:221], v[66:69]
	s_barrier
; #define PG8_STAGE(bufoff, gbase, voff) do { _Pragma("unroll") for (int _i = 0; _i < 2; ++_i) \
;         __builtin_amdgcn_global_load_lds((const unsigned*)((const char*)(gbase) + (voff)[_i]), (PG8_LAS unsigned*)(lds + (bufoff) + ldsw + _i * 8192), 16, 0, 0); } while (0)
; #define PG8_LDA(dst, b, h) do { _Pragma("unroll") for (int m = 0; m < 4; ++m) _Pragma("unroll") for (int k = 0; k < 2; ++k) dst[m][k] = *(const PG8_LAS bf16x8*)(lds + PG8_SA(b, h) + aoff + m * 2048 + k * 1024); } while (0)
; #define PG8_MMA(ai, bj, At, Bt) do { __builtin_amdgcn_s_setprio(1); _Pragma("unroll") for (int m = 0; m < 4; ++m) _Pragma("unroll") for (int n = 0; n < 2; ++n) _Pragma("unroll") for (int k = 0; k < 2; ++k) \
;         acc[ai][bj][m][n] = __builtin_amdgcn_mfma_f32_16x16x32_bf16(Bt[n][k], At[m][k], acc[ai][bj][m][n], 0, 0, 0); __builtin_amdgcn_s_setprio(0); } while (0)
; #define PG8_WAIT_V(n) asm volatile("s_waitcnt vmcnt(" #n ")" ::: "memory")
; #define PG8_WAIT_L(n) asm volatile("s_waitcnt lgkmcnt(" #n ")" ::: "memory")
; #define PG8_BAR __builtin_amdgcn_s_barrier()
; #define PG8_SCHED __builtin_amdgcn_sched_barrier(0)
; template <class Epi, class Sched, bool ALIGN_EPI = false, bool SP2 = false>
; __device__ __forceinline__ void gemm_phase(PG8_LAS unsigned char* lds, const Gemm g, const Sched& S, const Epi& E) {
;     ...
;             PG8_LDA(At, 1, 1); PG8_STAGE(PG8_SB(1, 0), b3, voffB); PG8_STAGE(PG8_SB(1, 1), b3 + hstep, voffB); PG8_STAGE(PG8_SA(1, 0), a3, voffA);
;             PG8_WAIT_V(8); PG8_WAIT_L(0); PG8_BAR; PG8_MMA(1, 0, At, B0); PG8_MMA(1, 1, At, B1); PG8_BAR; PG8_SCHED;
;     ...
;         }
;         if constexpr (ALIGN_EPI) { if (wr == 0) PG8_BAR; }
	s_add_i32 s34, s65, s42
	v_lshl_add_u64 v[150:151], v[150:151], 0, s[8:9]
	s_mov_b32 m0, s34
	ds_read_b128 v[190:193], v156 offset:49152
	ds_read_b128 v[194:197], v156 offset:50176
	ds_read_b128 v[198:201], v156 offset:51200
	ds_read_b128 v[202:205], v156 offset:52224
	ds_read_b128 v[206:209], v156 offset:53248
	ds_read_b128 v[210:213], v156 offset:54272
	ds_read_b128 v[214:217], v156 offset:55296
	ds_read_b128 v[218:221], v156 offset:56320
	global_load_lds_dwordx4 v[150:151], off
	s_add_i32 m0, s34, 0x2000
	s_add_u32 s30, s30, 0x40080
	v_lshl_add_u64 v[150:151], v[170:171], 0, s[8:9]
	s_addc_u32 s31, s31, 0
	s_add_i32 s34, s66, s42
	global_load_lds_dwordx4 v[150:151], off
	v_lshl_add_u64 v[150:151], s[30:31], 0, v[132:133]
	s_mov_b32 m0, s34
	s_nop 0
	global_load_lds_dwordx4 v[150:151], off
	v_lshl_add_u64 v[150:151], s[30:31], 0, v[136:137]
	s_add_i32 m0, s34, 0x2000
	s_nop 0
	global_load_lds_dwordx4 v[150:151], off
	v_lshl_add_u64 v[150:151], v[222:223], 0, s[8:9]
	s_mov_b32 m0, s53
	s_nop 0
	global_load_lds_dwordx4 v[150:151], off
	v_lshl_add_u64 v[150:151], v[224:225], 0, s[8:9]
	s_mov_b32 m0, s54
	s_nop 0
	global_load_lds_dwordx4 v[150:151], off
	s_waitcnt vmcnt(8)
	s_waitcnt lgkmcnt(0)
	s_barrier
	s_waitcnt lgkmcnt(0)
	v_mfma_f32_16x16x32_bf16 v[62:65], v[146:149], v[190:193], v[62:65]
	v_mfma_f32_16x16x32_bf16 v[58:61], v[162:165], v[190:193], v[58:61]
	v_mfma_f32_16x16x32_bf16 v[50:53], v[146:149], v[198:201], v[50:53]
	v_mfma_f32_16x16x32_bf16 v[42:45], v[162:165], v[198:201], v[42:45]
	v_mfma_f32_16x16x32_bf16 v[34:37], v[146:149], v[206:209], v[34:37]
	v_mfma_f32_16x16x32_bf16 v[26:29], v[162:165], v[206:209], v[26:29]
	v_mfma_f32_16x16x32_bf16 v[18:21], v[146:149], v[214:217], v[18:21]
	v_mfma_f32_16x16x32_bf16 v[10:13], v[162:165], v[214:217], v[10:13]
	v_mfma_f32_16x16x32_bf16 v[62:65], v[158:161], v[194:197], v[62:65]
	v_mfma_f32_16x16x32_bf16 v[58:61], v[166:169], v[194:197], v[58:61]
	v_mfma_f32_16x16x32_bf16 v[50:53], v[158:161], v[202:205], v[50:53]
	v_mfma_f32_16x16x32_bf16 v[42:45], v[166:169], v[202:205], v[42:45]
	v_mfma_f32_16x16x32_bf16 v[34:37], v[158:161], v[210:213], v[34:37]
	v_mfma_f32_16x16x32_bf16 v[26:29], v[166:169], v[210:213], v[26:29]
	v_mfma_f32_16x16x32_bf16 v[18:21], v[158:161], v[218:221], v[18:21]
	v_mfma_f32_16x16x32_bf16 v[10:13], v[166:169], v[218:221], v[10:13]
	v_mfma_f32_16x16x32_bf16 v[54:57], v[174:177], v[190:193], v[54:57]
	v_mfma_f32_16x16x32_bf16 v[46:49], v[182:185], v[190:193], v[46:49]
	v_mfma_f32_16x16x32_bf16 v[38:41], v[174:177], v[198:201], v[38:41]
	v_mfma_f32_16x16x32_bf16 v[30:33], v[182:185], v[198:201], v[30:33]
	v_mfma_f32_16x16x32_bf16 v[22:25], v[174:177], v[206:209], v[22:25]
	v_mfma_f32_16x16x32_bf16 v[14:17], v[182:185], v[206:209], v[14:17]
	v_mfma_f32_16x16x32_bf16 v[6:9], v[174:177], v[214:217], v[6:9]
	v_mfma_f32_16x16x32_bf16 v[2:5], v[182:185], v[214:217], v[2:5]
	v_mfma_f32_16x16x32_bf16 v[54:57], v[178:181], v[194:197], v[54:57]
	v_mfma_f32_16x16x32_bf16 v[46:49], v[186:189], v[194:197], v[46:49]
	v_mfma_f32_16x16x32_bf16 v[38:41], v[178:181], v[202:205], v[38:41]
	v_mfma_f32_16x16x32_bf16 v[30:33], v[186:189], v[202:205], v[30:33]
	v_mfma_f32_16x16x32_bf16 v[22:25], v[178:181], v[210:213], v[22:25]
	v_mfma_f32_16x16x32_bf16 v[14:17], v[186:189], v[210:213], v[14:17]
	v_mfma_f32_16x16x32_bf16 v[6:9], v[178:181], v[218:221], v[6:9]
	v_mfma_f32_16x16x32_bf16 v[2:5], v[186:189], v[218:221], v[2:5]
	s_barrier
	s_add_i32 s64, s64, 2
	s_add_u32 s28, s28, 0x100
	s_addc_u32 s29, s29, 0
	s_add_u32 s62, s62, 0x100
	s_addc_u32 s63, s63, 0
	s_cmp_gt_u32 s64, 13
	s_cbranch_scc0 .LBB0_1314
	s_and_b64 vcc, exec, s[10:11]
	s_cbranch_vccz .LBB0_1317
	s_barrier

; #define PG8_STAGE(bufoff, gbase, voff) do { _Pragma("unroll") for (int _i = 0; _i < 2; ++_i) \
;         __builtin_amdgcn_global_load_lds((const unsigned*)((const char*)(gbase) + (voff)[_i]), (PG8_LAS unsigned*)(lds + (bufoff) + ldsw + _i * 8192), 16, 0, 0); } while (0)
; #define PG8_LDA(dst, b, h) do { _Pragma("unroll") for (int m = 0; m < 4; ++m) _Pragma("unroll") for (int k = 0; k < 2; ++k) dst[m][k] = *(const PG8_LAS bf16x8*)(lds + PG8_SA(b, h) + aoff + m * 2048 + k * 1024); } while (0)
; #define PG8_LDB(dst, b, h) do { _Pragma("unroll") for (int n = 0; n < 2; ++n) _Pragma("unroll") for (int k = 0; k < 2; ++k) dst[n][k] = *(const PG8_LAS bf16x8*)(lds + PG8_SB(b, h) + boff + n * 2048 + k * 1024); } while (0)
; #define PG8_SCHED __builtin_amdgcn_sched_barrier(0)
; template <class Epi, class Sched, bool ALIGN_EPI = false, bool SP2 = false>
; __device__ __forceinline__ void gemm_phase(PG8_LAS unsigned char* lds, const Gemm g, const Sched& S, const Epi& E) {
;     ...
;         const bool has_next = S.next(ui + 1, nxt);
;         const char* nA = has_next ? (const char*)g.A + (size_t)nxt.pm * tstep : cA; const char* nB = has_next ? (const char*)g.Bt + (size_t)nxt.pn * tstep : cB;
; #pragma nounroll
;         for (int t = 0; t < nt; t += 2) {
;             const bool last = (t == nt - 2);
;             const char* a1 = cA + (size_t)(t + 1) * kstep;
;             const char* a2 = last ? nA : cA + (size_t)(t + 2) * kstep; const char* b2 = last ? nB : cB + (size_t)(t + 2) * kstep;
;             const char* a3 = a2 + kstep; const char* b3 = b2 + kstep;
;             if (last && has_next) S.a_ready(nxt);
;             if constexpr (SP2) {
;             PG8_LDB(B0, 0, 0); PG8_LDB(B1, 0, 1); PG8_SCHED; PG8_LDA(At, 0, 0); PG8_STAGE(PG8_SA(1, 1), a1 + hstep, voffA);
.LBB0_1338:
	s_ashr_i32 s25, s24, 31
	s_lshl_b64 s[26:27], s[24:25], 18
	s_add_u32 s26, s42, s26
	s_addc_u32 s27, s43, s27
	s_and_b64 s[28:29], s[2:3], exec
	s_cselect_b32 s25, s27, s35
	s_cselect_b32 s64, s26, s34
	s_ashr_i32 s23, s22, 31
	s_lshl_b64 s[28:29], s[22:23], 18
	s_add_u32 s28, s44, s28
	s_addc_u32 s29, s45, s29
	s_and_b64 s[40:41], s[2:3], exec
	s_cselect_b32 s23, s29, s39
	s_cselect_b32 s65, s28, s38
	s_add_u32 s34, s34, 0x20080
	s_addc_u32 s35, s35, 0
	s_add_u32 s66, s38, 0x100
	s_addc_u32 s67, s39, 0
	s_mov_b32 s68, -2
	ds_read_b128 v[146:149], v154
	ds_read_b128 v[158:161], v154 offset:1024
	ds_read_b128 v[162:165], v154 offset:2048
	ds_read_b128 v[166:169], v154 offset:3072
	ds_read_b128 v[174:177], v155
	ds_read_b128 v[178:181], v155 offset:1024
	ds_read_b128 v[182:185], v155 offset:2048
	ds_read_b128 v[186:189], v155 offset:3072
	s_add_u32 s38, s34, 0xfffe0080
	s_addc_u32 s39, s35, -1
	s_cmp_eq_u32 s68, 4
	s_cselect_b32 s41, s25, s39
	s_cselect_b32 s40, s64, s38
	s_cselect_b32 s39, s23, s67
	s_cselect_b32 s38, s65, s66

; #define PG8_STAGE(bufoff, gbase, voff) do { _Pragma("unroll") for (int _i = 0; _i < 2; ++_i) \
;         __builtin_amdgcn_global_load_lds((const unsigned*)((const char*)(gbase) + (voff)[_i]), (PG8_LAS unsigned*)(lds + (bufoff) + ldsw + _i * 8192), 16, 0, 0); } while (0)
; #define PG8_LDA(dst, b, h) do { _Pragma("unroll") for (int m = 0; m < 4; ++m) _Pragma("unroll") for (int k = 0; k < 2; ++k) dst[m][k] = *(const PG8_LAS bf16x8*)(lds + PG8_SA(b, h) + aoff + m * 2048 + k * 1024); } while (0)
; #define PG8_LDB(dst, b, h) do { _Pragma("unroll") for (int n = 0; n < 2; ++n) _Pragma("unroll") for (int k = 0; k < 2; ++k) dst[n][k] = *(const PG8_LAS bf16x8*)(lds + PG8_SB(b, h) + boff + n * 2048 + k * 1024); } while (0)
; #define PG8_MMA(ai, bj, At, Bt) do { __builtin_amdgcn_s_setprio(1); _Pragma("unroll") for (int m = 0; m < 4; ++m) _Pragma("unroll") for (int n = 0; n < 2; ++n) _Pragma("unroll") for (int k = 0; k < 2; ++k) \
;         acc[ai][bj][m][n] = __builtin_amdgcn_mfma_f32_16x16x32_bf16(Bt[n][k], At[m][k], acc[ai][bj][m][n], 0, 0, 0); __builtin_amdgcn_s_setprio(0); } while (0)
; #define PG8_WAIT_V(n) asm volatile("s_waitcnt vmcnt(" #n ")" ::: "memory")
; #define PG8_WAIT_L(n) asm volatile("s_waitcnt lgkmcnt(" #n ")" ::: "memory")
; #define PG8_BAR __builtin_amdgcn_s_barrier()
; #define PG8_SCHED __builtin_amdgcn_sched_barrier(0)
; template <class Epi, class Sched, bool ALIGN_EPI = false, bool SP2 = false>
; __device__ __forceinline__ void gemm_phase(PG8_LAS unsigned char* lds, const Gemm g, const Sched& S, const Epi& E) {
;     ...
;             PG8_LDB(B0, 0, 0); PG8_LDB(B1, 0, 1); PG8_SCHED; PG8_LDA(At, 0, 0); PG8_STAGE(PG8_SA(1, 1), a1 + hstep, voffA);
;             PG8_WAIT_V(8); PG8_WAIT_L(0); PG8_BAR; PG8_MMA(0, 0, At, B0); PG8_MMA(0, 1, At, B1); PG8_BAR; PG8_SCHED;
	v_lshl_add_u64 v[150:151], s[34:35], 0, v[138:139]
	s_add_i32 m0, s31, 0xc000
	ds_read_b128 v[190:193], v156
	ds_read_b128 v[194:197], v156 offset:1024
	ds_read_b128 v[198:201], v156 offset:2048
	ds_read_b128 v[202:205], v156 offset:3072
	ds_read_b128 v[206:209], v156 offset:4096
	ds_read_b128 v[210:213], v156 offset:5120
	ds_read_b128 v[214:217], v156 offset:6144
	ds_read_b128 v[218:221], v156 offset:7168
	global_load_lds_dwordx4 v[150:151], off
	v_lshl_add_u64 v[150:151], s[34:35], 0, v[140:141]
	s_add_i32 m0, s31, 0xe000
	s_nop 0
	global_load_lds_dwordx4 v[150:151], off
	s_waitcnt vmcnt(56)
	s_waitcnt lgkmcnt(0)
	s_barrier
	s_waitcnt lgkmcnt(0)
	v_mfma_f32_16x16x32_bf16 v[126:129], v[146:149], v[190:193], 0
	v_mfma_f32_16x16x32_bf16 v[122:125], v[162:165], v[190:193], 0
	v_mfma_f32_16x16x32_bf16 v[110:113], v[146:149], v[198:201], 0
	v_mfma_f32_16x16x32_bf16 v[106:109], v[162:165], v[198:201], 0
	v_mfma_f32_16x16x32_bf16 v[94:97], v[146:149], v[206:209], 0
	v_mfma_f32_16x16x32_bf16 v[90:93], v[162:165], v[206:209], 0
	v_mfma_f32_16x16x32_bf16 v[78:81], v[146:149], v[214:217], 0
	v_mfma_f32_16x16x32_bf16 v[74:77], v[162:165], v[214:217], 0
	v_mfma_f32_16x16x32_bf16 v[126:129], v[158:161], v[194:197], v[126:129]
	v_mfma_f32_16x16x32_bf16 v[122:125], v[166:169], v[194:197], v[122:125]
	v_mfma_f32_16x16x32_bf16 v[110:113], v[158:161], v[202:205], v[110:113]
	v_mfma_f32_16x16x32_bf16 v[106:109], v[166:169], v[202:205], v[106:109]
	v_mfma_f32_16x16x32_bf16 v[94:97], v[158:161], v[210:213], v[94:97]
	v_mfma_f32_16x16x32_bf16 v[90:93], v[166:169], v[210:213], v[90:93]
	v_mfma_f32_16x16x32_bf16 v[78:81], v[158:161], v[218:221], v[78:81]
	v_mfma_f32_16x16x32_bf16 v[74:77], v[166:169], v[218:221], v[74:77]
	v_mfma_f32_16x16x32_bf16 v[118:121], v[174:177], v[190:193], 0
	v_mfma_f32_16x16x32_bf16 v[114:117], v[182:185], v[190:193], 0
	v_mfma_f32_16x16x32_bf16 v[102:105], v[174:177], v[198:201], 0
	v_mfma_f32_16x16x32_bf16 v[98:101], v[182:185], v[198:201], 0
	v_mfma_f32_16x16x32_bf16 v[86:89], v[174:177], v[206:209], 0
	v_mfma_f32_16x16x32_bf16 v[82:85], v[182:185], v[206:209], 0
	v_mfma_f32_16x16x32_bf16 v[70:73], v[174:177], v[214:217], 0
	v_mfma_f32_16x16x32_bf16 v[66:69], v[182:185], v[214:217], 0
	v_mfma_f32_16x16x32_bf16 v[118:121], v[178:181], v[194:197], v[118:121]
	v_mfma_f32_16x16x32_bf16 v[114:117], v[186:189], v[194:197], v[114:117]
	v_mfma_f32_16x16x32_bf16 v[102:105], v[178:181], v[202:205], v[102:105]
	v_mfma_f32_16x16x32_bf16 v[98:101], v[186:189], v[202:205], v[98:101]
	v_mfma_f32_16x16x32_bf16 v[86:89], v[178:181], v[210:213], v[86:89]
	v_mfma_f32_16x16x32_bf16 v[82:85], v[186:189], v[210:213], v[82:85]
	v_mfma_f32_16x16x32_bf16 v[70:73], v[178:181], v[218:221], v[70:73]
	v_mfma_f32_16x16x32_bf16 v[66:69], v[186:189], v[218:221], v[66:69]
	s_barrier

; #define PG8_STAGE(bufoff, gbase, voff) do { _Pragma("unroll") for (int _i = 0; _i < 2; ++_i) \
;         __builtin_amdgcn_global_load_lds((const unsigned*)((const char*)(gbase) + (voff)[_i]), (PG8_LAS unsigned*)(lds + (bufoff) + ldsw + _i * 8192), 16, 0, 0); } while (0)
; #define PG8_LDA(dst, b, h) do { _Pragma("unroll") for (int m = 0; m < 4; ++m) _Pragma("unroll") for (int k = 0; k < 2; ++k) dst[m][k] = *(const PG8_LAS bf16x8*)(lds + PG8_SA(b, h) + aoff + m * 2048 + k * 1024); } while (0)
; #define PG8_MMA(ai, bj, At, Bt) do { __builtin_amdgcn_s_setprio(1); _Pragma("unroll") for (int m = 0; m < 4; ++m) _Pragma("unroll") for (int n = 0; n < 2; ++n) _Pragma("unroll") for (int k = 0; k < 2; ++k) \
;         acc[ai][bj][m][n] = __builtin_amdgcn_mfma_f32_16x16x32_bf16(Bt[n][k], At[m][k], acc[ai][bj][m][n], 0, 0, 0); __builtin_amdgcn_s_setprio(0); } while (0)
; #define PG8_WAIT_V(n) asm volatile("s_waitcnt vmcnt(" #n ")" ::: "memory")
; #define PG8_WAIT_L(n) asm volatile("s_waitcnt lgkmcnt(" #n ")" ::: "memory")
; #define PG8_BAR __builtin_amdgcn_s_barrier()
; #define PG8_SCHED __builtin_amdgcn_sched_barrier(0)
; template <class Epi, class Sched, bool ALIGN_EPI = false, bool SP2 = false>
; __device__ __forceinline__ void gemm_phase(PG8_LAS unsigned char* lds, const Gemm g, const Sched& S, const Epi& E) {
;     ...
;             PG8_LDA(At, 0, 1); PG8_STAGE(PG8_SB(0, 0), b2, voffB); PG8_STAGE(PG8_SB(0, 1), b2 + hstep, voffB); PG8_STAGE(PG8_SA(0, 0), a2, voffA);
;             PG8_WAIT_V(8); PG8_WAIT_L(0); PG8_BAR; PG8_MMA(1, 0, At, B0); PG8_MMA(1, 1, At, B1); PG8_BAR; PG8_SCHED;
	s_add_i32 s69, s61, s52
	v_lshl_add_u64 v[150:151], s[38:39], 0, v[132:133]
	s_mov_b32 m0, s69
	ds_read_b128 v[190:193], v156 offset:16384
	ds_read_b128 v[194:197], v156 offset:17408
	ds_read_b128 v[198:201], v156 offset:18432
	ds_read_b128 v[202:205], v156 offset:19456
	ds_read_b128 v[206:209], v156 offset:20480
	ds_read_b128 v[210:213], v156 offset:21504
	ds_read_b128 v[214:217], v156 offset:22528
	ds_read_b128 v[218:221], v156 offset:23552
	global_load_lds_dwordx4 v[150:151], off
	s_add_i32 m0, s69, 0x2000
	s_add_u32 s70, s38, 0x20000
	v_lshl_add_u64 v[170:171], s[38:39], 0, v[136:137]
	s_addc_u32 s71, s39, 0
	s_add_i32 s69, s62, s52
	global_load_lds_dwordx4 v[170:171], off
	v_lshl_add_u64 v[222:223], s[70:71], 0, v[132:133]
	s_mov_b32 m0, s69
	v_lshl_add_u64 v[224:225], s[40:41], 0, v[134:135]
	global_load_lds_dwordx4 v[222:223], off
	v_lshl_add_u64 v[222:223], s[70:71], 0, v[136:137]
	s_add_i32 m0, s69, 0x2000
	s_nop 0
	global_load_lds_dwordx4 v[222:223], off
	v_lshl_add_u64 v[222:223], s[40:41], 0, v[130:131]
	s_mov_b32 m0, s31
	s_nop 0
	global_load_lds_dwordx4 v[222:223], off
	s_mov_b32 m0, s53
	s_nop 0
	global_load_lds_dwordx4 v[224:225], off
	s_waitcnt vmcnt(56)
	s_waitcnt lgkmcnt(0)
	s_barrier
	s_waitcnt lgkmcnt(0)
	v_mfma_f32_16x16x32_bf16 v[62:65], v[146:149], v[190:193], 0
	v_mfma_f32_16x16x32_bf16 v[58:61], v[162:165], v[190:193], 0
	v_mfma_f32_16x16x32_bf16 v[46:49], v[146:149], v[198:201], 0
	v_mfma_f32_16x16x32_bf16 v[42:45], v[162:165], v[198:201], 0
	v_mfma_f32_16x16x32_bf16 v[30:33], v[146:149], v[206:209], 0
	v_mfma_f32_16x16x32_bf16 v[26:29], v[162:165], v[206:209], 0
	v_mfma_f32_16x16x32_bf16 v[14:17], v[146:149], v[214:217], 0
	v_mfma_f32_16x16x32_bf16 v[10:13], v[162:165], v[214:217], 0
	v_mfma_f32_16x16x32_bf16 v[62:65], v[158:161], v[194:197], v[62:65]
	v_mfma_f32_16x16x32_bf16 v[58:61], v[166:169], v[194:197], v[58:61]
	v_mfma_f32_16x16x32_bf16 v[46:49], v[158:161], v[202:205], v[46:49]
	v_mfma_f32_16x16x32_bf16 v[42:45], v[166:169], v[202:205], v[42:45]
	v_mfma_f32_16x16x32_bf16 v[30:33], v[158:161], v[210:213], v[30:33]
	v_mfma_f32_16x16x32_bf16 v[26:29], v[166:169], v[210:213], v[26:29]
	v_mfma_f32_16x16x32_bf16 v[14:17], v[158:161], v[218:221], v[14:17]
	v_mfma_f32_16x16x32_bf16 v[10:13], v[166:169], v[218:221], v[10:13]
	v_mfma_f32_16x16x32_bf16 v[54:57], v[174:177], v[190:193], 0
	v_mfma_f32_16x16x32_bf16 v[50:53], v[182:185], v[190:193], 0
	v_mfma_f32_16x16x32_bf16 v[38:41], v[174:177], v[198:201], 0
	v_mfma_f32_16x16x32_bf16 v[34:37], v[182:185], v[198:201], 0
	v_mfma_f32_16x16x32_bf16 v[22:25], v[174:177], v[206:209], 0
	v_mfma_f32_16x16x32_bf16 v[18:21], v[182:185], v[206:209], 0
	v_mfma_f32_16x16x32_bf16 v[6:9], v[174:177], v[214:217], 0
	v_mfma_f32_16x16x32_bf16 v[2:5], v[182:185], v[214:217], 0
	v_mfma_f32_16x16x32_bf16 v[54:57], v[178:181], v[194:197], v[54:57]
	v_mfma_f32_16x16x32_bf16 v[50:53], v[186:189], v[194:197], v[50:53]
	v_mfma_f32_16x16x32_bf16 v[38:41], v[178:181], v[202:205], v[38:41]
	v_mfma_f32_16x16x32_bf16 v[34:37], v[186:189], v[202:205], v[34:37]
	v_mfma_f32_16x16x32_bf16 v[22:25], v[178:181], v[210:213], v[22:25]
	v_mfma_f32_16x16x32_bf16 v[18:21], v[186:189], v[210:213], v[18:21]
	v_mfma_f32_16x16x32_bf16 v[6:9], v[178:181], v[218:221], v[6:9]
	v_mfma_f32_16x16x32_bf16 v[2:5], v[186:189], v[218:221], v[2:5]
	s_barrier

; #define PG8_STAGE(bufoff, gbase, voff) do { _Pragma("unroll") for (int _i = 0; _i < 2; ++_i) \
;         __builtin_amdgcn_global_load_lds((const unsigned*)((const char*)(gbase) + (voff)[_i]), (PG8_LAS unsigned*)(lds + (bufoff) + ldsw + _i * 8192), 16, 0, 0); } while (0)
; #define PG8_LDA(dst, b, h) do { _Pragma("unroll") for (int m = 0; m < 4; ++m) _Pragma("unroll") for (int k = 0; k < 2; ++k) dst[m][k] = *(const PG8_LAS bf16x8*)(lds + PG8_SA(b, h) + aoff + m * 2048 + k * 1024); } while (0)
; #define PG8_LDB(dst, b, h) do { _Pragma("unroll") for (int n = 0; n < 2; ++n) _Pragma("unroll") for (int k = 0; k < 2; ++k) dst[n][k] = *(const PG8_LAS bf16x8*)(lds + PG8_SB(b, h) + boff + n * 2048 + k * 1024); } while (0)
; #define PG8_SCHED __builtin_amdgcn_sched_barrier(0)
; template <class Epi, class Sched, bool ALIGN_EPI = false, bool SP2 = false>
; __device__ __forceinline__ void gemm_phase(PG8_LAS unsigned char* lds, const Gemm g, const Sched& S, const Epi& E) {
;     ...
;             PG8_LDB(B0, 1, 0); PG8_LDB(B1, 1, 1); PG8_SCHED; PG8_LDA(At, 1, 0); PG8_STAGE(PG8_SA(0, 1), a2 + hstep, voffA);
	s_add_i32 s69, 0, 0x18000
	v_add_u32_e32 v157, s69, v152
	s_add_i32 s70, 0, 0x1c000
	ds_read_b128 v[146:149], v157
	ds_read_b128 v[158:161], v157 offset:1024
	ds_read_b128 v[162:165], v157 offset:2048
	ds_read_b128 v[166:169], v157 offset:3072
	v_add_u32_e32 v157, s70, v152
	ds_read_b128 v[174:177], v157
	ds_read_b128 v[178:181], v157 offset:1024
	ds_read_b128 v[182:185], v157 offset:2048
	ds_read_b128 v[186:189], v157 offset:3072

; #define PG8_STAGE(bufoff, gbase, voff) do { _Pragma("unroll") for (int _i = 0; _i < 2; ++_i) \
;         __builtin_amdgcn_global_load_lds((const unsigned*)((const char*)(gbase) + (voff)[_i]), (PG8_LAS unsigned*)(lds + (bufoff) + ldsw + _i * 8192), 16, 0, 0); } while (0)
; #define PG8_LDA(dst, b, h) do { _Pragma("unroll") for (int m = 0; m < 4; ++m) _Pragma("unroll") for (int k = 0; k < 2; ++k) dst[m][k] = *(const PG8_LAS bf16x8*)(lds + PG8_SA(b, h) + aoff + m * 2048 + k * 1024); } while (0)
; #define PG8_LDB(dst, b, h) do { _Pragma("unroll") for (int n = 0; n < 2; ++n) _Pragma("unroll") for (int k = 0; k < 2; ++k) dst[n][k] = *(const PG8_LAS bf16x8*)(lds + PG8_SB(b, h) + boff + n * 2048 + k * 1024); } while (0)
; #define PG8_MMA(ai, bj, At, Bt) do { __builtin_amdgcn_s_setprio(1); _Pragma("unroll") for (int m = 0; m < 4; ++m) _Pragma("unroll") for (int n = 0; n < 2; ++n) _Pragma("unroll") for (int k = 0; k < 2; ++k) \
;         acc[ai][bj][m][n] = __builtin_amdgcn_mfma_f32_16x16x32_bf16(Bt[n][k], At[m][k], acc[ai][bj][m][n], 0, 0, 0); __builtin_amdgcn_s_setprio(0); } while (0)
; #define PG8_WAIT_V(n) asm volatile("s_waitcnt vmcnt(" #n ")" ::: "memory")
; #define PG8_WAIT_L(n) asm volatile("s_waitcnt lgkmcnt(" #n ")" ::: "memory")
; #define PG8_BAR __builtin_amdgcn_s_barrier()
; #define PG8_SCHED __builtin_amdgcn_sched_barrier(0)
; template <class Epi, class Sched, bool ALIGN_EPI = false, bool SP2 = false>
; __device__ __forceinline__ void gemm_phase(PG8_LAS unsigned char* lds, const Gemm g, const Sched& S, const Epi& E) {
;     ...
;             PG8_LDB(B0, 1, 0); PG8_LDB(B1, 1, 1); PG8_SCHED; PG8_LDA(At, 1, 0); PG8_STAGE(PG8_SA(0, 1), a2 + hstep, voffA);
;             PG8_WAIT_V(8); PG8_WAIT_L(0); PG8_BAR; PG8_MMA(0, 0, At, B0); PG8_MMA(0, 1, At, B1); PG8_BAR; PG8_SCHED;
	s_add_u32 s40, s40, 0x20000
	s_addc_u32 s41, s41, 0
	s_mov_b32 m0, s54
	v_lshl_add_u64 v[226:227], s[40:41], 0, v[130:131]
	ds_read_b128 v[190:193], v156 offset:32768
	ds_read_b128 v[194:197], v156 offset:33792
	ds_read_b128 v[198:201], v156 offset:34816
	ds_read_b128 v[202:205], v156 offset:35840
	ds_read_b128 v[206:209], v156 offset:36864
	ds_read_b128 v[210:213], v156 offset:37888
	ds_read_b128 v[214:217], v156 offset:38912
	ds_read_b128 v[218:221], v156 offset:39936
	global_load_lds_dwordx4 v[226:227], off
	v_lshl_add_u64 v[226:227], s[40:41], 0, v[134:135]
	s_mov_b32 m0, s55
	s_nop 0
	global_load_lds_dwordx4 v[226:227], off
	s_waitcnt vmcnt(8)
	s_waitcnt lgkmcnt(0)
	s_barrier
	s_waitcnt lgkmcnt(0)
	v_mfma_f32_16x16x32_bf16 v[126:129], v[146:149], v[190:193], v[126:129]
	v_mfma_f32_16x16x32_bf16 v[122:125], v[162:165], v[190:193], v[122:125]
	v_mfma_f32_16x16x32_bf16 v[110:113], v[146:149], v[198:201], v[110:113]
	v_mfma_f32_16x16x32_bf16 v[106:109], v[162:165], v[198:201], v[106:109]
	v_mfma_f32_16x16x32_bf16 v[94:97], v[146:149], v[206:209], v[94:97]
	v_mfma_f32_16x16x32_bf16 v[90:93], v[162:165], v[206:209], v[90:93]
	v_mfma_f32_16x16x32_bf16 v[78:81], v[146:149], v[214:217], v[78:81]
	v_mfma_f32_16x16x32_bf16 v[74:77], v[162:165], v[214:217], v[74:77]
	v_mfma_f32_16x16x32_bf16 v[126:129], v[158:161], v[194:197], v[126:129]
	v_mfma_f32_16x16x32_bf16 v[122:125], v[166:169], v[194:197], v[122:125]
	v_mfma_f32_16x16x32_bf16 v[110:113], v[158:161], v[202:205], v[110:113]
	v_mfma_f32_16x16x32_bf16 v[106:109], v[166:169], v[202:205], v[106:109]
	v_mfma_f32_16x16x32_bf16 v[94:97], v[158:161], v[210:213], v[94:97]
	v_mfma_f32_16x16x32_bf16 v[90:93], v[166:169], v[210:213], v[90:93]
	v_mfma_f32_16x16x32_bf16 v[78:81], v[158:161], v[218:221], v[78:81]
	v_mfma_f32_16x16x32_bf16 v[74:77], v[166:169], v[218:221], v[74:77]
	v_mfma_f32_16x16x32_bf16 v[118:121], v[174:177], v[190:193], v[118:121]
	v_mfma_f32_16x16x32_bf16 v[114:117], v[182:185], v[190:193], v[114:117]
	v_mfma_f32_16x16x32_bf16 v[102:105], v[174:177], v[198:201], v[102:105]
	v_mfma_f32_16x16x32_bf16 v[98:101], v[182:185], v[198:201], v[98:101]
	v_mfma_f32_16x16x32_bf16 v[86:89], v[174:177], v[206:209], v[86:89]
	v_mfma_f32_16x16x32_bf16 v[82:85], v[182:185], v[206:209], v[82:85]
	v_mfma_f32_16x16x32_bf16 v[70:73], v[174:177], v[214:217], v[70:73]
	v_mfma_f32_16x16x32_bf16 v[66:69], v[182:185], v[214:217], v[66:69]
	v_mfma_f32_16x16x32_bf16 v[118:121], v[178:181], v[194:197], v[118:121]
	v_mfma_f32_16x16x32_bf16 v[114:117], v[186:189], v[194:197], v[114:117]
	v_mfma_f32_16x16x32_bf16 v[102:105], v[178:181], v[202:205], v[102:105]
	v_mfma_f32_16x16x32_bf16 v[98:101], v[186:189], v[202:205], v[98:101]
	v_mfma_f32_16x16x32_bf16 v[86:89], v[178:181], v[210:213], v[86:89]
	v_mfma_f32_16x16x32_bf16 v[82:85], v[186:189], v[210:213], v[82:85]
	v_mfma_f32_16x16x32_bf16 v[70:73], v[178:181], v[218:221], v[70:73]
	v_mfma_f32_16x16x32_bf16 v[66:69], v[186:189], v[218:221], v[66:69]
	s_barrier

; #define PG8_STAGE(bufoff, gbase, voff) do { _Pragma("unroll") for (int _i = 0; _i < 2; ++_i) \
;         __builtin_amdgcn_global_load_lds((const unsigned*)((const char*)(gbase) + (voff)[_i]), (PG8_LAS unsigned*)(lds + (bufoff) + ldsw + _i * 8192), 16, 0, 0); } while (0)
; #define PG8_LDA(dst, b, h) do { _Pragma("unroll") for (int m = 0; m < 4; ++m) _Pragma("unroll") for (int k = 0; k < 2; ++k) dst[m][k] = *(const PG8_LAS bf16x8*)(lds + PG8_SA(b, h) + aoff + m * 2048 + k * 1024); } while (0)
; #define PG8_MMA(ai, bj, At, Bt) do { __builtin_amdgcn_s_setprio(1); _Pragma("unroll") for (int m = 0; m < 4; ++m) _Pragma("unroll") for (int n = 0; n < 2; ++n) _Pragma("unroll") for (int k = 0; k < 2; ++k) \
;         acc[ai][bj][m][n] = __builtin_amdgcn_mfma_f32_16x16x32_bf16(Bt[n][k], At[m][k], acc[ai][bj][m][n], 0, 0, 0); __builtin_amdgcn_s_setprio(0); } while (0)
; #define PG8_WAIT_V(n) asm volatile("s_waitcnt vmcnt(" #n ")" ::: "memory")
; #define PG8_WAIT_L(n) asm volatile("s_waitcnt lgkmcnt(" #n ")" ::: "memory")
; #define PG8_BAR __builtin_amdgcn_s_barrier()
; #define PG8_SCHED __builtin_amdgcn_sched_barrier(0)
; template <class Epi, class Sched, bool ALIGN_EPI = false, bool SP2 = false>
; __device__ __forceinline__ void gemm_phase(PG8_LAS unsigned char* lds, const Gemm g, const Sched& S, const Epi& E) {
;     ...
;             PG8_LDA(At, 1, 1); PG8_STAGE(PG8_SB(1, 0), b3, voffB); PG8_STAGE(PG8_SB(1, 1), b3 + hstep, voffB); PG8_STAGE(PG8_SA(1, 0), a3, voffA);
;             PG8_WAIT_V(8); PG8_WAIT_L(0); PG8_BAR; PG8_MMA(1, 0, At, B0); PG8_MMA(1, 1, At, B1); PG8_BAR; PG8_SCHED;
	s_add_i32 s40, s69, s52
	v_lshl_add_u64 v[150:151], v[150:151], 0, s[10:11]
	s_mov_b32 m0, s40
	ds_read_b128 v[190:193], v156 offset:49152
	ds_read_b128 v[194:197], v156 offset:50176
	ds_read_b128 v[198:201], v156 offset:51200
	ds_read_b128 v[202:205], v156 offset:52224
	ds_read_b128 v[206:209], v156 offset:53248
	ds_read_b128 v[210:213], v156 offset:54272
	ds_read_b128 v[214:217], v156 offset:55296
	ds_read_b128 v[218:221], v156 offset:56320
	global_load_lds_dwordx4 v[150:151], off
	s_add_i32 m0, s40, 0x2000
	s_add_u32 s38, s38, 0x20080
	v_lshl_add_u64 v[150:151], v[170:171], 0, s[10:11]
	s_addc_u32 s39, s39, 0
	s_add_i32 s40, s70, s52
	global_load_lds_dwordx4 v[150:151], off
	v_lshl_add_u64 v[150:151], s[38:39], 0, v[132:133]
	s_mov_b32 m0, s40
	s_nop 0
	global_load_lds_dwordx4 v[150:151], off
	v_lshl_add_u64 v[150:151], s[38:39], 0, v[136:137]
	s_add_i32 m0, s40, 0x2000
	s_nop 0
	global_load_lds_dwordx4 v[150:151], off
	v_lshl_add_u64 v[150:151], v[222:223], 0, s[10:11]
	s_mov_b32 m0, s57
	s_nop 0
	global_load_lds_dwordx4 v[150:151], off
	v_lshl_add_u64 v[150:151], v[224:225], 0, s[10:11]
	s_mov_b32 m0, s58
	s_nop 0
	global_load_lds_dwordx4 v[150:151], off
	s_waitcnt vmcnt(8)
	s_waitcnt lgkmcnt(0)
	s_barrier
	s_waitcnt lgkmcnt(0)
	v_mfma_f32_16x16x32_bf16 v[62:65], v[146:149], v[190:193], v[62:65]
	v_mfma_f32_16x16x32_bf16 v[58:61], v[162:165], v[190:193], v[58:61]
	v_mfma_f32_16x16x32_bf16 v[46:49], v[146:149], v[198:201], v[46:49]
	v_mfma_f32_16x16x32_bf16 v[42:45], v[162:165], v[198:201], v[42:45]
	v_mfma_f32_16x16x32_bf16 v[30:33], v[146:149], v[206:209], v[30:33]
	v_mfma_f32_16x16x32_bf16 v[26:29], v[162:165], v[206:209], v[26:29]
	v_mfma_f32_16x16x32_bf16 v[14:17], v[146:149], v[214:217], v[14:17]
	v_mfma_f32_16x16x32_bf16 v[10:13], v[162:165], v[214:217], v[10:13]
	v_mfma_f32_16x16x32_bf16 v[62:65], v[158:161], v[194:197], v[62:65]
	v_mfma_f32_16x16x32_bf16 v[58:61], v[166:169], v[194:197], v[58:61]
	v_mfma_f32_16x16x32_bf16 v[46:49], v[158:161], v[202:205], v[46:49]
	v_mfma_f32_16x16x32_bf16 v[42:45], v[166:169], v[202:205], v[42:45]
	v_mfma_f32_16x16x32_bf16 v[30:33], v[158:161], v[210:213], v[30:33]
	v_mfma_f32_16x16x32_bf16 v[26:29], v[166:169], v[210:213], v[26:29]
	v_mfma_f32_16x16x32_bf16 v[14:17], v[158:161], v[218:221], v[14:17]
	v_mfma_f32_16x16x32_bf16 v[10:13], v[166:169], v[218:221], v[10:13]
	v_mfma_f32_16x16x32_bf16 v[54:57], v[174:177], v[190:193], v[54:57]
	v_mfma_f32_16x16x32_bf16 v[50:53], v[182:185], v[190:193], v[50:53]
	v_mfma_f32_16x16x32_bf16 v[38:41], v[174:177], v[198:201], v[38:41]
	v_mfma_f32_16x16x32_bf16 v[34:37], v[182:185], v[198:201], v[34:37]
	v_mfma_f32_16x16x32_bf16 v[22:25], v[174:177], v[206:209], v[22:25]
	v_mfma_f32_16x16x32_bf16 v[18:21], v[182:185], v[206:209], v[18:21]
	v_mfma_f32_16x16x32_bf16 v[6:9], v[174:177], v[214:217], v[6:9]
	v_mfma_f32_16x16x32_bf16 v[2:5], v[182:185], v[214:217], v[2:5]
	v_mfma_f32_16x16x32_bf16 v[54:57], v[178:181], v[194:197], v[54:57]
	v_mfma_f32_16x16x32_bf16 v[50:53], v[186:189], v[194:197], v[50:53]
	v_mfma_f32_16x16x32_bf16 v[38:41], v[178:181], v[202:205], v[38:41]
	v_mfma_f32_16x16x32_bf16 v[34:37], v[186:189], v[202:205], v[34:37]
	v_mfma_f32_16x16x32_bf16 v[22:25], v[178:181], v[210:213], v[22:25]
	v_mfma_f32_16x16x32_bf16 v[18:21], v[186:189], v[210:213], v[18:21]
	v_mfma_f32_16x16x32_bf16 v[6:9], v[178:181], v[218:221], v[6:9]
	v_mfma_f32_16x16x32_bf16 v[2:5], v[186:189], v[218:221], v[2:5]
	s_barrier

; #define PG8_STAGE(bufoff, gbase, voff) do { _Pragma("unroll") for (int _i = 0; _i < 2; ++_i) \
;         __builtin_amdgcn_global_load_lds((const unsigned*)((const char*)(gbase) + (voff)[_i]), (PG8_LAS unsigned*)(lds + (bufoff) + ldsw + _i * 8192), 16, 0, 0); } while (0)
; #define PG8_LDA(dst, b, h) do { _Pragma("unroll") for (int m = 0; m < 4; ++m) _Pragma("unroll") for (int k = 0; k < 2; ++k) dst[m][k] = *(const PG8_LAS bf16x8*)(lds + PG8_SA(b, h) + aoff + m * 2048 + k * 1024); } while (0)
; #define PG8_LDB(dst, b, h) do { _Pragma("unroll") for (int n = 0; n < 2; ++n) _Pragma("unroll") for (int k = 0; k < 2; ++k) dst[n][k] = *(const PG8_LAS bf16x8*)(lds + PG8_SB(b, h) + boff + n * 2048 + k * 1024); } while (0)
; #define PG8_MMA(ai, bj, At, Bt) do { __builtin_amdgcn_s_setprio(1); _Pragma("unroll") for (int m = 0; m < 4; ++m) _Pragma("unroll") for (int n = 0; n < 2; ++n) _Pragma("unroll") for (int k = 0; k < 2; ++k) \
;         acc[ai][bj][m][n] = __builtin_amdgcn_mfma_f32_16x16x32_bf16(Bt[n][k], At[m][k], acc[ai][bj][m][n], 0, 0, 0); __builtin_amdgcn_s_setprio(0); } while (0)
; #define PG8_WAIT_V(n) asm volatile("s_waitcnt vmcnt(" #n ")" ::: "memory")
; #define PG8_BAR __builtin_amdgcn_s_barrier()
; template <class Epi, class Sched, bool ALIGN_EPI = false, bool SP2 = false>
; __device__ __forceinline__ void gemm_phase(PG8_LAS unsigned char* lds, const Gemm g, const Sched& S, const Epi& E) {
;     ...
;         for (int t = 0; t < nt; t += 2) {
;             const bool last = (t == nt - 2);
;             const char* a1 = cA + (size_t)(t + 1) * kstep;
;             const char* a2 = last ? nA : cA + (size_t)(t + 2) * kstep; const char* b2 = last ? nB : cB + (size_t)(t + 2) * kstep;
;             const char* a3 = a2 + kstep; const char* b3 = b2 + kstep;
;             if (last && has_next) S.a_ready(nxt);
;             if constexpr (SP2) {
;             PG8_LDB(B0, 0, 0); PG8_LDB(B1, 0, 1); PG8_SCHED; PG8_LDA(At, 0, 0); PG8_STAGE(PG8_SA(1, 1), a1 + hstep, voffA);
;             PG8_WAIT_V(8); PG8_WAIT_L(0); PG8_BAR; PG8_MMA(0, 0, At, B0); PG8_MMA(0, 1, At, B1); PG8_BAR; PG8_SCHED;
;             PG8_LDA(At, 0, 1); PG8_STAGE(PG8_SB(0, 0), b2, voffB); PG8_STAGE(PG8_SB(0, 1), b2 + hstep, voffB); PG8_STAGE(PG8_SA(0, 0), a2, voffA);
;             PG8_WAIT_V(8); PG8_WAIT_L(0); PG8_BAR; PG8_MMA(1, 0, At, B0); PG8_MMA(1, 1, At, B1); PG8_BAR; PG8_SCHED;
	s_add_i32 s68, s68, 2
	s_add_u32 s34, s34, 0x100
	s_addc_u32 s35, s35, 0
	s_add_u32 s66, s66, 0x100
	s_addc_u32 s67, s67, 0
.LBB0_1339:
	ds_read_b128 v[146:149], v154
	ds_read_b128 v[158:161], v154 offset:1024
	ds_read_b128 v[162:165], v154 offset:2048
	ds_read_b128 v[166:169], v154 offset:3072
	ds_read_b128 v[174:177], v155
	ds_read_b128 v[178:181], v155 offset:1024
	ds_read_b128 v[182:185], v155 offset:2048
	ds_read_b128 v[186:189], v155 offset:3072
	s_add_u32 s38, s34, 0xfffe0080
	s_addc_u32 s39, s35, -1
	s_cmp_eq_u32 s68, 4
	s_cselect_b32 s41, s25, s39
	s_cselect_b32 s40, s64, s38
	s_cselect_b32 s39, s23, s67
	s_cselect_b32 s38, s65, s66
	v_lshl_add_u64 v[150:151], s[34:35], 0, v[138:139]
	s_add_i32 m0, s31, 0xc000
	ds_read_b128 v[190:193], v156
	ds_read_b128 v[194:197], v156 offset:1024
	ds_read_b128 v[198:201], v156 offset:2048
	ds_read_b128 v[202:205], v156 offset:3072
	ds_read_b128 v[206:209], v156 offset:4096
	ds_read_b128 v[210:213], v156 offset:5120
	ds_read_b128 v[214:217], v156 offset:6144
	ds_read_b128 v[218:221], v156 offset:7168
	global_load_lds_dwordx4 v[150:151], off
	v_lshl_add_u64 v[150:151], s[34:35], 0, v[140:141]
	s_add_i32 m0, s31, 0xe000
	s_nop 0
	global_load_lds_dwordx4 v[150:151], off
	s_waitcnt vmcnt(8)
	s_waitcnt lgkmcnt(0)
	s_barrier
	s_waitcnt lgkmcnt(0)
	v_mfma_f32_16x16x32_bf16 v[126:129], v[146:149], v[190:193], v[126:129]
	v_mfma_f32_16x16x32_bf16 v[122:125], v[162:165], v[190:193], v[122:125]
	v_mfma_f32_16x16x32_bf16 v[110:113], v[146:149], v[198:201], v[110:113]
	v_mfma_f32_16x16x32_bf16 v[106:109], v[162:165], v[198:201], v[106:109]
	v_mfma_f32_16x16x32_bf16 v[94:97], v[146:149], v[206:209], v[94:97]
	v_mfma_f32_16x16x32_bf16 v[90:93], v[162:165], v[206:209], v[90:93]
	v_mfma_f32_16x16x32_bf16 v[78:81], v[146:149], v[214:217], v[78:81]
	v_mfma_f32_16x16x32_bf16 v[74:77], v[162:165], v[214:217], v[74:77]
	v_mfma_f32_16x16x32_bf16 v[126:129], v[158:161], v[194:197], v[126:129]
	v_mfma_f32_16x16x32_bf16 v[122:125], v[166:169], v[194:197], v[122:125]
	v_mfma_f32_16x16x32_bf16 v[110:113], v[158:161], v[202:205], v[110:113]
	v_mfma_f32_16x16x32_bf16 v[106:109], v[166:169], v[202:205], v[106:109]
	v_mfma_f32_16x16x32_bf16 v[94:97], v[158:161], v[210:213], v[94:97]
	v_mfma_f32_16x16x32_bf16 v[90:93], v[166:169], v[210:213], v[90:93]
	v_mfma_f32_16x16x32_bf16 v[78:81], v[158:161], v[218:221], v[78:81]
	v_mfma_f32_16x16x32_bf16 v[74:77], v[166:169], v[218:221], v[74:77]
	v_mfma_f32_16x16x32_bf16 v[118:121], v[174:177], v[190:193], v[118:121]
	v_mfma_f32_16x16x32_bf16 v[114:117], v[182:185], v[190:193], v[114:117]
	v_mfma_f32_16x16x32_bf16 v[102:105], v[174:177], v[198:201], v[102:105]
	v_mfma_f32_16x16x32_bf16 v[98:101], v[182:185], v[198:201], v[98:101]
	v_mfma_f32_16x16x32_bf16 v[86:89], v[174:177], v[206:209], v[86:89]
	v_mfma_f32_16x16x32_bf16 v[82:85], v[182:185], v[206:209], v[82:85]
	v_mfma_f32_16x16x32_bf16 v[70:73], v[174:177], v[214:217], v[70:73]
	v_mfma_f32_16x16x32_bf16 v[66:69], v[182:185], v[214:217], v[66:69]
	v_mfma_f32_16x16x32_bf16 v[118:121], v[178:181], v[194:197], v[118:121]
	v_mfma_f32_16x16x32_bf16 v[114:117], v[186:189], v[194:197], v[114:117]
	v_mfma_f32_16x16x32_bf16 v[102:105], v[178:181], v[202:205], v[102:105]
	v_mfma_f32_16x16x32_bf16 v[98:101], v[186:189], v[202:205], v[98:101]
	v_mfma_f32_16x16x32_bf16 v[86:89], v[178:181], v[210:213], v[86:89]
	v_mfma_f32_16x16x32_bf16 v[82:85], v[186:189], v[210:213], v[82:85]
	v_mfma_f32_16x16x32_bf16 v[70:73], v[178:181], v[218:221], v[70:73]
	v_mfma_f32_16x16x32_bf16 v[66:69], v[186:189], v[218:221], v[66:69]
	s_barrier
	s_add_i32 s69, s61, s52
	v_lshl_add_u64 v[150:151], s[38:39], 0, v[132:133]
	s_mov_b32 m0, s69
	ds_read_b128 v[190:193], v156 offset:16384
	ds_read_b128 v[194:197], v156 offset:17408
	ds_read_b128 v[198:201], v156 offset:18432
	ds_read_b128 v[202:205], v156 offset:19456
	ds_read_b128 v[206:209], v156 offset:20480
	ds_read_b128 v[210:213], v156 offset:21504
	ds_read_b128 v[214:217], v156 offset:22528
	ds_read_b128 v[218:221], v156 offset:23552
	global_load_lds_dwordx4 v[150:151], off
	s_add_i32 m0, s69, 0x2000
	s_add_u32 s70, s38, 0x20000
	v_lshl_add_u64 v[170:171], s[38:39], 0, v[136:137]
	s_addc_u32 s71, s39, 0
	s_add_i32 s69, s62, s52
	global_load_lds_dwordx4 v[170:171], off
	v_lshl_add_u64 v[222:223], s[70:71], 0, v[132:133]
	s_mov_b32 m0, s69
	v_lshl_add_u64 v[224:225], s[40:41], 0, v[134:135]
	global_load_lds_dwordx4 v[222:223], off
	v_lshl_add_u64 v[222:223], s[70:71], 0, v[136:137]
	s_add_i32 m0, s69, 0x2000
	s_nop 0
	global_load_lds_dwordx4 v[222:223], off
	v_lshl_add_u64 v[222:223], s[40:41], 0, v[130:131]
	s_mov_b32 m0, s31
	s_nop 0
	global_load_lds_dwordx4 v[222:223], off
	s_mov_b32 m0, s53
	s_nop 0
	global_load_lds_dwordx4 v[224:225], off
	s_waitcnt vmcnt(8)
	s_waitcnt lgkmcnt(0)
	s_barrier
; #define PG8_STAGE(bufoff, gbase, voff) do { _Pragma("unroll") for (int _i = 0; _i < 2; ++_i) \
;         __builtin_amdgcn_global_load_lds((const unsigned*)((const char*)(gbase) + (voff)[_i]), (PG8_LAS unsigned*)(lds + (bufoff) + ldsw + _i * 8192), 16, 0, 0); } while (0)
; #define PG8_LDA(dst, b, h) do { _Pragma("unroll") for (int m = 0; m < 4; ++m) _Pragma("unroll") for (int k = 0; k < 2; ++k) dst[m][k] = *(const PG8_LAS bf16x8*)(lds + PG8_SA(b, h) + aoff + m * 2048 + k * 1024); } while (0)
; #define PG8_LDB(dst, b, h) do { _Pragma("unroll") for (int n = 0; n < 2; ++n) _Pragma("unroll") for (int k = 0; k < 2; ++k) dst[n][k] = *(const PG8_LAS bf16x8*)(lds + PG8_SB(b, h) + boff + n * 2048 + k * 1024); } while (0)
; #define PG8_MMA(ai, bj, At, Bt) do { __builtin_amdgcn_s_setprio(1); _Pragma("unroll") for (int m = 0; m < 4; ++m) _Pragma("unroll") for (int n = 0; n < 2; ++n) _Pragma("unroll") for (int k = 0; k < 2; ++k) \
;         acc[ai][bj][m][n] = __builtin_amdgcn_mfma_f32_16x16x32_bf16(Bt[n][k], At[m][k], acc[ai][bj][m][n], 0, 0, 0); __builtin_amdgcn_s_setprio(0); } while (0)
; #define PG8_WAIT_V(n) asm volatile("s_waitcnt vmcnt(" #n ")" ::: "memory")
; #define PG8_WAIT_L(n) asm volatile("s_waitcnt lgkmcnt(" #n ")" ::: "memory")
; #define PG8_BAR __builtin_amdgcn_s_barrier()
; #define PG8_SCHED __builtin_amdgcn_sched_barrier(0)
; template <class Epi, class Sched, bool ALIGN_EPI = false, bool SP2 = false>
; __device__ __forceinline__ void gemm_phase(PG8_LAS unsigned char* lds, const Gemm g, const Sched& S, const Epi& E) {
;     ...
;             PG8_WAIT_V(8); PG8_WAIT_L(0); PG8_BAR; PG8_MMA(1, 0, At, B0); PG8_MMA(1, 1, At, B1); PG8_BAR; PG8_SCHED;
;             PG8_LDB(B0, 1, 0); PG8_LDB(B1, 1, 1); PG8_SCHED; PG8_LDA(At, 1, 0); PG8_STAGE(PG8_SA(0, 1), a2 + hstep, voffA);
;             PG8_WAIT_V(8); PG8_WAIT_L(0); PG8_BAR; PG8_MMA(0, 0, At, B0); PG8_MMA(0, 1, At, B1); PG8_BAR; PG8_SCHED;
	s_waitcnt lgkmcnt(0)
	v_mfma_f32_16x16x32_bf16 v[62:65], v[146:149], v[190:193], v[62:65]
	v_mfma_f32_16x16x32_bf16 v[58:61], v[162:165], v[190:193], v[58:61]
	v_mfma_f32_16x16x32_bf16 v[46:49], v[146:149], v[198:201], v[46:49]
	v_mfma_f32_16x16x32_bf16 v[42:45], v[162:165], v[198:201], v[42:45]
	v_mfma_f32_16x16x32_bf16 v[30:33], v[146:149], v[206:209], v[30:33]
	v_mfma_f32_16x16x32_bf16 v[26:29], v[162:165], v[206:209], v[26:29]
	v_mfma_f32_16x16x32_bf16 v[14:17], v[146:149], v[214:217], v[14:17]
	v_mfma_f32_16x16x32_bf16 v[10:13], v[162:165], v[214:217], v[10:13]
	v_mfma_f32_16x16x32_bf16 v[62:65], v[158:161], v[194:197], v[62:65]
	v_mfma_f32_16x16x32_bf16 v[58:61], v[166:169], v[194:197], v[58:61]
	v_mfma_f32_16x16x32_bf16 v[46:49], v[158:161], v[202:205], v[46:49]
	v_mfma_f32_16x16x32_bf16 v[42:45], v[166:169], v[202:205], v[42:45]
	v_mfma_f32_16x16x32_bf16 v[30:33], v[158:161], v[210:213], v[30:33]
	v_mfma_f32_16x16x32_bf16 v[26:29], v[166:169], v[210:213], v[26:29]
	v_mfma_f32_16x16x32_bf16 v[14:17], v[158:161], v[218:221], v[14:17]
	v_mfma_f32_16x16x32_bf16 v[10:13], v[166:169], v[218:221], v[10:13]
	v_mfma_f32_16x16x32_bf16 v[54:57], v[174:177], v[190:193], v[54:57]
	v_mfma_f32_16x16x32_bf16 v[50:53], v[182:185], v[190:193], v[50:53]
	v_mfma_f32_16x16x32_bf16 v[38:41], v[174:177], v[198:201], v[38:41]
	v_mfma_f32_16x16x32_bf16 v[34:37], v[182:185], v[198:201], v[34:37]
	v_mfma_f32_16x16x32_bf16 v[22:25], v[174:177], v[206:209], v[22:25]
	v_mfma_f32_16x16x32_bf16 v[18:21], v[182:185], v[206:209], v[18:21]
	v_mfma_f32_16x16x32_bf16 v[6:9], v[174:177], v[214:217], v[6:9]
	v_mfma_f32_16x16x32_bf16 v[2:5], v[182:185], v[214:217], v[2:5]
	v_mfma_f32_16x16x32_bf16 v[54:57], v[178:181], v[194:197], v[54:57]
	v_mfma_f32_16x16x32_bf16 v[50:53], v[186:189], v[194:197], v[50:53]
	v_mfma_f32_16x16x32_bf16 v[38:41], v[178:181], v[202:205], v[38:41]
	v_mfma_f32_16x16x32_bf16 v[34:37], v[186:189], v[202:205], v[34:37]
	v_mfma_f32_16x16x32_bf16 v[22:25], v[178:181], v[210:213], v[22:25]
	v_mfma_f32_16x16x32_bf16 v[18:21], v[186:189], v[210:213], v[18:21]
	v_mfma_f32_16x16x32_bf16 v[6:9], v[178:181], v[218:221], v[6:9]
	v_mfma_f32_16x16x32_bf16 v[2:5], v[186:189], v[218:221], v[2:5]
	s_barrier
	s_add_i32 s69, 0, 0x18000
	v_add_u32_e32 v157, s69, v152
	s_add_i32 s70, 0, 0x1c000
	ds_read_b128 v[146:149], v157
	ds_read_b128 v[158:161], v157 offset:1024
	ds_read_b128 v[162:165], v157 offset:2048
	ds_read_b128 v[166:169], v157 offset:3072
	v_add_u32_e32 v157, s70, v152
	ds_read_b128 v[174:177], v157
	ds_read_b128 v[178:181], v157 offset:1024
	ds_read_b128 v[182:185], v157 offset:2048
	ds_read_b128 v[186:189], v157 offset:3072
	s_add_u32 s40, s40, 0x20000
	s_addc_u32 s41, s41, 0
	s_mov_b32 m0, s54
	v_lshl_add_u64 v[226:227], s[40:41], 0, v[130:131]
	ds_read_b128 v[190:193], v156 offset:32768
	ds_read_b128 v[194:197], v156 offset:33792
	ds_read_b128 v[198:201], v156 offset:34816
	ds_read_b128 v[202:205], v156 offset:35840
	ds_read_b128 v[206:209], v156 offset:36864
	ds_read_b128 v[210:213], v156 offset:37888
	ds_read_b128 v[214:217], v156 offset:38912
	ds_read_b128 v[218:221], v156 offset:39936
	global_load_lds_dwordx4 v[226:227], off
	v_lshl_add_u64 v[226:227], s[40:41], 0, v[134:135]
	s_mov_b32 m0, s55
	s_nop 0
	global_load_lds_dwordx4 v[226:227], off
	s_waitcnt vmcnt(8)
	s_waitcnt lgkmcnt(0)
	s_barrier
	s_waitcnt lgkmcnt(0)
	v_mfma_f32_16x16x32_bf16 v[126:129], v[146:149], v[190:193], v[126:129]
	v_mfma_f32_16x16x32_bf16 v[122:125], v[162:165], v[190:193], v[122:125]
	v_mfma_f32_16x16x32_bf16 v[110:113], v[146:149], v[198:201], v[110:113]
	v_mfma_f32_16x16x32_bf16 v[106:109], v[162:165], v[198:201], v[106:109]
	v_mfma_f32_16x16x32_bf16 v[94:97], v[146:149], v[206:209], v[94:97]
	v_mfma_f32_16x16x32_bf16 v[90:93], v[162:165], v[206:209], v[90:93]
	v_mfma_f32_16x16x32_bf16 v[78:81], v[146:149], v[214:217], v[78:81]
	v_mfma_f32_16x16x32_bf16 v[74:77], v[162:165], v[214:217], v[74:77]
	v_mfma_f32_16x16x32_bf16 v[126:129], v[158:161], v[194:197], v[126:129]
	v_mfma_f32_16x16x32_bf16 v[122:125], v[166:169], v[194:197], v[122:125]
	v_mfma_f32_16x16x32_bf16 v[110:113], v[158:161], v[202:205], v[110:113]
	v_mfma_f32_16x16x32_bf16 v[106:109], v[166:169], v[202:205], v[106:109]
	v_mfma_f32_16x16x32_bf16 v[94:97], v[158:161], v[210:213], v[94:97]
	v_mfma_f32_16x16x32_bf16 v[90:93], v[166:169], v[210:213], v[90:93]
	v_mfma_f32_16x16x32_bf16 v[78:81], v[158:161], v[218:221], v[78:81]
	v_mfma_f32_16x16x32_bf16 v[74:77], v[166:169], v[218:221], v[74:77]
	v_mfma_f32_16x16x32_bf16 v[118:121], v[174:177], v[190:193], v[118:121]
	v_mfma_f32_16x16x32_bf16 v[114:117], v[182:185], v[190:193], v[114:117]
	v_mfma_f32_16x16x32_bf16 v[102:105], v[174:177], v[198:201], v[102:105]
	v_mfma_f32_16x16x32_bf16 v[98:101], v[182:185], v[198:201], v[98:101]
	v_mfma_f32_16x16x32_bf16 v[86:89], v[174:177], v[206:209], v[86:89]
	v_mfma_f32_16x16x32_bf16 v[82:85], v[182:185], v[206:209], v[82:85]
	v_mfma_f32_16x16x32_bf16 v[70:73], v[174:177], v[214:217], v[70:73]
	v_mfma_f32_16x16x32_bf16 v[66:69], v[182:185], v[214:217], v[66:69]
	v_mfma_f32_16x16x32_bf16 v[118:121], v[178:181], v[194:197], v[118:121]
	v_mfma_f32_16x16x32_bf16 v[114:117], v[186:189], v[194:197], v[114:117]
	v_mfma_f32_16x16x32_bf16 v[102:105], v[178:181], v[202:205], v[102:105]
	v_mfma_f32_16x16x32_bf16 v[98:101], v[186:189], v[202:205], v[98:101]
	v_mfma_f32_16x16x32_bf16 v[86:89], v[178:181], v[210:213], v[86:89]
	v_mfma_f32_16x16x32_bf16 v[82:85], v[186:189], v[210:213], v[82:85]
	v_mfma_f32_16x16x32_bf16 v[70:73], v[178:181], v[218:221], v[70:73]
	v_mfma_f32_16x16x32_bf16 v[66:69], v[186:189], v[218:221], v[66:69]
	s_barrier
; #define PG8_STAGE(bufoff, gbase, voff) do { _Pragma("unroll") for (int _i = 0; _i < 2; ++_i) \
;         __builtin_amdgcn_global_load_lds((const unsigned*)((const char*)(gbase) + (voff)[_i]), (PG8_LAS unsigned*)(lds + (bufoff) + ldsw + _i * 8192), 16, 0, 0); } while (0)
; #define PG8_LDA(dst, b, h) do { _Pragma("unroll") for (int m = 0; m < 4; ++m) _Pragma("unroll") for (int k = 0; k < 2; ++k) dst[m][k] = *(const PG8_LAS bf16x8*)(lds + PG8_SA(b, h) + aoff + m * 2048 + k * 1024); } while (0)
; #define PG8_MMA(ai, bj, At, Bt) do { __builtin_amdgcn_s_setprio(1); _Pragma("unroll") for (int m = 0; m < 4; ++m) _Pragma("unroll") for (int n = 0; n < 2; ++n) _Pragma("unroll") for (int k = 0; k < 2; ++k) \
;         acc[ai][bj][m][n] = __builtin_amdgcn_mfma_f32_16x16x32_bf16(Bt[n][k], At[m][k], acc[ai][bj][m][n], 0, 0, 0); __builtin_amdgcn_s_setprio(0); } while (0)
; #define PG8_WAIT_V(n) asm volatile("s_waitcnt vmcnt(" #n ")" ::: "memory")
; #define PG8_WAIT_L(n) asm volatile("s_waitcnt lgkmcnt(" #n ")" ::: "memory")
; #define PG8_BAR __builtin_amdgcn_s_barrier()
; #define PG8_SCHED __builtin_amdgcn_sched_barrier(0)
; template <class Epi, class Sched, bool ALIGN_EPI = false, bool SP2 = false>
; __device__ __forceinline__ void gemm_phase(PG8_LAS unsigned char* lds, const Gemm g, const Sched& S, const Epi& E) {
;     ...
;             PG8_LDA(At, 1, 1); PG8_STAGE(PG8_SB(1, 0), b3, voffB); PG8_STAGE(PG8_SB(1, 1), b3 + hstep, voffB); PG8_STAGE(PG8_SA(1, 0), a3, voffA);
;             PG8_WAIT_V(8); PG8_WAIT_L(0); PG8_BAR; PG8_MMA(1, 0, At, B0); PG8_MMA(1, 1, At, B1); PG8_BAR; PG8_SCHED;
;     ...
;         if constexpr (ALIGN_EPI) { if (wr == 0) PG8_BAR; }
	s_add_i32 s40, s69, s52
	v_lshl_add_u64 v[150:151], v[150:151], 0, s[10:11]
	s_mov_b32 m0, s40
	ds_read_b128 v[190:193], v156 offset:49152
	ds_read_b128 v[194:197], v156 offset:50176
	ds_read_b128 v[198:201], v156 offset:51200
	ds_read_b128 v[202:205], v156 offset:52224
	ds_read_b128 v[206:209], v156 offset:53248
	ds_read_b128 v[210:213], v156 offset:54272
	ds_read_b128 v[214:217], v156 offset:55296
	ds_read_b128 v[218:221], v156 offset:56320
	global_load_lds_dwordx4 v[150:151], off
	s_add_i32 m0, s40, 0x2000
	s_add_u32 s38, s38, 0x20080
	v_lshl_add_u64 v[150:151], v[170:171], 0, s[10:11]
	s_addc_u32 s39, s39, 0
	s_add_i32 s40, s70, s52
	global_load_lds_dwordx4 v[150:151], off
	v_lshl_add_u64 v[150:151], s[38:39], 0, v[132:133]
	s_mov_b32 m0, s40
	s_nop 0
	global_load_lds_dwordx4 v[150:151], off
	v_lshl_add_u64 v[150:151], s[38:39], 0, v[136:137]
	s_add_i32 m0, s40, 0x2000
	s_nop 0
	global_load_lds_dwordx4 v[150:151], off
	v_lshl_add_u64 v[150:151], v[222:223], 0, s[10:11]
	s_mov_b32 m0, s57
	s_nop 0
	global_load_lds_dwordx4 v[150:151], off
	v_lshl_add_u64 v[150:151], v[224:225], 0, s[10:11]
	s_mov_b32 m0, s58
	s_nop 0
	global_load_lds_dwordx4 v[150:151], off
	s_waitcnt vmcnt(8)
	s_waitcnt lgkmcnt(0)
	s_barrier
	s_waitcnt lgkmcnt(0)
	v_mfma_f32_16x16x32_bf16 v[62:65], v[146:149], v[190:193], v[62:65]
	v_mfma_f32_16x16x32_bf16 v[58:61], v[162:165], v[190:193], v[58:61]
	v_mfma_f32_16x16x32_bf16 v[46:49], v[146:149], v[198:201], v[46:49]
	v_mfma_f32_16x16x32_bf16 v[42:45], v[162:165], v[198:201], v[42:45]
	v_mfma_f32_16x16x32_bf16 v[30:33], v[146:149], v[206:209], v[30:33]
	v_mfma_f32_16x16x32_bf16 v[26:29], v[162:165], v[206:209], v[26:29]
	v_mfma_f32_16x16x32_bf16 v[14:17], v[146:149], v[214:217], v[14:17]
	v_mfma_f32_16x16x32_bf16 v[10:13], v[162:165], v[214:217], v[10:13]
	v_mfma_f32_16x16x32_bf16 v[62:65], v[158:161], v[194:197], v[62:65]
	v_mfma_f32_16x16x32_bf16 v[58:61], v[166:169], v[194:197], v[58:61]
	v_mfma_f32_16x16x32_bf16 v[46:49], v[158:161], v[202:205], v[46:49]
	v_mfma_f32_16x16x32_bf16 v[42:45], v[166:169], v[202:205], v[42:45]
	v_mfma_f32_16x16x32_bf16 v[30:33], v[158:161], v[210:213], v[30:33]
	v_mfma_f32_16x16x32_bf16 v[26:29], v[166:169], v[210:213], v[26:29]
	v_mfma_f32_16x16x32_bf16 v[14:17], v[158:161], v[218:221], v[14:17]
	v_mfma_f32_16x16x32_bf16 v[10:13], v[166:169], v[218:221], v[10:13]
	v_mfma_f32_16x16x32_bf16 v[54:57], v[174:177], v[190:193], v[54:57]
	v_mfma_f32_16x16x32_bf16 v[50:53], v[182:185], v[190:193], v[50:53]
	v_mfma_f32_16x16x32_bf16 v[38:41], v[174:177], v[198:201], v[38:41]
	v_mfma_f32_16x16x32_bf16 v[34:37], v[182:185], v[198:201], v[34:37]
	v_mfma_f32_16x16x32_bf16 v[22:25], v[174:177], v[206:209], v[22:25]
	v_mfma_f32_16x16x32_bf16 v[18:21], v[182:185], v[206:209], v[18:21]
	v_mfma_f32_16x16x32_bf16 v[6:9], v[174:177], v[214:217], v[6:9]
	v_mfma_f32_16x16x32_bf16 v[2:5], v[182:185], v[214:217], v[2:5]
	v_mfma_f32_16x16x32_bf16 v[54:57], v[178:181], v[194:197], v[54:57]
	v_mfma_f32_16x16x32_bf16 v[50:53], v[186:189], v[194:197], v[50:53]
	v_mfma_f32_16x16x32_bf16 v[38:41], v[178:181], v[202:205], v[38:41]
	v_mfma_f32_16x16x32_bf16 v[34:37], v[186:189], v[202:205], v[34:37]
	v_mfma_f32_16x16x32_bf16 v[22:25], v[178:181], v[210:213], v[22:25]
	v_mfma_f32_16x16x32_bf16 v[18:21], v[186:189], v[210:213], v[18:21]
	v_mfma_f32_16x16x32_bf16 v[6:9], v[178:181], v[218:221], v[6:9]
	v_mfma_f32_16x16x32_bf16 v[2:5], v[186:189], v[218:221], v[2:5]
	s_barrier
	s_add_i32 s68, s68, 2
	s_add_u32 s34, s34, 0x100
	s_addc_u32 s35, s35, 0
	s_add_u32 s66, s66, 0x100
	s_addc_u32 s67, s67, 0
	s_cmp_gt_u32 s68, 5
	s_cbranch_scc0 .LBB0_1339
	s_and_b64 vcc, exec, s[12:13]
	s_cbranch_vccz .LBB0_1342
	s_barrier

; #define PG8_STAGE(bufoff, gbase, voff) do { _Pragma("unroll") for (int _i = 0; _i < 2; ++_i) \
;         __builtin_amdgcn_global_load_lds((const unsigned*)((const char*)(gbase) + (voff)[_i]), (PG8_LAS unsigned*)(lds + (bufoff) + ldsw + _i * 8192), 16, 0, 0); } while (0)
; #define PG8_LDA(dst, b, h) do { _Pragma("unroll") for (int m = 0; m < 4; ++m) _Pragma("unroll") for (int k = 0; k < 2; ++k) dst[m][k] = *(const PG8_LAS bf16x8*)(lds + PG8_SA(b, h) + aoff + m * 2048 + k * 1024); } while (0)
; #define PG8_LDB(dst, b, h) do { _Pragma("unroll") for (int n = 0; n < 2; ++n) _Pragma("unroll") for (int k = 0; k < 2; ++k) dst[n][k] = *(const PG8_LAS bf16x8*)(lds + PG8_SB(b, h) + boff + n * 2048 + k * 1024); } while (0)
; #define PG8_SCHED __builtin_amdgcn_sched_barrier(0)
; template <class Epi, class Sched, bool ALIGN_EPI = false, bool SP2 = false>
; __device__ __forceinline__ void gemm_phase(PG8_LAS unsigned char* lds, const Gemm g, const Sched& S, const Epi& E) {
;     ...
;         const bool has_next = S.next(ui + 1, nxt);
;         const char* nA = has_next ? (const char*)g.A + (size_t)nxt.pm * tstep : cA; const char* nB = has_next ? (const char*)g.Bt + (size_t)nxt.pn * tstep : cB;
; #pragma nounroll
;         for (int t = 0; t < nt; t += 2) {
;             const bool last = (t == nt - 2);
;             const char* a1 = cA + (size_t)(t + 1) * kstep;
;             const char* a2 = last ? nA : cA + (size_t)(t + 2) * kstep; const char* b2 = last ? nB : cB + (size_t)(t + 2) * kstep;
;             const char* a3 = a2 + kstep; const char* b3 = b2 + kstep;
;             if (last && has_next) S.a_ready(nxt);
;             if constexpr (SP2) {
;             PG8_LDB(B0, 0, 0); PG8_LDB(B1, 0, 1); PG8_SCHED; PG8_LDA(At, 0, 0); PG8_STAGE(PG8_SA(1, 1), a1 + hstep, voffA);
.LBB0_1431:
	s_ashr_i32 s21, s20, 31
	s_lshl_b64 s[22:23], s[20:21], 19
	s_add_u32 s22, s38, s22
	s_addc_u32 s23, s39, s23
	s_and_b64 s[24:25], s[2:3], exec
	s_cselect_b32 s21, s23, s29
	s_cselect_b32 s64, s22, s28
	s_ashr_i32 s19, s18, 31
	s_lshl_b64 s[24:25], s[18:19], 19
	s_add_u32 s24, s40, s24
	s_addc_u32 s25, s41, s25
	s_and_b64 s[34:35], s[2:3], exec
	s_cselect_b32 s19, s25, s31
	s_cselect_b32 s65, s24, s30
	s_add_u32 s28, s28, 0x40080
	s_addc_u32 s29, s29, 0
	s_add_u32 s66, s30, 0x100
	s_addc_u32 s67, s31, 0
	s_mov_b32 s68, -2
	ds_read_b128 v[154:157], v150
	ds_read_b128 v[158:161], v150 offset:1024
	ds_read_b128 v[162:165], v150 offset:2048
	ds_read_b128 v[166:169], v150 offset:3072
	ds_read_b128 v[174:177], v151
	ds_read_b128 v[178:181], v151 offset:1024
	ds_read_b128 v[182:185], v151 offset:2048
	ds_read_b128 v[186:189], v151 offset:3072
	s_add_u32 s30, s28, 0xfffc0080
	s_addc_u32 s31, s29, -1
	s_cmp_eq_u32 s68, 12
	s_cselect_b32 s35, s21, s31
	s_cselect_b32 s34, s64, s30
	s_cselect_b32 s31, s19, s67
	s_cselect_b32 s30, s65, s66

; #define PG8_STAGE(bufoff, gbase, voff) do { _Pragma("unroll") for (int _i = 0; _i < 2; ++_i) \
;         __builtin_amdgcn_global_load_lds((const unsigned*)((const char*)(gbase) + (voff)[_i]), (PG8_LAS unsigned*)(lds + (bufoff) + ldsw + _i * 8192), 16, 0, 0); } while (0)
; #define PG8_LDA(dst, b, h) do { _Pragma("unroll") for (int m = 0; m < 4; ++m) _Pragma("unroll") for (int k = 0; k < 2; ++k) dst[m][k] = *(const PG8_LAS bf16x8*)(lds + PG8_SA(b, h) + aoff + m * 2048 + k * 1024); } while (0)
; #define PG8_LDB(dst, b, h) do { _Pragma("unroll") for (int n = 0; n < 2; ++n) _Pragma("unroll") for (int k = 0; k < 2; ++k) dst[n][k] = *(const PG8_LAS bf16x8*)(lds + PG8_SB(b, h) + boff + n * 2048 + k * 1024); } while (0)
; #define PG8_MMA(ai, bj, At, Bt) do { __builtin_amdgcn_s_setprio(1); _Pragma("unroll") for (int m = 0; m < 4; ++m) _Pragma("unroll") for (int n = 0; n < 2; ++n) _Pragma("unroll") for (int k = 0; k < 2; ++k) \
;         acc[ai][bj][m][n] = __builtin_amdgcn_mfma_f32_16x16x32_bf16(Bt[n][k], At[m][k], acc[ai][bj][m][n], 0, 0, 0); __builtin_amdgcn_s_setprio(0); } while (0)
; #define PG8_WAIT_V(n) asm volatile("s_waitcnt vmcnt(" #n ")" ::: "memory")
; #define PG8_WAIT_L(n) asm volatile("s_waitcnt lgkmcnt(" #n ")" ::: "memory")
; #define PG8_BAR __builtin_amdgcn_s_barrier()
; #define PG8_SCHED __builtin_amdgcn_sched_barrier(0)
; template <class Epi, class Sched, bool ALIGN_EPI = false, bool SP2 = false>
; __device__ __forceinline__ void gemm_phase(PG8_LAS unsigned char* lds, const Gemm g, const Sched& S, const Epi& E) {
;     ...
;             PG8_LDB(B0, 0, 0); PG8_LDB(B1, 0, 1); PG8_SCHED; PG8_LDA(At, 0, 0); PG8_STAGE(PG8_SA(1, 1), a1 + hstep, voffA);
;             PG8_WAIT_V(8); PG8_WAIT_L(0); PG8_BAR; PG8_MMA(0, 0, At, B0); PG8_MMA(0, 1, At, B1); PG8_BAR; PG8_SCHED;
	v_lshl_add_u64 v[146:147], s[28:29], 0, v[138:139]
	s_add_i32 m0, s27, 0xc000
	ds_read_b128 v[190:193], v152
	ds_read_b128 v[194:197], v152 offset:1024
	ds_read_b128 v[198:201], v152 offset:2048
	ds_read_b128 v[202:205], v152 offset:3072
	ds_read_b128 v[206:209], v152 offset:4096
	ds_read_b128 v[210:213], v152 offset:5120
	ds_read_b128 v[214:217], v152 offset:6144
	ds_read_b128 v[218:221], v152 offset:7168
	global_load_lds_dwordx4 v[146:147], off
	v_lshl_add_u64 v[146:147], s[28:29], 0, v[140:141]
	s_add_i32 m0, s27, 0xe000
	s_nop 0
	global_load_lds_dwordx4 v[146:147], off
	s_waitcnt vmcnt(24)
	s_waitcnt lgkmcnt(0)
	s_barrier
	s_waitcnt lgkmcnt(0)
	v_mfma_f32_16x16x32_bf16 v[126:129], v[154:157], v[190:193], 0
	v_mfma_f32_16x16x32_bf16 v[122:125], v[162:165], v[190:193], 0
	v_mfma_f32_16x16x32_bf16 v[118:121], v[154:157], v[198:201], 0
	v_mfma_f32_16x16x32_bf16 v[110:113], v[162:165], v[198:201], 0
	v_mfma_f32_16x16x32_bf16 v[102:105], v[154:157], v[206:209], 0
	v_mfma_f32_16x16x32_bf16 v[94:97], v[162:165], v[206:209], 0
	v_mfma_f32_16x16x32_bf16 v[86:89], v[154:157], v[214:217], 0
	v_mfma_f32_16x16x32_bf16 v[78:81], v[162:165], v[214:217], 0
	v_mfma_f32_16x16x32_bf16 v[126:129], v[158:161], v[194:197], v[126:129]
	v_mfma_f32_16x16x32_bf16 v[122:125], v[166:169], v[194:197], v[122:125]
	v_mfma_f32_16x16x32_bf16 v[118:121], v[158:161], v[202:205], v[118:121]
	v_mfma_f32_16x16x32_bf16 v[110:113], v[166:169], v[202:205], v[110:113]
	v_mfma_f32_16x16x32_bf16 v[102:105], v[158:161], v[210:213], v[102:105]
	v_mfma_f32_16x16x32_bf16 v[94:97], v[166:169], v[210:213], v[94:97]
	v_mfma_f32_16x16x32_bf16 v[86:89], v[158:161], v[218:221], v[86:89]
	v_mfma_f32_16x16x32_bf16 v[78:81], v[166:169], v[218:221], v[78:81]
	v_mfma_f32_16x16x32_bf16 v[114:117], v[174:177], v[190:193], 0
	v_mfma_f32_16x16x32_bf16 v[106:109], v[182:185], v[190:193], 0
	v_mfma_f32_16x16x32_bf16 v[98:101], v[174:177], v[198:201], 0
	v_mfma_f32_16x16x32_bf16 v[90:93], v[182:185], v[198:201], 0
	v_mfma_f32_16x16x32_bf16 v[82:85], v[174:177], v[206:209], 0
	v_mfma_f32_16x16x32_bf16 v[74:77], v[182:185], v[206:209], 0
	v_mfma_f32_16x16x32_bf16 v[70:73], v[174:177], v[214:217], 0
	v_mfma_f32_16x16x32_bf16 v[66:69], v[182:185], v[214:217], 0
	v_mfma_f32_16x16x32_bf16 v[114:117], v[178:181], v[194:197], v[114:117]
	v_mfma_f32_16x16x32_bf16 v[106:109], v[186:189], v[194:197], v[106:109]
	v_mfma_f32_16x16x32_bf16 v[98:101], v[178:181], v[202:205], v[98:101]
	v_mfma_f32_16x16x32_bf16 v[90:93], v[186:189], v[202:205], v[90:93]
	v_mfma_f32_16x16x32_bf16 v[82:85], v[178:181], v[210:213], v[82:85]
	v_mfma_f32_16x16x32_bf16 v[74:77], v[186:189], v[210:213], v[74:77]
	v_mfma_f32_16x16x32_bf16 v[70:73], v[178:181], v[218:221], v[70:73]
	v_mfma_f32_16x16x32_bf16 v[66:69], v[186:189], v[218:221], v[66:69]
	s_barrier

; #define PG8_STAGE(bufoff, gbase, voff) do { _Pragma("unroll") for (int _i = 0; _i < 2; ++_i) \
;         __builtin_amdgcn_global_load_lds((const unsigned*)((const char*)(gbase) + (voff)[_i]), (PG8_LAS unsigned*)(lds + (bufoff) + ldsw + _i * 8192), 16, 0, 0); } while (0)
; #define PG8_LDA(dst, b, h) do { _Pragma("unroll") for (int m = 0; m < 4; ++m) _Pragma("unroll") for (int k = 0; k < 2; ++k) dst[m][k] = *(const PG8_LAS bf16x8*)(lds + PG8_SA(b, h) + aoff + m * 2048 + k * 1024); } while (0)
; #define PG8_MMA(ai, bj, At, Bt) do { __builtin_amdgcn_s_setprio(1); _Pragma("unroll") for (int m = 0; m < 4; ++m) _Pragma("unroll") for (int n = 0; n < 2; ++n) _Pragma("unroll") for (int k = 0; k < 2; ++k) \
;         acc[ai][bj][m][n] = __builtin_amdgcn_mfma_f32_16x16x32_bf16(Bt[n][k], At[m][k], acc[ai][bj][m][n], 0, 0, 0); __builtin_amdgcn_s_setprio(0); } while (0)
; #define PG8_WAIT_V(n) asm volatile("s_waitcnt vmcnt(" #n ")" ::: "memory")
; #define PG8_WAIT_L(n) asm volatile("s_waitcnt lgkmcnt(" #n ")" ::: "memory")
; #define PG8_BAR __builtin_amdgcn_s_barrier()
; #define PG8_SCHED __builtin_amdgcn_sched_barrier(0)
; template <class Epi, class Sched, bool ALIGN_EPI = false, bool SP2 = false>
; __device__ __forceinline__ void gemm_phase(PG8_LAS unsigned char* lds, const Gemm g, const Sched& S, const Epi& E) {
;     ...
;             PG8_LDA(At, 0, 1); PG8_STAGE(PG8_SB(0, 0), b2, voffB); PG8_STAGE(PG8_SB(0, 1), b2 + hstep, voffB); PG8_STAGE(PG8_SA(0, 0), a2, voffA);
;             PG8_WAIT_V(8); PG8_WAIT_L(0); PG8_BAR; PG8_MMA(1, 0, At, B0); PG8_MMA(1, 1, At, B1); PG8_BAR; PG8_SCHED;
	s_add_i32 s69, s57, s42
	v_lshl_add_u64 v[146:147], s[30:31], 0, v[132:133]
	s_mov_b32 m0, s69
	ds_read_b128 v[190:193], v152 offset:16384
	ds_read_b128 v[194:197], v152 offset:17408
	ds_read_b128 v[198:201], v152 offset:18432
	ds_read_b128 v[202:205], v152 offset:19456
	ds_read_b128 v[206:209], v152 offset:20480
	ds_read_b128 v[210:213], v152 offset:21504
	ds_read_b128 v[214:217], v152 offset:22528
	ds_read_b128 v[218:221], v152 offset:23552
	global_load_lds_dwordx4 v[146:147], off
	s_add_i32 m0, s69, 0x2000
	s_add_u32 s70, s30, 0x40000
	v_lshl_add_u64 v[170:171], s[30:31], 0, v[136:137]
	s_addc_u32 s71, s31, 0
	s_add_i32 s69, s58, s42
	global_load_lds_dwordx4 v[170:171], off
	v_lshl_add_u64 v[222:223], s[70:71], 0, v[132:133]
	s_mov_b32 m0, s69
	v_lshl_add_u64 v[224:225], s[34:35], 0, v[134:135]
	global_load_lds_dwordx4 v[222:223], off
	v_lshl_add_u64 v[222:223], s[70:71], 0, v[136:137]
	s_add_i32 m0, s69, 0x2000
	s_nop 0
	global_load_lds_dwordx4 v[222:223], off
	v_lshl_add_u64 v[222:223], s[34:35], 0, v[130:131]
	s_mov_b32 m0, s27
	s_nop 0
	global_load_lds_dwordx4 v[222:223], off
	s_mov_b32 m0, s43
	s_nop 0
	global_load_lds_dwordx4 v[224:225], off
	s_waitcnt vmcnt(24)
	s_waitcnt lgkmcnt(0)
	s_barrier
	s_waitcnt lgkmcnt(0)
	v_mfma_f32_16x16x32_bf16 v[62:65], v[154:157], v[190:193], 0
	v_mfma_f32_16x16x32_bf16 v[58:61], v[162:165], v[190:193], 0
	v_mfma_f32_16x16x32_bf16 v[54:57], v[154:157], v[198:201], 0
	v_mfma_f32_16x16x32_bf16 v[46:49], v[162:165], v[198:201], 0
	v_mfma_f32_16x16x32_bf16 v[38:41], v[154:157], v[206:209], 0
	v_mfma_f32_16x16x32_bf16 v[30:33], v[162:165], v[206:209], 0
	v_mfma_f32_16x16x32_bf16 v[22:25], v[154:157], v[214:217], 0
	v_mfma_f32_16x16x32_bf16 v[14:17], v[162:165], v[214:217], 0
	v_mfma_f32_16x16x32_bf16 v[62:65], v[158:161], v[194:197], v[62:65]
	v_mfma_f32_16x16x32_bf16 v[58:61], v[166:169], v[194:197], v[58:61]
	v_mfma_f32_16x16x32_bf16 v[54:57], v[158:161], v[202:205], v[54:57]
	v_mfma_f32_16x16x32_bf16 v[46:49], v[166:169], v[202:205], v[46:49]
	v_mfma_f32_16x16x32_bf16 v[38:41], v[158:161], v[210:213], v[38:41]
	v_mfma_f32_16x16x32_bf16 v[30:33], v[166:169], v[210:213], v[30:33]
	v_mfma_f32_16x16x32_bf16 v[22:25], v[158:161], v[218:221], v[22:25]
	v_mfma_f32_16x16x32_bf16 v[14:17], v[166:169], v[218:221], v[14:17]
	v_mfma_f32_16x16x32_bf16 v[50:53], v[174:177], v[190:193], 0
	v_mfma_f32_16x16x32_bf16 v[42:45], v[182:185], v[190:193], 0
	v_mfma_f32_16x16x32_bf16 v[34:37], v[174:177], v[198:201], 0
	v_mfma_f32_16x16x32_bf16 v[26:29], v[182:185], v[198:201], 0
	v_mfma_f32_16x16x32_bf16 v[18:21], v[174:177], v[206:209], 0
	v_mfma_f32_16x16x32_bf16 v[10:13], v[182:185], v[206:209], 0
	v_mfma_f32_16x16x32_bf16 v[6:9], v[174:177], v[214:217], 0
	v_mfma_f32_16x16x32_bf16 v[2:5], v[182:185], v[214:217], 0
	v_mfma_f32_16x16x32_bf16 v[50:53], v[178:181], v[194:197], v[50:53]
	v_mfma_f32_16x16x32_bf16 v[42:45], v[186:189], v[194:197], v[42:45]
	v_mfma_f32_16x16x32_bf16 v[34:37], v[178:181], v[202:205], v[34:37]
	v_mfma_f32_16x16x32_bf16 v[26:29], v[186:189], v[202:205], v[26:29]
	v_mfma_f32_16x16x32_bf16 v[18:21], v[178:181], v[210:213], v[18:21]
	v_mfma_f32_16x16x32_bf16 v[10:13], v[186:189], v[210:213], v[10:13]
	v_mfma_f32_16x16x32_bf16 v[6:9], v[178:181], v[218:221], v[6:9]
	v_mfma_f32_16x16x32_bf16 v[2:5], v[186:189], v[218:221], v[2:5]
	s_barrier

; #define PG8_STAGE(bufoff, gbase, voff) do { _Pragma("unroll") for (int _i = 0; _i < 2; ++_i) \
;         __builtin_amdgcn_global_load_lds((const unsigned*)((const char*)(gbase) + (voff)[_i]), (PG8_LAS unsigned*)(lds + (bufoff) + ldsw + _i * 8192), 16, 0, 0); } while (0)
; #define PG8_LDA(dst, b, h) do { _Pragma("unroll") for (int m = 0; m < 4; ++m) _Pragma("unroll") for (int k = 0; k < 2; ++k) dst[m][k] = *(const PG8_LAS bf16x8*)(lds + PG8_SA(b, h) + aoff + m * 2048 + k * 1024); } while (0)
; #define PG8_LDB(dst, b, h) do { _Pragma("unroll") for (int n = 0; n < 2; ++n) _Pragma("unroll") for (int k = 0; k < 2; ++k) dst[n][k] = *(const PG8_LAS bf16x8*)(lds + PG8_SB(b, h) + boff + n * 2048 + k * 1024); } while (0)
; #define PG8_SCHED __builtin_amdgcn_sched_barrier(0)
; template <class Epi, class Sched, bool ALIGN_EPI = false, bool SP2 = false>
; __device__ __forceinline__ void gemm_phase(PG8_LAS unsigned char* lds, const Gemm g, const Sched& S, const Epi& E) {
;     ...
;             PG8_LDB(B0, 1, 0); PG8_LDB(B1, 1, 1); PG8_SCHED; PG8_LDA(At, 1, 0); PG8_STAGE(PG8_SA(0, 1), a2 + hstep, voffA);
	s_add_i32 s69, 0, 0x18000
	v_add_u32_e32 v153, s69, v148
	s_add_i32 s70, 0, 0x1c000
	ds_read_b128 v[154:157], v153
	ds_read_b128 v[158:161], v153 offset:1024
	ds_read_b128 v[162:165], v153 offset:2048
	ds_read_b128 v[166:169], v153 offset:3072
	v_add_u32_e32 v153, s70, v148
	ds_read_b128 v[174:177], v153
	ds_read_b128 v[178:181], v153 offset:1024
	ds_read_b128 v[182:185], v153 offset:2048
	ds_read_b128 v[186:189], v153 offset:3072

; #define PG8_STAGE(bufoff, gbase, voff) do { _Pragma("unroll") for (int _i = 0; _i < 2; ++_i) \
;         __builtin_amdgcn_global_load_lds((const unsigned*)((const char*)(gbase) + (voff)[_i]), (PG8_LAS unsigned*)(lds + (bufoff) + ldsw + _i * 8192), 16, 0, 0); } while (0)
; #define PG8_LDA(dst, b, h) do { _Pragma("unroll") for (int m = 0; m < 4; ++m) _Pragma("unroll") for (int k = 0; k < 2; ++k) dst[m][k] = *(const PG8_LAS bf16x8*)(lds + PG8_SA(b, h) + aoff + m * 2048 + k * 1024); } while (0)
; #define PG8_LDB(dst, b, h) do { _Pragma("unroll") for (int n = 0; n < 2; ++n) _Pragma("unroll") for (int k = 0; k < 2; ++k) dst[n][k] = *(const PG8_LAS bf16x8*)(lds + PG8_SB(b, h) + boff + n * 2048 + k * 1024); } while (0)
; #define PG8_MMA(ai, bj, At, Bt) do { __builtin_amdgcn_s_setprio(1); _Pragma("unroll") for (int m = 0; m < 4; ++m) _Pragma("unroll") for (int n = 0; n < 2; ++n) _Pragma("unroll") for (int k = 0; k < 2; ++k) \
;         acc[ai][bj][m][n] = __builtin_amdgcn_mfma_f32_16x16x32_bf16(Bt[n][k], At[m][k], acc[ai][bj][m][n], 0, 0, 0); __builtin_amdgcn_s_setprio(0); } while (0)
; #define PG8_WAIT_V(n) asm volatile("s_waitcnt vmcnt(" #n ")" ::: "memory")
; #define PG8_WAIT_L(n) asm volatile("s_waitcnt lgkmcnt(" #n ")" ::: "memory")
; #define PG8_BAR __builtin_amdgcn_s_barrier()
; #define PG8_SCHED __builtin_amdgcn_sched_barrier(0)
; template <class Epi, class Sched, bool ALIGN_EPI = false, bool SP2 = false>
; __device__ __forceinline__ void gemm_phase(PG8_LAS unsigned char* lds, const Gemm g, const Sched& S, const Epi& E) {
;     ...
;             PG8_LDB(B0, 1, 0); PG8_LDB(B1, 1, 1); PG8_SCHED; PG8_LDA(At, 1, 0); PG8_STAGE(PG8_SA(0, 1), a2 + hstep, voffA);
;             PG8_WAIT_V(8); PG8_WAIT_L(0); PG8_BAR; PG8_MMA(0, 0, At, B0); PG8_MMA(0, 1, At, B1); PG8_BAR; PG8_SCHED;
	s_add_u32 s34, s34, 0x40000
	s_addc_u32 s35, s35, 0
	s_mov_b32 m0, s44
	v_lshl_add_u64 v[226:227], s[34:35], 0, v[130:131]
	ds_read_b128 v[190:193], v152 offset:32768
	ds_read_b128 v[194:197], v152 offset:33792
	ds_read_b128 v[198:201], v152 offset:34816
	ds_read_b128 v[202:205], v152 offset:35840
	ds_read_b128 v[206:209], v152 offset:36864
	ds_read_b128 v[210:213], v152 offset:37888
	ds_read_b128 v[214:217], v152 offset:38912
	ds_read_b128 v[218:221], v152 offset:39936
	global_load_lds_dwordx4 v[226:227], off
	v_lshl_add_u64 v[226:227], s[34:35], 0, v[134:135]
	s_mov_b32 m0, s45
	s_nop 0
	global_load_lds_dwordx4 v[226:227], off
	s_waitcnt vmcnt(8)
	s_waitcnt lgkmcnt(0)
	s_barrier
	s_waitcnt lgkmcnt(0)
	v_mfma_f32_16x16x32_bf16 v[126:129], v[154:157], v[190:193], v[126:129]
	v_mfma_f32_16x16x32_bf16 v[122:125], v[162:165], v[190:193], v[122:125]
	v_mfma_f32_16x16x32_bf16 v[118:121], v[154:157], v[198:201], v[118:121]
	v_mfma_f32_16x16x32_bf16 v[110:113], v[162:165], v[198:201], v[110:113]
	v_mfma_f32_16x16x32_bf16 v[102:105], v[154:157], v[206:209], v[102:105]
	v_mfma_f32_16x16x32_bf16 v[94:97], v[162:165], v[206:209], v[94:97]
	v_mfma_f32_16x16x32_bf16 v[86:89], v[154:157], v[214:217], v[86:89]
	v_mfma_f32_16x16x32_bf16 v[78:81], v[162:165], v[214:217], v[78:81]
	v_mfma_f32_16x16x32_bf16 v[126:129], v[158:161], v[194:197], v[126:129]
	v_mfma_f32_16x16x32_bf16 v[122:125], v[166:169], v[194:197], v[122:125]
	v_mfma_f32_16x16x32_bf16 v[118:121], v[158:161], v[202:205], v[118:121]
	v_mfma_f32_16x16x32_bf16 v[110:113], v[166:169], v[202:205], v[110:113]
	v_mfma_f32_16x16x32_bf16 v[102:105], v[158:161], v[210:213], v[102:105]
	v_mfma_f32_16x16x32_bf16 v[94:97], v[166:169], v[210:213], v[94:97]
	v_mfma_f32_16x16x32_bf16 v[86:89], v[158:161], v[218:221], v[86:89]
	v_mfma_f32_16x16x32_bf16 v[78:81], v[166:169], v[218:221], v[78:81]
	v_mfma_f32_16x16x32_bf16 v[114:117], v[174:177], v[190:193], v[114:117]
	v_mfma_f32_16x16x32_bf16 v[106:109], v[182:185], v[190:193], v[106:109]
	v_mfma_f32_16x16x32_bf16 v[98:101], v[174:177], v[198:201], v[98:101]
	v_mfma_f32_16x16x32_bf16 v[90:93], v[182:185], v[198:201], v[90:93]
	v_mfma_f32_16x16x32_bf16 v[82:85], v[174:177], v[206:209], v[82:85]
	v_mfma_f32_16x16x32_bf16 v[74:77], v[182:185], v[206:209], v[74:77]
	v_mfma_f32_16x16x32_bf16 v[70:73], v[174:177], v[214:217], v[70:73]
	v_mfma_f32_16x16x32_bf16 v[66:69], v[182:185], v[214:217], v[66:69]
	v_mfma_f32_16x16x32_bf16 v[114:117], v[178:181], v[194:197], v[114:117]
	v_mfma_f32_16x16x32_bf16 v[106:109], v[186:189], v[194:197], v[106:109]
	v_mfma_f32_16x16x32_bf16 v[98:101], v[178:181], v[202:205], v[98:101]
	v_mfma_f32_16x16x32_bf16 v[90:93], v[186:189], v[202:205], v[90:93]
	v_mfma_f32_16x16x32_bf16 v[82:85], v[178:181], v[210:213], v[82:85]
	v_mfma_f32_16x16x32_bf16 v[74:77], v[186:189], v[210:213], v[74:77]
	v_mfma_f32_16x16x32_bf16 v[70:73], v[178:181], v[218:221], v[70:73]
	v_mfma_f32_16x16x32_bf16 v[66:69], v[186:189], v[218:221], v[66:69]
	s_barrier

; #define PG8_STAGE(bufoff, gbase, voff) do { _Pragma("unroll") for (int _i = 0; _i < 2; ++_i) \
;         __builtin_amdgcn_global_load_lds((const unsigned*)((const char*)(gbase) + (voff)[_i]), (PG8_LAS unsigned*)(lds + (bufoff) + ldsw + _i * 8192), 16, 0, 0); } while (0)
; #define PG8_LDA(dst, b, h) do { _Pragma("unroll") for (int m = 0; m < 4; ++m) _Pragma("unroll") for (int k = 0; k < 2; ++k) dst[m][k] = *(const PG8_LAS bf16x8*)(lds + PG8_SA(b, h) + aoff + m * 2048 + k * 1024); } while (0)
; #define PG8_MMA(ai, bj, At, Bt) do { __builtin_amdgcn_s_setprio(1); _Pragma("unroll") for (int m = 0; m < 4; ++m) _Pragma("unroll") for (int n = 0; n < 2; ++n) _Pragma("unroll") for (int k = 0; k < 2; ++k) \
;         acc[ai][bj][m][n] = __builtin_amdgcn_mfma_f32_16x16x32_bf16(Bt[n][k], At[m][k], acc[ai][bj][m][n], 0, 0, 0); __builtin_amdgcn_s_setprio(0); } while (0)
; #define PG8_WAIT_V(n) asm volatile("s_waitcnt vmcnt(" #n ")" ::: "memory")
; #define PG8_WAIT_L(n) asm volatile("s_waitcnt lgkmcnt(" #n ")" ::: "memory")
; #define PG8_BAR __builtin_amdgcn_s_barrier()
; #define PG8_SCHED __builtin_amdgcn_sched_barrier(0)
; template <class Epi, class Sched, bool ALIGN_EPI = false, bool SP2 = false>
; __device__ __forceinline__ void gemm_phase(PG8_LAS unsigned char* lds, const Gemm g, const Sched& S, const Epi& E) {
;     ...
;             PG8_LDA(At, 1, 1); PG8_STAGE(PG8_SB(1, 0), b3, voffB); PG8_STAGE(PG8_SB(1, 1), b3 + hstep, voffB); PG8_STAGE(PG8_SA(1, 0), a3, voffA);
;             PG8_WAIT_V(8); PG8_WAIT_L(0); PG8_BAR; PG8_MMA(1, 0, At, B0); PG8_MMA(1, 1, At, B1); PG8_BAR; PG8_SCHED;
	s_add_i32 s34, s69, s42
	v_lshl_add_u64 v[146:147], v[146:147], 0, s[8:9]
	s_mov_b32 m0, s34
	ds_read_b128 v[190:193], v152 offset:49152
	ds_read_b128 v[194:197], v152 offset:50176
	ds_read_b128 v[198:201], v152 offset:51200
	ds_read_b128 v[202:205], v152 offset:52224
	ds_read_b128 v[206:209], v152 offset:53248
	ds_read_b128 v[210:213], v152 offset:54272
	ds_read_b128 v[214:217], v152 offset:55296
	ds_read_b128 v[218:221], v152 offset:56320
	global_load_lds_dwordx4 v[146:147], off
	s_add_i32 m0, s34, 0x2000
	s_add_u32 s30, s30, 0x40080
	v_lshl_add_u64 v[146:147], v[170:171], 0, s[8:9]
	s_addc_u32 s31, s31, 0
	s_add_i32 s34, s70, s42
	global_load_lds_dwordx4 v[146:147], off
	v_lshl_add_u64 v[146:147], s[30:31], 0, v[132:133]
	s_mov_b32 m0, s34
	s_nop 0
	global_load_lds_dwordx4 v[146:147], off
	v_lshl_add_u64 v[146:147], s[30:31], 0, v[136:137]
	s_add_i32 m0, s34, 0x2000
	s_nop 0
	global_load_lds_dwordx4 v[146:147], off
	v_lshl_add_u64 v[146:147], v[222:223], 0, s[8:9]
	s_mov_b32 m0, s53
	s_nop 0
	global_load_lds_dwordx4 v[146:147], off
	v_lshl_add_u64 v[146:147], v[224:225], 0, s[8:9]
	s_mov_b32 m0, s54
	s_nop 0
	global_load_lds_dwordx4 v[146:147], off
	s_waitcnt vmcnt(8)
	s_waitcnt lgkmcnt(0)
	s_barrier
	s_waitcnt lgkmcnt(0)
	v_mfma_f32_16x16x32_bf16 v[62:65], v[154:157], v[190:193], v[62:65]
	v_mfma_f32_16x16x32_bf16 v[58:61], v[162:165], v[190:193], v[58:61]
	v_mfma_f32_16x16x32_bf16 v[54:57], v[154:157], v[198:201], v[54:57]
	v_mfma_f32_16x16x32_bf16 v[46:49], v[162:165], v[198:201], v[46:49]
	v_mfma_f32_16x16x32_bf16 v[38:41], v[154:157], v[206:209], v[38:41]
	v_mfma_f32_16x16x32_bf16 v[30:33], v[162:165], v[206:209], v[30:33]
	v_mfma_f32_16x16x32_bf16 v[22:25], v[154:157], v[214:217], v[22:25]
	v_mfma_f32_16x16x32_bf16 v[14:17], v[162:165], v[214:217], v[14:17]
	v_mfma_f32_16x16x32_bf16 v[62:65], v[158:161], v[194:197], v[62:65]
	v_mfma_f32_16x16x32_bf16 v[58:61], v[166:169], v[194:197], v[58:61]
	v_mfma_f32_16x16x32_bf16 v[54:57], v[158:161], v[202:205], v[54:57]
	v_mfma_f32_16x16x32_bf16 v[46:49], v[166:169], v[202:205], v[46:49]
	v_mfma_f32_16x16x32_bf16 v[38:41], v[158:161], v[210:213], v[38:41]
	v_mfma_f32_16x16x32_bf16 v[30:33], v[166:169], v[210:213], v[30:33]
	v_mfma_f32_16x16x32_bf16 v[22:25], v[158:161], v[218:221], v[22:25]
	v_mfma_f32_16x16x32_bf16 v[14:17], v[166:169], v[218:221], v[14:17]
	v_mfma_f32_16x16x32_bf16 v[50:53], v[174:177], v[190:193], v[50:53]
	v_mfma_f32_16x16x32_bf16 v[42:45], v[182:185], v[190:193], v[42:45]
	v_mfma_f32_16x16x32_bf16 v[34:37], v[174:177], v[198:201], v[34:37]
	v_mfma_f32_16x16x32_bf16 v[26:29], v[182:185], v[198:201], v[26:29]
	v_mfma_f32_16x16x32_bf16 v[18:21], v[174:177], v[206:209], v[18:21]
	v_mfma_f32_16x16x32_bf16 v[10:13], v[182:185], v[206:209], v[10:13]
	v_mfma_f32_16x16x32_bf16 v[6:9], v[174:177], v[214:217], v[6:9]
	v_mfma_f32_16x16x32_bf16 v[2:5], v[182:185], v[214:217], v[2:5]
	v_mfma_f32_16x16x32_bf16 v[50:53], v[178:181], v[194:197], v[50:53]
	v_mfma_f32_16x16x32_bf16 v[42:45], v[186:189], v[194:197], v[42:45]
	v_mfma_f32_16x16x32_bf16 v[34:37], v[178:181], v[202:205], v[34:37]
	v_mfma_f32_16x16x32_bf16 v[26:29], v[186:189], v[202:205], v[26:29]
	v_mfma_f32_16x16x32_bf16 v[18:21], v[178:181], v[210:213], v[18:21]
	v_mfma_f32_16x16x32_bf16 v[10:13], v[186:189], v[210:213], v[10:13]
	v_mfma_f32_16x16x32_bf16 v[6:9], v[178:181], v[218:221], v[6:9]
	v_mfma_f32_16x16x32_bf16 v[2:5], v[186:189], v[218:221], v[2:5]
	s_barrier

; #define PG8_STAGE(bufoff, gbase, voff) do { _Pragma("unroll") for (int _i = 0; _i < 2; ++_i) \
;         __builtin_amdgcn_global_load_lds((const unsigned*)((const char*)(gbase) + (voff)[_i]), (PG8_LAS unsigned*)(lds + (bufoff) + ldsw + _i * 8192), 16, 0, 0); } while (0)
; #define PG8_LDA(dst, b, h) do { _Pragma("unroll") for (int m = 0; m < 4; ++m) _Pragma("unroll") for (int k = 0; k < 2; ++k) dst[m][k] = *(const PG8_LAS bf16x8*)(lds + PG8_SA(b, h) + aoff + m * 2048 + k * 1024); } while (0)
; #define PG8_LDB(dst, b, h) do { _Pragma("unroll") for (int n = 0; n < 2; ++n) _Pragma("unroll") for (int k = 0; k < 2; ++k) dst[n][k] = *(const PG8_LAS bf16x8*)(lds + PG8_SB(b, h) + boff + n * 2048 + k * 1024); } while (0)
; #define PG8_MMA(ai, bj, At, Bt) do { __builtin_amdgcn_s_setprio(1); _Pragma("unroll") for (int m = 0; m < 4; ++m) _Pragma("unroll") for (int n = 0; n < 2; ++n) _Pragma("unroll") for (int k = 0; k < 2; ++k) \
;         acc[ai][bj][m][n] = __builtin_amdgcn_mfma_f32_16x16x32_bf16(Bt[n][k], At[m][k], acc[ai][bj][m][n], 0, 0, 0); __builtin_amdgcn_s_setprio(0); } while (0)
; #define PG8_WAIT_V(n) asm volatile("s_waitcnt vmcnt(" #n ")" ::: "memory")
; #define PG8_BAR __builtin_amdgcn_s_barrier()
; template <class Epi, class Sched, bool ALIGN_EPI = false, bool SP2 = false>
; __device__ __forceinline__ void gemm_phase(PG8_LAS unsigned char* lds, const Gemm g, const Sched& S, const Epi& E) {
;     ...
;         for (int t = 0; t < nt; t += 2) {
;             const bool last = (t == nt - 2);
;             const char* a1 = cA + (size_t)(t + 1) * kstep;
;             const char* a2 = last ? nA : cA + (size_t)(t + 2) * kstep; const char* b2 = last ? nB : cB + (size_t)(t + 2) * kstep;
;             const char* a3 = a2 + kstep; const char* b3 = b2 + kstep;
;             if (last && has_next) S.a_ready(nxt);
;             if constexpr (SP2) {
;             PG8_LDB(B0, 0, 0); PG8_LDB(B1, 0, 1); PG8_SCHED; PG8_LDA(At, 0, 0); PG8_STAGE(PG8_SA(1, 1), a1 + hstep, voffA);
;             PG8_WAIT_V(8); PG8_WAIT_L(0); PG8_BAR; PG8_MMA(0, 0, At, B0); PG8_MMA(0, 1, At, B1); PG8_BAR; PG8_SCHED;
;             PG8_LDA(At, 0, 1); PG8_STAGE(PG8_SB(0, 0), b2, voffB); PG8_STAGE(PG8_SB(0, 1), b2 + hstep, voffB); PG8_STAGE(PG8_SA(0, 0), a2, voffA);
;             PG8_WAIT_V(8); PG8_WAIT_L(0); PG8_BAR; PG8_MMA(1, 0, At, B0); PG8_MMA(1, 1, At, B1); PG8_BAR; PG8_SCHED;
	s_add_i32 s68, s68, 2
	s_add_u32 s28, s28, 0x100
	s_addc_u32 s29, s29, 0
	s_add_u32 s66, s66, 0x100
	s_addc_u32 s67, s67, 0
.LBB0_1432:
	ds_read_b128 v[154:157], v150
	ds_read_b128 v[158:161], v150 offset:1024
	ds_read_b128 v[162:165], v150 offset:2048
	ds_read_b128 v[166:169], v150 offset:3072
	ds_read_b128 v[174:177], v151
	ds_read_b128 v[178:181], v151 offset:1024
	ds_read_b128 v[182:185], v151 offset:2048
	ds_read_b128 v[186:189], v151 offset:3072
	s_add_u32 s30, s28, 0xfffc0080
	s_addc_u32 s31, s29, -1
	s_cmp_eq_u32 s68, 12
	s_cselect_b32 s35, s21, s31
	s_cselect_b32 s34, s64, s30
	s_cselect_b32 s31, s19, s67
	s_cselect_b32 s30, s65, s66
	v_lshl_add_u64 v[146:147], s[28:29], 0, v[138:139]
	s_add_i32 m0, s27, 0xc000
	ds_read_b128 v[190:193], v152
	ds_read_b128 v[194:197], v152 offset:1024
	ds_read_b128 v[198:201], v152 offset:2048
	ds_read_b128 v[202:205], v152 offset:3072
	ds_read_b128 v[206:209], v152 offset:4096
	ds_read_b128 v[210:213], v152 offset:5120
	ds_read_b128 v[214:217], v152 offset:6144
	ds_read_b128 v[218:221], v152 offset:7168
	global_load_lds_dwordx4 v[146:147], off
	v_lshl_add_u64 v[146:147], s[28:29], 0, v[140:141]
	s_add_i32 m0, s27, 0xe000
	s_nop 0
	global_load_lds_dwordx4 v[146:147], off
	s_waitcnt vmcnt(8)
	s_waitcnt lgkmcnt(0)
	s_barrier
	s_waitcnt lgkmcnt(0)
	v_mfma_f32_16x16x32_bf16 v[126:129], v[154:157], v[190:193], v[126:129]
	v_mfma_f32_16x16x32_bf16 v[122:125], v[162:165], v[190:193], v[122:125]
	v_mfma_f32_16x16x32_bf16 v[118:121], v[154:157], v[198:201], v[118:121]
	v_mfma_f32_16x16x32_bf16 v[110:113], v[162:165], v[198:201], v[110:113]
	v_mfma_f32_16x16x32_bf16 v[102:105], v[154:157], v[206:209], v[102:105]
	v_mfma_f32_16x16x32_bf16 v[94:97], v[162:165], v[206:209], v[94:97]
	v_mfma_f32_16x16x32_bf16 v[86:89], v[154:157], v[214:217], v[86:89]
	v_mfma_f32_16x16x32_bf16 v[78:81], v[162:165], v[214:217], v[78:81]
	v_mfma_f32_16x16x32_bf16 v[126:129], v[158:161], v[194:197], v[126:129]
	v_mfma_f32_16x16x32_bf16 v[122:125], v[166:169], v[194:197], v[122:125]
	v_mfma_f32_16x16x32_bf16 v[118:121], v[158:161], v[202:205], v[118:121]
	v_mfma_f32_16x16x32_bf16 v[110:113], v[166:169], v[202:205], v[110:113]
	v_mfma_f32_16x16x32_bf16 v[102:105], v[158:161], v[210:213], v[102:105]
	v_mfma_f32_16x16x32_bf16 v[94:97], v[166:169], v[210:213], v[94:97]
	v_mfma_f32_16x16x32_bf16 v[86:89], v[158:161], v[218:221], v[86:89]
	v_mfma_f32_16x16x32_bf16 v[78:81], v[166:169], v[218:221], v[78:81]
	v_mfma_f32_16x16x32_bf16 v[114:117], v[174:177], v[190:193], v[114:117]
	v_mfma_f32_16x16x32_bf16 v[106:109], v[182:185], v[190:193], v[106:109]
	v_mfma_f32_16x16x32_bf16 v[98:101], v[174:177], v[198:201], v[98:101]
	v_mfma_f32_16x16x32_bf16 v[90:93], v[182:185], v[198:201], v[90:93]
	v_mfma_f32_16x16x32_bf16 v[82:85], v[174:177], v[206:209], v[82:85]
	v_mfma_f32_16x16x32_bf16 v[74:77], v[182:185], v[206:209], v[74:77]
	v_mfma_f32_16x16x32_bf16 v[70:73], v[174:177], v[214:217], v[70:73]
	v_mfma_f32_16x16x32_bf16 v[66:69], v[182:185], v[214:217], v[66:69]
	v_mfma_f32_16x16x32_bf16 v[114:117], v[178:181], v[194:197], v[114:117]
	v_mfma_f32_16x16x32_bf16 v[106:109], v[186:189], v[194:197], v[106:109]
	v_mfma_f32_16x16x32_bf16 v[98:101], v[178:181], v[202:205], v[98:101]
	v_mfma_f32_16x16x32_bf16 v[90:93], v[186:189], v[202:205], v[90:93]
	v_mfma_f32_16x16x32_bf16 v[82:85], v[178:181], v[210:213], v[82:85]
	v_mfma_f32_16x16x32_bf16 v[74:77], v[186:189], v[210:213], v[74:77]
	v_mfma_f32_16x16x32_bf16 v[70:73], v[178:181], v[218:221], v[70:73]
	v_mfma_f32_16x16x32_bf16 v[66:69], v[186:189], v[218:221], v[66:69]
	s_barrier
	s_add_i32 s69, s57, s42
	v_lshl_add_u64 v[146:147], s[30:31], 0, v[132:133]
	s_mov_b32 m0, s69
	ds_read_b128 v[190:193], v152 offset:16384
	ds_read_b128 v[194:197], v152 offset:17408
	ds_read_b128 v[198:201], v152 offset:18432
	ds_read_b128 v[202:205], v152 offset:19456
	ds_read_b128 v[206:209], v152 offset:20480
	ds_read_b128 v[210:213], v152 offset:21504
	ds_read_b128 v[214:217], v152 offset:22528
	ds_read_b128 v[218:221], v152 offset:23552
	global_load_lds_dwordx4 v[146:147], off
	s_add_i32 m0, s69, 0x2000
	s_add_u32 s70, s30, 0x40000
	v_lshl_add_u64 v[170:171], s[30:31], 0, v[136:137]
	s_addc_u32 s71, s31, 0
	s_add_i32 s69, s58, s42
	global_load_lds_dwordx4 v[170:171], off
	v_lshl_add_u64 v[222:223], s[70:71], 0, v[132:133]
	s_mov_b32 m0, s69
	v_lshl_add_u64 v[224:225], s[34:35], 0, v[134:135]
	global_load_lds_dwordx4 v[222:223], off
	v_lshl_add_u64 v[222:223], s[70:71], 0, v[136:137]
	s_add_i32 m0, s69, 0x2000
	s_nop 0
	global_load_lds_dwordx4 v[222:223], off
	v_lshl_add_u64 v[222:223], s[34:35], 0, v[130:131]
	s_mov_b32 m0, s27
	s_nop 0
	global_load_lds_dwordx4 v[222:223], off
	s_mov_b32 m0, s43
	s_nop 0
	global_load_lds_dwordx4 v[224:225], off
	s_waitcnt vmcnt(8)
	s_waitcnt lgkmcnt(0)
	s_barrier
; #define PG8_STAGE(bufoff, gbase, voff) do { _Pragma("unroll") for (int _i = 0; _i < 2; ++_i) \
;         __builtin_amdgcn_global_load_lds((const unsigned*)((const char*)(gbase) + (voff)[_i]), (PG8_LAS unsigned*)(lds + (bufoff) + ldsw + _i * 8192), 16, 0, 0); } while (0)
; #define PG8_LDA(dst, b, h) do { _Pragma("unroll") for (int m = 0; m < 4; ++m) _Pragma("unroll") for (int k = 0; k < 2; ++k) dst[m][k] = *(const PG8_LAS bf16x8*)(lds + PG8_SA(b, h) + aoff + m * 2048 + k * 1024); } while (0)
; #define PG8_LDB(dst, b, h) do { _Pragma("unroll") for (int n = 0; n < 2; ++n) _Pragma("unroll") for (int k = 0; k < 2; ++k) dst[n][k] = *(const PG8_LAS bf16x8*)(lds + PG8_SB(b, h) + boff + n * 2048 + k * 1024); } while (0)
; #define PG8_MMA(ai, bj, At, Bt) do { __builtin_amdgcn_s_setprio(1); _Pragma("unroll") for (int m = 0; m < 4; ++m) _Pragma("unroll") for (int n = 0; n < 2; ++n) _Pragma("unroll") for (int k = 0; k < 2; ++k) \
;         acc[ai][bj][m][n] = __builtin_amdgcn_mfma_f32_16x16x32_bf16(Bt[n][k], At[m][k], acc[ai][bj][m][n], 0, 0, 0); __builtin_amdgcn_s_setprio(0); } while (0)
; #define PG8_WAIT_V(n) asm volatile("s_waitcnt vmcnt(" #n ")" ::: "memory")
; #define PG8_WAIT_L(n) asm volatile("s_waitcnt lgkmcnt(" #n ")" ::: "memory")
; #define PG8_BAR __builtin_amdgcn_s_barrier()
; #define PG8_SCHED __builtin_amdgcn_sched_barrier(0)
; template <class Epi, class Sched, bool ALIGN_EPI = false, bool SP2 = false>
; __device__ __forceinline__ void gemm_phase(PG8_LAS unsigned char* lds, const Gemm g, const Sched& S, const Epi& E) {
;     ...
;             PG8_WAIT_V(8); PG8_WAIT_L(0); PG8_BAR; PG8_MMA(1, 0, At, B0); PG8_MMA(1, 1, At, B1); PG8_BAR; PG8_SCHED;
;             PG8_LDB(B0, 1, 0); PG8_LDB(B1, 1, 1); PG8_SCHED; PG8_LDA(At, 1, 0); PG8_STAGE(PG8_SA(0, 1), a2 + hstep, voffA);
;             PG8_WAIT_V(8); PG8_WAIT_L(0); PG8_BAR; PG8_MMA(0, 0, At, B0); PG8_MMA(0, 1, At, B1); PG8_BAR; PG8_SCHED;
	s_waitcnt lgkmcnt(0)
	v_mfma_f32_16x16x32_bf16 v[62:65], v[154:157], v[190:193], v[62:65]
	v_mfma_f32_16x16x32_bf16 v[58:61], v[162:165], v[190:193], v[58:61]
	v_mfma_f32_16x16x32_bf16 v[54:57], v[154:157], v[198:201], v[54:57]
	v_mfma_f32_16x16x32_bf16 v[46:49], v[162:165], v[198:201], v[46:49]
	v_mfma_f32_16x16x32_bf16 v[38:41], v[154:157], v[206:209], v[38:41]
	v_mfma_f32_16x16x32_bf16 v[30:33], v[162:165], v[206:209], v[30:33]
	v_mfma_f32_16x16x32_bf16 v[22:25], v[154:157], v[214:217], v[22:25]
	v_mfma_f32_16x16x32_bf16 v[14:17], v[162:165], v[214:217], v[14:17]
	v_mfma_f32_16x16x32_bf16 v[62:65], v[158:161], v[194:197], v[62:65]
	v_mfma_f32_16x16x32_bf16 v[58:61], v[166:169], v[194:197], v[58:61]
	v_mfma_f32_16x16x32_bf16 v[54:57], v[158:161], v[202:205], v[54:57]
	v_mfma_f32_16x16x32_bf16 v[46:49], v[166:169], v[202:205], v[46:49]
	v_mfma_f32_16x16x32_bf16 v[38:41], v[158:161], v[210:213], v[38:41]
	v_mfma_f32_16x16x32_bf16 v[30:33], v[166:169], v[210:213], v[30:33]
	v_mfma_f32_16x16x32_bf16 v[22:25], v[158:161], v[218:221], v[22:25]
	v_mfma_f32_16x16x32_bf16 v[14:17], v[166:169], v[218:221], v[14:17]
	v_mfma_f32_16x16x32_bf16 v[50:53], v[174:177], v[190:193], v[50:53]
	v_mfma_f32_16x16x32_bf16 v[42:45], v[182:185], v[190:193], v[42:45]
	v_mfma_f32_16x16x32_bf16 v[34:37], v[174:177], v[198:201], v[34:37]
	v_mfma_f32_16x16x32_bf16 v[26:29], v[182:185], v[198:201], v[26:29]
	v_mfma_f32_16x16x32_bf16 v[18:21], v[174:177], v[206:209], v[18:21]
	v_mfma_f32_16x16x32_bf16 v[10:13], v[182:185], v[206:209], v[10:13]
	v_mfma_f32_16x16x32_bf16 v[6:9], v[174:177], v[214:217], v[6:9]
	v_mfma_f32_16x16x32_bf16 v[2:5], v[182:185], v[214:217], v[2:5]
	v_mfma_f32_16x16x32_bf16 v[50:53], v[178:181], v[194:197], v[50:53]
	v_mfma_f32_16x16x32_bf16 v[42:45], v[186:189], v[194:197], v[42:45]
	v_mfma_f32_16x16x32_bf16 v[34:37], v[178:181], v[202:205], v[34:37]
	v_mfma_f32_16x16x32_bf16 v[26:29], v[186:189], v[202:205], v[26:29]
	v_mfma_f32_16x16x32_bf16 v[18:21], v[178:181], v[210:213], v[18:21]
	v_mfma_f32_16x16x32_bf16 v[10:13], v[186:189], v[210:213], v[10:13]
	v_mfma_f32_16x16x32_bf16 v[6:9], v[178:181], v[218:221], v[6:9]
	v_mfma_f32_16x16x32_bf16 v[2:5], v[186:189], v[218:221], v[2:5]
	s_barrier
	s_add_i32 s69, 0, 0x18000
	v_add_u32_e32 v153, s69, v148
	s_add_i32 s70, 0, 0x1c000
	ds_read_b128 v[154:157], v153
	ds_read_b128 v[158:161], v153 offset:1024
	ds_read_b128 v[162:165], v153 offset:2048
	ds_read_b128 v[166:169], v153 offset:3072
	v_add_u32_e32 v153, s70, v148
	ds_read_b128 v[174:177], v153
	ds_read_b128 v[178:181], v153 offset:1024
	ds_read_b128 v[182:185], v153 offset:2048
	ds_read_b128 v[186:189], v153 offset:3072
	s_add_u32 s34, s34, 0x40000
	s_addc_u32 s35, s35, 0
	s_mov_b32 m0, s44
	v_lshl_add_u64 v[226:227], s[34:35], 0, v[130:131]
	ds_read_b128 v[190:193], v152 offset:32768
	ds_read_b128 v[194:197], v152 offset:33792
	ds_read_b128 v[198:201], v152 offset:34816
	ds_read_b128 v[202:205], v152 offset:35840
	ds_read_b128 v[206:209], v152 offset:36864
	ds_read_b128 v[210:213], v152 offset:37888
	ds_read_b128 v[214:217], v152 offset:38912
	ds_read_b128 v[218:221], v152 offset:39936
	global_load_lds_dwordx4 v[226:227], off
	v_lshl_add_u64 v[226:227], s[34:35], 0, v[134:135]
	s_mov_b32 m0, s45
	s_nop 0
	global_load_lds_dwordx4 v[226:227], off
	s_waitcnt vmcnt(8)
	s_waitcnt lgkmcnt(0)
	s_barrier
	s_waitcnt lgkmcnt(0)
	v_mfma_f32_16x16x32_bf16 v[126:129], v[154:157], v[190:193], v[126:129]
	v_mfma_f32_16x16x32_bf16 v[122:125], v[162:165], v[190:193], v[122:125]
	v_mfma_f32_16x16x32_bf16 v[118:121], v[154:157], v[198:201], v[118:121]
	v_mfma_f32_16x16x32_bf16 v[110:113], v[162:165], v[198:201], v[110:113]
	v_mfma_f32_16x16x32_bf16 v[102:105], v[154:157], v[206:209], v[102:105]
	v_mfma_f32_16x16x32_bf16 v[94:97], v[162:165], v[206:209], v[94:97]
	v_mfma_f32_16x16x32_bf16 v[86:89], v[154:157], v[214:217], v[86:89]
	v_mfma_f32_16x16x32_bf16 v[78:81], v[162:165], v[214:217], v[78:81]
	v_mfma_f32_16x16x32_bf16 v[126:129], v[158:161], v[194:197], v[126:129]
	v_mfma_f32_16x16x32_bf16 v[122:125], v[166:169], v[194:197], v[122:125]
	v_mfma_f32_16x16x32_bf16 v[118:121], v[158:161], v[202:205], v[118:121]
	v_mfma_f32_16x16x32_bf16 v[110:113], v[166:169], v[202:205], v[110:113]
	v_mfma_f32_16x16x32_bf16 v[102:105], v[158:161], v[210:213], v[102:105]
	v_mfma_f32_16x16x32_bf16 v[94:97], v[166:169], v[210:213], v[94:97]
	v_mfma_f32_16x16x32_bf16 v[86:89], v[158:161], v[218:221], v[86:89]
	v_mfma_f32_16x16x32_bf16 v[78:81], v[166:169], v[218:221], v[78:81]
	v_mfma_f32_16x16x32_bf16 v[114:117], v[174:177], v[190:193], v[114:117]
	v_mfma_f32_16x16x32_bf16 v[106:109], v[182:185], v[190:193], v[106:109]
	v_mfma_f32_16x16x32_bf16 v[98:101], v[174:177], v[198:201], v[98:101]
	v_mfma_f32_16x16x32_bf16 v[90:93], v[182:185], v[198:201], v[90:93]
	v_mfma_f32_16x16x32_bf16 v[82:85], v[174:177], v[206:209], v[82:85]
	v_mfma_f32_16x16x32_bf16 v[74:77], v[182:185], v[206:209], v[74:77]
	v_mfma_f32_16x16x32_bf16 v[70:73], v[174:177], v[214:217], v[70:73]
	v_mfma_f32_16x16x32_bf16 v[66:69], v[182:185], v[214:217], v[66:69]
	v_mfma_f32_16x16x32_bf16 v[114:117], v[178:181], v[194:197], v[114:117]
	v_mfma_f32_16x16x32_bf16 v[106:109], v[186:189], v[194:197], v[106:109]
	v_mfma_f32_16x16x32_bf16 v[98:101], v[178:181], v[202:205], v[98:101]
	v_mfma_f32_16x16x32_bf16 v[90:93], v[186:189], v[202:205], v[90:93]
	v_mfma_f32_16x16x32_bf16 v[82:85], v[178:181], v[210:213], v[82:85]
	v_mfma_f32_16x16x32_bf16 v[74:77], v[186:189], v[210:213], v[74:77]
	v_mfma_f32_16x16x32_bf16 v[70:73], v[178:181], v[218:221], v[70:73]
	v_mfma_f32_16x16x32_bf16 v[66:69], v[186:189], v[218:221], v[66:69]
	s_barrier
; #define PG8_STAGE(bufoff, gbase, voff) do { _Pragma("unroll") for (int _i = 0; _i < 2; ++_i) \
;         __builtin_amdgcn_global_load_lds((const unsigned*)((const char*)(gbase) + (voff)[_i]), (PG8_LAS unsigned*)(lds + (bufoff) + ldsw + _i * 8192), 16, 0, 0); } while (0)
; #define PG8_LDA(dst, b, h) do { _Pragma("unroll") for (int m = 0; m < 4; ++m) _Pragma("unroll") for (int k = 0; k < 2; ++k) dst[m][k] = *(const PG8_LAS bf16x8*)(lds + PG8_SA(b, h) + aoff + m * 2048 + k * 1024); } while (0)
; #define PG8_MMA(ai, bj, At, Bt) do { __builtin_amdgcn_s_setprio(1); _Pragma("unroll") for (int m = 0; m < 4; ++m) _Pragma("unroll") for (int n = 0; n < 2; ++n) _Pragma("unroll") for (int k = 0; k < 2; ++k) \
;         acc[ai][bj][m][n] = __builtin_amdgcn_mfma_f32_16x16x32_bf16(Bt[n][k], At[m][k], acc[ai][bj][m][n], 0, 0, 0); __builtin_amdgcn_s_setprio(0); } while (0)
; #define PG8_WAIT_V(n) asm volatile("s_waitcnt vmcnt(" #n ")" ::: "memory")
; #define PG8_WAIT_L(n) asm volatile("s_waitcnt lgkmcnt(" #n ")" ::: "memory")
; #define PG8_BAR __builtin_amdgcn_s_barrier()
; #define PG8_SCHED __builtin_amdgcn_sched_barrier(0)
; template <class Epi, class Sched, bool ALIGN_EPI = false, bool SP2 = false>
; __device__ __forceinline__ void gemm_phase(PG8_LAS unsigned char* lds, const Gemm g, const Sched& S, const Epi& E) {
;     ...
;             PG8_LDA(At, 1, 1); PG8_STAGE(PG8_SB(1, 0), b3, voffB); PG8_STAGE(PG8_SB(1, 1), b3 + hstep, voffB); PG8_STAGE(PG8_SA(1, 0), a3, voffA);
;             PG8_WAIT_V(8); PG8_WAIT_L(0); PG8_BAR; PG8_MMA(1, 0, At, B0); PG8_MMA(1, 1, At, B1); PG8_BAR; PG8_SCHED;
;     ...
;         if constexpr (ALIGN_EPI) { if (wr == 0) PG8_BAR; }
	s_add_i32 s34, s69, s42
	v_lshl_add_u64 v[146:147], v[146:147], 0, s[8:9]
	s_mov_b32 m0, s34
	ds_read_b128 v[190:193], v152 offset:49152
	ds_read_b128 v[194:197], v152 offset:50176
	ds_read_b128 v[198:201], v152 offset:51200
	ds_read_b128 v[202:205], v152 offset:52224
	ds_read_b128 v[206:209], v152 offset:53248
	ds_read_b128 v[210:213], v152 offset:54272
	ds_read_b128 v[214:217], v152 offset:55296
	ds_read_b128 v[218:221], v152 offset:56320
	global_load_lds_dwordx4 v[146:147], off
	s_add_i32 m0, s34, 0x2000
	s_add_u32 s30, s30, 0x40080
	v_lshl_add_u64 v[146:147], v[170:171], 0, s[8:9]
	s_addc_u32 s31, s31, 0
	s_add_i32 s34, s70, s42
	global_load_lds_dwordx4 v[146:147], off
	v_lshl_add_u64 v[146:147], s[30:31], 0, v[132:133]
	s_mov_b32 m0, s34
	s_nop 0
	global_load_lds_dwordx4 v[146:147], off
	v_lshl_add_u64 v[146:147], s[30:31], 0, v[136:137]
	s_add_i32 m0, s34, 0x2000
	s_nop 0
	global_load_lds_dwordx4 v[146:147], off
	v_lshl_add_u64 v[146:147], v[222:223], 0, s[8:9]
	s_mov_b32 m0, s53
	s_nop 0
	global_load_lds_dwordx4 v[146:147], off
	v_lshl_add_u64 v[146:147], v[224:225], 0, s[8:9]
	s_mov_b32 m0, s54
	s_nop 0
	global_load_lds_dwordx4 v[146:147], off
	s_waitcnt vmcnt(8)
	s_waitcnt lgkmcnt(0)
	s_barrier
	s_waitcnt lgkmcnt(0)
	v_mfma_f32_16x16x32_bf16 v[62:65], v[154:157], v[190:193], v[62:65]
	v_mfma_f32_16x16x32_bf16 v[58:61], v[162:165], v[190:193], v[58:61]
	v_mfma_f32_16x16x32_bf16 v[54:57], v[154:157], v[198:201], v[54:57]
	v_mfma_f32_16x16x32_bf16 v[46:49], v[162:165], v[198:201], v[46:49]
	v_mfma_f32_16x16x32_bf16 v[38:41], v[154:157], v[206:209], v[38:41]
	v_mfma_f32_16x16x32_bf16 v[30:33], v[162:165], v[206:209], v[30:33]
	v_mfma_f32_16x16x32_bf16 v[22:25], v[154:157], v[214:217], v[22:25]
	v_mfma_f32_16x16x32_bf16 v[14:17], v[162:165], v[214:217], v[14:17]
	v_mfma_f32_16x16x32_bf16 v[62:65], v[158:161], v[194:197], v[62:65]
	v_mfma_f32_16x16x32_bf16 v[58:61], v[166:169], v[194:197], v[58:61]
	v_mfma_f32_16x16x32_bf16 v[54:57], v[158:161], v[202:205], v[54:57]
	v_mfma_f32_16x16x32_bf16 v[46:49], v[166:169], v[202:205], v[46:49]
	v_mfma_f32_16x16x32_bf16 v[38:41], v[158:161], v[210:213], v[38:41]
	v_mfma_f32_16x16x32_bf16 v[30:33], v[166:169], v[210:213], v[30:33]
	v_mfma_f32_16x16x32_bf16 v[22:25], v[158:161], v[218:221], v[22:25]
	v_mfma_f32_16x16x32_bf16 v[14:17], v[166:169], v[218:221], v[14:17]
	v_mfma_f32_16x16x32_bf16 v[50:53], v[174:177], v[190:193], v[50:53]
	v_mfma_f32_16x16x32_bf16 v[42:45], v[182:185], v[190:193], v[42:45]
	v_mfma_f32_16x16x32_bf16 v[34:37], v[174:177], v[198:201], v[34:37]
	v_mfma_f32_16x16x32_bf16 v[26:29], v[182:185], v[198:201], v[26:29]
	v_mfma_f32_16x16x32_bf16 v[18:21], v[174:177], v[206:209], v[18:21]
	v_mfma_f32_16x16x32_bf16 v[10:13], v[182:185], v[206:209], v[10:13]
	v_mfma_f32_16x16x32_bf16 v[6:9], v[174:177], v[214:217], v[6:9]
	v_mfma_f32_16x16x32_bf16 v[2:5], v[182:185], v[214:217], v[2:5]
	v_mfma_f32_16x16x32_bf16 v[50:53], v[178:181], v[194:197], v[50:53]
	v_mfma_f32_16x16x32_bf16 v[42:45], v[186:189], v[194:197], v[42:45]
	v_mfma_f32_16x16x32_bf16 v[34:37], v[178:181], v[202:205], v[34:37]
	v_mfma_f32_16x16x32_bf16 v[26:29], v[186:189], v[202:205], v[26:29]
	v_mfma_f32_16x16x32_bf16 v[18:21], v[178:181], v[210:213], v[18:21]
	v_mfma_f32_16x16x32_bf16 v[10:13], v[186:189], v[210:213], v[10:13]
	v_mfma_f32_16x16x32_bf16 v[6:9], v[178:181], v[218:221], v[6:9]
	v_mfma_f32_16x16x32_bf16 v[2:5], v[186:189], v[218:221], v[2:5]
	s_barrier
	s_add_i32 s68, s68, 2
	s_add_u32 s28, s28, 0x100
	s_addc_u32 s29, s29, 0
	s_add_u32 s66, s66, 0x100
	s_addc_u32 s67, s67, 0
	s_cmp_gt_u32 s68, 13
	s_cbranch_scc0 .LBB0_1432
	s_and_b64 vcc, exec, s[10:11]
	s_cbranch_vccz .LBB0_1435
	s_barrier

; #define PG8_STAGE(bufoff, gbase, voff) do { _Pragma("unroll") for (int _i = 0; _i < 2; ++_i) \
;         __builtin_amdgcn_global_load_lds((const unsigned*)((const char*)(gbase) + (voff)[_i]), (PG8_LAS unsigned*)(lds + (bufoff) + ldsw + _i * 8192), 16, 0, 0); } while (0)
; #define PG8_LDA(dst, b, h) do { _Pragma("unroll") for (int m = 0; m < 4; ++m) _Pragma("unroll") for (int k = 0; k < 2; ++k) dst[m][k] = *(const PG8_LAS bf16x8*)(lds + PG8_SA(b, h) + aoff + m * 2048 + k * 1024); } while (0)
; #define PG8_LDB(dst, b, h) do { _Pragma("unroll") for (int n = 0; n < 2; ++n) _Pragma("unroll") for (int k = 0; k < 2; ++k) dst[n][k] = *(const PG8_LAS bf16x8*)(lds + PG8_SB(b, h) + boff + n * 2048 + k * 1024); } while (0)
; #define PG8_SCHED __builtin_amdgcn_sched_barrier(0)
; template <class Epi, class Sched, bool ALIGN_EPI = false, bool SP2 = false>
; __device__ __forceinline__ void gemm_phase(PG8_LAS unsigned char* lds, const Gemm g, const Sched& S, const Epi& E) {
;     ...
;         const bool has_next = S.next(ui + 1, nxt);
;         const char* nA = has_next ? (const char*)g.A + (size_t)nxt.pm * tstep : cA; const char* nB = has_next ? (const char*)g.Bt + (size_t)nxt.pn * tstep : cB;
; #pragma nounroll
;         for (int t = 0; t < nt; t += 2) {
;             const bool last = (t == nt - 2);
;             const char* a1 = cA + (size_t)(t + 1) * kstep;
;             const char* a2 = last ? nA : cA + (size_t)(t + 2) * kstep; const char* b2 = last ? nB : cB + (size_t)(t + 2) * kstep;
;             const char* a3 = a2 + kstep; const char* b3 = b2 + kstep;
;             if (last && has_next) S.a_ready(nxt);
;             if constexpr (SP2) {
;             PG8_LDB(B0, 0, 0); PG8_LDB(B1, 0, 1); PG8_SCHED; PG8_LDA(At, 0, 0); PG8_STAGE(PG8_SA(1, 1), a1 + hstep, voffA);
.LBB0_1590:
	s_ashr_i32 s13, s12, 31
	s_lshl_b64 s[14:15], s[12:13], 19
	s_add_u32 s14, s26, s14
	s_addc_u32 s15, s27, s15
	s_and_b64 s[16:17], s[2:3], exec
	s_cselect_b32 s13, s15, s21
	s_cselect_b32 s52, s14, s20
	s_ashr_i32 s11, s10, 31
	s_lshl_b64 s[16:17], s[10:11], 19
	s_add_u32 s16, s28, s16
	s_addc_u32 s17, s29, s17
	s_and_b64 s[24:25], s[2:3], exec
	s_cselect_b32 s11, s17, s23
	s_cselect_b32 s53, s16, s22
	s_add_u32 s20, s20, 0x40080
	s_addc_u32 s21, s21, 0
	s_add_u32 s54, s22, 0x100
	s_addc_u32 s55, s23, 0
	s_mov_b32 s56, -2
	ds_read_b128 v[152:155], v149
	ds_read_b128 v[156:159], v149 offset:1024
	ds_read_b128 v[160:163], v149 offset:2048
	ds_read_b128 v[164:167], v149 offset:3072
	ds_read_b128 v[168:171], v150
	ds_read_b128 v[174:177], v150 offset:1024
	ds_read_b128 v[178:181], v150 offset:2048
	ds_read_b128 v[182:185], v150 offset:3072
	s_add_u32 s22, s20, 0xfffc0080
	s_addc_u32 s23, s21, -1
	s_cmp_eq_u32 s56, 12
	s_cselect_b32 s25, s13, s23
	s_cselect_b32 s24, s52, s22
	s_cselect_b32 s23, s11, s55
	s_cselect_b32 s22, s53, s54

; #define PG8_STAGE(bufoff, gbase, voff) do { _Pragma("unroll") for (int _i = 0; _i < 2; ++_i) \
;         __builtin_amdgcn_global_load_lds((const unsigned*)((const char*)(gbase) + (voff)[_i]), (PG8_LAS unsigned*)(lds + (bufoff) + ldsw + _i * 8192), 16, 0, 0); } while (0)
; #define PG8_LDA(dst, b, h) do { _Pragma("unroll") for (int m = 0; m < 4; ++m) _Pragma("unroll") for (int k = 0; k < 2; ++k) dst[m][k] = *(const PG8_LAS bf16x8*)(lds + PG8_SA(b, h) + aoff + m * 2048 + k * 1024); } while (0)
; #define PG8_LDB(dst, b, h) do { _Pragma("unroll") for (int n = 0; n < 2; ++n) _Pragma("unroll") for (int k = 0; k < 2; ++k) dst[n][k] = *(const PG8_LAS bf16x8*)(lds + PG8_SB(b, h) + boff + n * 2048 + k * 1024); } while (0)
; #define PG8_MMA(ai, bj, At, Bt) do { __builtin_amdgcn_s_setprio(1); _Pragma("unroll") for (int m = 0; m < 4; ++m) _Pragma("unroll") for (int n = 0; n < 2; ++n) _Pragma("unroll") for (int k = 0; k < 2; ++k) \
;         acc[ai][bj][m][n] = __builtin_amdgcn_mfma_f32_16x16x32_bf16(Bt[n][k], At[m][k], acc[ai][bj][m][n], 0, 0, 0); __builtin_amdgcn_s_setprio(0); } while (0)
; #define PG8_WAIT_V(n) asm volatile("s_waitcnt vmcnt(" #n ")" ::: "memory")
; #define PG8_WAIT_L(n) asm volatile("s_waitcnt lgkmcnt(" #n ")" ::: "memory")
; #define PG8_BAR __builtin_amdgcn_s_barrier()
; #define PG8_SCHED __builtin_amdgcn_sched_barrier(0)
; template <class Epi, class Sched, bool ALIGN_EPI = false, bool SP2 = false>
; __device__ __forceinline__ void gemm_phase(PG8_LAS unsigned char* lds, const Gemm g, const Sched& S, const Epi& E) {
;     ...
;             PG8_LDB(B0, 0, 0); PG8_LDB(B1, 0, 1); PG8_SCHED; PG8_LDA(At, 0, 0); PG8_STAGE(PG8_SA(1, 1), a1 + hstep, voffA);
;             PG8_WAIT_V(8); PG8_WAIT_L(0); PG8_BAR; PG8_MMA(0, 0, At, B0); PG8_MMA(0, 1, At, B1); PG8_BAR; PG8_SCHED;
	v_lshl_add_u64 v[218:219], s[20:21], 0, v[140:141]
	s_add_i32 m0, s34, 0xc000
	ds_read_b128 v[186:189], v151
	ds_read_b128 v[190:193], v151 offset:1024
	ds_read_b128 v[194:197], v151 offset:2048
	ds_read_b128 v[198:201], v151 offset:3072
	ds_read_b128 v[202:205], v151 offset:4096
	ds_read_b128 v[206:209], v151 offset:5120
	ds_read_b128 v[210:213], v151 offset:6144
	ds_read_b128 v[214:217], v151 offset:7168
	global_load_lds_dwordx4 v[218:219], off
	v_lshl_add_u64 v[218:219], s[20:21], 0, v[142:143]
	s_add_i32 m0, s34, 0xe000
	s_nop 0
	global_load_lds_dwordx4 v[218:219], off
	s_waitcnt vmcnt(16)
	s_waitcnt lgkmcnt(0)
	s_barrier
	s_waitcnt lgkmcnt(0)
	v_mfma_f32_16x16x32_bf16 v[126:129], v[152:155], v[186:189], 0
	v_mfma_f32_16x16x32_bf16 v[122:125], v[160:163], v[186:189], 0
	v_mfma_f32_16x16x32_bf16 v[110:113], v[152:155], v[194:197], 0
	v_mfma_f32_16x16x32_bf16 v[106:109], v[160:163], v[194:197], 0
	v_mfma_f32_16x16x32_bf16 v[94:97], v[152:155], v[202:205], 0
	v_mfma_f32_16x16x32_bf16 v[90:93], v[160:163], v[202:205], 0
	v_mfma_f32_16x16x32_bf16 v[78:81], v[152:155], v[210:213], 0
	v_mfma_f32_16x16x32_bf16 v[74:77], v[160:163], v[210:213], 0
	v_mfma_f32_16x16x32_bf16 v[126:129], v[156:159], v[190:193], v[126:129]
	v_mfma_f32_16x16x32_bf16 v[122:125], v[164:167], v[190:193], v[122:125]
	v_mfma_f32_16x16x32_bf16 v[110:113], v[156:159], v[198:201], v[110:113]
	v_mfma_f32_16x16x32_bf16 v[106:109], v[164:167], v[198:201], v[106:109]
	v_mfma_f32_16x16x32_bf16 v[94:97], v[156:159], v[206:209], v[94:97]
	v_mfma_f32_16x16x32_bf16 v[90:93], v[164:167], v[206:209], v[90:93]
	v_mfma_f32_16x16x32_bf16 v[78:81], v[156:159], v[214:217], v[78:81]
	v_mfma_f32_16x16x32_bf16 v[74:77], v[164:167], v[214:217], v[74:77]
	v_mfma_f32_16x16x32_bf16 v[118:121], v[168:171], v[186:189], 0
	v_mfma_f32_16x16x32_bf16 v[114:117], v[178:181], v[186:189], 0
	v_mfma_f32_16x16x32_bf16 v[102:105], v[168:171], v[194:197], 0
	v_mfma_f32_16x16x32_bf16 v[98:101], v[178:181], v[194:197], 0
	v_mfma_f32_16x16x32_bf16 v[86:89], v[168:171], v[202:205], 0
	v_mfma_f32_16x16x32_bf16 v[82:85], v[178:181], v[202:205], 0
	v_mfma_f32_16x16x32_bf16 v[70:73], v[168:171], v[210:213], 0
	v_mfma_f32_16x16x32_bf16 v[66:69], v[178:181], v[210:213], 0
	v_mfma_f32_16x16x32_bf16 v[118:121], v[174:177], v[190:193], v[118:121]
	v_mfma_f32_16x16x32_bf16 v[114:117], v[182:185], v[190:193], v[114:117]
	v_mfma_f32_16x16x32_bf16 v[102:105], v[174:177], v[198:201], v[102:105]
	v_mfma_f32_16x16x32_bf16 v[98:101], v[182:185], v[198:201], v[98:101]
	v_mfma_f32_16x16x32_bf16 v[86:89], v[174:177], v[206:209], v[86:89]
	v_mfma_f32_16x16x32_bf16 v[82:85], v[182:185], v[206:209], v[82:85]
	v_mfma_f32_16x16x32_bf16 v[70:73], v[174:177], v[214:217], v[70:73]
	v_mfma_f32_16x16x32_bf16 v[66:69], v[182:185], v[214:217], v[66:69]
	s_barrier

; #define PG8_STAGE(bufoff, gbase, voff) do { _Pragma("unroll") for (int _i = 0; _i < 2; ++_i) \
;         __builtin_amdgcn_global_load_lds((const unsigned*)((const char*)(gbase) + (voff)[_i]), (PG8_LAS unsigned*)(lds + (bufoff) + ldsw + _i * 8192), 16, 0, 0); } while (0)
; #define PG8_LDA(dst, b, h) do { _Pragma("unroll") for (int m = 0; m < 4; ++m) _Pragma("unroll") for (int k = 0; k < 2; ++k) dst[m][k] = *(const PG8_LAS bf16x8*)(lds + PG8_SA(b, h) + aoff + m * 2048 + k * 1024); } while (0)
; #define PG8_MMA(ai, bj, At, Bt) do { __builtin_amdgcn_s_setprio(1); _Pragma("unroll") for (int m = 0; m < 4; ++m) _Pragma("unroll") for (int n = 0; n < 2; ++n) _Pragma("unroll") for (int k = 0; k < 2; ++k) \
;         acc[ai][bj][m][n] = __builtin_amdgcn_mfma_f32_16x16x32_bf16(Bt[n][k], At[m][k], acc[ai][bj][m][n], 0, 0, 0); __builtin_amdgcn_s_setprio(0); } while (0)
; #define PG8_WAIT_V(n) asm volatile("s_waitcnt vmcnt(" #n ")" ::: "memory")
; #define PG8_WAIT_L(n) asm volatile("s_waitcnt lgkmcnt(" #n ")" ::: "memory")
; #define PG8_BAR __builtin_amdgcn_s_barrier()
; #define PG8_SCHED __builtin_amdgcn_sched_barrier(0)
; template <class Epi, class Sched, bool ALIGN_EPI = false, bool SP2 = false>
; __device__ __forceinline__ void gemm_phase(PG8_LAS unsigned char* lds, const Gemm g, const Sched& S, const Epi& E) {
;     ...
;             PG8_LDA(At, 0, 1); PG8_STAGE(PG8_SB(0, 0), b2, voffB); PG8_STAGE(PG8_SB(0, 1), b2 + hstep, voffB); PG8_STAGE(PG8_SA(0, 0), a2, voffA);
;             PG8_WAIT_V(8); PG8_WAIT_L(0); PG8_BAR; PG8_MMA(1, 0, At, B0); PG8_MMA(1, 1, At, B1); PG8_BAR; PG8_SCHED;
	s_add_i32 s57, s45, s30
	v_lshl_add_u64 v[218:219], s[22:23], 0, v[134:135]
	s_mov_b32 m0, s57
	ds_read_b128 v[186:189], v151 offset:16384
	ds_read_b128 v[190:193], v151 offset:17408
	ds_read_b128 v[194:197], v151 offset:18432
	ds_read_b128 v[198:201], v151 offset:19456
	ds_read_b128 v[202:205], v151 offset:20480
	ds_read_b128 v[206:209], v151 offset:21504
	ds_read_b128 v[210:213], v151 offset:22528
	ds_read_b128 v[214:217], v151 offset:23552
	global_load_lds_dwordx4 v[218:219], off
	s_add_i32 m0, s57, 0x2000
	s_add_u32 s58, s22, 0x40000
	v_lshl_add_u64 v[220:221], s[22:23], 0, v[130:131]
	s_addc_u32 s59, s23, 0
	s_add_i32 s57, s48, s30
	global_load_lds_dwordx4 v[220:221], off
	v_lshl_add_u64 v[222:223], s[58:59], 0, v[134:135]
	s_mov_b32 m0, s57
	v_lshl_add_u64 v[224:225], s[24:25], 0, v[132:133]
	global_load_lds_dwordx4 v[222:223], off
	v_lshl_add_u64 v[222:223], s[58:59], 0, v[130:131]
	s_add_i32 m0, s57, 0x2000
	s_nop 0
	global_load_lds_dwordx4 v[222:223], off
	v_lshl_add_u64 v[222:223], s[24:25], 0, v[136:137]
	s_mov_b32 m0, s34
	s_nop 0
	global_load_lds_dwordx4 v[222:223], off
	s_mov_b32 m0, s35
	s_nop 0
	global_load_lds_dwordx4 v[224:225], off
	s_waitcnt vmcnt(16)
	s_waitcnt lgkmcnt(0)
	s_barrier
	s_waitcnt lgkmcnt(0)
	v_mfma_f32_16x16x32_bf16 v[62:65], v[152:155], v[186:189], 0
	v_mfma_f32_16x16x32_bf16 v[58:61], v[160:163], v[186:189], 0
	v_mfma_f32_16x16x32_bf16 v[46:49], v[152:155], v[194:197], 0
	v_mfma_f32_16x16x32_bf16 v[42:45], v[160:163], v[194:197], 0
	v_mfma_f32_16x16x32_bf16 v[30:33], v[152:155], v[202:205], 0
	v_mfma_f32_16x16x32_bf16 v[26:29], v[160:163], v[202:205], 0
	v_mfma_f32_16x16x32_bf16 v[14:17], v[152:155], v[210:213], 0
	v_mfma_f32_16x16x32_bf16 v[10:13], v[160:163], v[210:213], 0
	v_mfma_f32_16x16x32_bf16 v[62:65], v[156:159], v[190:193], v[62:65]
	v_mfma_f32_16x16x32_bf16 v[58:61], v[164:167], v[190:193], v[58:61]
	v_mfma_f32_16x16x32_bf16 v[46:49], v[156:159], v[198:201], v[46:49]
	v_mfma_f32_16x16x32_bf16 v[42:45], v[164:167], v[198:201], v[42:45]
	v_mfma_f32_16x16x32_bf16 v[30:33], v[156:159], v[206:209], v[30:33]
	v_mfma_f32_16x16x32_bf16 v[26:29], v[164:167], v[206:209], v[26:29]
	v_mfma_f32_16x16x32_bf16 v[14:17], v[156:159], v[214:217], v[14:17]
	v_mfma_f32_16x16x32_bf16 v[10:13], v[164:167], v[214:217], v[10:13]
	v_mfma_f32_16x16x32_bf16 v[54:57], v[168:171], v[186:189], 0
	v_mfma_f32_16x16x32_bf16 v[50:53], v[178:181], v[186:189], 0
	v_mfma_f32_16x16x32_bf16 v[38:41], v[168:171], v[194:197], 0
	v_mfma_f32_16x16x32_bf16 v[34:37], v[178:181], v[194:197], 0
	v_mfma_f32_16x16x32_bf16 v[22:25], v[168:171], v[202:205], 0
	v_mfma_f32_16x16x32_bf16 v[18:21], v[178:181], v[202:205], 0
	v_mfma_f32_16x16x32_bf16 v[6:9], v[168:171], v[210:213], 0
	v_mfma_f32_16x16x32_bf16 v[2:5], v[178:181], v[210:213], 0
	v_mfma_f32_16x16x32_bf16 v[54:57], v[174:177], v[190:193], v[54:57]
	v_mfma_f32_16x16x32_bf16 v[50:53], v[182:185], v[190:193], v[50:53]
	v_mfma_f32_16x16x32_bf16 v[38:41], v[174:177], v[198:201], v[38:41]
	v_mfma_f32_16x16x32_bf16 v[34:37], v[182:185], v[198:201], v[34:37]
	v_mfma_f32_16x16x32_bf16 v[22:25], v[174:177], v[206:209], v[22:25]
	v_mfma_f32_16x16x32_bf16 v[18:21], v[182:185], v[206:209], v[18:21]
	v_mfma_f32_16x16x32_bf16 v[6:9], v[174:177], v[214:217], v[6:9]
	v_mfma_f32_16x16x32_bf16 v[2:5], v[182:185], v[214:217], v[2:5]
	s_barrier

; #define PG8_STAGE(bufoff, gbase, voff) do { _Pragma("unroll") for (int _i = 0; _i < 2; ++_i) \
;         __builtin_amdgcn_global_load_lds((const unsigned*)((const char*)(gbase) + (voff)[_i]), (PG8_LAS unsigned*)(lds + (bufoff) + ldsw + _i * 8192), 16, 0, 0); } while (0)
; #define PG8_LDA(dst, b, h) do { _Pragma("unroll") for (int m = 0; m < 4; ++m) _Pragma("unroll") for (int k = 0; k < 2; ++k) dst[m][k] = *(const PG8_LAS bf16x8*)(lds + PG8_SA(b, h) + aoff + m * 2048 + k * 1024); } while (0)
; #define PG8_LDB(dst, b, h) do { _Pragma("unroll") for (int n = 0; n < 2; ++n) _Pragma("unroll") for (int k = 0; k < 2; ++k) dst[n][k] = *(const PG8_LAS bf16x8*)(lds + PG8_SB(b, h) + boff + n * 2048 + k * 1024); } while (0)
; #define PG8_SCHED __builtin_amdgcn_sched_barrier(0)
; template <class Epi, class Sched, bool ALIGN_EPI = false, bool SP2 = false>
; __device__ __forceinline__ void gemm_phase(PG8_LAS unsigned char* lds, const Gemm g, const Sched& S, const Epi& E) {
;     ...
;             PG8_LDB(B0, 1, 0); PG8_LDB(B1, 1, 1); PG8_SCHED; PG8_LDA(At, 1, 0); PG8_STAGE(PG8_SA(0, 1), a2 + hstep, voffA);
	s_add_i32 s57, 0, 0x18000
	s_add_i32 s58, 0, 0x1c000
	v_add_u32_e32 v164, s57, v148
	v_add_u32_e32 v182, s58, v148
	ds_read_b128 v[152:155], v164
	ds_read_b128 v[156:159], v164 offset:1024
	ds_read_b128 v[160:163], v164 offset:2048
	ds_read_b128 v[164:167], v164 offset:3072
	ds_read_b128 v[168:171], v182
	ds_read_b128 v[174:177], v182 offset:1024
	ds_read_b128 v[178:181], v182 offset:2048
	ds_read_b128 v[182:185], v182 offset:3072

; #define PG8_STAGE(bufoff, gbase, voff) do { _Pragma("unroll") for (int _i = 0; _i < 2; ++_i) \
;         __builtin_amdgcn_global_load_lds((const unsigned*)((const char*)(gbase) + (voff)[_i]), (PG8_LAS unsigned*)(lds + (bufoff) + ldsw + _i * 8192), 16, 0, 0); } while (0)
; #define PG8_LDA(dst, b, h) do { _Pragma("unroll") for (int m = 0; m < 4; ++m) _Pragma("unroll") for (int k = 0; k < 2; ++k) dst[m][k] = *(const PG8_LAS bf16x8*)(lds + PG8_SA(b, h) + aoff + m * 2048 + k * 1024); } while (0)
; #define PG8_LDB(dst, b, h) do { _Pragma("unroll") for (int n = 0; n < 2; ++n) _Pragma("unroll") for (int k = 0; k < 2; ++k) dst[n][k] = *(const PG8_LAS bf16x8*)(lds + PG8_SB(b, h) + boff + n * 2048 + k * 1024); } while (0)
; #define PG8_MMA(ai, bj, At, Bt) do { __builtin_amdgcn_s_setprio(1); _Pragma("unroll") for (int m = 0; m < 4; ++m) _Pragma("unroll") for (int n = 0; n < 2; ++n) _Pragma("unroll") for (int k = 0; k < 2; ++k) \
;         acc[ai][bj][m][n] = __builtin_amdgcn_mfma_f32_16x16x32_bf16(Bt[n][k], At[m][k], acc[ai][bj][m][n], 0, 0, 0); __builtin_amdgcn_s_setprio(0); } while (0)
; #define PG8_WAIT_V(n) asm volatile("s_waitcnt vmcnt(" #n ")" ::: "memory")
; #define PG8_WAIT_L(n) asm volatile("s_waitcnt lgkmcnt(" #n ")" ::: "memory")
; #define PG8_BAR __builtin_amdgcn_s_barrier()
; #define PG8_SCHED __builtin_amdgcn_sched_barrier(0)
; template <class Epi, class Sched, bool ALIGN_EPI = false, bool SP2 = false>
; __device__ __forceinline__ void gemm_phase(PG8_LAS unsigned char* lds, const Gemm g, const Sched& S, const Epi& E) {
;     ...
;             PG8_LDB(B0, 1, 0); PG8_LDB(B1, 1, 1); PG8_SCHED; PG8_LDA(At, 1, 0); PG8_STAGE(PG8_SA(0, 1), a2 + hstep, voffA);
;             PG8_WAIT_V(8); PG8_WAIT_L(0); PG8_BAR; PG8_MMA(0, 0, At, B0); PG8_MMA(0, 1, At, B1); PG8_BAR; PG8_SCHED;
	s_add_u32 s24, s24, 0x40000
	s_addc_u32 s25, s25, 0
	s_mov_b32 m0, s38
	v_lshl_add_u64 v[226:227], s[24:25], 0, v[136:137]
	ds_read_b128 v[186:189], v151 offset:32768
	ds_read_b128 v[190:193], v151 offset:33792
	ds_read_b128 v[194:197], v151 offset:34816
	ds_read_b128 v[198:201], v151 offset:35840
	ds_read_b128 v[202:205], v151 offset:36864
	ds_read_b128 v[206:209], v151 offset:37888
	ds_read_b128 v[210:213], v151 offset:38912
	ds_read_b128 v[214:217], v151 offset:39936
	global_load_lds_dwordx4 v[226:227], off
	v_lshl_add_u64 v[226:227], s[24:25], 0, v[132:133]
	s_mov_b32 m0, s39
	s_nop 0
	global_load_lds_dwordx4 v[226:227], off
	s_waitcnt vmcnt(8)
	s_waitcnt lgkmcnt(0)
	s_barrier
	s_waitcnt lgkmcnt(0)
	v_mfma_f32_16x16x32_bf16 v[126:129], v[152:155], v[186:189], v[126:129]
	v_mfma_f32_16x16x32_bf16 v[122:125], v[160:163], v[186:189], v[122:125]
	v_mfma_f32_16x16x32_bf16 v[110:113], v[152:155], v[194:197], v[110:113]
	v_mfma_f32_16x16x32_bf16 v[106:109], v[160:163], v[194:197], v[106:109]
	v_mfma_f32_16x16x32_bf16 v[94:97], v[152:155], v[202:205], v[94:97]
	v_mfma_f32_16x16x32_bf16 v[90:93], v[160:163], v[202:205], v[90:93]
	v_mfma_f32_16x16x32_bf16 v[78:81], v[152:155], v[210:213], v[78:81]
	v_mfma_f32_16x16x32_bf16 v[74:77], v[160:163], v[210:213], v[74:77]
	v_mfma_f32_16x16x32_bf16 v[126:129], v[156:159], v[190:193], v[126:129]
	v_mfma_f32_16x16x32_bf16 v[122:125], v[164:167], v[190:193], v[122:125]
	v_mfma_f32_16x16x32_bf16 v[110:113], v[156:159], v[198:201], v[110:113]
	v_mfma_f32_16x16x32_bf16 v[106:109], v[164:167], v[198:201], v[106:109]
	v_mfma_f32_16x16x32_bf16 v[94:97], v[156:159], v[206:209], v[94:97]
	v_mfma_f32_16x16x32_bf16 v[90:93], v[164:167], v[206:209], v[90:93]
	v_mfma_f32_16x16x32_bf16 v[78:81], v[156:159], v[214:217], v[78:81]
	v_mfma_f32_16x16x32_bf16 v[74:77], v[164:167], v[214:217], v[74:77]
	v_mfma_f32_16x16x32_bf16 v[118:121], v[168:171], v[186:189], v[118:121]
	v_mfma_f32_16x16x32_bf16 v[114:117], v[178:181], v[186:189], v[114:117]
	v_mfma_f32_16x16x32_bf16 v[102:105], v[168:171], v[194:197], v[102:105]
	v_mfma_f32_16x16x32_bf16 v[98:101], v[178:181], v[194:197], v[98:101]
	v_mfma_f32_16x16x32_bf16 v[86:89], v[168:171], v[202:205], v[86:89]
	v_mfma_f32_16x16x32_bf16 v[82:85], v[178:181], v[202:205], v[82:85]
	v_mfma_f32_16x16x32_bf16 v[70:73], v[168:171], v[210:213], v[70:73]
	v_mfma_f32_16x16x32_bf16 v[66:69], v[178:181], v[210:213], v[66:69]
	v_mfma_f32_16x16x32_bf16 v[118:121], v[174:177], v[190:193], v[118:121]
	v_mfma_f32_16x16x32_bf16 v[114:117], v[182:185], v[190:193], v[114:117]
	v_mfma_f32_16x16x32_bf16 v[102:105], v[174:177], v[198:201], v[102:105]
	v_mfma_f32_16x16x32_bf16 v[98:101], v[182:185], v[198:201], v[98:101]
	v_mfma_f32_16x16x32_bf16 v[86:89], v[174:177], v[206:209], v[86:89]
	v_mfma_f32_16x16x32_bf16 v[82:85], v[182:185], v[206:209], v[82:85]
	v_mfma_f32_16x16x32_bf16 v[70:73], v[174:177], v[214:217], v[70:73]
	v_mfma_f32_16x16x32_bf16 v[66:69], v[182:185], v[214:217], v[66:69]
	s_barrier

; #define PG8_STAGE(bufoff, gbase, voff) do { _Pragma("unroll") for (int _i = 0; _i < 2; ++_i) \
;         __builtin_amdgcn_global_load_lds((const unsigned*)((const char*)(gbase) + (voff)[_i]), (PG8_LAS unsigned*)(lds + (bufoff) + ldsw + _i * 8192), 16, 0, 0); } while (0)
; #define PG8_LDA(dst, b, h) do { _Pragma("unroll") for (int m = 0; m < 4; ++m) _Pragma("unroll") for (int k = 0; k < 2; ++k) dst[m][k] = *(const PG8_LAS bf16x8*)(lds + PG8_SA(b, h) + aoff + m * 2048 + k * 1024); } while (0)
; #define PG8_MMA(ai, bj, At, Bt) do { __builtin_amdgcn_s_setprio(1); _Pragma("unroll") for (int m = 0; m < 4; ++m) _Pragma("unroll") for (int n = 0; n < 2; ++n) _Pragma("unroll") for (int k = 0; k < 2; ++k) \
;         acc[ai][bj][m][n] = __builtin_amdgcn_mfma_f32_16x16x32_bf16(Bt[n][k], At[m][k], acc[ai][bj][m][n], 0, 0, 0); __builtin_amdgcn_s_setprio(0); } while (0)
; #define PG8_WAIT_V(n) asm volatile("s_waitcnt vmcnt(" #n ")" ::: "memory")
; #define PG8_WAIT_L(n) asm volatile("s_waitcnt lgkmcnt(" #n ")" ::: "memory")
; #define PG8_BAR __builtin_amdgcn_s_barrier()
; #define PG8_SCHED __builtin_amdgcn_sched_barrier(0)
; template <class Epi, class Sched, bool ALIGN_EPI = false, bool SP2 = false>
; __device__ __forceinline__ void gemm_phase(PG8_LAS unsigned char* lds, const Gemm g, const Sched& S, const Epi& E) {
;     ...
;             PG8_LDA(At, 1, 1); PG8_STAGE(PG8_SB(1, 0), b3, voffB); PG8_STAGE(PG8_SB(1, 1), b3 + hstep, voffB); PG8_STAGE(PG8_SA(1, 0), a3, voffA);
;             PG8_WAIT_V(8); PG8_WAIT_L(0); PG8_BAR; PG8_MMA(1, 0, At, B0); PG8_MMA(1, 1, At, B1); PG8_BAR; PG8_SCHED;
	s_add_i32 s24, s57, s30
	v_lshl_add_u64 v[218:219], v[218:219], 0, s[6:7]
	s_mov_b32 m0, s24
	ds_read_b128 v[186:189], v151 offset:49152
	ds_read_b128 v[190:193], v151 offset:50176
	ds_read_b128 v[194:197], v151 offset:51200
	ds_read_b128 v[198:201], v151 offset:52224
	ds_read_b128 v[202:205], v151 offset:53248
	ds_read_b128 v[206:209], v151 offset:54272
	ds_read_b128 v[210:213], v151 offset:55296
	ds_read_b128 v[214:217], v151 offset:56320
	global_load_lds_dwordx4 v[218:219], off
	s_add_i32 m0, s24, 0x2000
	s_add_u32 s22, s22, 0x40080
	v_lshl_add_u64 v[218:219], v[220:221], 0, s[6:7]
	s_addc_u32 s23, s23, 0
	s_add_i32 s24, s58, s30
	global_load_lds_dwordx4 v[218:219], off
	v_lshl_add_u64 v[218:219], s[22:23], 0, v[134:135]
	s_mov_b32 m0, s24
	s_nop 0
	global_load_lds_dwordx4 v[218:219], off
	v_lshl_add_u64 v[218:219], s[22:23], 0, v[130:131]
	s_add_i32 m0, s24, 0x2000
	s_nop 0
	global_load_lds_dwordx4 v[218:219], off
	v_lshl_add_u64 v[218:219], v[222:223], 0, s[6:7]
	s_mov_b32 m0, s41
	s_nop 0
	global_load_lds_dwordx4 v[218:219], off
	v_lshl_add_u64 v[218:219], v[224:225], 0, s[6:7]
	s_mov_b32 m0, s42
	s_nop 0
	global_load_lds_dwordx4 v[218:219], off
	s_waitcnt vmcnt(8)
	s_waitcnt lgkmcnt(0)
	s_barrier
	s_waitcnt lgkmcnt(0)
	v_mfma_f32_16x16x32_bf16 v[62:65], v[152:155], v[186:189], v[62:65]
	v_mfma_f32_16x16x32_bf16 v[58:61], v[160:163], v[186:189], v[58:61]
	v_mfma_f32_16x16x32_bf16 v[46:49], v[152:155], v[194:197], v[46:49]
	v_mfma_f32_16x16x32_bf16 v[42:45], v[160:163], v[194:197], v[42:45]
	v_mfma_f32_16x16x32_bf16 v[30:33], v[152:155], v[202:205], v[30:33]
	v_mfma_f32_16x16x32_bf16 v[26:29], v[160:163], v[202:205], v[26:29]
	v_mfma_f32_16x16x32_bf16 v[14:17], v[152:155], v[210:213], v[14:17]
	v_mfma_f32_16x16x32_bf16 v[10:13], v[160:163], v[210:213], v[10:13]
	v_mfma_f32_16x16x32_bf16 v[62:65], v[156:159], v[190:193], v[62:65]
	v_mfma_f32_16x16x32_bf16 v[58:61], v[164:167], v[190:193], v[58:61]
	v_mfma_f32_16x16x32_bf16 v[46:49], v[156:159], v[198:201], v[46:49]
	v_mfma_f32_16x16x32_bf16 v[42:45], v[164:167], v[198:201], v[42:45]
	v_mfma_f32_16x16x32_bf16 v[30:33], v[156:159], v[206:209], v[30:33]
	v_mfma_f32_16x16x32_bf16 v[26:29], v[164:167], v[206:209], v[26:29]
	v_mfma_f32_16x16x32_bf16 v[14:17], v[156:159], v[214:217], v[14:17]
	v_mfma_f32_16x16x32_bf16 v[10:13], v[164:167], v[214:217], v[10:13]
	v_mfma_f32_16x16x32_bf16 v[54:57], v[168:171], v[186:189], v[54:57]
	v_mfma_f32_16x16x32_bf16 v[50:53], v[178:181], v[186:189], v[50:53]
	v_mfma_f32_16x16x32_bf16 v[38:41], v[168:171], v[194:197], v[38:41]
	v_mfma_f32_16x16x32_bf16 v[34:37], v[178:181], v[194:197], v[34:37]
	v_mfma_f32_16x16x32_bf16 v[22:25], v[168:171], v[202:205], v[22:25]
	v_mfma_f32_16x16x32_bf16 v[18:21], v[178:181], v[202:205], v[18:21]
	v_mfma_f32_16x16x32_bf16 v[6:9], v[168:171], v[210:213], v[6:9]
	v_mfma_f32_16x16x32_bf16 v[2:5], v[178:181], v[210:213], v[2:5]
	v_mfma_f32_16x16x32_bf16 v[54:57], v[174:177], v[190:193], v[54:57]
	v_mfma_f32_16x16x32_bf16 v[50:53], v[182:185], v[190:193], v[50:53]
	v_mfma_f32_16x16x32_bf16 v[38:41], v[174:177], v[198:201], v[38:41]
	v_mfma_f32_16x16x32_bf16 v[34:37], v[182:185], v[198:201], v[34:37]
	v_mfma_f32_16x16x32_bf16 v[22:25], v[174:177], v[206:209], v[22:25]
	v_mfma_f32_16x16x32_bf16 v[18:21], v[182:185], v[206:209], v[18:21]
	v_mfma_f32_16x16x32_bf16 v[6:9], v[174:177], v[214:217], v[6:9]
	v_mfma_f32_16x16x32_bf16 v[2:5], v[182:185], v[214:217], v[2:5]
	s_barrier

; #define PG8_STAGE(bufoff, gbase, voff) do { _Pragma("unroll") for (int _i = 0; _i < 2; ++_i) \
;         __builtin_amdgcn_global_load_lds((const unsigned*)((const char*)(gbase) + (voff)[_i]), (PG8_LAS unsigned*)(lds + (bufoff) + ldsw + _i * 8192), 16, 0, 0); } while (0)
; #define PG8_LDA(dst, b, h) do { _Pragma("unroll") for (int m = 0; m < 4; ++m) _Pragma("unroll") for (int k = 0; k < 2; ++k) dst[m][k] = *(const PG8_LAS bf16x8*)(lds + PG8_SA(b, h) + aoff + m * 2048 + k * 1024); } while (0)
; #define PG8_LDB(dst, b, h) do { _Pragma("unroll") for (int n = 0; n < 2; ++n) _Pragma("unroll") for (int k = 0; k < 2; ++k) dst[n][k] = *(const PG8_LAS bf16x8*)(lds + PG8_SB(b, h) + boff + n * 2048 + k * 1024); } while (0)
; #define PG8_MMA(ai, bj, At, Bt) do { __builtin_amdgcn_s_setprio(1); _Pragma("unroll") for (int m = 0; m < 4; ++m) _Pragma("unroll") for (int n = 0; n < 2; ++n) _Pragma("unroll") for (int k = 0; k < 2; ++k) \
;         acc[ai][bj][m][n] = __builtin_amdgcn_mfma_f32_16x16x32_bf16(Bt[n][k], At[m][k], acc[ai][bj][m][n], 0, 0, 0); __builtin_amdgcn_s_setprio(0); } while (0)
; #define PG8_WAIT_V(n) asm volatile("s_waitcnt vmcnt(" #n ")" ::: "memory")
; #define PG8_BAR __builtin_amdgcn_s_barrier()
; template <class Epi, class Sched, bool ALIGN_EPI = false, bool SP2 = false>
; __device__ __forceinline__ void gemm_phase(PG8_LAS unsigned char* lds, const Gemm g, const Sched& S, const Epi& E) {
;     ...
;         for (int t = 0; t < nt; t += 2) {
;             const bool last = (t == nt - 2);
;             const char* a1 = cA + (size_t)(t + 1) * kstep;
;             const char* a2 = last ? nA : cA + (size_t)(t + 2) * kstep; const char* b2 = last ? nB : cB + (size_t)(t + 2) * kstep;
;             const char* a3 = a2 + kstep; const char* b3 = b2 + kstep;
;             if (last && has_next) S.a_ready(nxt);
;             if constexpr (SP2) {
;             PG8_LDB(B0, 0, 0); PG8_LDB(B1, 0, 1); PG8_SCHED; PG8_LDA(At, 0, 0); PG8_STAGE(PG8_SA(1, 1), a1 + hstep, voffA);
;             PG8_WAIT_V(8); PG8_WAIT_L(0); PG8_BAR; PG8_MMA(0, 0, At, B0); PG8_MMA(0, 1, At, B1); PG8_BAR; PG8_SCHED;
;             PG8_LDA(At, 0, 1); PG8_STAGE(PG8_SB(0, 0), b2, voffB); PG8_STAGE(PG8_SB(0, 1), b2 + hstep, voffB); PG8_STAGE(PG8_SA(0, 0), a2, voffA);
;             PG8_WAIT_V(8); PG8_WAIT_L(0); PG8_BAR; PG8_MMA(1, 0, At, B0); PG8_MMA(1, 1, At, B1); PG8_BAR; PG8_SCHED;
	s_add_i32 s56, s56, 2
	s_add_u32 s20, s20, 0x100
	s_addc_u32 s21, s21, 0
	s_add_u32 s54, s54, 0x100
	s_addc_u32 s55, s55, 0
.LBB0_1591:
	ds_read_b128 v[152:155], v149
	ds_read_b128 v[156:159], v149 offset:1024
	ds_read_b128 v[160:163], v149 offset:2048
	ds_read_b128 v[164:167], v149 offset:3072
	ds_read_b128 v[168:171], v150
	ds_read_b128 v[174:177], v150 offset:1024
	ds_read_b128 v[178:181], v150 offset:2048
	ds_read_b128 v[182:185], v150 offset:3072
	s_add_u32 s22, s20, 0xfffc0080
	s_addc_u32 s23, s21, -1
	s_cmp_eq_u32 s56, 12
	s_cselect_b32 s25, s13, s23
	s_cselect_b32 s24, s52, s22
	s_cselect_b32 s23, s11, s55
	s_cselect_b32 s22, s53, s54
	v_lshl_add_u64 v[218:219], s[20:21], 0, v[140:141]
	s_add_i32 m0, s34, 0xc000
	ds_read_b128 v[186:189], v151
	ds_read_b128 v[190:193], v151 offset:1024
	ds_read_b128 v[194:197], v151 offset:2048
	ds_read_b128 v[198:201], v151 offset:3072
	ds_read_b128 v[202:205], v151 offset:4096
	ds_read_b128 v[206:209], v151 offset:5120
	ds_read_b128 v[210:213], v151 offset:6144
	ds_read_b128 v[214:217], v151 offset:7168
	global_load_lds_dwordx4 v[218:219], off
	v_lshl_add_u64 v[218:219], s[20:21], 0, v[142:143]
	s_add_i32 m0, s34, 0xe000
	s_nop 0
	global_load_lds_dwordx4 v[218:219], off
	s_waitcnt vmcnt(8)
	s_waitcnt lgkmcnt(0)
	s_barrier
	s_waitcnt lgkmcnt(0)
	v_mfma_f32_16x16x32_bf16 v[126:129], v[152:155], v[186:189], v[126:129]
	v_mfma_f32_16x16x32_bf16 v[122:125], v[160:163], v[186:189], v[122:125]
	v_mfma_f32_16x16x32_bf16 v[110:113], v[152:155], v[194:197], v[110:113]
	v_mfma_f32_16x16x32_bf16 v[106:109], v[160:163], v[194:197], v[106:109]
	v_mfma_f32_16x16x32_bf16 v[94:97], v[152:155], v[202:205], v[94:97]
	v_mfma_f32_16x16x32_bf16 v[90:93], v[160:163], v[202:205], v[90:93]
	v_mfma_f32_16x16x32_bf16 v[78:81], v[152:155], v[210:213], v[78:81]
	v_mfma_f32_16x16x32_bf16 v[74:77], v[160:163], v[210:213], v[74:77]
	v_mfma_f32_16x16x32_bf16 v[126:129], v[156:159], v[190:193], v[126:129]
	v_mfma_f32_16x16x32_bf16 v[122:125], v[164:167], v[190:193], v[122:125]
	v_mfma_f32_16x16x32_bf16 v[110:113], v[156:159], v[198:201], v[110:113]
	v_mfma_f32_16x16x32_bf16 v[106:109], v[164:167], v[198:201], v[106:109]
	v_mfma_f32_16x16x32_bf16 v[94:97], v[156:159], v[206:209], v[94:97]
	v_mfma_f32_16x16x32_bf16 v[90:93], v[164:167], v[206:209], v[90:93]
	v_mfma_f32_16x16x32_bf16 v[78:81], v[156:159], v[214:217], v[78:81]
	v_mfma_f32_16x16x32_bf16 v[74:77], v[164:167], v[214:217], v[74:77]
	v_mfma_f32_16x16x32_bf16 v[118:121], v[168:171], v[186:189], v[118:121]
	v_mfma_f32_16x16x32_bf16 v[114:117], v[178:181], v[186:189], v[114:117]
	v_mfma_f32_16x16x32_bf16 v[102:105], v[168:171], v[194:197], v[102:105]
	v_mfma_f32_16x16x32_bf16 v[98:101], v[178:181], v[194:197], v[98:101]
	v_mfma_f32_16x16x32_bf16 v[86:89], v[168:171], v[202:205], v[86:89]
	v_mfma_f32_16x16x32_bf16 v[82:85], v[178:181], v[202:205], v[82:85]
	v_mfma_f32_16x16x32_bf16 v[70:73], v[168:171], v[210:213], v[70:73]
	v_mfma_f32_16x16x32_bf16 v[66:69], v[178:181], v[210:213], v[66:69]
	v_mfma_f32_16x16x32_bf16 v[118:121], v[174:177], v[190:193], v[118:121]
	v_mfma_f32_16x16x32_bf16 v[114:117], v[182:185], v[190:193], v[114:117]
	v_mfma_f32_16x16x32_bf16 v[102:105], v[174:177], v[198:201], v[102:105]
	v_mfma_f32_16x16x32_bf16 v[98:101], v[182:185], v[198:201], v[98:101]
	v_mfma_f32_16x16x32_bf16 v[86:89], v[174:177], v[206:209], v[86:89]
	v_mfma_f32_16x16x32_bf16 v[82:85], v[182:185], v[206:209], v[82:85]
	v_mfma_f32_16x16x32_bf16 v[70:73], v[174:177], v[214:217], v[70:73]
	v_mfma_f32_16x16x32_bf16 v[66:69], v[182:185], v[214:217], v[66:69]
	s_barrier
	s_add_i32 s57, s45, s30
	v_lshl_add_u64 v[218:219], s[22:23], 0, v[134:135]
	s_mov_b32 m0, s57
	ds_read_b128 v[186:189], v151 offset:16384
	ds_read_b128 v[190:193], v151 offset:17408
	ds_read_b128 v[194:197], v151 offset:18432
	ds_read_b128 v[198:201], v151 offset:19456
	ds_read_b128 v[202:205], v151 offset:20480
	ds_read_b128 v[206:209], v151 offset:21504
	ds_read_b128 v[210:213], v151 offset:22528
	ds_read_b128 v[214:217], v151 offset:23552
	global_load_lds_dwordx4 v[218:219], off
	s_add_i32 m0, s57, 0x2000
	s_add_u32 s58, s22, 0x40000
	v_lshl_add_u64 v[220:221], s[22:23], 0, v[130:131]
	s_addc_u32 s59, s23, 0
	s_add_i32 s57, s48, s30
	global_load_lds_dwordx4 v[220:221], off
	v_lshl_add_u64 v[222:223], s[58:59], 0, v[134:135]
	s_mov_b32 m0, s57
	v_lshl_add_u64 v[224:225], s[24:25], 0, v[132:133]
	global_load_lds_dwordx4 v[222:223], off
	v_lshl_add_u64 v[222:223], s[58:59], 0, v[130:131]
	s_add_i32 m0, s57, 0x2000
	s_nop 0
	global_load_lds_dwordx4 v[222:223], off
	v_lshl_add_u64 v[222:223], s[24:25], 0, v[136:137]
	s_mov_b32 m0, s34
	s_nop 0
	global_load_lds_dwordx4 v[222:223], off
	s_mov_b32 m0, s35
	s_nop 0
	global_load_lds_dwordx4 v[224:225], off
	s_waitcnt vmcnt(8)
	s_waitcnt lgkmcnt(0)
	s_barrier
; #define PG8_STAGE(bufoff, gbase, voff) do { _Pragma("unroll") for (int _i = 0; _i < 2; ++_i) \
;         __builtin_amdgcn_global_load_lds((const unsigned*)((const char*)(gbase) + (voff)[_i]), (PG8_LAS unsigned*)(lds + (bufoff) + ldsw + _i * 8192), 16, 0, 0); } while (0)
; #define PG8_LDA(dst, b, h) do { _Pragma("unroll") for (int m = 0; m < 4; ++m) _Pragma("unroll") for (int k = 0; k < 2; ++k) dst[m][k] = *(const PG8_LAS bf16x8*)(lds + PG8_SA(b, h) + aoff + m * 2048 + k * 1024); } while (0)
; #define PG8_LDB(dst, b, h) do { _Pragma("unroll") for (int n = 0; n < 2; ++n) _Pragma("unroll") for (int k = 0; k < 2; ++k) dst[n][k] = *(const PG8_LAS bf16x8*)(lds + PG8_SB(b, h) + boff + n * 2048 + k * 1024); } while (0)
; #define PG8_MMA(ai, bj, At, Bt) do { __builtin_amdgcn_s_setprio(1); _Pragma("unroll") for (int m = 0; m < 4; ++m) _Pragma("unroll") for (int n = 0; n < 2; ++n) _Pragma("unroll") for (int k = 0; k < 2; ++k) \
;         acc[ai][bj][m][n] = __builtin_amdgcn_mfma_f32_16x16x32_bf16(Bt[n][k], At[m][k], acc[ai][bj][m][n], 0, 0, 0); __builtin_amdgcn_s_setprio(0); } while (0)
; #define PG8_WAIT_V(n) asm volatile("s_waitcnt vmcnt(" #n ")" ::: "memory")
; #define PG8_WAIT_L(n) asm volatile("s_waitcnt lgkmcnt(" #n ")" ::: "memory")
; #define PG8_BAR __builtin_amdgcn_s_barrier()
; #define PG8_SCHED __builtin_amdgcn_sched_barrier(0)
; template <class Epi, class Sched, bool ALIGN_EPI = false, bool SP2 = false>
; __device__ __forceinline__ void gemm_phase(PG8_LAS unsigned char* lds, const Gemm g, const Sched& S, const Epi& E) {
;     ...
;             PG8_WAIT_V(8); PG8_WAIT_L(0); PG8_BAR; PG8_MMA(1, 0, At, B0); PG8_MMA(1, 1, At, B1); PG8_BAR; PG8_SCHED;
;             PG8_LDB(B0, 1, 0); PG8_LDB(B1, 1, 1); PG8_SCHED; PG8_LDA(At, 1, 0); PG8_STAGE(PG8_SA(0, 1), a2 + hstep, voffA);
;             PG8_WAIT_V(8); PG8_WAIT_L(0); PG8_BAR; PG8_MMA(0, 0, At, B0); PG8_MMA(0, 1, At, B1); PG8_BAR; PG8_SCHED;
	s_waitcnt lgkmcnt(0)
	v_mfma_f32_16x16x32_bf16 v[62:65], v[152:155], v[186:189], v[62:65]
	v_mfma_f32_16x16x32_bf16 v[58:61], v[160:163], v[186:189], v[58:61]
	v_mfma_f32_16x16x32_bf16 v[46:49], v[152:155], v[194:197], v[46:49]
	v_mfma_f32_16x16x32_bf16 v[42:45], v[160:163], v[194:197], v[42:45]
	v_mfma_f32_16x16x32_bf16 v[30:33], v[152:155], v[202:205], v[30:33]
	v_mfma_f32_16x16x32_bf16 v[26:29], v[160:163], v[202:205], v[26:29]
	v_mfma_f32_16x16x32_bf16 v[14:17], v[152:155], v[210:213], v[14:17]
	v_mfma_f32_16x16x32_bf16 v[10:13], v[160:163], v[210:213], v[10:13]
	v_mfma_f32_16x16x32_bf16 v[62:65], v[156:159], v[190:193], v[62:65]
	v_mfma_f32_16x16x32_bf16 v[58:61], v[164:167], v[190:193], v[58:61]
	v_mfma_f32_16x16x32_bf16 v[46:49], v[156:159], v[198:201], v[46:49]
	v_mfma_f32_16x16x32_bf16 v[42:45], v[164:167], v[198:201], v[42:45]
	v_mfma_f32_16x16x32_bf16 v[30:33], v[156:159], v[206:209], v[30:33]
	v_mfma_f32_16x16x32_bf16 v[26:29], v[164:167], v[206:209], v[26:29]
	v_mfma_f32_16x16x32_bf16 v[14:17], v[156:159], v[214:217], v[14:17]
	v_mfma_f32_16x16x32_bf16 v[10:13], v[164:167], v[214:217], v[10:13]
	v_mfma_f32_16x16x32_bf16 v[54:57], v[168:171], v[186:189], v[54:57]
	v_mfma_f32_16x16x32_bf16 v[50:53], v[178:181], v[186:189], v[50:53]
	v_mfma_f32_16x16x32_bf16 v[38:41], v[168:171], v[194:197], v[38:41]
	v_mfma_f32_16x16x32_bf16 v[34:37], v[178:181], v[194:197], v[34:37]
	v_mfma_f32_16x16x32_bf16 v[22:25], v[168:171], v[202:205], v[22:25]
	v_mfma_f32_16x16x32_bf16 v[18:21], v[178:181], v[202:205], v[18:21]
	v_mfma_f32_16x16x32_bf16 v[6:9], v[168:171], v[210:213], v[6:9]
	v_mfma_f32_16x16x32_bf16 v[2:5], v[178:181], v[210:213], v[2:5]
	v_mfma_f32_16x16x32_bf16 v[54:57], v[174:177], v[190:193], v[54:57]
	v_mfma_f32_16x16x32_bf16 v[50:53], v[182:185], v[190:193], v[50:53]
	v_mfma_f32_16x16x32_bf16 v[38:41], v[174:177], v[198:201], v[38:41]
	v_mfma_f32_16x16x32_bf16 v[34:37], v[182:185], v[198:201], v[34:37]
	v_mfma_f32_16x16x32_bf16 v[22:25], v[174:177], v[206:209], v[22:25]
	v_mfma_f32_16x16x32_bf16 v[18:21], v[182:185], v[206:209], v[18:21]
	v_mfma_f32_16x16x32_bf16 v[6:9], v[174:177], v[214:217], v[6:9]
	v_mfma_f32_16x16x32_bf16 v[2:5], v[182:185], v[214:217], v[2:5]
	s_barrier
	s_add_i32 s57, 0, 0x18000
	s_add_i32 s58, 0, 0x1c000
	v_add_u32_e32 v164, s57, v148
	v_add_u32_e32 v182, s58, v148
	ds_read_b128 v[152:155], v164
	ds_read_b128 v[156:159], v164 offset:1024
	ds_read_b128 v[160:163], v164 offset:2048
	ds_read_b128 v[164:167], v164 offset:3072
	ds_read_b128 v[168:171], v182
	ds_read_b128 v[174:177], v182 offset:1024
	ds_read_b128 v[178:181], v182 offset:2048
	ds_read_b128 v[182:185], v182 offset:3072
	s_add_u32 s24, s24, 0x40000
	s_addc_u32 s25, s25, 0
	s_mov_b32 m0, s38
	v_lshl_add_u64 v[226:227], s[24:25], 0, v[136:137]
	ds_read_b128 v[186:189], v151 offset:32768
	ds_read_b128 v[190:193], v151 offset:33792
	ds_read_b128 v[194:197], v151 offset:34816
	ds_read_b128 v[198:201], v151 offset:35840
	ds_read_b128 v[202:205], v151 offset:36864
	ds_read_b128 v[206:209], v151 offset:37888
	ds_read_b128 v[210:213], v151 offset:38912
	ds_read_b128 v[214:217], v151 offset:39936
	global_load_lds_dwordx4 v[226:227], off
	v_lshl_add_u64 v[226:227], s[24:25], 0, v[132:133]
	s_mov_b32 m0, s39
	s_nop 0
	global_load_lds_dwordx4 v[226:227], off
	s_waitcnt vmcnt(8)
	s_waitcnt lgkmcnt(0)
	s_barrier
	s_waitcnt lgkmcnt(0)
	v_mfma_f32_16x16x32_bf16 v[126:129], v[152:155], v[186:189], v[126:129]
	v_mfma_f32_16x16x32_bf16 v[122:125], v[160:163], v[186:189], v[122:125]
	v_mfma_f32_16x16x32_bf16 v[110:113], v[152:155], v[194:197], v[110:113]
	v_mfma_f32_16x16x32_bf16 v[106:109], v[160:163], v[194:197], v[106:109]
	v_mfma_f32_16x16x32_bf16 v[94:97], v[152:155], v[202:205], v[94:97]
	v_mfma_f32_16x16x32_bf16 v[90:93], v[160:163], v[202:205], v[90:93]
	v_mfma_f32_16x16x32_bf16 v[78:81], v[152:155], v[210:213], v[78:81]
	v_mfma_f32_16x16x32_bf16 v[74:77], v[160:163], v[210:213], v[74:77]
	v_mfma_f32_16x16x32_bf16 v[126:129], v[156:159], v[190:193], v[126:129]
	v_mfma_f32_16x16x32_bf16 v[122:125], v[164:167], v[190:193], v[122:125]
	v_mfma_f32_16x16x32_bf16 v[110:113], v[156:159], v[198:201], v[110:113]
	v_mfma_f32_16x16x32_bf16 v[106:109], v[164:167], v[198:201], v[106:109]
	v_mfma_f32_16x16x32_bf16 v[94:97], v[156:159], v[206:209], v[94:97]
	v_mfma_f32_16x16x32_bf16 v[90:93], v[164:167], v[206:209], v[90:93]
	v_mfma_f32_16x16x32_bf16 v[78:81], v[156:159], v[214:217], v[78:81]
	v_mfma_f32_16x16x32_bf16 v[74:77], v[164:167], v[214:217], v[74:77]
	v_mfma_f32_16x16x32_bf16 v[118:121], v[168:171], v[186:189], v[118:121]
	v_mfma_f32_16x16x32_bf16 v[114:117], v[178:181], v[186:189], v[114:117]
	v_mfma_f32_16x16x32_bf16 v[102:105], v[168:171], v[194:197], v[102:105]
	v_mfma_f32_16x16x32_bf16 v[98:101], v[178:181], v[194:197], v[98:101]
	v_mfma_f32_16x16x32_bf16 v[86:89], v[168:171], v[202:205], v[86:89]
	v_mfma_f32_16x16x32_bf16 v[82:85], v[178:181], v[202:205], v[82:85]
	v_mfma_f32_16x16x32_bf16 v[70:73], v[168:171], v[210:213], v[70:73]
	v_mfma_f32_16x16x32_bf16 v[66:69], v[178:181], v[210:213], v[66:69]
	v_mfma_f32_16x16x32_bf16 v[118:121], v[174:177], v[190:193], v[118:121]
	v_mfma_f32_16x16x32_bf16 v[114:117], v[182:185], v[190:193], v[114:117]
	v_mfma_f32_16x16x32_bf16 v[102:105], v[174:177], v[198:201], v[102:105]
	v_mfma_f32_16x16x32_bf16 v[98:101], v[182:185], v[198:201], v[98:101]
	v_mfma_f32_16x16x32_bf16 v[86:89], v[174:177], v[206:209], v[86:89]
	v_mfma_f32_16x16x32_bf16 v[82:85], v[182:185], v[206:209], v[82:85]
	v_mfma_f32_16x16x32_bf16 v[70:73], v[174:177], v[214:217], v[70:73]
	v_mfma_f32_16x16x32_bf16 v[66:69], v[182:185], v[214:217], v[66:69]
	s_barrier
; #define PG8_STAGE(bufoff, gbase, voff) do { _Pragma("unroll") for (int _i = 0; _i < 2; ++_i) \
;         __builtin_amdgcn_global_load_lds((const unsigned*)((const char*)(gbase) + (voff)[_i]), (PG8_LAS unsigned*)(lds + (bufoff) + ldsw + _i * 8192), 16, 0, 0); } while (0)
; #define PG8_LDA(dst, b, h) do { _Pragma("unroll") for (int m = 0; m < 4; ++m) _Pragma("unroll") for (int k = 0; k < 2; ++k) dst[m][k] = *(const PG8_LAS bf16x8*)(lds + PG8_SA(b, h) + aoff + m * 2048 + k * 1024); } while (0)
; #define PG8_MMA(ai, bj, At, Bt) do { __builtin_amdgcn_s_setprio(1); _Pragma("unroll") for (int m = 0; m < 4; ++m) _Pragma("unroll") for (int n = 0; n < 2; ++n) _Pragma("unroll") for (int k = 0; k < 2; ++k) \
;         acc[ai][bj][m][n] = __builtin_amdgcn_mfma_f32_16x16x32_bf16(Bt[n][k], At[m][k], acc[ai][bj][m][n], 0, 0, 0); __builtin_amdgcn_s_setprio(0); } while (0)
; #define PG8_WAIT_V(n) asm volatile("s_waitcnt vmcnt(" #n ")" ::: "memory")
; #define PG8_WAIT_L(n) asm volatile("s_waitcnt lgkmcnt(" #n ")" ::: "memory")
; #define PG8_BAR __builtin_amdgcn_s_barrier()
; #define PG8_SCHED __builtin_amdgcn_sched_barrier(0)
; template <class Epi, class Sched, bool ALIGN_EPI = false, bool SP2 = false>
; __device__ __forceinline__ void gemm_phase(PG8_LAS unsigned char* lds, const Gemm g, const Sched& S, const Epi& E) {
;     ...
;             PG8_LDA(At, 1, 1); PG8_STAGE(PG8_SB(1, 0), b3, voffB); PG8_STAGE(PG8_SB(1, 1), b3 + hstep, voffB); PG8_STAGE(PG8_SA(1, 0), a3, voffA);
;             PG8_WAIT_V(8); PG8_WAIT_L(0); PG8_BAR; PG8_MMA(1, 0, At, B0); PG8_MMA(1, 1, At, B1); PG8_BAR; PG8_SCHED;
;     ...
;         if constexpr (ALIGN_EPI) { if (wr == 0) PG8_BAR; }
	s_add_i32 s24, s57, s30
	v_lshl_add_u64 v[218:219], v[218:219], 0, s[6:7]
	s_mov_b32 m0, s24
	ds_read_b128 v[186:189], v151 offset:49152
	ds_read_b128 v[190:193], v151 offset:50176
	ds_read_b128 v[194:197], v151 offset:51200
	ds_read_b128 v[198:201], v151 offset:52224
	ds_read_b128 v[202:205], v151 offset:53248
	ds_read_b128 v[206:209], v151 offset:54272
	ds_read_b128 v[210:213], v151 offset:55296
	ds_read_b128 v[214:217], v151 offset:56320
	global_load_lds_dwordx4 v[218:219], off
	s_add_i32 m0, s24, 0x2000
	s_add_u32 s22, s22, 0x40080
	v_lshl_add_u64 v[218:219], v[220:221], 0, s[6:7]
	s_addc_u32 s23, s23, 0
	s_add_i32 s24, s58, s30
	global_load_lds_dwordx4 v[218:219], off
	v_lshl_add_u64 v[218:219], s[22:23], 0, v[134:135]
	s_mov_b32 m0, s24
	s_nop 0
	global_load_lds_dwordx4 v[218:219], off
	v_lshl_add_u64 v[218:219], s[22:23], 0, v[130:131]
	s_add_i32 m0, s24, 0x2000
	s_nop 0
	global_load_lds_dwordx4 v[218:219], off
	v_lshl_add_u64 v[218:219], v[222:223], 0, s[6:7]
	s_mov_b32 m0, s41
	s_nop 0
	global_load_lds_dwordx4 v[218:219], off
	v_lshl_add_u64 v[218:219], v[224:225], 0, s[6:7]
	s_mov_b32 m0, s42
	s_nop 0
	global_load_lds_dwordx4 v[218:219], off
	s_waitcnt vmcnt(8)
	s_waitcnt lgkmcnt(0)
	s_barrier
	s_waitcnt lgkmcnt(0)
	v_mfma_f32_16x16x32_bf16 v[62:65], v[152:155], v[186:189], v[62:65]
	v_mfma_f32_16x16x32_bf16 v[58:61], v[160:163], v[186:189], v[58:61]
	v_mfma_f32_16x16x32_bf16 v[46:49], v[152:155], v[194:197], v[46:49]
	v_mfma_f32_16x16x32_bf16 v[42:45], v[160:163], v[194:197], v[42:45]
	v_mfma_f32_16x16x32_bf16 v[30:33], v[152:155], v[202:205], v[30:33]
	v_mfma_f32_16x16x32_bf16 v[26:29], v[160:163], v[202:205], v[26:29]
	v_mfma_f32_16x16x32_bf16 v[14:17], v[152:155], v[210:213], v[14:17]
	v_mfma_f32_16x16x32_bf16 v[10:13], v[160:163], v[210:213], v[10:13]
	v_mfma_f32_16x16x32_bf16 v[62:65], v[156:159], v[190:193], v[62:65]
	v_mfma_f32_16x16x32_bf16 v[58:61], v[164:167], v[190:193], v[58:61]
	v_mfma_f32_16x16x32_bf16 v[46:49], v[156:159], v[198:201], v[46:49]
	v_mfma_f32_16x16x32_bf16 v[42:45], v[164:167], v[198:201], v[42:45]
	v_mfma_f32_16x16x32_bf16 v[30:33], v[156:159], v[206:209], v[30:33]
	v_mfma_f32_16x16x32_bf16 v[26:29], v[164:167], v[206:209], v[26:29]
	v_mfma_f32_16x16x32_bf16 v[14:17], v[156:159], v[214:217], v[14:17]
	v_mfma_f32_16x16x32_bf16 v[10:13], v[164:167], v[214:217], v[10:13]
	v_mfma_f32_16x16x32_bf16 v[54:57], v[168:171], v[186:189], v[54:57]
	v_mfma_f32_16x16x32_bf16 v[50:53], v[178:181], v[186:189], v[50:53]
	v_mfma_f32_16x16x32_bf16 v[38:41], v[168:171], v[194:197], v[38:41]
	v_mfma_f32_16x16x32_bf16 v[34:37], v[178:181], v[194:197], v[34:37]
	v_mfma_f32_16x16x32_bf16 v[22:25], v[168:171], v[202:205], v[22:25]
	v_mfma_f32_16x16x32_bf16 v[18:21], v[178:181], v[202:205], v[18:21]
	v_mfma_f32_16x16x32_bf16 v[6:9], v[168:171], v[210:213], v[6:9]
	v_mfma_f32_16x16x32_bf16 v[2:5], v[178:181], v[210:213], v[2:5]
	v_mfma_f32_16x16x32_bf16 v[54:57], v[174:177], v[190:193], v[54:57]
	v_mfma_f32_16x16x32_bf16 v[50:53], v[182:185], v[190:193], v[50:53]
	v_mfma_f32_16x16x32_bf16 v[38:41], v[174:177], v[198:201], v[38:41]
	v_mfma_f32_16x16x32_bf16 v[34:37], v[182:185], v[198:201], v[34:37]
	v_mfma_f32_16x16x32_bf16 v[22:25], v[174:177], v[206:209], v[22:25]
	v_mfma_f32_16x16x32_bf16 v[18:21], v[182:185], v[206:209], v[18:21]
	v_mfma_f32_16x16x32_bf16 v[6:9], v[174:177], v[214:217], v[6:9]
	v_mfma_f32_16x16x32_bf16 v[2:5], v[182:185], v[214:217], v[2:5]
	s_barrier
	s_add_i32 s56, s56, 2
	s_add_u32 s20, s20, 0x100
	s_addc_u32 s21, s21, 0
	s_add_u32 s54, s54, 0x100
	s_addc_u32 s55, s55, 0
	s_cmp_gt_u32 s56, 13
	s_cbranch_scc0 .LBB0_1591
	s_and_b64 vcc, exec, s[8:9]
	s_cbranch_vccz .LBB0_1594
	s_barrier

; #define PG8_STAGE(bufoff, gbase, voff) do { _Pragma("unroll") for (int _i = 0; _i < 2; ++_i) \
;         __builtin_amdgcn_global_load_lds((const unsigned*)((const char*)(gbase) + (voff)[_i]), (PG8_LAS unsigned*)(lds + (bufoff) + ldsw + _i * 8192), 16, 0, 0); } while (0)
; #define PG8_LDA(dst, b, h) do { _Pragma("unroll") for (int m = 0; m < 4; ++m) _Pragma("unroll") for (int k = 0; k < 2; ++k) dst[m][k] = *(const PG8_LAS bf16x8*)(lds + PG8_SA(b, h) + aoff + m * 2048 + k * 1024); } while (0)
; #define PG8_LDB(dst, b, h) do { _Pragma("unroll") for (int n = 0; n < 2; ++n) _Pragma("unroll") for (int k = 0; k < 2; ++k) dst[n][k] = *(const PG8_LAS bf16x8*)(lds + PG8_SB(b, h) + boff + n * 2048 + k * 1024); } while (0)
; #define PG8_SCHED __builtin_amdgcn_sched_barrier(0)
; template <class Epi, class Sched, bool ALIGN_EPI = false, bool SP2 = false>
; __device__ __forceinline__ void gemm_phase(PG8_LAS unsigned char* lds, const Gemm g, const Sched& S, const Epi& E) {
;     ...
;             const char* a1 = cA + (size_t)(t + 1) * kstep;
;             const char* a2 = last ? nA : cA + (size_t)(t + 2) * kstep; const char* b2 = last ? nB : cB + (size_t)(t + 2) * kstep;
;             const char* a3 = a2 + kstep; const char* b3 = b2 + kstep;
;             if (last && has_next) S.a_ready(nxt);
;             if constexpr (SP2) {
;             PG8_LDB(B0, 0, 0); PG8_LDB(B1, 0, 1); PG8_SCHED; PG8_LDA(At, 0, 0); PG8_STAGE(PG8_SA(1, 1), a1 + hstep, voffA);
.LBB0_1687:
	s_add_u32 s22, s22, 0xb0080
	s_addc_u32 s23, s23, 0
	s_add_u32 s60, s24, 0x100
	s_addc_u32 s61, s25, 0
	s_mov_b32 s62, -2
	ds_read_b128 v[154:157], v150
	ds_read_b128 v[158:161], v150 offset:1024
	ds_read_b128 v[162:165], v150 offset:2048
	ds_read_b128 v[166:169], v150 offset:3072
	ds_read_b128 v[174:177], v151
	ds_read_b128 v[178:181], v151 offset:1024
	ds_read_b128 v[182:185], v151 offset:2048
	ds_read_b128 v[186:189], v151 offset:3072
	s_add_u32 s24, s22, 0xfff50080
	s_addc_u32 s25, s23, -1
	s_cmp_eq_u32 s62, 40
	s_cselect_b32 s27, s5, s25
	s_cselect_b32 s26, s4, s24
	s_cselect_b32 s25, s21, s61
	s_cselect_b32 s24, s20, s60

; #define PG8_STAGE(bufoff, gbase, voff) do { _Pragma("unroll") for (int _i = 0; _i < 2; ++_i) \
;         __builtin_amdgcn_global_load_lds((const unsigned*)((const char*)(gbase) + (voff)[_i]), (PG8_LAS unsigned*)(lds + (bufoff) + ldsw + _i * 8192), 16, 0, 0); } while (0)
; #define PG8_LDA(dst, b, h) do { _Pragma("unroll") for (int m = 0; m < 4; ++m) _Pragma("unroll") for (int k = 0; k < 2; ++k) dst[m][k] = *(const PG8_LAS bf16x8*)(lds + PG8_SA(b, h) + aoff + m * 2048 + k * 1024); } while (0)
; #define PG8_LDB(dst, b, h) do { _Pragma("unroll") for (int n = 0; n < 2; ++n) _Pragma("unroll") for (int k = 0; k < 2; ++k) dst[n][k] = *(const PG8_LAS bf16x8*)(lds + PG8_SB(b, h) + boff + n * 2048 + k * 1024); } while (0)
; #define PG8_MMA(ai, bj, At, Bt) do { __builtin_amdgcn_s_setprio(1); _Pragma("unroll") for (int m = 0; m < 4; ++m) _Pragma("unroll") for (int n = 0; n < 2; ++n) _Pragma("unroll") for (int k = 0; k < 2; ++k) \
;         acc[ai][bj][m][n] = __builtin_amdgcn_mfma_f32_16x16x32_bf16(Bt[n][k], At[m][k], acc[ai][bj][m][n], 0, 0, 0); __builtin_amdgcn_s_setprio(0); } while (0)
; #define PG8_WAIT_V(n) asm volatile("s_waitcnt vmcnt(" #n ")" ::: "memory")
; #define PG8_WAIT_L(n) asm volatile("s_waitcnt lgkmcnt(" #n ")" ::: "memory")
; #define PG8_BAR __builtin_amdgcn_s_barrier()
; #define PG8_SCHED __builtin_amdgcn_sched_barrier(0)
; template <class Epi, class Sched, bool ALIGN_EPI = false, bool SP2 = false>
; __device__ __forceinline__ void gemm_phase(PG8_LAS unsigned char* lds, const Gemm g, const Sched& S, const Epi& E) {
;     ...
;             PG8_LDB(B0, 0, 0); PG8_LDB(B1, 0, 1); PG8_SCHED; PG8_LDA(At, 0, 0); PG8_STAGE(PG8_SA(1, 1), a1 + hstep, voffA);
;             PG8_WAIT_V(8); PG8_WAIT_L(0); PG8_BAR; PG8_MMA(0, 0, At, B0); PG8_MMA(0, 1, At, B1); PG8_BAR; PG8_SCHED;
	v_lshl_add_u64 v[146:147], s[22:23], 0, v[138:139]
	s_add_i32 m0, s35, 0xc000
	ds_read_b128 v[190:193], v152
	ds_read_b128 v[194:197], v152 offset:1024
	ds_read_b128 v[198:201], v152 offset:2048
	ds_read_b128 v[202:205], v152 offset:3072
	ds_read_b128 v[206:209], v152 offset:4096
	ds_read_b128 v[210:213], v152 offset:5120
	ds_read_b128 v[214:217], v152 offset:6144
	ds_read_b128 v[218:221], v152 offset:7168
	global_load_lds_dwordx4 v[146:147], off
	v_lshl_add_u64 v[146:147], s[22:23], 0, v[140:141]
	s_add_i32 m0, s35, 0xe000
	s_nop 0
	global_load_lds_dwordx4 v[146:147], off
	s_waitcnt vmcnt(24)
	s_waitcnt lgkmcnt(0)
	s_barrier
	s_waitcnt lgkmcnt(0)
	v_mfma_f32_16x16x32_bf16 v[126:129], v[154:157], v[190:193], 0
	v_mfma_f32_16x16x32_bf16 v[122:125], v[162:165], v[190:193], 0
	v_mfma_f32_16x16x32_bf16 v[118:121], v[154:157], v[198:201], 0
	v_mfma_f32_16x16x32_bf16 v[110:113], v[162:165], v[198:201], 0
	v_mfma_f32_16x16x32_bf16 v[102:105], v[154:157], v[206:209], 0
	v_mfma_f32_16x16x32_bf16 v[94:97], v[162:165], v[206:209], 0
	v_mfma_f32_16x16x32_bf16 v[86:89], v[154:157], v[214:217], 0
	v_mfma_f32_16x16x32_bf16 v[78:81], v[162:165], v[214:217], 0
	v_mfma_f32_16x16x32_bf16 v[126:129], v[158:161], v[194:197], v[126:129]
	v_mfma_f32_16x16x32_bf16 v[122:125], v[166:169], v[194:197], v[122:125]
	v_mfma_f32_16x16x32_bf16 v[118:121], v[158:161], v[202:205], v[118:121]
	v_mfma_f32_16x16x32_bf16 v[110:113], v[166:169], v[202:205], v[110:113]
	v_mfma_f32_16x16x32_bf16 v[102:105], v[158:161], v[210:213], v[102:105]
	v_mfma_f32_16x16x32_bf16 v[94:97], v[166:169], v[210:213], v[94:97]
	v_mfma_f32_16x16x32_bf16 v[86:89], v[158:161], v[218:221], v[86:89]
	v_mfma_f32_16x16x32_bf16 v[78:81], v[166:169], v[218:221], v[78:81]
	v_mfma_f32_16x16x32_bf16 v[114:117], v[174:177], v[190:193], 0
	v_mfma_f32_16x16x32_bf16 v[106:109], v[182:185], v[190:193], 0
	v_mfma_f32_16x16x32_bf16 v[98:101], v[174:177], v[198:201], 0
	v_mfma_f32_16x16x32_bf16 v[90:93], v[182:185], v[198:201], 0
	v_mfma_f32_16x16x32_bf16 v[82:85], v[174:177], v[206:209], 0
	v_mfma_f32_16x16x32_bf16 v[74:77], v[182:185], v[206:209], 0
	v_mfma_f32_16x16x32_bf16 v[70:73], v[174:177], v[214:217], 0
	v_mfma_f32_16x16x32_bf16 v[66:69], v[182:185], v[214:217], 0
	v_mfma_f32_16x16x32_bf16 v[114:117], v[178:181], v[194:197], v[114:117]
	v_mfma_f32_16x16x32_bf16 v[106:109], v[186:189], v[194:197], v[106:109]
	v_mfma_f32_16x16x32_bf16 v[98:101], v[178:181], v[202:205], v[98:101]
	v_mfma_f32_16x16x32_bf16 v[90:93], v[186:189], v[202:205], v[90:93]
	v_mfma_f32_16x16x32_bf16 v[82:85], v[178:181], v[210:213], v[82:85]
	v_mfma_f32_16x16x32_bf16 v[74:77], v[186:189], v[210:213], v[74:77]
	v_mfma_f32_16x16x32_bf16 v[70:73], v[178:181], v[218:221], v[70:73]
	v_mfma_f32_16x16x32_bf16 v[66:69], v[186:189], v[218:221], v[66:69]
	s_barrier

; #define PG8_STAGE(bufoff, gbase, voff) do { _Pragma("unroll") for (int _i = 0; _i < 2; ++_i) \
;         __builtin_amdgcn_global_load_lds((const unsigned*)((const char*)(gbase) + (voff)[_i]), (PG8_LAS unsigned*)(lds + (bufoff) + ldsw + _i * 8192), 16, 0, 0); } while (0)
; #define PG8_LDA(dst, b, h) do { _Pragma("unroll") for (int m = 0; m < 4; ++m) _Pragma("unroll") for (int k = 0; k < 2; ++k) dst[m][k] = *(const PG8_LAS bf16x8*)(lds + PG8_SA(b, h) + aoff + m * 2048 + k * 1024); } while (0)
; #define PG8_MMA(ai, bj, At, Bt) do { __builtin_amdgcn_s_setprio(1); _Pragma("unroll") for (int m = 0; m < 4; ++m) _Pragma("unroll") for (int n = 0; n < 2; ++n) _Pragma("unroll") for (int k = 0; k < 2; ++k) \
;         acc[ai][bj][m][n] = __builtin_amdgcn_mfma_f32_16x16x32_bf16(Bt[n][k], At[m][k], acc[ai][bj][m][n], 0, 0, 0); __builtin_amdgcn_s_setprio(0); } while (0)
; #define PG8_WAIT_V(n) asm volatile("s_waitcnt vmcnt(" #n ")" ::: "memory")
; #define PG8_WAIT_L(n) asm volatile("s_waitcnt lgkmcnt(" #n ")" ::: "memory")
; #define PG8_BAR __builtin_amdgcn_s_barrier()
; #define PG8_SCHED __builtin_amdgcn_sched_barrier(0)
; template <class Epi, class Sched, bool ALIGN_EPI = false, bool SP2 = false>
; __device__ __forceinline__ void gemm_phase(PG8_LAS unsigned char* lds, const Gemm g, const Sched& S, const Epi& E) {
;     ...
;             PG8_LDA(At, 0, 1); PG8_STAGE(PG8_SB(0, 0), b2, voffB); PG8_STAGE(PG8_SB(0, 1), b2 + hstep, voffB); PG8_STAGE(PG8_SA(0, 0), a2, voffA);
;             PG8_WAIT_V(8); PG8_WAIT_L(0); PG8_BAR; PG8_MMA(1, 0, At, B0); PG8_MMA(1, 1, At, B1); PG8_BAR; PG8_SCHED;
	s_add_i32 s63, s48, s34
	v_lshl_add_u64 v[146:147], s[24:25], 0, v[132:133]
	s_mov_b32 m0, s63
	ds_read_b128 v[190:193], v152 offset:16384
	ds_read_b128 v[194:197], v152 offset:17408
	ds_read_b128 v[198:201], v152 offset:18432
	ds_read_b128 v[202:205], v152 offset:19456
	ds_read_b128 v[206:209], v152 offset:20480
	ds_read_b128 v[210:213], v152 offset:21504
	ds_read_b128 v[214:217], v152 offset:22528
	ds_read_b128 v[218:221], v152 offset:23552
	global_load_lds_dwordx4 v[146:147], off
	s_add_i32 m0, s63, 0x2000
	s_add_u32 s64, s24, 0xb0000
	v_lshl_add_u64 v[170:171], s[24:25], 0, v[136:137]
	s_addc_u32 s65, s25, 0
	s_add_i32 s63, s49, s34
	global_load_lds_dwordx4 v[170:171], off
	v_lshl_add_u64 v[222:223], s[64:65], 0, v[132:133]
	s_mov_b32 m0, s63
	v_lshl_add_u64 v[224:225], s[26:27], 0, v[134:135]
	global_load_lds_dwordx4 v[222:223], off
	v_lshl_add_u64 v[222:223], s[64:65], 0, v[136:137]
	s_add_i32 m0, s63, 0x2000
	s_nop 0
	global_load_lds_dwordx4 v[222:223], off
	v_lshl_add_u64 v[222:223], s[26:27], 0, v[130:131]
	s_mov_b32 m0, s35
	s_nop 0
	global_load_lds_dwordx4 v[222:223], off
	s_mov_b32 m0, s38
	s_nop 0
	global_load_lds_dwordx4 v[224:225], off
	s_waitcnt vmcnt(24)
	s_waitcnt lgkmcnt(0)
	s_barrier
	s_waitcnt lgkmcnt(0)
	v_mfma_f32_16x16x32_bf16 v[62:65], v[154:157], v[190:193], 0
	v_mfma_f32_16x16x32_bf16 v[58:61], v[162:165], v[190:193], 0
	v_mfma_f32_16x16x32_bf16 v[54:57], v[154:157], v[198:201], 0
	v_mfma_f32_16x16x32_bf16 v[46:49], v[162:165], v[198:201], 0
	v_mfma_f32_16x16x32_bf16 v[38:41], v[154:157], v[206:209], 0
	v_mfma_f32_16x16x32_bf16 v[30:33], v[162:165], v[206:209], 0
	v_mfma_f32_16x16x32_bf16 v[22:25], v[154:157], v[214:217], 0
	v_mfma_f32_16x16x32_bf16 v[14:17], v[162:165], v[214:217], 0
	v_mfma_f32_16x16x32_bf16 v[62:65], v[158:161], v[194:197], v[62:65]
	v_mfma_f32_16x16x32_bf16 v[58:61], v[166:169], v[194:197], v[58:61]
	v_mfma_f32_16x16x32_bf16 v[54:57], v[158:161], v[202:205], v[54:57]
	v_mfma_f32_16x16x32_bf16 v[46:49], v[166:169], v[202:205], v[46:49]
	v_mfma_f32_16x16x32_bf16 v[38:41], v[158:161], v[210:213], v[38:41]
	v_mfma_f32_16x16x32_bf16 v[30:33], v[166:169], v[210:213], v[30:33]
	v_mfma_f32_16x16x32_bf16 v[22:25], v[158:161], v[218:221], v[22:25]
	v_mfma_f32_16x16x32_bf16 v[14:17], v[166:169], v[218:221], v[14:17]
	v_mfma_f32_16x16x32_bf16 v[50:53], v[174:177], v[190:193], 0
	v_mfma_f32_16x16x32_bf16 v[42:45], v[182:185], v[190:193], 0
	v_mfma_f32_16x16x32_bf16 v[34:37], v[174:177], v[198:201], 0
	v_mfma_f32_16x16x32_bf16 v[26:29], v[182:185], v[198:201], 0
	v_mfma_f32_16x16x32_bf16 v[18:21], v[174:177], v[206:209], 0
	v_mfma_f32_16x16x32_bf16 v[10:13], v[182:185], v[206:209], 0
	v_mfma_f32_16x16x32_bf16 v[6:9], v[174:177], v[214:217], 0
	v_mfma_f32_16x16x32_bf16 v[2:5], v[182:185], v[214:217], 0
	v_mfma_f32_16x16x32_bf16 v[50:53], v[178:181], v[194:197], v[50:53]
	v_mfma_f32_16x16x32_bf16 v[42:45], v[186:189], v[194:197], v[42:45]
	v_mfma_f32_16x16x32_bf16 v[34:37], v[178:181], v[202:205], v[34:37]
	v_mfma_f32_16x16x32_bf16 v[26:29], v[186:189], v[202:205], v[26:29]
	v_mfma_f32_16x16x32_bf16 v[18:21], v[178:181], v[210:213], v[18:21]
	v_mfma_f32_16x16x32_bf16 v[10:13], v[186:189], v[210:213], v[10:13]
	v_mfma_f32_16x16x32_bf16 v[6:9], v[178:181], v[218:221], v[6:9]
	v_mfma_f32_16x16x32_bf16 v[2:5], v[186:189], v[218:221], v[2:5]
	s_barrier

; #define PG8_STAGE(bufoff, gbase, voff) do { _Pragma("unroll") for (int _i = 0; _i < 2; ++_i) \
;         __builtin_amdgcn_global_load_lds((const unsigned*)((const char*)(gbase) + (voff)[_i]), (PG8_LAS unsigned*)(lds + (bufoff) + ldsw + _i * 8192), 16, 0, 0); } while (0)
; #define PG8_LDA(dst, b, h) do { _Pragma("unroll") for (int m = 0; m < 4; ++m) _Pragma("unroll") for (int k = 0; k < 2; ++k) dst[m][k] = *(const PG8_LAS bf16x8*)(lds + PG8_SA(b, h) + aoff + m * 2048 + k * 1024); } while (0)
; #define PG8_LDB(dst, b, h) do { _Pragma("unroll") for (int n = 0; n < 2; ++n) _Pragma("unroll") for (int k = 0; k < 2; ++k) dst[n][k] = *(const PG8_LAS bf16x8*)(lds + PG8_SB(b, h) + boff + n * 2048 + k * 1024); } while (0)
; #define PG8_SCHED __builtin_amdgcn_sched_barrier(0)
; template <class Epi, class Sched, bool ALIGN_EPI = false, bool SP2 = false>
; __device__ __forceinline__ void gemm_phase(PG8_LAS unsigned char* lds, const Gemm g, const Sched& S, const Epi& E) {
;     ...
;             PG8_LDB(B0, 1, 0); PG8_LDB(B1, 1, 1); PG8_SCHED; PG8_LDA(At, 1, 0); PG8_STAGE(PG8_SA(0, 1), a2 + hstep, voffA);
	s_add_i32 s63, 0, 0x18000
	v_add_u32_e32 v153, s63, v148
	s_add_i32 s64, 0, 0x1c000
	ds_read_b128 v[154:157], v153
	ds_read_b128 v[158:161], v153 offset:1024
	ds_read_b128 v[162:165], v153 offset:2048
	ds_read_b128 v[166:169], v153 offset:3072
	v_add_u32_e32 v153, s64, v148
	ds_read_b128 v[174:177], v153
	ds_read_b128 v[178:181], v153 offset:1024
	ds_read_b128 v[182:185], v153 offset:2048
	ds_read_b128 v[186:189], v153 offset:3072

; #define PG8_STAGE(bufoff, gbase, voff) do { _Pragma("unroll") for (int _i = 0; _i < 2; ++_i) \
;         __builtin_amdgcn_global_load_lds((const unsigned*)((const char*)(gbase) + (voff)[_i]), (PG8_LAS unsigned*)(lds + (bufoff) + ldsw + _i * 8192), 16, 0, 0); } while (0)
; #define PG8_LDA(dst, b, h) do { _Pragma("unroll") for (int m = 0; m < 4; ++m) _Pragma("unroll") for (int k = 0; k < 2; ++k) dst[m][k] = *(const PG8_LAS bf16x8*)(lds + PG8_SA(b, h) + aoff + m * 2048 + k * 1024); } while (0)
; #define PG8_LDB(dst, b, h) do { _Pragma("unroll") for (int n = 0; n < 2; ++n) _Pragma("unroll") for (int k = 0; k < 2; ++k) dst[n][k] = *(const PG8_LAS bf16x8*)(lds + PG8_SB(b, h) + boff + n * 2048 + k * 1024); } while (0)
; #define PG8_MMA(ai, bj, At, Bt) do { __builtin_amdgcn_s_setprio(1); _Pragma("unroll") for (int m = 0; m < 4; ++m) _Pragma("unroll") for (int n = 0; n < 2; ++n) _Pragma("unroll") for (int k = 0; k < 2; ++k) \
;         acc[ai][bj][m][n] = __builtin_amdgcn_mfma_f32_16x16x32_bf16(Bt[n][k], At[m][k], acc[ai][bj][m][n], 0, 0, 0); __builtin_amdgcn_s_setprio(0); } while (0)
; #define PG8_WAIT_V(n) asm volatile("s_waitcnt vmcnt(" #n ")" ::: "memory")
; #define PG8_WAIT_L(n) asm volatile("s_waitcnt lgkmcnt(" #n ")" ::: "memory")
; #define PG8_BAR __builtin_amdgcn_s_barrier()
; #define PG8_SCHED __builtin_amdgcn_sched_barrier(0)
; template <class Epi, class Sched, bool ALIGN_EPI = false, bool SP2 = false>
; __device__ __forceinline__ void gemm_phase(PG8_LAS unsigned char* lds, const Gemm g, const Sched& S, const Epi& E) {
;     ...
;             PG8_LDB(B0, 1, 0); PG8_LDB(B1, 1, 1); PG8_SCHED; PG8_LDA(At, 1, 0); PG8_STAGE(PG8_SA(0, 1), a2 + hstep, voffA);
;             PG8_WAIT_V(8); PG8_WAIT_L(0); PG8_BAR; PG8_MMA(0, 0, At, B0); PG8_MMA(0, 1, At, B1); PG8_BAR; PG8_SCHED;
	s_add_u32 s26, s26, 0xb0000
	s_addc_u32 s27, s27, 0
	s_mov_b32 m0, s39
	v_lshl_add_u64 v[226:227], s[26:27], 0, v[130:131]
	ds_read_b128 v[190:193], v152 offset:32768
	ds_read_b128 v[194:197], v152 offset:33792
	ds_read_b128 v[198:201], v152 offset:34816
	ds_read_b128 v[202:205], v152 offset:35840
	ds_read_b128 v[206:209], v152 offset:36864
	ds_read_b128 v[210:213], v152 offset:37888
	ds_read_b128 v[214:217], v152 offset:38912
	ds_read_b128 v[218:221], v152 offset:39936
	global_load_lds_dwordx4 v[226:227], off
	v_lshl_add_u64 v[226:227], s[26:27], 0, v[134:135]
	s_mov_b32 m0, s40
	s_nop 0
	global_load_lds_dwordx4 v[226:227], off
	s_waitcnt vmcnt(8)
	s_waitcnt lgkmcnt(0)
	s_barrier
	s_waitcnt lgkmcnt(0)
	v_mfma_f32_16x16x32_bf16 v[126:129], v[154:157], v[190:193], v[126:129]
	v_mfma_f32_16x16x32_bf16 v[122:125], v[162:165], v[190:193], v[122:125]
	v_mfma_f32_16x16x32_bf16 v[118:121], v[154:157], v[198:201], v[118:121]
	v_mfma_f32_16x16x32_bf16 v[110:113], v[162:165], v[198:201], v[110:113]
	v_mfma_f32_16x16x32_bf16 v[102:105], v[154:157], v[206:209], v[102:105]
	v_mfma_f32_16x16x32_bf16 v[94:97], v[162:165], v[206:209], v[94:97]
	v_mfma_f32_16x16x32_bf16 v[86:89], v[154:157], v[214:217], v[86:89]
	v_mfma_f32_16x16x32_bf16 v[78:81], v[162:165], v[214:217], v[78:81]
	v_mfma_f32_16x16x32_bf16 v[126:129], v[158:161], v[194:197], v[126:129]
	v_mfma_f32_16x16x32_bf16 v[122:125], v[166:169], v[194:197], v[122:125]
	v_mfma_f32_16x16x32_bf16 v[118:121], v[158:161], v[202:205], v[118:121]
	v_mfma_f32_16x16x32_bf16 v[110:113], v[166:169], v[202:205], v[110:113]
	v_mfma_f32_16x16x32_bf16 v[102:105], v[158:161], v[210:213], v[102:105]
	v_mfma_f32_16x16x32_bf16 v[94:97], v[166:169], v[210:213], v[94:97]
	v_mfma_f32_16x16x32_bf16 v[86:89], v[158:161], v[218:221], v[86:89]
	v_mfma_f32_16x16x32_bf16 v[78:81], v[166:169], v[218:221], v[78:81]
	v_mfma_f32_16x16x32_bf16 v[114:117], v[174:177], v[190:193], v[114:117]
	v_mfma_f32_16x16x32_bf16 v[106:109], v[182:185], v[190:193], v[106:109]
	v_mfma_f32_16x16x32_bf16 v[98:101], v[174:177], v[198:201], v[98:101]
	v_mfma_f32_16x16x32_bf16 v[90:93], v[182:185], v[198:201], v[90:93]
	v_mfma_f32_16x16x32_bf16 v[82:85], v[174:177], v[206:209], v[82:85]
	v_mfma_f32_16x16x32_bf16 v[74:77], v[182:185], v[206:209], v[74:77]
	v_mfma_f32_16x16x32_bf16 v[70:73], v[174:177], v[214:217], v[70:73]
	v_mfma_f32_16x16x32_bf16 v[66:69], v[182:185], v[214:217], v[66:69]
	v_mfma_f32_16x16x32_bf16 v[114:117], v[178:181], v[194:197], v[114:117]
	v_mfma_f32_16x16x32_bf16 v[106:109], v[186:189], v[194:197], v[106:109]
	v_mfma_f32_16x16x32_bf16 v[98:101], v[178:181], v[202:205], v[98:101]
	v_mfma_f32_16x16x32_bf16 v[90:93], v[186:189], v[202:205], v[90:93]
	v_mfma_f32_16x16x32_bf16 v[82:85], v[178:181], v[210:213], v[82:85]
	v_mfma_f32_16x16x32_bf16 v[74:77], v[186:189], v[210:213], v[74:77]
	v_mfma_f32_16x16x32_bf16 v[70:73], v[178:181], v[218:221], v[70:73]
	v_mfma_f32_16x16x32_bf16 v[66:69], v[186:189], v[218:221], v[66:69]
	s_barrier

; #define PG8_STAGE(bufoff, gbase, voff) do { _Pragma("unroll") for (int _i = 0; _i < 2; ++_i) \
;         __builtin_amdgcn_global_load_lds((const unsigned*)((const char*)(gbase) + (voff)[_i]), (PG8_LAS unsigned*)(lds + (bufoff) + ldsw + _i * 8192), 16, 0, 0); } while (0)
; #define PG8_LDA(dst, b, h) do { _Pragma("unroll") for (int m = 0; m < 4; ++m) _Pragma("unroll") for (int k = 0; k < 2; ++k) dst[m][k] = *(const PG8_LAS bf16x8*)(lds + PG8_SA(b, h) + aoff + m * 2048 + k * 1024); } while (0)
; #define PG8_MMA(ai, bj, At, Bt) do { __builtin_amdgcn_s_setprio(1); _Pragma("unroll") for (int m = 0; m < 4; ++m) _Pragma("unroll") for (int n = 0; n < 2; ++n) _Pragma("unroll") for (int k = 0; k < 2; ++k) \
;         acc[ai][bj][m][n] = __builtin_amdgcn_mfma_f32_16x16x32_bf16(Bt[n][k], At[m][k], acc[ai][bj][m][n], 0, 0, 0); __builtin_amdgcn_s_setprio(0); } while (0)
; #define PG8_WAIT_V(n) asm volatile("s_waitcnt vmcnt(" #n ")" ::: "memory")
; #define PG8_WAIT_L(n) asm volatile("s_waitcnt lgkmcnt(" #n ")" ::: "memory")
; #define PG8_BAR __builtin_amdgcn_s_barrier()
; #define PG8_SCHED __builtin_amdgcn_sched_barrier(0)
; template <class Epi, class Sched, bool ALIGN_EPI = false, bool SP2 = false>
; __device__ __forceinline__ void gemm_phase(PG8_LAS unsigned char* lds, const Gemm g, const Sched& S, const Epi& E) {
;     ...
;             PG8_LDA(At, 1, 1); PG8_STAGE(PG8_SB(1, 0), b3, voffB); PG8_STAGE(PG8_SB(1, 1), b3 + hstep, voffB); PG8_STAGE(PG8_SA(1, 0), a3, voffA);
;             PG8_WAIT_V(8); PG8_WAIT_L(0); PG8_BAR; PG8_MMA(1, 0, At, B0); PG8_MMA(1, 1, At, B1); PG8_BAR; PG8_SCHED;
	s_add_i32 s26, s63, s34
	v_lshl_add_u64 v[146:147], v[146:147], 0, s[8:9]
	s_mov_b32 m0, s26
	ds_read_b128 v[190:193], v152 offset:49152
	ds_read_b128 v[194:197], v152 offset:50176
	ds_read_b128 v[198:201], v152 offset:51200
	ds_read_b128 v[202:205], v152 offset:52224
	ds_read_b128 v[206:209], v152 offset:53248
	ds_read_b128 v[210:213], v152 offset:54272
	ds_read_b128 v[214:217], v152 offset:55296
	ds_read_b128 v[218:221], v152 offset:56320
	global_load_lds_dwordx4 v[146:147], off
	s_add_i32 m0, s26, 0x2000
	s_add_u32 s24, s24, 0xb0080
	v_lshl_add_u64 v[146:147], v[170:171], 0, s[8:9]
	s_addc_u32 s25, s25, 0
	s_add_i32 s26, s64, s34
	global_load_lds_dwordx4 v[146:147], off
	v_lshl_add_u64 v[146:147], s[24:25], 0, v[132:133]
	s_mov_b32 m0, s26
	s_nop 0
	global_load_lds_dwordx4 v[146:147], off
	v_lshl_add_u64 v[146:147], s[24:25], 0, v[136:137]
	s_add_i32 m0, s26, 0x2000
	s_nop 0
	global_load_lds_dwordx4 v[146:147], off
	v_lshl_add_u64 v[146:147], v[222:223], 0, s[8:9]
	s_mov_b32 m0, s42
	s_nop 0
	global_load_lds_dwordx4 v[146:147], off
	v_lshl_add_u64 v[146:147], v[224:225], 0, s[8:9]
	s_mov_b32 m0, s43
	s_nop 0
	global_load_lds_dwordx4 v[146:147], off
	s_waitcnt vmcnt(8)
	s_waitcnt lgkmcnt(0)
	s_barrier
	s_waitcnt lgkmcnt(0)
	v_mfma_f32_16x16x32_bf16 v[62:65], v[154:157], v[190:193], v[62:65]
	v_mfma_f32_16x16x32_bf16 v[58:61], v[162:165], v[190:193], v[58:61]
	v_mfma_f32_16x16x32_bf16 v[54:57], v[154:157], v[198:201], v[54:57]
	v_mfma_f32_16x16x32_bf16 v[46:49], v[162:165], v[198:201], v[46:49]
	v_mfma_f32_16x16x32_bf16 v[38:41], v[154:157], v[206:209], v[38:41]
	v_mfma_f32_16x16x32_bf16 v[30:33], v[162:165], v[206:209], v[30:33]
	v_mfma_f32_16x16x32_bf16 v[22:25], v[154:157], v[214:217], v[22:25]
	v_mfma_f32_16x16x32_bf16 v[14:17], v[162:165], v[214:217], v[14:17]
	v_mfma_f32_16x16x32_bf16 v[62:65], v[158:161], v[194:197], v[62:65]
	v_mfma_f32_16x16x32_bf16 v[58:61], v[166:169], v[194:197], v[58:61]
	v_mfma_f32_16x16x32_bf16 v[54:57], v[158:161], v[202:205], v[54:57]
	v_mfma_f32_16x16x32_bf16 v[46:49], v[166:169], v[202:205], v[46:49]
	v_mfma_f32_16x16x32_bf16 v[38:41], v[158:161], v[210:213], v[38:41]
	v_mfma_f32_16x16x32_bf16 v[30:33], v[166:169], v[210:213], v[30:33]
	v_mfma_f32_16x16x32_bf16 v[22:25], v[158:161], v[218:221], v[22:25]
	v_mfma_f32_16x16x32_bf16 v[14:17], v[166:169], v[218:221], v[14:17]
	v_mfma_f32_16x16x32_bf16 v[50:53], v[174:177], v[190:193], v[50:53]
	v_mfma_f32_16x16x32_bf16 v[42:45], v[182:185], v[190:193], v[42:45]
	v_mfma_f32_16x16x32_bf16 v[34:37], v[174:177], v[198:201], v[34:37]
	v_mfma_f32_16x16x32_bf16 v[26:29], v[182:185], v[198:201], v[26:29]
	v_mfma_f32_16x16x32_bf16 v[18:21], v[174:177], v[206:209], v[18:21]
	v_mfma_f32_16x16x32_bf16 v[10:13], v[182:185], v[206:209], v[10:13]
	v_mfma_f32_16x16x32_bf16 v[6:9], v[174:177], v[214:217], v[6:9]
	v_mfma_f32_16x16x32_bf16 v[2:5], v[182:185], v[214:217], v[2:5]
	v_mfma_f32_16x16x32_bf16 v[50:53], v[178:181], v[194:197], v[50:53]
	v_mfma_f32_16x16x32_bf16 v[42:45], v[186:189], v[194:197], v[42:45]
	v_mfma_f32_16x16x32_bf16 v[34:37], v[178:181], v[202:205], v[34:37]
	v_mfma_f32_16x16x32_bf16 v[26:29], v[186:189], v[202:205], v[26:29]
	v_mfma_f32_16x16x32_bf16 v[18:21], v[178:181], v[210:213], v[18:21]
	v_mfma_f32_16x16x32_bf16 v[10:13], v[186:189], v[210:213], v[10:13]
	v_mfma_f32_16x16x32_bf16 v[6:9], v[178:181], v[218:221], v[6:9]
	v_mfma_f32_16x16x32_bf16 v[2:5], v[186:189], v[218:221], v[2:5]
	s_barrier

; #define PG8_STAGE(bufoff, gbase, voff) do { _Pragma("unroll") for (int _i = 0; _i < 2; ++_i) \
;         __builtin_amdgcn_global_load_lds((const unsigned*)((const char*)(gbase) + (voff)[_i]), (PG8_LAS unsigned*)(lds + (bufoff) + ldsw + _i * 8192), 16, 0, 0); } while (0)
; #define PG8_LDA(dst, b, h) do { _Pragma("unroll") for (int m = 0; m < 4; ++m) _Pragma("unroll") for (int k = 0; k < 2; ++k) dst[m][k] = *(const PG8_LAS bf16x8*)(lds + PG8_SA(b, h) + aoff + m * 2048 + k * 1024); } while (0)
; #define PG8_LDB(dst, b, h) do { _Pragma("unroll") for (int n = 0; n < 2; ++n) _Pragma("unroll") for (int k = 0; k < 2; ++k) dst[n][k] = *(const PG8_LAS bf16x8*)(lds + PG8_SB(b, h) + boff + n * 2048 + k * 1024); } while (0)
; #define PG8_MMA(ai, bj, At, Bt) do { __builtin_amdgcn_s_setprio(1); _Pragma("unroll") for (int m = 0; m < 4; ++m) _Pragma("unroll") for (int n = 0; n < 2; ++n) _Pragma("unroll") for (int k = 0; k < 2; ++k) \
;         acc[ai][bj][m][n] = __builtin_amdgcn_mfma_f32_16x16x32_bf16(Bt[n][k], At[m][k], acc[ai][bj][m][n], 0, 0, 0); __builtin_amdgcn_s_setprio(0); } while (0)
; #define PG8_WAIT_V(n) asm volatile("s_waitcnt vmcnt(" #n ")" ::: "memory")
; #define PG8_BAR __builtin_amdgcn_s_barrier()
; template <class Epi, class Sched, bool ALIGN_EPI = false, bool SP2 = false>
; __device__ __forceinline__ void gemm_phase(PG8_LAS unsigned char* lds, const Gemm g, const Sched& S, const Epi& E) {
;     ...
;         for (int t = 0; t < nt; t += 2) {
;             const bool last = (t == nt - 2);
;             const char* a1 = cA + (size_t)(t + 1) * kstep;
;             const char* a2 = last ? nA : cA + (size_t)(t + 2) * kstep; const char* b2 = last ? nB : cB + (size_t)(t + 2) * kstep;
;             const char* a3 = a2 + kstep; const char* b3 = b2 + kstep;
;             if (last && has_next) S.a_ready(nxt);
;             if constexpr (SP2) {
;             PG8_LDB(B0, 0, 0); PG8_LDB(B1, 0, 1); PG8_SCHED; PG8_LDA(At, 0, 0); PG8_STAGE(PG8_SA(1, 1), a1 + hstep, voffA);
;             PG8_WAIT_V(8); PG8_WAIT_L(0); PG8_BAR; PG8_MMA(0, 0, At, B0); PG8_MMA(0, 1, At, B1); PG8_BAR; PG8_SCHED;
;             PG8_LDA(At, 0, 1); PG8_STAGE(PG8_SB(0, 0), b2, voffB); PG8_STAGE(PG8_SB(0, 1), b2 + hstep, voffB); PG8_STAGE(PG8_SA(0, 0), a2, voffA);
;             PG8_WAIT_V(8); PG8_WAIT_L(0); PG8_BAR; PG8_MMA(1, 0, At, B0); PG8_MMA(1, 1, At, B1); PG8_BAR; PG8_SCHED;
	s_add_i32 s62, s62, 2
	s_add_u32 s22, s22, 0x100
	s_addc_u32 s23, s23, 0
	s_add_u32 s60, s60, 0x100
	s_addc_u32 s61, s61, 0
.LBB0_1688:
	ds_read_b128 v[154:157], v150
	ds_read_b128 v[158:161], v150 offset:1024
	ds_read_b128 v[162:165], v150 offset:2048
	ds_read_b128 v[166:169], v150 offset:3072
	ds_read_b128 v[174:177], v151
	ds_read_b128 v[178:181], v151 offset:1024
	ds_read_b128 v[182:185], v151 offset:2048
	ds_read_b128 v[186:189], v151 offset:3072
	s_add_u32 s24, s22, 0xfff50080
	s_addc_u32 s25, s23, -1
	s_cmp_eq_u32 s62, 40
	s_cselect_b32 s27, s5, s25
	s_cselect_b32 s26, s4, s24
	s_cselect_b32 s25, s21, s61
	s_cselect_b32 s24, s20, s60
	v_lshl_add_u64 v[146:147], s[22:23], 0, v[138:139]
	s_add_i32 m0, s35, 0xc000
	ds_read_b128 v[190:193], v152
	ds_read_b128 v[194:197], v152 offset:1024
	ds_read_b128 v[198:201], v152 offset:2048
	ds_read_b128 v[202:205], v152 offset:3072
	ds_read_b128 v[206:209], v152 offset:4096
	ds_read_b128 v[210:213], v152 offset:5120
	ds_read_b128 v[214:217], v152 offset:6144
	ds_read_b128 v[218:221], v152 offset:7168
	global_load_lds_dwordx4 v[146:147], off
	v_lshl_add_u64 v[146:147], s[22:23], 0, v[140:141]
	s_add_i32 m0, s35, 0xe000
	s_nop 0
	global_load_lds_dwordx4 v[146:147], off
	s_waitcnt vmcnt(8)
	s_waitcnt lgkmcnt(0)
	s_barrier
	s_waitcnt lgkmcnt(0)
	v_mfma_f32_16x16x32_bf16 v[126:129], v[154:157], v[190:193], v[126:129]
	v_mfma_f32_16x16x32_bf16 v[122:125], v[162:165], v[190:193], v[122:125]
	v_mfma_f32_16x16x32_bf16 v[118:121], v[154:157], v[198:201], v[118:121]
	v_mfma_f32_16x16x32_bf16 v[110:113], v[162:165], v[198:201], v[110:113]
	v_mfma_f32_16x16x32_bf16 v[102:105], v[154:157], v[206:209], v[102:105]
	v_mfma_f32_16x16x32_bf16 v[94:97], v[162:165], v[206:209], v[94:97]
	v_mfma_f32_16x16x32_bf16 v[86:89], v[154:157], v[214:217], v[86:89]
	v_mfma_f32_16x16x32_bf16 v[78:81], v[162:165], v[214:217], v[78:81]
	v_mfma_f32_16x16x32_bf16 v[126:129], v[158:161], v[194:197], v[126:129]
	v_mfma_f32_16x16x32_bf16 v[122:125], v[166:169], v[194:197], v[122:125]
	v_mfma_f32_16x16x32_bf16 v[118:121], v[158:161], v[202:205], v[118:121]
	v_mfma_f32_16x16x32_bf16 v[110:113], v[166:169], v[202:205], v[110:113]
	v_mfma_f32_16x16x32_bf16 v[102:105], v[158:161], v[210:213], v[102:105]
	v_mfma_f32_16x16x32_bf16 v[94:97], v[166:169], v[210:213], v[94:97]
	v_mfma_f32_16x16x32_bf16 v[86:89], v[158:161], v[218:221], v[86:89]
	v_mfma_f32_16x16x32_bf16 v[78:81], v[166:169], v[218:221], v[78:81]
	v_mfma_f32_16x16x32_bf16 v[114:117], v[174:177], v[190:193], v[114:117]
	v_mfma_f32_16x16x32_bf16 v[106:109], v[182:185], v[190:193], v[106:109]
	v_mfma_f32_16x16x32_bf16 v[98:101], v[174:177], v[198:201], v[98:101]
	v_mfma_f32_16x16x32_bf16 v[90:93], v[182:185], v[198:201], v[90:93]
	v_mfma_f32_16x16x32_bf16 v[82:85], v[174:177], v[206:209], v[82:85]
	v_mfma_f32_16x16x32_bf16 v[74:77], v[182:185], v[206:209], v[74:77]
	v_mfma_f32_16x16x32_bf16 v[70:73], v[174:177], v[214:217], v[70:73]
	v_mfma_f32_16x16x32_bf16 v[66:69], v[182:185], v[214:217], v[66:69]
	v_mfma_f32_16x16x32_bf16 v[114:117], v[178:181], v[194:197], v[114:117]
	v_mfma_f32_16x16x32_bf16 v[106:109], v[186:189], v[194:197], v[106:109]
	v_mfma_f32_16x16x32_bf16 v[98:101], v[178:181], v[202:205], v[98:101]
	v_mfma_f32_16x16x32_bf16 v[90:93], v[186:189], v[202:205], v[90:93]
	v_mfma_f32_16x16x32_bf16 v[82:85], v[178:181], v[210:213], v[82:85]
	v_mfma_f32_16x16x32_bf16 v[74:77], v[186:189], v[210:213], v[74:77]
	v_mfma_f32_16x16x32_bf16 v[70:73], v[178:181], v[218:221], v[70:73]
	v_mfma_f32_16x16x32_bf16 v[66:69], v[186:189], v[218:221], v[66:69]
	s_barrier
	s_add_i32 s63, s48, s34
	v_lshl_add_u64 v[146:147], s[24:25], 0, v[132:133]
	s_mov_b32 m0, s63
	ds_read_b128 v[190:193], v152 offset:16384
	ds_read_b128 v[194:197], v152 offset:17408
	ds_read_b128 v[198:201], v152 offset:18432
	ds_read_b128 v[202:205], v152 offset:19456
	ds_read_b128 v[206:209], v152 offset:20480
	ds_read_b128 v[210:213], v152 offset:21504
	ds_read_b128 v[214:217], v152 offset:22528
	ds_read_b128 v[218:221], v152 offset:23552
	global_load_lds_dwordx4 v[146:147], off
	s_add_i32 m0, s63, 0x2000
	s_add_u32 s64, s24, 0xb0000
	v_lshl_add_u64 v[170:171], s[24:25], 0, v[136:137]
	s_addc_u32 s65, s25, 0
	s_add_i32 s63, s49, s34
	global_load_lds_dwordx4 v[170:171], off
	v_lshl_add_u64 v[222:223], s[64:65], 0, v[132:133]
	s_mov_b32 m0, s63
	v_lshl_add_u64 v[224:225], s[26:27], 0, v[134:135]
	global_load_lds_dwordx4 v[222:223], off
	v_lshl_add_u64 v[222:223], s[64:65], 0, v[136:137]
	s_add_i32 m0, s63, 0x2000
	s_nop 0
	global_load_lds_dwordx4 v[222:223], off
	v_lshl_add_u64 v[222:223], s[26:27], 0, v[130:131]
	s_mov_b32 m0, s35
	s_nop 0
	global_load_lds_dwordx4 v[222:223], off
	s_mov_b32 m0, s38
	s_nop 0
	global_load_lds_dwordx4 v[224:225], off
	s_waitcnt vmcnt(8)
	s_waitcnt lgkmcnt(0)
	s_barrier
; #define PG8_STAGE(bufoff, gbase, voff) do { _Pragma("unroll") for (int _i = 0; _i < 2; ++_i) \
;         __builtin_amdgcn_global_load_lds((const unsigned*)((const char*)(gbase) + (voff)[_i]), (PG8_LAS unsigned*)(lds + (bufoff) + ldsw + _i * 8192), 16, 0, 0); } while (0)
; #define PG8_LDA(dst, b, h) do { _Pragma("unroll") for (int m = 0; m < 4; ++m) _Pragma("unroll") for (int k = 0; k < 2; ++k) dst[m][k] = *(const PG8_LAS bf16x8*)(lds + PG8_SA(b, h) + aoff + m * 2048 + k * 1024); } while (0)
; #define PG8_LDB(dst, b, h) do { _Pragma("unroll") for (int n = 0; n < 2; ++n) _Pragma("unroll") for (int k = 0; k < 2; ++k) dst[n][k] = *(const PG8_LAS bf16x8*)(lds + PG8_SB(b, h) + boff + n * 2048 + k * 1024); } while (0)
; #define PG8_MMA(ai, bj, At, Bt) do { __builtin_amdgcn_s_setprio(1); _Pragma("unroll") for (int m = 0; m < 4; ++m) _Pragma("unroll") for (int n = 0; n < 2; ++n) _Pragma("unroll") for (int k = 0; k < 2; ++k) \
;         acc[ai][bj][m][n] = __builtin_amdgcn_mfma_f32_16x16x32_bf16(Bt[n][k], At[m][k], acc[ai][bj][m][n], 0, 0, 0); __builtin_amdgcn_s_setprio(0); } while (0)
; #define PG8_WAIT_V(n) asm volatile("s_waitcnt vmcnt(" #n ")" ::: "memory")
; #define PG8_WAIT_L(n) asm volatile("s_waitcnt lgkmcnt(" #n ")" ::: "memory")
; #define PG8_BAR __builtin_amdgcn_s_barrier()
; #define PG8_SCHED __builtin_amdgcn_sched_barrier(0)
; template <class Epi, class Sched, bool ALIGN_EPI = false, bool SP2 = false>
; __device__ __forceinline__ void gemm_phase(PG8_LAS unsigned char* lds, const Gemm g, const Sched& S, const Epi& E) {
;     ...
;             PG8_WAIT_V(8); PG8_WAIT_L(0); PG8_BAR; PG8_MMA(1, 0, At, B0); PG8_MMA(1, 1, At, B1); PG8_BAR; PG8_SCHED;
;             PG8_LDB(B0, 1, 0); PG8_LDB(B1, 1, 1); PG8_SCHED; PG8_LDA(At, 1, 0); PG8_STAGE(PG8_SA(0, 1), a2 + hstep, voffA);
;             PG8_WAIT_V(8); PG8_WAIT_L(0); PG8_BAR; PG8_MMA(0, 0, At, B0); PG8_MMA(0, 1, At, B1); PG8_BAR; PG8_SCHED;
	s_waitcnt lgkmcnt(0)
	v_mfma_f32_16x16x32_bf16 v[62:65], v[154:157], v[190:193], v[62:65]
	v_mfma_f32_16x16x32_bf16 v[58:61], v[162:165], v[190:193], v[58:61]
	v_mfma_f32_16x16x32_bf16 v[54:57], v[154:157], v[198:201], v[54:57]
	v_mfma_f32_16x16x32_bf16 v[46:49], v[162:165], v[198:201], v[46:49]
	v_mfma_f32_16x16x32_bf16 v[38:41], v[154:157], v[206:209], v[38:41]
	v_mfma_f32_16x16x32_bf16 v[30:33], v[162:165], v[206:209], v[30:33]
	v_mfma_f32_16x16x32_bf16 v[22:25], v[154:157], v[214:217], v[22:25]
	v_mfma_f32_16x16x32_bf16 v[14:17], v[162:165], v[214:217], v[14:17]
	v_mfma_f32_16x16x32_bf16 v[62:65], v[158:161], v[194:197], v[62:65]
	v_mfma_f32_16x16x32_bf16 v[58:61], v[166:169], v[194:197], v[58:61]
	v_mfma_f32_16x16x32_bf16 v[54:57], v[158:161], v[202:205], v[54:57]
	v_mfma_f32_16x16x32_bf16 v[46:49], v[166:169], v[202:205], v[46:49]
	v_mfma_f32_16x16x32_bf16 v[38:41], v[158:161], v[210:213], v[38:41]
	v_mfma_f32_16x16x32_bf16 v[30:33], v[166:169], v[210:213], v[30:33]
	v_mfma_f32_16x16x32_bf16 v[22:25], v[158:161], v[218:221], v[22:25]
	v_mfma_f32_16x16x32_bf16 v[14:17], v[166:169], v[218:221], v[14:17]
	v_mfma_f32_16x16x32_bf16 v[50:53], v[174:177], v[190:193], v[50:53]
	v_mfma_f32_16x16x32_bf16 v[42:45], v[182:185], v[190:193], v[42:45]
	v_mfma_f32_16x16x32_bf16 v[34:37], v[174:177], v[198:201], v[34:37]
	v_mfma_f32_16x16x32_bf16 v[26:29], v[182:185], v[198:201], v[26:29]
	v_mfma_f32_16x16x32_bf16 v[18:21], v[174:177], v[206:209], v[18:21]
	v_mfma_f32_16x16x32_bf16 v[10:13], v[182:185], v[206:209], v[10:13]
	v_mfma_f32_16x16x32_bf16 v[6:9], v[174:177], v[214:217], v[6:9]
	v_mfma_f32_16x16x32_bf16 v[2:5], v[182:185], v[214:217], v[2:5]
	v_mfma_f32_16x16x32_bf16 v[50:53], v[178:181], v[194:197], v[50:53]
	v_mfma_f32_16x16x32_bf16 v[42:45], v[186:189], v[194:197], v[42:45]
	v_mfma_f32_16x16x32_bf16 v[34:37], v[178:181], v[202:205], v[34:37]
	v_mfma_f32_16x16x32_bf16 v[26:29], v[186:189], v[202:205], v[26:29]
	v_mfma_f32_16x16x32_bf16 v[18:21], v[178:181], v[210:213], v[18:21]
	v_mfma_f32_16x16x32_bf16 v[10:13], v[186:189], v[210:213], v[10:13]
	v_mfma_f32_16x16x32_bf16 v[6:9], v[178:181], v[218:221], v[6:9]
	v_mfma_f32_16x16x32_bf16 v[2:5], v[186:189], v[218:221], v[2:5]
	s_barrier
	s_add_i32 s63, 0, 0x18000
	v_add_u32_e32 v153, s63, v148
	s_add_i32 s64, 0, 0x1c000
	ds_read_b128 v[154:157], v153
	ds_read_b128 v[158:161], v153 offset:1024
	ds_read_b128 v[162:165], v153 offset:2048
	ds_read_b128 v[166:169], v153 offset:3072
	v_add_u32_e32 v153, s64, v148
	ds_read_b128 v[174:177], v153
	ds_read_b128 v[178:181], v153 offset:1024
	ds_read_b128 v[182:185], v153 offset:2048
	ds_read_b128 v[186:189], v153 offset:3072
	s_add_u32 s26, s26, 0xb0000
	s_addc_u32 s27, s27, 0
	s_mov_b32 m0, s39
	v_lshl_add_u64 v[226:227], s[26:27], 0, v[130:131]
	ds_read_b128 v[190:193], v152 offset:32768
	ds_read_b128 v[194:197], v152 offset:33792
	ds_read_b128 v[198:201], v152 offset:34816
	ds_read_b128 v[202:205], v152 offset:35840
	ds_read_b128 v[206:209], v152 offset:36864
	ds_read_b128 v[210:213], v152 offset:37888
	ds_read_b128 v[214:217], v152 offset:38912
	ds_read_b128 v[218:221], v152 offset:39936
	global_load_lds_dwordx4 v[226:227], off
	v_lshl_add_u64 v[226:227], s[26:27], 0, v[134:135]
	s_mov_b32 m0, s40
	s_nop 0
	global_load_lds_dwordx4 v[226:227], off
	s_waitcnt vmcnt(8)
	s_waitcnt lgkmcnt(0)
	s_barrier
	s_waitcnt lgkmcnt(0)
	v_mfma_f32_16x16x32_bf16 v[126:129], v[154:157], v[190:193], v[126:129]
	v_mfma_f32_16x16x32_bf16 v[122:125], v[162:165], v[190:193], v[122:125]
	v_mfma_f32_16x16x32_bf16 v[118:121], v[154:157], v[198:201], v[118:121]
	v_mfma_f32_16x16x32_bf16 v[110:113], v[162:165], v[198:201], v[110:113]
	v_mfma_f32_16x16x32_bf16 v[102:105], v[154:157], v[206:209], v[102:105]
	v_mfma_f32_16x16x32_bf16 v[94:97], v[162:165], v[206:209], v[94:97]
	v_mfma_f32_16x16x32_bf16 v[86:89], v[154:157], v[214:217], v[86:89]
	v_mfma_f32_16x16x32_bf16 v[78:81], v[162:165], v[214:217], v[78:81]
	v_mfma_f32_16x16x32_bf16 v[126:129], v[158:161], v[194:197], v[126:129]
	v_mfma_f32_16x16x32_bf16 v[122:125], v[166:169], v[194:197], v[122:125]
	v_mfma_f32_16x16x32_bf16 v[118:121], v[158:161], v[202:205], v[118:121]
	v_mfma_f32_16x16x32_bf16 v[110:113], v[166:169], v[202:205], v[110:113]
	v_mfma_f32_16x16x32_bf16 v[102:105], v[158:161], v[210:213], v[102:105]
	v_mfma_f32_16x16x32_bf16 v[94:97], v[166:169], v[210:213], v[94:97]
	v_mfma_f32_16x16x32_bf16 v[86:89], v[158:161], v[218:221], v[86:89]
	v_mfma_f32_16x16x32_bf16 v[78:81], v[166:169], v[218:221], v[78:81]
	v_mfma_f32_16x16x32_bf16 v[114:117], v[174:177], v[190:193], v[114:117]
	v_mfma_f32_16x16x32_bf16 v[106:109], v[182:185], v[190:193], v[106:109]
	v_mfma_f32_16x16x32_bf16 v[98:101], v[174:177], v[198:201], v[98:101]
	v_mfma_f32_16x16x32_bf16 v[90:93], v[182:185], v[198:201], v[90:93]
	v_mfma_f32_16x16x32_bf16 v[82:85], v[174:177], v[206:209], v[82:85]
	v_mfma_f32_16x16x32_bf16 v[74:77], v[182:185], v[206:209], v[74:77]
	v_mfma_f32_16x16x32_bf16 v[70:73], v[174:177], v[214:217], v[70:73]
	v_mfma_f32_16x16x32_bf16 v[66:69], v[182:185], v[214:217], v[66:69]
	v_mfma_f32_16x16x32_bf16 v[114:117], v[178:181], v[194:197], v[114:117]
	v_mfma_f32_16x16x32_bf16 v[106:109], v[186:189], v[194:197], v[106:109]
	v_mfma_f32_16x16x32_bf16 v[98:101], v[178:181], v[202:205], v[98:101]
	v_mfma_f32_16x16x32_bf16 v[90:93], v[186:189], v[202:205], v[90:93]
	v_mfma_f32_16x16x32_bf16 v[82:85], v[178:181], v[210:213], v[82:85]
	v_mfma_f32_16x16x32_bf16 v[74:77], v[186:189], v[210:213], v[74:77]
	v_mfma_f32_16x16x32_bf16 v[70:73], v[178:181], v[218:221], v[70:73]
	v_mfma_f32_16x16x32_bf16 v[66:69], v[186:189], v[218:221], v[66:69]
	s_barrier
; #define PG8_STAGE(bufoff, gbase, voff) do { _Pragma("unroll") for (int _i = 0; _i < 2; ++_i) \
;         __builtin_amdgcn_global_load_lds((const unsigned*)((const char*)(gbase) + (voff)[_i]), (PG8_LAS unsigned*)(lds + (bufoff) + ldsw + _i * 8192), 16, 0, 0); } while (0)
; #define PG8_LDA(dst, b, h) do { _Pragma("unroll") for (int m = 0; m < 4; ++m) _Pragma("unroll") for (int k = 0; k < 2; ++k) dst[m][k] = *(const PG8_LAS bf16x8*)(lds + PG8_SA(b, h) + aoff + m * 2048 + k * 1024); } while (0)
; #define PG8_MMA(ai, bj, At, Bt) do { __builtin_amdgcn_s_setprio(1); _Pragma("unroll") for (int m = 0; m < 4; ++m) _Pragma("unroll") for (int n = 0; n < 2; ++n) _Pragma("unroll") for (int k = 0; k < 2; ++k) \
;         acc[ai][bj][m][n] = __builtin_amdgcn_mfma_f32_16x16x32_bf16(Bt[n][k], At[m][k], acc[ai][bj][m][n], 0, 0, 0); __builtin_amdgcn_s_setprio(0); } while (0)
; #define PG8_WAIT_V(n) asm volatile("s_waitcnt vmcnt(" #n ")" ::: "memory")
; #define PG8_WAIT_L(n) asm volatile("s_waitcnt lgkmcnt(" #n ")" ::: "memory")
; #define PG8_BAR __builtin_amdgcn_s_barrier()
; #define PG8_SCHED __builtin_amdgcn_sched_barrier(0)
; template <class Epi, class Sched, bool ALIGN_EPI = false, bool SP2 = false>
; __device__ __forceinline__ void gemm_phase(PG8_LAS unsigned char* lds, const Gemm g, const Sched& S, const Epi& E) {
;     ...
;             PG8_LDA(At, 1, 1); PG8_STAGE(PG8_SB(1, 0), b3, voffB); PG8_STAGE(PG8_SB(1, 1), b3 + hstep, voffB); PG8_STAGE(PG8_SA(1, 0), a3, voffA);
;             PG8_WAIT_V(8); PG8_WAIT_L(0); PG8_BAR; PG8_MMA(1, 0, At, B0); PG8_MMA(1, 1, At, B1); PG8_BAR; PG8_SCHED;
;     ...
;         if constexpr (ALIGN_EPI) { if (wr == 0) PG8_BAR; }
	s_add_i32 s26, s63, s34
	v_lshl_add_u64 v[146:147], v[146:147], 0, s[8:9]
	s_mov_b32 m0, s26
	ds_read_b128 v[190:193], v152 offset:49152
	ds_read_b128 v[194:197], v152 offset:50176
	ds_read_b128 v[198:201], v152 offset:51200
	ds_read_b128 v[202:205], v152 offset:52224
	ds_read_b128 v[206:209], v152 offset:53248
	ds_read_b128 v[210:213], v152 offset:54272
	ds_read_b128 v[214:217], v152 offset:55296
	ds_read_b128 v[218:221], v152 offset:56320
	global_load_lds_dwordx4 v[146:147], off
	s_add_i32 m0, s26, 0x2000
	s_add_u32 s24, s24, 0xb0080
	v_lshl_add_u64 v[146:147], v[170:171], 0, s[8:9]
	s_addc_u32 s25, s25, 0
	s_add_i32 s26, s64, s34
	global_load_lds_dwordx4 v[146:147], off
	v_lshl_add_u64 v[146:147], s[24:25], 0, v[132:133]
	s_mov_b32 m0, s26
	s_nop 0
	global_load_lds_dwordx4 v[146:147], off
	v_lshl_add_u64 v[146:147], s[24:25], 0, v[136:137]
	s_add_i32 m0, s26, 0x2000
	s_nop 0
	global_load_lds_dwordx4 v[146:147], off
	v_lshl_add_u64 v[146:147], v[222:223], 0, s[8:9]
	s_mov_b32 m0, s42
	s_nop 0
	global_load_lds_dwordx4 v[146:147], off
	v_lshl_add_u64 v[146:147], v[224:225], 0, s[8:9]
	s_mov_b32 m0, s43
	s_nop 0
	global_load_lds_dwordx4 v[146:147], off
	s_waitcnt vmcnt(8)
	s_waitcnt lgkmcnt(0)
	s_barrier
	s_waitcnt lgkmcnt(0)
	v_mfma_f32_16x16x32_bf16 v[62:65], v[154:157], v[190:193], v[62:65]
	v_mfma_f32_16x16x32_bf16 v[58:61], v[162:165], v[190:193], v[58:61]
	v_mfma_f32_16x16x32_bf16 v[54:57], v[154:157], v[198:201], v[54:57]
	v_mfma_f32_16x16x32_bf16 v[46:49], v[162:165], v[198:201], v[46:49]
	v_mfma_f32_16x16x32_bf16 v[38:41], v[154:157], v[206:209], v[38:41]
	v_mfma_f32_16x16x32_bf16 v[30:33], v[162:165], v[206:209], v[30:33]
	v_mfma_f32_16x16x32_bf16 v[22:25], v[154:157], v[214:217], v[22:25]
	v_mfma_f32_16x16x32_bf16 v[14:17], v[162:165], v[214:217], v[14:17]
	v_mfma_f32_16x16x32_bf16 v[62:65], v[158:161], v[194:197], v[62:65]
	v_mfma_f32_16x16x32_bf16 v[58:61], v[166:169], v[194:197], v[58:61]
	v_mfma_f32_16x16x32_bf16 v[54:57], v[158:161], v[202:205], v[54:57]
	v_mfma_f32_16x16x32_bf16 v[46:49], v[166:169], v[202:205], v[46:49]
	v_mfma_f32_16x16x32_bf16 v[38:41], v[158:161], v[210:213], v[38:41]
	v_mfma_f32_16x16x32_bf16 v[30:33], v[166:169], v[210:213], v[30:33]
	v_mfma_f32_16x16x32_bf16 v[22:25], v[158:161], v[218:221], v[22:25]
	v_mfma_f32_16x16x32_bf16 v[14:17], v[166:169], v[218:221], v[14:17]
	v_mfma_f32_16x16x32_bf16 v[50:53], v[174:177], v[190:193], v[50:53]
	v_mfma_f32_16x16x32_bf16 v[42:45], v[182:185], v[190:193], v[42:45]
	v_mfma_f32_16x16x32_bf16 v[34:37], v[174:177], v[198:201], v[34:37]
	v_mfma_f32_16x16x32_bf16 v[26:29], v[182:185], v[198:201], v[26:29]
	v_mfma_f32_16x16x32_bf16 v[18:21], v[174:177], v[206:209], v[18:21]
	v_mfma_f32_16x16x32_bf16 v[10:13], v[182:185], v[206:209], v[10:13]
	v_mfma_f32_16x16x32_bf16 v[6:9], v[174:177], v[214:217], v[6:9]
	v_mfma_f32_16x16x32_bf16 v[2:5], v[182:185], v[214:217], v[2:5]
	v_mfma_f32_16x16x32_bf16 v[50:53], v[178:181], v[194:197], v[50:53]
	v_mfma_f32_16x16x32_bf16 v[42:45], v[186:189], v[194:197], v[42:45]
	v_mfma_f32_16x16x32_bf16 v[34:37], v[178:181], v[202:205], v[34:37]
	v_mfma_f32_16x16x32_bf16 v[26:29], v[186:189], v[202:205], v[26:29]
	v_mfma_f32_16x16x32_bf16 v[18:21], v[178:181], v[210:213], v[18:21]
	v_mfma_f32_16x16x32_bf16 v[10:13], v[186:189], v[210:213], v[10:13]
	v_mfma_f32_16x16x32_bf16 v[6:9], v[178:181], v[218:221], v[6:9]
	v_mfma_f32_16x16x32_bf16 v[2:5], v[186:189], v[218:221], v[2:5]
	s_barrier
	s_add_i32 s62, s62, 2
	s_add_u32 s22, s22, 0x100
	s_addc_u32 s23, s23, 0
	s_add_u32 s60, s60, 0x100
	s_addc_u32 s61, s61, 0
	s_cmp_gt_u32 s62, 41
	s_cbranch_scc0 .LBB0_1688
	s_and_b64 vcc, exec, s[10:11]
	s_cbranch_vccz .LBB0_1691
	s_barrier
